# opt22 loop-edge edit: K-loop pointer increments moved from the back edge (load-segment head) to behind the last load segment's barrier; on the v051 stack
# baseline (speedup 1.0000x reference)
.Lmy_nobar2_2:
	ds_read_b128 v[152:155], v157
	ds_read_b128 v[160:163], v157 offset:1024
	ds_read_b128 v[164:167], v157 offset:2048
	ds_read_b128 v[168:171], v157 offset:3072
	ds_read_b128 v[172:175], v158
	ds_read_b128 v[176:179], v158 offset:1024
	ds_read_b128 v[180:183], v158 offset:2048
	ds_read_b128 v[184:187], v158 offset:3072
	s_add_u32 s34, s50, 0xfffc0080
	s_addc_u32 s35, s51, -1
	s_cmp_eq_u32 s86, 12
	s_cselect_b32 s55, s7, s35
	s_cselect_b32 s54, s8, s34
	s_cselect_b32 s53, s12, s41
	s_cselect_b32 s52, s13, s29
	v_lshl_add_u64 v[220:221], s[50:51], 0, v[144:145]
	s_add_i32 m0, s63, 0xc000
	ds_read_b128 v[188:191], v159
	ds_read_b128 v[192:195], v159 offset:1024
	ds_read_b128 v[196:199], v159 offset:2048
	ds_read_b128 v[200:203], v159 offset:3072
	ds_read_b128 v[204:207], v159 offset:4096
	ds_read_b128 v[208:211], v159 offset:5120
	ds_read_b128 v[212:215], v159 offset:6144
	ds_read_b128 v[216:219], v159 offset:7168
	global_load_lds_dwordx4 v[220:221], off
	v_lshl_add_u64 v[220:221], s[50:51], 0, v[146:147]
	s_add_i32 m0, s63, 0xe000
	s_nop 0
	global_load_lds_dwordx4 v[220:221], off
	s_waitcnt vmcnt(8)
	s_waitcnt lgkmcnt(0)
	s_barrier
	s_setprio 1
	s_waitcnt lgkmcnt(0)
	v_mfma_f32_16x16x32_bf16 v[124:127], v[152:155], v[188:191], 0
	v_mfma_f32_16x16x32_bf16 v[120:123], v[164:167], v[188:191], 0
	v_mfma_f32_16x16x32_bf16 v[108:111], v[152:155], v[196:199], 0
	v_mfma_f32_16x16x32_bf16 v[104:107], v[164:167], v[196:199], 0
	v_mfma_f32_16x16x32_bf16 v[92:95], v[152:155], v[204:207], 0
	v_mfma_f32_16x16x32_bf16 v[88:91], v[164:167], v[204:207], 0
	v_mfma_f32_16x16x32_bf16 v[76:79], v[152:155], v[212:215], 0
	v_mfma_f32_16x16x32_bf16 v[72:75], v[164:167], v[212:215], 0
	v_mfma_f32_16x16x32_bf16 v[124:127], v[160:163], v[192:195], v[124:127]
	v_mfma_f32_16x16x32_bf16 v[120:123], v[168:171], v[192:195], v[120:123]
	v_mfma_f32_16x16x32_bf16 v[108:111], v[160:163], v[200:203], v[108:111]
	v_mfma_f32_16x16x32_bf16 v[104:107], v[168:171], v[200:203], v[104:107]
	v_mfma_f32_16x16x32_bf16 v[92:95], v[160:163], v[208:211], v[92:95]
	v_mfma_f32_16x16x32_bf16 v[88:91], v[168:171], v[208:211], v[88:91]
	v_mfma_f32_16x16x32_bf16 v[76:79], v[160:163], v[216:219], v[76:79]
	v_mfma_f32_16x16x32_bf16 v[72:75], v[168:171], v[216:219], v[72:75]
	s_setprio 0
	s_setprio 1
	v_mfma_f32_16x16x32_bf16 v[116:119], v[172:175], v[188:191], 0
	v_mfma_f32_16x16x32_bf16 v[112:115], v[180:183], v[188:191], 0
	v_mfma_f32_16x16x32_bf16 v[100:103], v[172:175], v[196:199], 0
	v_mfma_f32_16x16x32_bf16 v[96:99], v[180:183], v[196:199], 0
	v_mfma_f32_16x16x32_bf16 v[84:87], v[172:175], v[204:207], 0
	v_mfma_f32_16x16x32_bf16 v[80:83], v[180:183], v[204:207], 0
	v_mfma_f32_16x16x32_bf16 v[68:71], v[172:175], v[212:215], 0
	v_mfma_f32_16x16x32_bf16 v[64:67], v[180:183], v[212:215], 0
	v_mfma_f32_16x16x32_bf16 v[116:119], v[176:179], v[192:195], v[116:119]
	v_mfma_f32_16x16x32_bf16 v[112:115], v[184:187], v[192:195], v[112:115]
	v_mfma_f32_16x16x32_bf16 v[100:103], v[176:179], v[200:203], v[100:103]
	v_mfma_f32_16x16x32_bf16 v[96:99], v[184:187], v[200:203], v[96:99]
	v_mfma_f32_16x16x32_bf16 v[84:87], v[176:179], v[208:211], v[84:87]
	v_mfma_f32_16x16x32_bf16 v[80:83], v[184:187], v[208:211], v[80:83]
	v_mfma_f32_16x16x32_bf16 v[68:71], v[176:179], v[216:219], v[68:71]
	v_mfma_f32_16x16x32_bf16 v[64:67], v[184:187], v[216:219], v[64:67]
	s_setprio 0
	s_barrier
	s_add_i32 s34, s82, s58
	v_lshl_add_u64 v[220:221], s[52:53], 0, v[136:137]
	s_mov_b32 m0, s34
	ds_read_b128 v[188:191], v159 offset:16384
	ds_read_b128 v[192:195], v159 offset:17408
	ds_read_b128 v[196:199], v159 offset:18432
	ds_read_b128 v[200:203], v159 offset:19456
	ds_read_b128 v[204:207], v159 offset:20480
	ds_read_b128 v[208:211], v159 offset:21504
	ds_read_b128 v[212:215], v159 offset:22528
	ds_read_b128 v[216:219], v159 offset:23552
	global_load_lds_dwordx4 v[220:221], off
	s_add_i32 m0, s34, 0x2000
	s_add_u32 s34, s52, 0x40000
	v_lshl_add_u64 v[222:223], s[52:53], 0, v[140:141]
	s_addc_u32 s35, s53, 0
	s_add_i32 s87, s83, s58
	global_load_lds_dwordx4 v[222:223], off
	v_lshl_add_u64 v[224:225], s[34:35], 0, v[136:137]
	s_mov_b32 m0, s87
	v_lshl_add_u64 v[226:227], s[54:55], 0, v[138:139]
	global_load_lds_dwordx4 v[224:225], off
	v_lshl_add_u64 v[224:225], s[34:35], 0, v[140:141]
	s_add_i32 m0, s87, 0x2000
	s_nop 0
	global_load_lds_dwordx4 v[224:225], off
	v_lshl_add_u64 v[224:225], s[54:55], 0, v[134:135]
	s_mov_b32 m0, s63
	s_nop 0
	global_load_lds_dwordx4 v[224:225], off
	s_mov_b32 m0, s64
	s_nop 0
	global_load_lds_dwordx4 v[226:227], off
	s_waitcnt vmcnt(8)
	s_waitcnt lgkmcnt(0)
	s_barrier
	s_setprio 1
	s_waitcnt lgkmcnt(0)
	v_mfma_f32_16x16x32_bf16 v[60:63], v[152:155], v[188:191], 0
	v_mfma_f32_16x16x32_bf16 v[56:59], v[164:167], v[188:191], 0
	v_mfma_f32_16x16x32_bf16 v[44:47], v[152:155], v[196:199], 0
	v_mfma_f32_16x16x32_bf16 v[40:43], v[164:167], v[196:199], 0
	v_mfma_f32_16x16x32_bf16 v[28:31], v[152:155], v[204:207], 0
	v_mfma_f32_16x16x32_bf16 v[24:27], v[164:167], v[204:207], 0
	v_mfma_f32_16x16x32_bf16 v[12:15], v[152:155], v[212:215], 0
	v_mfma_f32_16x16x32_bf16 v[8:11], v[164:167], v[212:215], 0
	v_mfma_f32_16x16x32_bf16 v[60:63], v[160:163], v[192:195], v[60:63]
	v_mfma_f32_16x16x32_bf16 v[56:59], v[168:171], v[192:195], v[56:59]
	v_mfma_f32_16x16x32_bf16 v[44:47], v[160:163], v[200:203], v[44:47]
	v_mfma_f32_16x16x32_bf16 v[40:43], v[168:171], v[200:203], v[40:43]
	v_mfma_f32_16x16x32_bf16 v[28:31], v[160:163], v[208:211], v[28:31]
	v_mfma_f32_16x16x32_bf16 v[24:27], v[168:171], v[208:211], v[24:27]
	v_mfma_f32_16x16x32_bf16 v[12:15], v[160:163], v[216:219], v[12:15]
	v_mfma_f32_16x16x32_bf16 v[8:11], v[168:171], v[216:219], v[8:11]
	s_setprio 0
	s_setprio 1
	v_mfma_f32_16x16x32_bf16 v[52:55], v[172:175], v[188:191], 0
	v_mfma_f32_16x16x32_bf16 v[48:51], v[180:183], v[188:191], 0
	v_mfma_f32_16x16x32_bf16 v[36:39], v[172:175], v[196:199], 0
	v_mfma_f32_16x16x32_bf16 v[32:35], v[180:183], v[196:199], 0
	v_mfma_f32_16x16x32_bf16 v[20:23], v[172:175], v[204:207], 0
	v_mfma_f32_16x16x32_bf16 v[16:19], v[180:183], v[204:207], 0
	v_mfma_f32_16x16x32_bf16 v[4:7], v[172:175], v[212:215], 0
	v_mfma_f32_16x16x32_bf16 v[0:3], v[180:183], v[212:215], 0
	v_mfma_f32_16x16x32_bf16 v[52:55], v[176:179], v[192:195], v[52:55]
	v_mfma_f32_16x16x32_bf16 v[48:51], v[184:187], v[192:195], v[48:51]
	v_mfma_f32_16x16x32_bf16 v[36:39], v[176:179], v[200:203], v[36:39]
	v_mfma_f32_16x16x32_bf16 v[32:35], v[184:187], v[200:203], v[32:35]
	v_mfma_f32_16x16x32_bf16 v[20:23], v[176:179], v[208:211], v[20:23]
	v_mfma_f32_16x16x32_bf16 v[16:19], v[184:187], v[208:211], v[16:19]
	v_mfma_f32_16x16x32_bf16 v[4:7], v[176:179], v[216:219], v[4:7]
	v_mfma_f32_16x16x32_bf16 v[0:3], v[184:187], v[216:219], v[0:3]
	s_setprio 0
	s_barrier
	s_add_i32 s87, 0, 0x18000
	v_add_u32_e32 v142, s87, v133
	s_add_i32 s88, 0, 0x1c000
	ds_read_b128 v[152:155], v142
	ds_read_b128 v[160:163], v142 offset:1024
	ds_read_b128 v[164:167], v142 offset:2048
	ds_read_b128 v[168:171], v142 offset:3072
	v_add_u32_e32 v142, s88, v133
	ds_read_b128 v[172:175], v142
	ds_read_b128 v[176:179], v142 offset:1024
	ds_read_b128 v[180:183], v142 offset:2048
	ds_read_b128 v[184:187], v142 offset:3072
	s_add_u32 s34, s54, 0x40000
	s_addc_u32 s35, s55, 0
	s_mov_b32 m0, s65
	v_lshl_add_u64 v[228:229], s[34:35], 0, v[134:135]
	ds_read_b128 v[188:191], v159 offset:32768
	ds_read_b128 v[192:195], v159 offset:33792
	ds_read_b128 v[196:199], v159 offset:34816
	ds_read_b128 v[200:203], v159 offset:35840
	ds_read_b128 v[204:207], v159 offset:36864
	ds_read_b128 v[208:211], v159 offset:37888
	ds_read_b128 v[212:215], v159 offset:38912
	ds_read_b128 v[216:219], v159 offset:39936
	global_load_lds_dwordx4 v[228:229], off
	v_lshl_add_u64 v[228:229], s[34:35], 0, v[138:139]
	s_mov_b32 m0, s66
	s_nop 0
	global_load_lds_dwordx4 v[228:229], off
	s_waitcnt vmcnt(8)
	s_waitcnt lgkmcnt(0)
	s_barrier
	s_setprio 1
	s_waitcnt lgkmcnt(0)
	v_mfma_f32_16x16x32_bf16 v[124:127], v[152:155], v[188:191], v[124:127]
	v_mfma_f32_16x16x32_bf16 v[120:123], v[164:167], v[188:191], v[120:123]
	v_mfma_f32_16x16x32_bf16 v[108:111], v[152:155], v[196:199], v[108:111]
	v_mfma_f32_16x16x32_bf16 v[104:107], v[164:167], v[196:199], v[104:107]
	v_mfma_f32_16x16x32_bf16 v[92:95], v[152:155], v[204:207], v[92:95]
	v_mfma_f32_16x16x32_bf16 v[88:91], v[164:167], v[204:207], v[88:91]
	v_mfma_f32_16x16x32_bf16 v[76:79], v[152:155], v[212:215], v[76:79]
	v_mfma_f32_16x16x32_bf16 v[72:75], v[164:167], v[212:215], v[72:75]
	v_mfma_f32_16x16x32_bf16 v[124:127], v[160:163], v[192:195], v[124:127]
	v_mfma_f32_16x16x32_bf16 v[120:123], v[168:171], v[192:195], v[120:123]
	v_mfma_f32_16x16x32_bf16 v[108:111], v[160:163], v[200:203], v[108:111]
	v_mfma_f32_16x16x32_bf16 v[104:107], v[168:171], v[200:203], v[104:107]
	v_mfma_f32_16x16x32_bf16 v[92:95], v[160:163], v[208:211], v[92:95]
	v_mfma_f32_16x16x32_bf16 v[88:91], v[168:171], v[208:211], v[88:91]
	v_mfma_f32_16x16x32_bf16 v[76:79], v[160:163], v[216:219], v[76:79]
	v_mfma_f32_16x16x32_bf16 v[72:75], v[168:171], v[216:219], v[72:75]
	s_setprio 0
	s_setprio 1
	v_mfma_f32_16x16x32_bf16 v[116:119], v[172:175], v[188:191], v[116:119]
	v_mfma_f32_16x16x32_bf16 v[112:115], v[180:183], v[188:191], v[112:115]
	v_mfma_f32_16x16x32_bf16 v[100:103], v[172:175], v[196:199], v[100:103]
	v_mfma_f32_16x16x32_bf16 v[96:99], v[180:183], v[196:199], v[96:99]
	v_mfma_f32_16x16x32_bf16 v[84:87], v[172:175], v[204:207], v[84:87]
	v_mfma_f32_16x16x32_bf16 v[80:83], v[180:183], v[204:207], v[80:83]
	v_mfma_f32_16x16x32_bf16 v[68:71], v[172:175], v[212:215], v[68:71]
	v_mfma_f32_16x16x32_bf16 v[64:67], v[180:183], v[212:215], v[64:67]
	v_mfma_f32_16x16x32_bf16 v[116:119], v[176:179], v[192:195], v[116:119]
	v_mfma_f32_16x16x32_bf16 v[112:115], v[184:187], v[192:195], v[112:115]
	v_mfma_f32_16x16x32_bf16 v[100:103], v[176:179], v[200:203], v[100:103]
	v_mfma_f32_16x16x32_bf16 v[96:99], v[184:187], v[200:203], v[96:99]
	v_mfma_f32_16x16x32_bf16 v[84:87], v[176:179], v[208:211], v[84:87]
	v_mfma_f32_16x16x32_bf16 v[80:83], v[184:187], v[208:211], v[80:83]
	v_mfma_f32_16x16x32_bf16 v[68:71], v[176:179], v[216:219], v[68:71]
	v_mfma_f32_16x16x32_bf16 v[64:67], v[184:187], v[216:219], v[64:67]
	s_setprio 0
	s_barrier
	s_add_i32 s34, s87, s58
	v_lshl_add_u64 v[220:221], v[220:221], 0, s[22:23]
	s_mov_b32 m0, s34
	ds_read_b128 v[188:191], v159 offset:49152
	ds_read_b128 v[192:195], v159 offset:50176
	ds_read_b128 v[196:199], v159 offset:51200
	ds_read_b128 v[200:203], v159 offset:52224
	ds_read_b128 v[204:207], v159 offset:53248
	ds_read_b128 v[208:211], v159 offset:54272
	ds_read_b128 v[212:215], v159 offset:55296
	ds_read_b128 v[216:219], v159 offset:56320
	global_load_lds_dwordx4 v[220:221], off
	s_add_i32 m0, s34, 0x2000
	s_add_u32 s34, s52, 0x40080
	v_lshl_add_u64 v[220:221], v[222:223], 0, s[22:23]
	s_addc_u32 s35, s53, 0
	s_add_i32 s52, s88, s58
	global_load_lds_dwordx4 v[220:221], off
	v_lshl_add_u64 v[220:221], s[34:35], 0, v[136:137]
	s_mov_b32 m0, s52
	s_nop 0
	global_load_lds_dwordx4 v[220:221], off
	v_lshl_add_u64 v[220:221], s[34:35], 0, v[140:141]
	s_add_i32 m0, s52, 0x2000
	s_nop 0
	global_load_lds_dwordx4 v[220:221], off
	v_lshl_add_u64 v[220:221], v[224:225], 0, s[22:23]
	s_mov_b32 m0, s79
	s_nop 0
	global_load_lds_dwordx4 v[220:221], off
	v_lshl_add_u64 v[220:221], v[226:227], 0, s[22:23]
	s_mov_b32 m0, s81
	s_nop 0
	global_load_lds_dwordx4 v[220:221], off
	s_waitcnt vmcnt(8)
	s_waitcnt lgkmcnt(0)
	s_barrier
	s_add_u32 s50, s50, 0x100
	s_addc_u32 s51, s51, 0
	s_add_u32 s29, s29, 0x100
	s_addc_u32 s41, s41, 0
	s_setprio 1
	s_waitcnt lgkmcnt(0)
	v_mfma_f32_16x16x32_bf16 v[60:63], v[152:155], v[188:191], v[60:63]
	v_mfma_f32_16x16x32_bf16 v[56:59], v[164:167], v[188:191], v[56:59]
	v_mfma_f32_16x16x32_bf16 v[44:47], v[152:155], v[196:199], v[44:47]
	v_mfma_f32_16x16x32_bf16 v[40:43], v[164:167], v[196:199], v[40:43]
	v_mfma_f32_16x16x32_bf16 v[28:31], v[152:155], v[204:207], v[28:31]
	v_mfma_f32_16x16x32_bf16 v[24:27], v[164:167], v[204:207], v[24:27]
	v_mfma_f32_16x16x32_bf16 v[12:15], v[152:155], v[212:215], v[12:15]
	v_mfma_f32_16x16x32_bf16 v[8:11], v[164:167], v[212:215], v[8:11]
	v_mfma_f32_16x16x32_bf16 v[60:63], v[160:163], v[192:195], v[60:63]
	v_mfma_f32_16x16x32_bf16 v[56:59], v[168:171], v[192:195], v[56:59]
	v_mfma_f32_16x16x32_bf16 v[44:47], v[160:163], v[200:203], v[44:47]
	v_mfma_f32_16x16x32_bf16 v[40:43], v[168:171], v[200:203], v[40:43]
	v_mfma_f32_16x16x32_bf16 v[28:31], v[160:163], v[208:211], v[28:31]
	v_mfma_f32_16x16x32_bf16 v[24:27], v[168:171], v[208:211], v[24:27]
	v_mfma_f32_16x16x32_bf16 v[12:15], v[160:163], v[216:219], v[12:15]
	v_mfma_f32_16x16x32_bf16 v[8:11], v[168:171], v[216:219], v[8:11]
	s_setprio 0
	s_setprio 1
	v_mfma_f32_16x16x32_bf16 v[52:55], v[172:175], v[188:191], v[52:55]
	v_mfma_f32_16x16x32_bf16 v[48:51], v[180:183], v[188:191], v[48:51]
	v_mfma_f32_16x16x32_bf16 v[36:39], v[172:175], v[196:199], v[36:39]
	v_mfma_f32_16x16x32_bf16 v[32:35], v[180:183], v[196:199], v[32:35]
	v_mfma_f32_16x16x32_bf16 v[20:23], v[172:175], v[204:207], v[20:23]
	v_mfma_f32_16x16x32_bf16 v[16:19], v[180:183], v[204:207], v[16:19]
	v_mfma_f32_16x16x32_bf16 v[4:7], v[172:175], v[212:215], v[4:7]
	v_mfma_f32_16x16x32_bf16 v[0:3], v[180:183], v[212:215], v[0:3]
	v_mfma_f32_16x16x32_bf16 v[52:55], v[176:179], v[192:195], v[52:55]
	v_mfma_f32_16x16x32_bf16 v[48:51], v[184:187], v[192:195], v[48:51]
	v_mfma_f32_16x16x32_bf16 v[36:39], v[176:179], v[200:203], v[36:39]
	v_mfma_f32_16x16x32_bf16 v[32:35], v[184:187], v[200:203], v[32:35]
	v_mfma_f32_16x16x32_bf16 v[20:23], v[176:179], v[208:211], v[20:23]
	v_mfma_f32_16x16x32_bf16 v[16:19], v[184:187], v[208:211], v[16:19]
	v_mfma_f32_16x16x32_bf16 v[4:7], v[176:179], v[216:219], v[4:7]
	v_mfma_f32_16x16x32_bf16 v[0:3], v[184:187], v[216:219], v[0:3]
	s_setprio 0
	s_barrier
	s_add_i32 s86, s86, 2
.LBB0_211:
	ds_read_b128 v[152:155], v157
	ds_read_b128 v[160:163], v157 offset:1024
	ds_read_b128 v[164:167], v157 offset:2048
	ds_read_b128 v[168:171], v157 offset:3072
	ds_read_b128 v[172:175], v158
	ds_read_b128 v[176:179], v158 offset:1024
	ds_read_b128 v[180:183], v158 offset:2048
	ds_read_b128 v[184:187], v158 offset:3072
	s_add_u32 s34, s50, 0xfffc0080
	s_addc_u32 s35, s51, -1
	s_cmp_eq_u32 s86, 12
	s_cselect_b32 s55, s7, s35
	s_cselect_b32 s54, s8, s34
	s_cselect_b32 s53, s12, s41
	s_cselect_b32 s52, s13, s29
	v_lshl_add_u64 v[220:221], s[50:51], 0, v[144:145]
	s_add_i32 m0, s63, 0xc000
	ds_read_b128 v[188:191], v159
	ds_read_b128 v[192:195], v159 offset:1024
	ds_read_b128 v[196:199], v159 offset:2048
	ds_read_b128 v[200:203], v159 offset:3072
	ds_read_b128 v[204:207], v159 offset:4096
	ds_read_b128 v[208:211], v159 offset:5120
	ds_read_b128 v[212:215], v159 offset:6144
	ds_read_b128 v[216:219], v159 offset:7168
	global_load_lds_dwordx4 v[220:221], off
	v_lshl_add_u64 v[220:221], s[50:51], 0, v[146:147]
	s_add_i32 m0, s63, 0xe000
	s_nop 0
	global_load_lds_dwordx4 v[220:221], off
	s_waitcnt vmcnt(8)
	s_waitcnt lgkmcnt(0)
	s_barrier
	s_setprio 1
	s_waitcnt lgkmcnt(0)
	v_mfma_f32_16x16x32_bf16 v[124:127], v[152:155], v[188:191], v[124:127]
	v_mfma_f32_16x16x32_bf16 v[120:123], v[164:167], v[188:191], v[120:123]
	v_mfma_f32_16x16x32_bf16 v[108:111], v[152:155], v[196:199], v[108:111]
	v_mfma_f32_16x16x32_bf16 v[104:107], v[164:167], v[196:199], v[104:107]
	v_mfma_f32_16x16x32_bf16 v[92:95], v[152:155], v[204:207], v[92:95]
	v_mfma_f32_16x16x32_bf16 v[88:91], v[164:167], v[204:207], v[88:91]
	v_mfma_f32_16x16x32_bf16 v[76:79], v[152:155], v[212:215], v[76:79]
	v_mfma_f32_16x16x32_bf16 v[72:75], v[164:167], v[212:215], v[72:75]
	v_mfma_f32_16x16x32_bf16 v[124:127], v[160:163], v[192:195], v[124:127]
	v_mfma_f32_16x16x32_bf16 v[120:123], v[168:171], v[192:195], v[120:123]
	v_mfma_f32_16x16x32_bf16 v[108:111], v[160:163], v[200:203], v[108:111]
	v_mfma_f32_16x16x32_bf16 v[104:107], v[168:171], v[200:203], v[104:107]
	v_mfma_f32_16x16x32_bf16 v[92:95], v[160:163], v[208:211], v[92:95]
	v_mfma_f32_16x16x32_bf16 v[88:91], v[168:171], v[208:211], v[88:91]
	v_mfma_f32_16x16x32_bf16 v[76:79], v[160:163], v[216:219], v[76:79]
	v_mfma_f32_16x16x32_bf16 v[72:75], v[168:171], v[216:219], v[72:75]
	s_setprio 0
	s_setprio 1
	v_mfma_f32_16x16x32_bf16 v[116:119], v[172:175], v[188:191], v[116:119]
	v_mfma_f32_16x16x32_bf16 v[112:115], v[180:183], v[188:191], v[112:115]
	v_mfma_f32_16x16x32_bf16 v[100:103], v[172:175], v[196:199], v[100:103]
	v_mfma_f32_16x16x32_bf16 v[96:99], v[180:183], v[196:199], v[96:99]
	v_mfma_f32_16x16x32_bf16 v[84:87], v[172:175], v[204:207], v[84:87]
	v_mfma_f32_16x16x32_bf16 v[80:83], v[180:183], v[204:207], v[80:83]
	v_mfma_f32_16x16x32_bf16 v[68:71], v[172:175], v[212:215], v[68:71]
	v_mfma_f32_16x16x32_bf16 v[64:67], v[180:183], v[212:215], v[64:67]
	v_mfma_f32_16x16x32_bf16 v[116:119], v[176:179], v[192:195], v[116:119]
	v_mfma_f32_16x16x32_bf16 v[112:115], v[184:187], v[192:195], v[112:115]
	v_mfma_f32_16x16x32_bf16 v[100:103], v[176:179], v[200:203], v[100:103]
	v_mfma_f32_16x16x32_bf16 v[96:99], v[184:187], v[200:203], v[96:99]
	v_mfma_f32_16x16x32_bf16 v[84:87], v[176:179], v[208:211], v[84:87]
	v_mfma_f32_16x16x32_bf16 v[80:83], v[184:187], v[208:211], v[80:83]
	v_mfma_f32_16x16x32_bf16 v[68:71], v[176:179], v[216:219], v[68:71]
	v_mfma_f32_16x16x32_bf16 v[64:67], v[184:187], v[216:219], v[64:67]
	s_setprio 0
	s_barrier
	s_add_i32 s34, s82, s58
	v_lshl_add_u64 v[220:221], s[52:53], 0, v[136:137]
	s_mov_b32 m0, s34
	ds_read_b128 v[188:191], v159 offset:16384
	ds_read_b128 v[192:195], v159 offset:17408
	ds_read_b128 v[196:199], v159 offset:18432
	ds_read_b128 v[200:203], v159 offset:19456
	ds_read_b128 v[204:207], v159 offset:20480
	ds_read_b128 v[208:211], v159 offset:21504
	ds_read_b128 v[212:215], v159 offset:22528
	ds_read_b128 v[216:219], v159 offset:23552
	global_load_lds_dwordx4 v[220:221], off
	s_add_i32 m0, s34, 0x2000
	s_add_u32 s34, s52, 0x40000
	v_lshl_add_u64 v[222:223], s[52:53], 0, v[140:141]
	s_addc_u32 s35, s53, 0
	s_add_i32 s87, s83, s58
	global_load_lds_dwordx4 v[222:223], off
	v_lshl_add_u64 v[224:225], s[34:35], 0, v[136:137]
	s_mov_b32 m0, s87
	v_lshl_add_u64 v[226:227], s[54:55], 0, v[138:139]
	global_load_lds_dwordx4 v[224:225], off
	v_lshl_add_u64 v[224:225], s[34:35], 0, v[140:141]
	s_add_i32 m0, s87, 0x2000
	s_nop 0
	global_load_lds_dwordx4 v[224:225], off
	v_lshl_add_u64 v[224:225], s[54:55], 0, v[134:135]
	s_mov_b32 m0, s63
	s_nop 0
	global_load_lds_dwordx4 v[224:225], off
	s_mov_b32 m0, s64
	s_nop 0
	global_load_lds_dwordx4 v[226:227], off
	s_waitcnt vmcnt(8)
	s_waitcnt lgkmcnt(0)
	s_barrier
	s_setprio 1
	s_waitcnt lgkmcnt(0)
	v_mfma_f32_16x16x32_bf16 v[60:63], v[152:155], v[188:191], v[60:63]
	v_mfma_f32_16x16x32_bf16 v[56:59], v[164:167], v[188:191], v[56:59]
	v_mfma_f32_16x16x32_bf16 v[44:47], v[152:155], v[196:199], v[44:47]
	v_mfma_f32_16x16x32_bf16 v[40:43], v[164:167], v[196:199], v[40:43]
	v_mfma_f32_16x16x32_bf16 v[28:31], v[152:155], v[204:207], v[28:31]
	v_mfma_f32_16x16x32_bf16 v[24:27], v[164:167], v[204:207], v[24:27]
	v_mfma_f32_16x16x32_bf16 v[12:15], v[152:155], v[212:215], v[12:15]
	v_mfma_f32_16x16x32_bf16 v[8:11], v[164:167], v[212:215], v[8:11]
	v_mfma_f32_16x16x32_bf16 v[60:63], v[160:163], v[192:195], v[60:63]
	v_mfma_f32_16x16x32_bf16 v[56:59], v[168:171], v[192:195], v[56:59]
	v_mfma_f32_16x16x32_bf16 v[44:47], v[160:163], v[200:203], v[44:47]
	v_mfma_f32_16x16x32_bf16 v[40:43], v[168:171], v[200:203], v[40:43]
	v_mfma_f32_16x16x32_bf16 v[28:31], v[160:163], v[208:211], v[28:31]
	v_mfma_f32_16x16x32_bf16 v[24:27], v[168:171], v[208:211], v[24:27]
	v_mfma_f32_16x16x32_bf16 v[12:15], v[160:163], v[216:219], v[12:15]
	v_mfma_f32_16x16x32_bf16 v[8:11], v[168:171], v[216:219], v[8:11]
	s_setprio 0
	s_setprio 1
	v_mfma_f32_16x16x32_bf16 v[52:55], v[172:175], v[188:191], v[52:55]
	v_mfma_f32_16x16x32_bf16 v[48:51], v[180:183], v[188:191], v[48:51]
	v_mfma_f32_16x16x32_bf16 v[36:39], v[172:175], v[196:199], v[36:39]
	v_mfma_f32_16x16x32_bf16 v[32:35], v[180:183], v[196:199], v[32:35]
	v_mfma_f32_16x16x32_bf16 v[20:23], v[172:175], v[204:207], v[20:23]
	v_mfma_f32_16x16x32_bf16 v[16:19], v[180:183], v[204:207], v[16:19]
	v_mfma_f32_16x16x32_bf16 v[4:7], v[172:175], v[212:215], v[4:7]
	v_mfma_f32_16x16x32_bf16 v[0:3], v[180:183], v[212:215], v[0:3]
	v_mfma_f32_16x16x32_bf16 v[52:55], v[176:179], v[192:195], v[52:55]
	v_mfma_f32_16x16x32_bf16 v[48:51], v[184:187], v[192:195], v[48:51]
	v_mfma_f32_16x16x32_bf16 v[36:39], v[176:179], v[200:203], v[36:39]
	v_mfma_f32_16x16x32_bf16 v[32:35], v[184:187], v[200:203], v[32:35]
	v_mfma_f32_16x16x32_bf16 v[20:23], v[176:179], v[208:211], v[20:23]
	v_mfma_f32_16x16x32_bf16 v[16:19], v[184:187], v[208:211], v[16:19]
	v_mfma_f32_16x16x32_bf16 v[4:7], v[176:179], v[216:219], v[4:7]
	v_mfma_f32_16x16x32_bf16 v[0:3], v[184:187], v[216:219], v[0:3]
	s_setprio 0
	s_barrier
	s_add_i32 s87, 0, 0x18000
	v_add_u32_e32 v142, s87, v133
	s_add_i32 s88, 0, 0x1c000
	ds_read_b128 v[152:155], v142
	ds_read_b128 v[160:163], v142 offset:1024
	ds_read_b128 v[164:167], v142 offset:2048
	ds_read_b128 v[168:171], v142 offset:3072
	v_add_u32_e32 v142, s88, v133
	ds_read_b128 v[172:175], v142
	ds_read_b128 v[176:179], v142 offset:1024
	ds_read_b128 v[180:183], v142 offset:2048
	ds_read_b128 v[184:187], v142 offset:3072
	s_add_u32 s34, s54, 0x40000
	s_addc_u32 s35, s55, 0
	s_mov_b32 m0, s65
	v_lshl_add_u64 v[228:229], s[34:35], 0, v[134:135]
	ds_read_b128 v[188:191], v159 offset:32768
	ds_read_b128 v[192:195], v159 offset:33792
	ds_read_b128 v[196:199], v159 offset:34816
	ds_read_b128 v[200:203], v159 offset:35840
	ds_read_b128 v[204:207], v159 offset:36864
	ds_read_b128 v[208:211], v159 offset:37888
	ds_read_b128 v[212:215], v159 offset:38912
	ds_read_b128 v[216:219], v159 offset:39936
	global_load_lds_dwordx4 v[228:229], off
	v_lshl_add_u64 v[228:229], s[34:35], 0, v[138:139]
	s_mov_b32 m0, s66
	s_nop 0
	global_load_lds_dwordx4 v[228:229], off
	s_waitcnt vmcnt(8)
	s_waitcnt lgkmcnt(0)
	s_barrier
	s_setprio 1
	s_waitcnt lgkmcnt(0)
	v_mfma_f32_16x16x32_bf16 v[124:127], v[152:155], v[188:191], v[124:127]
	v_mfma_f32_16x16x32_bf16 v[120:123], v[164:167], v[188:191], v[120:123]
	v_mfma_f32_16x16x32_bf16 v[108:111], v[152:155], v[196:199], v[108:111]
	v_mfma_f32_16x16x32_bf16 v[104:107], v[164:167], v[196:199], v[104:107]
	v_mfma_f32_16x16x32_bf16 v[92:95], v[152:155], v[204:207], v[92:95]
	v_mfma_f32_16x16x32_bf16 v[88:91], v[164:167], v[204:207], v[88:91]
	v_mfma_f32_16x16x32_bf16 v[76:79], v[152:155], v[212:215], v[76:79]
	v_mfma_f32_16x16x32_bf16 v[72:75], v[164:167], v[212:215], v[72:75]
	v_mfma_f32_16x16x32_bf16 v[124:127], v[160:163], v[192:195], v[124:127]
	v_mfma_f32_16x16x32_bf16 v[120:123], v[168:171], v[192:195], v[120:123]
	v_mfma_f32_16x16x32_bf16 v[108:111], v[160:163], v[200:203], v[108:111]
	v_mfma_f32_16x16x32_bf16 v[104:107], v[168:171], v[200:203], v[104:107]
	v_mfma_f32_16x16x32_bf16 v[92:95], v[160:163], v[208:211], v[92:95]
	v_mfma_f32_16x16x32_bf16 v[88:91], v[168:171], v[208:211], v[88:91]
	v_mfma_f32_16x16x32_bf16 v[76:79], v[160:163], v[216:219], v[76:79]
	v_mfma_f32_16x16x32_bf16 v[72:75], v[168:171], v[216:219], v[72:75]
	s_setprio 0
	s_setprio 1
	v_mfma_f32_16x16x32_bf16 v[116:119], v[172:175], v[188:191], v[116:119]
	v_mfma_f32_16x16x32_bf16 v[112:115], v[180:183], v[188:191], v[112:115]
	v_mfma_f32_16x16x32_bf16 v[100:103], v[172:175], v[196:199], v[100:103]
	v_mfma_f32_16x16x32_bf16 v[96:99], v[180:183], v[196:199], v[96:99]
	v_mfma_f32_16x16x32_bf16 v[84:87], v[172:175], v[204:207], v[84:87]
	v_mfma_f32_16x16x32_bf16 v[80:83], v[180:183], v[204:207], v[80:83]
	v_mfma_f32_16x16x32_bf16 v[68:71], v[172:175], v[212:215], v[68:71]
	v_mfma_f32_16x16x32_bf16 v[64:67], v[180:183], v[212:215], v[64:67]
	v_mfma_f32_16x16x32_bf16 v[116:119], v[176:179], v[192:195], v[116:119]
	v_mfma_f32_16x16x32_bf16 v[112:115], v[184:187], v[192:195], v[112:115]
	v_mfma_f32_16x16x32_bf16 v[100:103], v[176:179], v[200:203], v[100:103]
	v_mfma_f32_16x16x32_bf16 v[96:99], v[184:187], v[200:203], v[96:99]
	v_mfma_f32_16x16x32_bf16 v[84:87], v[176:179], v[208:211], v[84:87]
	v_mfma_f32_16x16x32_bf16 v[80:83], v[184:187], v[208:211], v[80:83]
	v_mfma_f32_16x16x32_bf16 v[68:71], v[176:179], v[216:219], v[68:71]
	v_mfma_f32_16x16x32_bf16 v[64:67], v[184:187], v[216:219], v[64:67]
	s_setprio 0
	s_barrier
	s_add_i32 s34, s87, s58
	v_lshl_add_u64 v[220:221], v[220:221], 0, s[22:23]
	s_mov_b32 m0, s34
	ds_read_b128 v[188:191], v159 offset:49152
	ds_read_b128 v[192:195], v159 offset:50176
	ds_read_b128 v[196:199], v159 offset:51200
	ds_read_b128 v[200:203], v159 offset:52224
	ds_read_b128 v[204:207], v159 offset:53248
	ds_read_b128 v[208:211], v159 offset:54272
	ds_read_b128 v[212:215], v159 offset:55296
	ds_read_b128 v[216:219], v159 offset:56320
	global_load_lds_dwordx4 v[220:221], off
	s_add_i32 m0, s34, 0x2000
	s_add_u32 s34, s52, 0x40080
	v_lshl_add_u64 v[220:221], v[222:223], 0, s[22:23]
	s_addc_u32 s35, s53, 0
	s_add_i32 s52, s88, s58
	global_load_lds_dwordx4 v[220:221], off
	v_lshl_add_u64 v[220:221], s[34:35], 0, v[136:137]
	s_mov_b32 m0, s52
	s_nop 0
	global_load_lds_dwordx4 v[220:221], off
	v_lshl_add_u64 v[220:221], s[34:35], 0, v[140:141]
	s_add_i32 m0, s52, 0x2000
	s_nop 0
	global_load_lds_dwordx4 v[220:221], off
	v_lshl_add_u64 v[220:221], v[224:225], 0, s[22:23]
	s_mov_b32 m0, s79
	s_nop 0
	global_load_lds_dwordx4 v[220:221], off
	v_lshl_add_u64 v[220:221], v[226:227], 0, s[22:23]
	s_mov_b32 m0, s81
	s_nop 0
	global_load_lds_dwordx4 v[220:221], off
	s_waitcnt vmcnt(8)
	s_waitcnt lgkmcnt(0)
	s_barrier
	s_add_u32 s50, s50, 0x100
	s_addc_u32 s51, s51, 0
	s_add_u32 s29, s29, 0x100
	s_addc_u32 s41, s41, 0
	s_setprio 1
	s_waitcnt lgkmcnt(0)
	v_mfma_f32_16x16x32_bf16 v[60:63], v[152:155], v[188:191], v[60:63]
	v_mfma_f32_16x16x32_bf16 v[56:59], v[164:167], v[188:191], v[56:59]
	v_mfma_f32_16x16x32_bf16 v[44:47], v[152:155], v[196:199], v[44:47]
	v_mfma_f32_16x16x32_bf16 v[40:43], v[164:167], v[196:199], v[40:43]
	v_mfma_f32_16x16x32_bf16 v[28:31], v[152:155], v[204:207], v[28:31]
	v_mfma_f32_16x16x32_bf16 v[24:27], v[164:167], v[204:207], v[24:27]
	v_mfma_f32_16x16x32_bf16 v[12:15], v[152:155], v[212:215], v[12:15]
	v_mfma_f32_16x16x32_bf16 v[8:11], v[164:167], v[212:215], v[8:11]
	v_mfma_f32_16x16x32_bf16 v[60:63], v[160:163], v[192:195], v[60:63]
	v_mfma_f32_16x16x32_bf16 v[56:59], v[168:171], v[192:195], v[56:59]
	v_mfma_f32_16x16x32_bf16 v[44:47], v[160:163], v[200:203], v[44:47]
	v_mfma_f32_16x16x32_bf16 v[40:43], v[168:171], v[200:203], v[40:43]
	v_mfma_f32_16x16x32_bf16 v[28:31], v[160:163], v[208:211], v[28:31]
	v_mfma_f32_16x16x32_bf16 v[24:27], v[168:171], v[208:211], v[24:27]
	v_mfma_f32_16x16x32_bf16 v[12:15], v[160:163], v[216:219], v[12:15]
	v_mfma_f32_16x16x32_bf16 v[8:11], v[168:171], v[216:219], v[8:11]
	s_setprio 0
	s_setprio 1
	v_mfma_f32_16x16x32_bf16 v[52:55], v[172:175], v[188:191], v[52:55]
	v_mfma_f32_16x16x32_bf16 v[48:51], v[180:183], v[188:191], v[48:51]
	v_mfma_f32_16x16x32_bf16 v[36:39], v[172:175], v[196:199], v[36:39]
	v_mfma_f32_16x16x32_bf16 v[32:35], v[180:183], v[196:199], v[32:35]
	v_mfma_f32_16x16x32_bf16 v[20:23], v[172:175], v[204:207], v[20:23]
	v_mfma_f32_16x16x32_bf16 v[16:19], v[180:183], v[204:207], v[16:19]
	v_mfma_f32_16x16x32_bf16 v[4:7], v[172:175], v[212:215], v[4:7]
	v_mfma_f32_16x16x32_bf16 v[0:3], v[180:183], v[212:215], v[0:3]
	v_mfma_f32_16x16x32_bf16 v[52:55], v[176:179], v[192:195], v[52:55]
	v_mfma_f32_16x16x32_bf16 v[48:51], v[184:187], v[192:195], v[48:51]
	v_mfma_f32_16x16x32_bf16 v[36:39], v[176:179], v[200:203], v[36:39]
	v_mfma_f32_16x16x32_bf16 v[32:35], v[184:187], v[200:203], v[32:35]
	v_mfma_f32_16x16x32_bf16 v[20:23], v[176:179], v[208:211], v[20:23]
	v_mfma_f32_16x16x32_bf16 v[16:19], v[184:187], v[208:211], v[16:19]
	v_mfma_f32_16x16x32_bf16 v[4:7], v[176:179], v[216:219], v[4:7]
	v_mfma_f32_16x16x32_bf16 v[0:3], v[184:187], v[216:219], v[0:3]
	s_setprio 0
	s_cmp_eq_u32 s86, s98
	s_cbranch_scc1 .Lmy_nobar_2
	s_barrier
.Lmy_nobar_2:
	s_add_i32 s86, s86, 2
	s_cmp_gt_u32 s86, 13
	s_cbranch_scc0 .LBB0_211
	s_and_b64 vcc, exec, s[26:27]
	s_cbranch_vccz .LBB0_214
	s_nop 0

.Lmy_nobar2_4:
	ds_read_b128 v[148:151], v154
	ds_read_b128 v[160:163], v154 offset:1024
	ds_read_b128 v[164:167], v154 offset:2048
	ds_read_b128 v[168:171], v154 offset:3072
	ds_read_b128 v[172:175], v155
	ds_read_b128 v[176:179], v155 offset:1024
	ds_read_b128 v[180:183], v155 offset:2048
	ds_read_b128 v[184:187], v155 offset:3072
	s_add_u32 s34, s50, 0xfffc0080
	s_addc_u32 s35, s51, -1
	s_cmp_eq_u32 s85, 12
	s_cselect_b32 s55, s12, s35
	s_cselect_b32 s54, s13, s34
	s_cselect_b32 s53, s27, s77
	s_cselect_b32 s52, s29, s49
	v_lshl_add_u64 v[220:221], s[50:51], 0, v[140:141]
	s_add_i32 m0, s58, 0xc000
	ds_read_b128 v[188:191], v157
	ds_read_b128 v[192:195], v157 offset:1024
	ds_read_b128 v[196:199], v157 offset:2048
	ds_read_b128 v[200:203], v157 offset:3072
	ds_read_b128 v[204:207], v157 offset:4096
	ds_read_b128 v[208:211], v157 offset:5120
	ds_read_b128 v[212:215], v157 offset:6144
	ds_read_b128 v[216:219], v157 offset:7168
	global_load_lds_dwordx4 v[220:221], off
	v_lshl_add_u64 v[220:221], s[50:51], 0, v[142:143]
	s_add_i32 m0, s58, 0xe000
	s_nop 0
	global_load_lds_dwordx4 v[220:221], off
	s_waitcnt vmcnt(8)
	s_waitcnt lgkmcnt(0)
	s_barrier
	s_setprio 1
	s_waitcnt lgkmcnt(0)
	v_mfma_f32_16x16x32_bf16 v[124:127], v[148:151], v[188:191], 0
	v_mfma_f32_16x16x32_bf16 v[120:123], v[164:167], v[188:191], 0
	v_mfma_f32_16x16x32_bf16 v[108:111], v[148:151], v[196:199], 0
	v_mfma_f32_16x16x32_bf16 v[104:107], v[164:167], v[196:199], 0
	v_mfma_f32_16x16x32_bf16 v[92:95], v[148:151], v[204:207], 0
	v_mfma_f32_16x16x32_bf16 v[88:91], v[164:167], v[204:207], 0
	v_mfma_f32_16x16x32_bf16 v[76:79], v[148:151], v[212:215], 0
	v_mfma_f32_16x16x32_bf16 v[72:75], v[164:167], v[212:215], 0
	v_mfma_f32_16x16x32_bf16 v[124:127], v[160:163], v[192:195], v[124:127]
	v_mfma_f32_16x16x32_bf16 v[120:123], v[168:171], v[192:195], v[120:123]
	v_mfma_f32_16x16x32_bf16 v[108:111], v[160:163], v[200:203], v[108:111]
	v_mfma_f32_16x16x32_bf16 v[104:107], v[168:171], v[200:203], v[104:107]
	v_mfma_f32_16x16x32_bf16 v[92:95], v[160:163], v[208:211], v[92:95]
	v_mfma_f32_16x16x32_bf16 v[88:91], v[168:171], v[208:211], v[88:91]
	v_mfma_f32_16x16x32_bf16 v[76:79], v[160:163], v[216:219], v[76:79]
	v_mfma_f32_16x16x32_bf16 v[72:75], v[168:171], v[216:219], v[72:75]
	s_setprio 0
	s_setprio 1
	v_mfma_f32_16x16x32_bf16 v[116:119], v[172:175], v[188:191], 0
	v_mfma_f32_16x16x32_bf16 v[112:115], v[180:183], v[188:191], 0
	v_mfma_f32_16x16x32_bf16 v[100:103], v[172:175], v[196:199], 0
	v_mfma_f32_16x16x32_bf16 v[96:99], v[180:183], v[196:199], 0
	v_mfma_f32_16x16x32_bf16 v[84:87], v[172:175], v[204:207], 0
	v_mfma_f32_16x16x32_bf16 v[80:83], v[180:183], v[204:207], 0
	v_mfma_f32_16x16x32_bf16 v[68:71], v[172:175], v[212:215], 0
	v_mfma_f32_16x16x32_bf16 v[64:67], v[180:183], v[212:215], 0
	v_mfma_f32_16x16x32_bf16 v[116:119], v[176:179], v[192:195], v[116:119]
	v_mfma_f32_16x16x32_bf16 v[112:115], v[184:187], v[192:195], v[112:115]
	v_mfma_f32_16x16x32_bf16 v[100:103], v[176:179], v[200:203], v[100:103]
	v_mfma_f32_16x16x32_bf16 v[96:99], v[184:187], v[200:203], v[96:99]
	v_mfma_f32_16x16x32_bf16 v[84:87], v[176:179], v[208:211], v[84:87]
	v_mfma_f32_16x16x32_bf16 v[80:83], v[184:187], v[208:211], v[80:83]
	v_mfma_f32_16x16x32_bf16 v[68:71], v[176:179], v[216:219], v[68:71]
	v_mfma_f32_16x16x32_bf16 v[64:67], v[184:187], v[216:219], v[64:67]
	s_setprio 0
	s_barrier
	s_add_i32 s34, s82, s57
	v_lshl_add_u64 v[220:221], s[52:53], 0, v[134:135]
	s_mov_b32 m0, s34
	ds_read_b128 v[188:191], v157 offset:16384
	ds_read_b128 v[192:195], v157 offset:17408
	ds_read_b128 v[196:199], v157 offset:18432
	ds_read_b128 v[200:203], v157 offset:19456
	ds_read_b128 v[204:207], v157 offset:20480
	ds_read_b128 v[208:211], v157 offset:21504
	ds_read_b128 v[212:215], v157 offset:22528
	ds_read_b128 v[216:219], v157 offset:23552
	global_load_lds_dwordx4 v[220:221], off
	s_add_i32 m0, s34, 0x2000
	s_add_u32 s34, s52, 0x40000
	v_lshl_add_u64 v[222:223], s[52:53], 0, v[138:139]
	s_addc_u32 s35, s53, 0
	s_add_i32 s86, s83, s57
	global_load_lds_dwordx4 v[222:223], off
	v_lshl_add_u64 v[224:225], s[34:35], 0, v[134:135]
	s_mov_b32 m0, s86
	v_lshl_add_u64 v[226:227], s[54:55], 0, v[136:137]
	global_load_lds_dwordx4 v[224:225], off
	v_lshl_add_u64 v[224:225], s[34:35], 0, v[138:139]
	s_add_i32 m0, s86, 0x2000
	s_nop 0
	global_load_lds_dwordx4 v[224:225], off
	v_lshl_add_u64 v[224:225], s[54:55], 0, v[132:133]
	s_mov_b32 m0, s58
	s_nop 0
	global_load_lds_dwordx4 v[224:225], off
	s_mov_b32 m0, s59
	s_nop 0
	global_load_lds_dwordx4 v[226:227], off
	s_waitcnt vmcnt(8)
	s_waitcnt lgkmcnt(0)
	s_barrier
	s_setprio 1
	s_waitcnt lgkmcnt(0)
	v_mfma_f32_16x16x32_bf16 v[60:63], v[148:151], v[188:191], 0
	v_mfma_f32_16x16x32_bf16 v[56:59], v[164:167], v[188:191], 0
	v_mfma_f32_16x16x32_bf16 v[44:47], v[148:151], v[196:199], 0
	v_mfma_f32_16x16x32_bf16 v[40:43], v[164:167], v[196:199], 0
	v_mfma_f32_16x16x32_bf16 v[28:31], v[148:151], v[204:207], 0
	v_mfma_f32_16x16x32_bf16 v[24:27], v[164:167], v[204:207], 0
	v_mfma_f32_16x16x32_bf16 v[12:15], v[148:151], v[212:215], 0
	v_mfma_f32_16x16x32_bf16 v[8:11], v[164:167], v[212:215], 0
	v_mfma_f32_16x16x32_bf16 v[60:63], v[160:163], v[192:195], v[60:63]
	v_mfma_f32_16x16x32_bf16 v[56:59], v[168:171], v[192:195], v[56:59]
	v_mfma_f32_16x16x32_bf16 v[44:47], v[160:163], v[200:203], v[44:47]
	v_mfma_f32_16x16x32_bf16 v[40:43], v[168:171], v[200:203], v[40:43]
	v_mfma_f32_16x16x32_bf16 v[28:31], v[160:163], v[208:211], v[28:31]
	v_mfma_f32_16x16x32_bf16 v[24:27], v[168:171], v[208:211], v[24:27]
	v_mfma_f32_16x16x32_bf16 v[12:15], v[160:163], v[216:219], v[12:15]
	v_mfma_f32_16x16x32_bf16 v[8:11], v[168:171], v[216:219], v[8:11]
	s_setprio 0
	s_setprio 1
	v_mfma_f32_16x16x32_bf16 v[52:55], v[172:175], v[188:191], 0
	v_mfma_f32_16x16x32_bf16 v[48:51], v[180:183], v[188:191], 0
	v_mfma_f32_16x16x32_bf16 v[36:39], v[172:175], v[196:199], 0
	v_mfma_f32_16x16x32_bf16 v[32:35], v[180:183], v[196:199], 0
	v_mfma_f32_16x16x32_bf16 v[20:23], v[172:175], v[204:207], 0
	v_mfma_f32_16x16x32_bf16 v[16:19], v[180:183], v[204:207], 0
	v_mfma_f32_16x16x32_bf16 v[4:7], v[172:175], v[212:215], 0
	v_mfma_f32_16x16x32_bf16 v[0:3], v[180:183], v[212:215], 0
	v_mfma_f32_16x16x32_bf16 v[52:55], v[176:179], v[192:195], v[52:55]
	v_mfma_f32_16x16x32_bf16 v[48:51], v[184:187], v[192:195], v[48:51]
	v_mfma_f32_16x16x32_bf16 v[36:39], v[176:179], v[200:203], v[36:39]
	v_mfma_f32_16x16x32_bf16 v[32:35], v[184:187], v[200:203], v[32:35]
	v_mfma_f32_16x16x32_bf16 v[20:23], v[176:179], v[208:211], v[20:23]
	v_mfma_f32_16x16x32_bf16 v[16:19], v[184:187], v[208:211], v[16:19]
	v_mfma_f32_16x16x32_bf16 v[4:7], v[176:179], v[216:219], v[4:7]
	v_mfma_f32_16x16x32_bf16 v[0:3], v[184:187], v[216:219], v[0:3]
	s_setprio 0
	s_barrier
	s_add_i32 s86, 0, 0x18000
	v_add_u32_e32 v159, s86, v152
	s_add_i32 s87, 0, 0x1c000
	ds_read_b128 v[148:151], v159
	ds_read_b128 v[160:163], v159 offset:1024
	ds_read_b128 v[164:167], v159 offset:2048
	ds_read_b128 v[168:171], v159 offset:3072
	v_add_u32_e32 v159, s87, v152
	ds_read_b128 v[172:175], v159
	ds_read_b128 v[176:179], v159 offset:1024
	ds_read_b128 v[180:183], v159 offset:2048
	ds_read_b128 v[184:187], v159 offset:3072
	s_add_u32 s34, s54, 0x40000
	s_addc_u32 s35, s55, 0
	s_mov_b32 m0, s62
	v_lshl_add_u64 v[228:229], s[34:35], 0, v[132:133]
	ds_read_b128 v[188:191], v157 offset:32768
	ds_read_b128 v[192:195], v157 offset:33792
	ds_read_b128 v[196:199], v157 offset:34816
	ds_read_b128 v[200:203], v157 offset:35840
	ds_read_b128 v[204:207], v157 offset:36864
	ds_read_b128 v[208:211], v157 offset:37888
	ds_read_b128 v[212:215], v157 offset:38912
	ds_read_b128 v[216:219], v157 offset:39936
	global_load_lds_dwordx4 v[228:229], off
	v_lshl_add_u64 v[228:229], s[34:35], 0, v[136:137]
	s_mov_b32 m0, s63
	s_nop 0
	global_load_lds_dwordx4 v[228:229], off
	s_waitcnt vmcnt(8)
	s_waitcnt lgkmcnt(0)
	s_barrier
	s_setprio 1
	s_waitcnt lgkmcnt(0)
	v_mfma_f32_16x16x32_bf16 v[124:127], v[148:151], v[188:191], v[124:127]
	v_mfma_f32_16x16x32_bf16 v[120:123], v[164:167], v[188:191], v[120:123]
	v_mfma_f32_16x16x32_bf16 v[108:111], v[148:151], v[196:199], v[108:111]
	v_mfma_f32_16x16x32_bf16 v[104:107], v[164:167], v[196:199], v[104:107]
	v_mfma_f32_16x16x32_bf16 v[92:95], v[148:151], v[204:207], v[92:95]
	v_mfma_f32_16x16x32_bf16 v[88:91], v[164:167], v[204:207], v[88:91]
	v_mfma_f32_16x16x32_bf16 v[76:79], v[148:151], v[212:215], v[76:79]
	v_mfma_f32_16x16x32_bf16 v[72:75], v[164:167], v[212:215], v[72:75]
	v_mfma_f32_16x16x32_bf16 v[124:127], v[160:163], v[192:195], v[124:127]
	v_mfma_f32_16x16x32_bf16 v[120:123], v[168:171], v[192:195], v[120:123]
	v_mfma_f32_16x16x32_bf16 v[108:111], v[160:163], v[200:203], v[108:111]
	v_mfma_f32_16x16x32_bf16 v[104:107], v[168:171], v[200:203], v[104:107]
	v_mfma_f32_16x16x32_bf16 v[92:95], v[160:163], v[208:211], v[92:95]
	v_mfma_f32_16x16x32_bf16 v[88:91], v[168:171], v[208:211], v[88:91]
	v_mfma_f32_16x16x32_bf16 v[76:79], v[160:163], v[216:219], v[76:79]
	v_mfma_f32_16x16x32_bf16 v[72:75], v[168:171], v[216:219], v[72:75]
	s_setprio 0
	s_setprio 1
	v_mfma_f32_16x16x32_bf16 v[116:119], v[172:175], v[188:191], v[116:119]
	v_mfma_f32_16x16x32_bf16 v[112:115], v[180:183], v[188:191], v[112:115]
	v_mfma_f32_16x16x32_bf16 v[100:103], v[172:175], v[196:199], v[100:103]
	v_mfma_f32_16x16x32_bf16 v[96:99], v[180:183], v[196:199], v[96:99]
	v_mfma_f32_16x16x32_bf16 v[84:87], v[172:175], v[204:207], v[84:87]
	v_mfma_f32_16x16x32_bf16 v[80:83], v[180:183], v[204:207], v[80:83]
	v_mfma_f32_16x16x32_bf16 v[68:71], v[172:175], v[212:215], v[68:71]
	v_mfma_f32_16x16x32_bf16 v[64:67], v[180:183], v[212:215], v[64:67]
	v_mfma_f32_16x16x32_bf16 v[116:119], v[176:179], v[192:195], v[116:119]
	v_mfma_f32_16x16x32_bf16 v[112:115], v[184:187], v[192:195], v[112:115]
	v_mfma_f32_16x16x32_bf16 v[100:103], v[176:179], v[200:203], v[100:103]
	v_mfma_f32_16x16x32_bf16 v[96:99], v[184:187], v[200:203], v[96:99]
	v_mfma_f32_16x16x32_bf16 v[84:87], v[176:179], v[208:211], v[84:87]
	v_mfma_f32_16x16x32_bf16 v[80:83], v[184:187], v[208:211], v[80:83]
	v_mfma_f32_16x16x32_bf16 v[68:71], v[176:179], v[216:219], v[68:71]
	v_mfma_f32_16x16x32_bf16 v[64:67], v[184:187], v[216:219], v[64:67]
	s_setprio 0
	s_barrier
	s_add_i32 s34, s86, s57
	v_lshl_add_u64 v[220:221], v[220:221], 0, s[10:11]
	s_mov_b32 m0, s34
	ds_read_b128 v[188:191], v157 offset:49152
	ds_read_b128 v[192:195], v157 offset:50176
	ds_read_b128 v[196:199], v157 offset:51200
	ds_read_b128 v[200:203], v157 offset:52224
	ds_read_b128 v[204:207], v157 offset:53248
	ds_read_b128 v[208:211], v157 offset:54272
	ds_read_b128 v[212:215], v157 offset:55296
	ds_read_b128 v[216:219], v157 offset:56320
	global_load_lds_dwordx4 v[220:221], off
	s_add_i32 m0, s34, 0x2000
	s_add_u32 s34, s52, 0x40080
	v_lshl_add_u64 v[220:221], v[222:223], 0, s[10:11]
	s_addc_u32 s35, s53, 0
	s_add_i32 s52, s87, s57
	global_load_lds_dwordx4 v[220:221], off
	v_lshl_add_u64 v[220:221], s[34:35], 0, v[134:135]
	s_mov_b32 m0, s52
	s_nop 0
	global_load_lds_dwordx4 v[220:221], off
	v_lshl_add_u64 v[220:221], s[34:35], 0, v[138:139]
	s_add_i32 m0, s52, 0x2000
	s_nop 0
	global_load_lds_dwordx4 v[220:221], off
	v_lshl_add_u64 v[220:221], v[224:225], 0, s[10:11]
	s_mov_b32 m0, s65
	s_nop 0
	global_load_lds_dwordx4 v[220:221], off
	v_lshl_add_u64 v[220:221], v[226:227], 0, s[10:11]
	s_mov_b32 m0, s66
	s_nop 0
	global_load_lds_dwordx4 v[220:221], off
	s_waitcnt vmcnt(8)
	s_waitcnt lgkmcnt(0)
	s_barrier
	s_add_u32 s50, s50, 0x100
	s_addc_u32 s51, s51, 0
	s_add_u32 s49, s49, 0x100
	s_addc_u32 s77, s77, 0
	s_setprio 1
	s_waitcnt lgkmcnt(0)
	v_mfma_f32_16x16x32_bf16 v[60:63], v[148:151], v[188:191], v[60:63]
	v_mfma_f32_16x16x32_bf16 v[56:59], v[164:167], v[188:191], v[56:59]
	v_mfma_f32_16x16x32_bf16 v[44:47], v[148:151], v[196:199], v[44:47]
	v_mfma_f32_16x16x32_bf16 v[40:43], v[164:167], v[196:199], v[40:43]
	v_mfma_f32_16x16x32_bf16 v[28:31], v[148:151], v[204:207], v[28:31]
	v_mfma_f32_16x16x32_bf16 v[24:27], v[164:167], v[204:207], v[24:27]
	v_mfma_f32_16x16x32_bf16 v[12:15], v[148:151], v[212:215], v[12:15]
	v_mfma_f32_16x16x32_bf16 v[8:11], v[164:167], v[212:215], v[8:11]
	v_mfma_f32_16x16x32_bf16 v[60:63], v[160:163], v[192:195], v[60:63]
	v_mfma_f32_16x16x32_bf16 v[56:59], v[168:171], v[192:195], v[56:59]
	v_mfma_f32_16x16x32_bf16 v[44:47], v[160:163], v[200:203], v[44:47]
	v_mfma_f32_16x16x32_bf16 v[40:43], v[168:171], v[200:203], v[40:43]
	v_mfma_f32_16x16x32_bf16 v[28:31], v[160:163], v[208:211], v[28:31]
	v_mfma_f32_16x16x32_bf16 v[24:27], v[168:171], v[208:211], v[24:27]
	v_mfma_f32_16x16x32_bf16 v[12:15], v[160:163], v[216:219], v[12:15]
	v_mfma_f32_16x16x32_bf16 v[8:11], v[168:171], v[216:219], v[8:11]
	s_setprio 0
	s_setprio 1
	v_mfma_f32_16x16x32_bf16 v[52:55], v[172:175], v[188:191], v[52:55]
	v_mfma_f32_16x16x32_bf16 v[48:51], v[180:183], v[188:191], v[48:51]
	v_mfma_f32_16x16x32_bf16 v[36:39], v[172:175], v[196:199], v[36:39]
	v_mfma_f32_16x16x32_bf16 v[32:35], v[180:183], v[196:199], v[32:35]
	v_mfma_f32_16x16x32_bf16 v[20:23], v[172:175], v[204:207], v[20:23]
	v_mfma_f32_16x16x32_bf16 v[16:19], v[180:183], v[204:207], v[16:19]
	v_mfma_f32_16x16x32_bf16 v[4:7], v[172:175], v[212:215], v[4:7]
	v_mfma_f32_16x16x32_bf16 v[0:3], v[180:183], v[212:215], v[0:3]
	v_mfma_f32_16x16x32_bf16 v[52:55], v[176:179], v[192:195], v[52:55]
	v_mfma_f32_16x16x32_bf16 v[48:51], v[184:187], v[192:195], v[48:51]
	v_mfma_f32_16x16x32_bf16 v[36:39], v[176:179], v[200:203], v[36:39]
	v_mfma_f32_16x16x32_bf16 v[32:35], v[184:187], v[200:203], v[32:35]
	v_mfma_f32_16x16x32_bf16 v[20:23], v[176:179], v[208:211], v[20:23]
	v_mfma_f32_16x16x32_bf16 v[16:19], v[184:187], v[208:211], v[16:19]
	v_mfma_f32_16x16x32_bf16 v[4:7], v[176:179], v[216:219], v[4:7]
	v_mfma_f32_16x16x32_bf16 v[0:3], v[184:187], v[216:219], v[0:3]
	s_setprio 0
	s_barrier
	s_add_i32 s85, s85, 2
.LBB0_386:
	ds_read_b128 v[148:151], v154
	ds_read_b128 v[160:163], v154 offset:1024
	ds_read_b128 v[164:167], v154 offset:2048
	ds_read_b128 v[168:171], v154 offset:3072
	ds_read_b128 v[172:175], v155
	ds_read_b128 v[176:179], v155 offset:1024
	ds_read_b128 v[180:183], v155 offset:2048
	ds_read_b128 v[184:187], v155 offset:3072
	s_add_u32 s34, s50, 0xfffc0080
	s_addc_u32 s35, s51, -1
	s_cmp_eq_u32 s85, 12
	s_cselect_b32 s55, s12, s35
	s_cselect_b32 s54, s13, s34
	s_cselect_b32 s53, s27, s77
	s_cselect_b32 s52, s29, s49
	v_lshl_add_u64 v[220:221], s[50:51], 0, v[140:141]
	s_add_i32 m0, s58, 0xc000
	ds_read_b128 v[188:191], v157
	ds_read_b128 v[192:195], v157 offset:1024
	ds_read_b128 v[196:199], v157 offset:2048
	ds_read_b128 v[200:203], v157 offset:3072
	ds_read_b128 v[204:207], v157 offset:4096
	ds_read_b128 v[208:211], v157 offset:5120
	ds_read_b128 v[212:215], v157 offset:6144
	ds_read_b128 v[216:219], v157 offset:7168
	global_load_lds_dwordx4 v[220:221], off
	v_lshl_add_u64 v[220:221], s[50:51], 0, v[142:143]
	s_add_i32 m0, s58, 0xe000
	s_nop 0
	global_load_lds_dwordx4 v[220:221], off
	s_waitcnt vmcnt(8)
	s_waitcnt lgkmcnt(0)
	s_barrier
	s_setprio 1
	s_waitcnt lgkmcnt(0)
	v_mfma_f32_16x16x32_bf16 v[124:127], v[148:151], v[188:191], v[124:127]
	v_mfma_f32_16x16x32_bf16 v[120:123], v[164:167], v[188:191], v[120:123]
	v_mfma_f32_16x16x32_bf16 v[108:111], v[148:151], v[196:199], v[108:111]
	v_mfma_f32_16x16x32_bf16 v[104:107], v[164:167], v[196:199], v[104:107]
	v_mfma_f32_16x16x32_bf16 v[92:95], v[148:151], v[204:207], v[92:95]
	v_mfma_f32_16x16x32_bf16 v[88:91], v[164:167], v[204:207], v[88:91]
	v_mfma_f32_16x16x32_bf16 v[76:79], v[148:151], v[212:215], v[76:79]
	v_mfma_f32_16x16x32_bf16 v[72:75], v[164:167], v[212:215], v[72:75]
	v_mfma_f32_16x16x32_bf16 v[124:127], v[160:163], v[192:195], v[124:127]
	v_mfma_f32_16x16x32_bf16 v[120:123], v[168:171], v[192:195], v[120:123]
	v_mfma_f32_16x16x32_bf16 v[108:111], v[160:163], v[200:203], v[108:111]
	v_mfma_f32_16x16x32_bf16 v[104:107], v[168:171], v[200:203], v[104:107]
	v_mfma_f32_16x16x32_bf16 v[92:95], v[160:163], v[208:211], v[92:95]
	v_mfma_f32_16x16x32_bf16 v[88:91], v[168:171], v[208:211], v[88:91]
	v_mfma_f32_16x16x32_bf16 v[76:79], v[160:163], v[216:219], v[76:79]
	v_mfma_f32_16x16x32_bf16 v[72:75], v[168:171], v[216:219], v[72:75]
	s_setprio 0
	s_setprio 1
	v_mfma_f32_16x16x32_bf16 v[116:119], v[172:175], v[188:191], v[116:119]
	v_mfma_f32_16x16x32_bf16 v[112:115], v[180:183], v[188:191], v[112:115]
	v_mfma_f32_16x16x32_bf16 v[100:103], v[172:175], v[196:199], v[100:103]
	v_mfma_f32_16x16x32_bf16 v[96:99], v[180:183], v[196:199], v[96:99]
	v_mfma_f32_16x16x32_bf16 v[84:87], v[172:175], v[204:207], v[84:87]
	v_mfma_f32_16x16x32_bf16 v[80:83], v[180:183], v[204:207], v[80:83]
	v_mfma_f32_16x16x32_bf16 v[68:71], v[172:175], v[212:215], v[68:71]
	v_mfma_f32_16x16x32_bf16 v[64:67], v[180:183], v[212:215], v[64:67]
	v_mfma_f32_16x16x32_bf16 v[116:119], v[176:179], v[192:195], v[116:119]
	v_mfma_f32_16x16x32_bf16 v[112:115], v[184:187], v[192:195], v[112:115]
	v_mfma_f32_16x16x32_bf16 v[100:103], v[176:179], v[200:203], v[100:103]
	v_mfma_f32_16x16x32_bf16 v[96:99], v[184:187], v[200:203], v[96:99]
	v_mfma_f32_16x16x32_bf16 v[84:87], v[176:179], v[208:211], v[84:87]
	v_mfma_f32_16x16x32_bf16 v[80:83], v[184:187], v[208:211], v[80:83]
	v_mfma_f32_16x16x32_bf16 v[68:71], v[176:179], v[216:219], v[68:71]
	v_mfma_f32_16x16x32_bf16 v[64:67], v[184:187], v[216:219], v[64:67]
	s_setprio 0
	s_barrier
	s_add_i32 s34, s82, s57
	v_lshl_add_u64 v[220:221], s[52:53], 0, v[134:135]
	s_mov_b32 m0, s34
	ds_read_b128 v[188:191], v157 offset:16384
	ds_read_b128 v[192:195], v157 offset:17408
	ds_read_b128 v[196:199], v157 offset:18432
	ds_read_b128 v[200:203], v157 offset:19456
	ds_read_b128 v[204:207], v157 offset:20480
	ds_read_b128 v[208:211], v157 offset:21504
	ds_read_b128 v[212:215], v157 offset:22528
	ds_read_b128 v[216:219], v157 offset:23552
	global_load_lds_dwordx4 v[220:221], off
	s_add_i32 m0, s34, 0x2000
	s_add_u32 s34, s52, 0x40000
	v_lshl_add_u64 v[222:223], s[52:53], 0, v[138:139]
	s_addc_u32 s35, s53, 0
	s_add_i32 s86, s83, s57
	global_load_lds_dwordx4 v[222:223], off
	v_lshl_add_u64 v[224:225], s[34:35], 0, v[134:135]
	s_mov_b32 m0, s86
	v_lshl_add_u64 v[226:227], s[54:55], 0, v[136:137]
	global_load_lds_dwordx4 v[224:225], off
	v_lshl_add_u64 v[224:225], s[34:35], 0, v[138:139]
	s_add_i32 m0, s86, 0x2000
	s_nop 0
	global_load_lds_dwordx4 v[224:225], off
	v_lshl_add_u64 v[224:225], s[54:55], 0, v[132:133]
	s_mov_b32 m0, s58
	s_nop 0
	global_load_lds_dwordx4 v[224:225], off
	s_mov_b32 m0, s59
	s_nop 0
	global_load_lds_dwordx4 v[226:227], off
	s_waitcnt vmcnt(8)
	s_waitcnt lgkmcnt(0)
	s_barrier
	s_setprio 1
	s_waitcnt lgkmcnt(0)
	v_mfma_f32_16x16x32_bf16 v[60:63], v[148:151], v[188:191], v[60:63]
	v_mfma_f32_16x16x32_bf16 v[56:59], v[164:167], v[188:191], v[56:59]
	v_mfma_f32_16x16x32_bf16 v[44:47], v[148:151], v[196:199], v[44:47]
	v_mfma_f32_16x16x32_bf16 v[40:43], v[164:167], v[196:199], v[40:43]
	v_mfma_f32_16x16x32_bf16 v[28:31], v[148:151], v[204:207], v[28:31]
	v_mfma_f32_16x16x32_bf16 v[24:27], v[164:167], v[204:207], v[24:27]
	v_mfma_f32_16x16x32_bf16 v[12:15], v[148:151], v[212:215], v[12:15]
	v_mfma_f32_16x16x32_bf16 v[8:11], v[164:167], v[212:215], v[8:11]
	v_mfma_f32_16x16x32_bf16 v[60:63], v[160:163], v[192:195], v[60:63]
	v_mfma_f32_16x16x32_bf16 v[56:59], v[168:171], v[192:195], v[56:59]
	v_mfma_f32_16x16x32_bf16 v[44:47], v[160:163], v[200:203], v[44:47]
	v_mfma_f32_16x16x32_bf16 v[40:43], v[168:171], v[200:203], v[40:43]
	v_mfma_f32_16x16x32_bf16 v[28:31], v[160:163], v[208:211], v[28:31]
	v_mfma_f32_16x16x32_bf16 v[24:27], v[168:171], v[208:211], v[24:27]
	v_mfma_f32_16x16x32_bf16 v[12:15], v[160:163], v[216:219], v[12:15]
	v_mfma_f32_16x16x32_bf16 v[8:11], v[168:171], v[216:219], v[8:11]
	s_setprio 0
	s_setprio 1
	v_mfma_f32_16x16x32_bf16 v[52:55], v[172:175], v[188:191], v[52:55]
	v_mfma_f32_16x16x32_bf16 v[48:51], v[180:183], v[188:191], v[48:51]
	v_mfma_f32_16x16x32_bf16 v[36:39], v[172:175], v[196:199], v[36:39]
	v_mfma_f32_16x16x32_bf16 v[32:35], v[180:183], v[196:199], v[32:35]
	v_mfma_f32_16x16x32_bf16 v[20:23], v[172:175], v[204:207], v[20:23]
	v_mfma_f32_16x16x32_bf16 v[16:19], v[180:183], v[204:207], v[16:19]
	v_mfma_f32_16x16x32_bf16 v[4:7], v[172:175], v[212:215], v[4:7]
	v_mfma_f32_16x16x32_bf16 v[0:3], v[180:183], v[212:215], v[0:3]
	v_mfma_f32_16x16x32_bf16 v[52:55], v[176:179], v[192:195], v[52:55]
	v_mfma_f32_16x16x32_bf16 v[48:51], v[184:187], v[192:195], v[48:51]
	v_mfma_f32_16x16x32_bf16 v[36:39], v[176:179], v[200:203], v[36:39]
	v_mfma_f32_16x16x32_bf16 v[32:35], v[184:187], v[200:203], v[32:35]
	v_mfma_f32_16x16x32_bf16 v[20:23], v[176:179], v[208:211], v[20:23]
	v_mfma_f32_16x16x32_bf16 v[16:19], v[184:187], v[208:211], v[16:19]
	v_mfma_f32_16x16x32_bf16 v[4:7], v[176:179], v[216:219], v[4:7]
	v_mfma_f32_16x16x32_bf16 v[0:3], v[184:187], v[216:219], v[0:3]
	s_setprio 0
	s_barrier
	s_add_i32 s86, 0, 0x18000
	v_add_u32_e32 v159, s86, v152
	s_add_i32 s87, 0, 0x1c000
	ds_read_b128 v[148:151], v159
	ds_read_b128 v[160:163], v159 offset:1024
	ds_read_b128 v[164:167], v159 offset:2048
	ds_read_b128 v[168:171], v159 offset:3072
	v_add_u32_e32 v159, s87, v152
	ds_read_b128 v[172:175], v159
	ds_read_b128 v[176:179], v159 offset:1024
	ds_read_b128 v[180:183], v159 offset:2048
	ds_read_b128 v[184:187], v159 offset:3072
	s_add_u32 s34, s54, 0x40000
	s_addc_u32 s35, s55, 0
	s_mov_b32 m0, s62
	v_lshl_add_u64 v[228:229], s[34:35], 0, v[132:133]
	ds_read_b128 v[188:191], v157 offset:32768
	ds_read_b128 v[192:195], v157 offset:33792
	ds_read_b128 v[196:199], v157 offset:34816
	ds_read_b128 v[200:203], v157 offset:35840
	ds_read_b128 v[204:207], v157 offset:36864
	ds_read_b128 v[208:211], v157 offset:37888
	ds_read_b128 v[212:215], v157 offset:38912
	ds_read_b128 v[216:219], v157 offset:39936
	global_load_lds_dwordx4 v[228:229], off
	v_lshl_add_u64 v[228:229], s[34:35], 0, v[136:137]
	s_mov_b32 m0, s63
	s_nop 0
	global_load_lds_dwordx4 v[228:229], off
	s_waitcnt vmcnt(8)
	s_waitcnt lgkmcnt(0)
	s_barrier
	s_setprio 1
	s_waitcnt lgkmcnt(0)
	v_mfma_f32_16x16x32_bf16 v[124:127], v[148:151], v[188:191], v[124:127]
	v_mfma_f32_16x16x32_bf16 v[120:123], v[164:167], v[188:191], v[120:123]
	v_mfma_f32_16x16x32_bf16 v[108:111], v[148:151], v[196:199], v[108:111]
	v_mfma_f32_16x16x32_bf16 v[104:107], v[164:167], v[196:199], v[104:107]
	v_mfma_f32_16x16x32_bf16 v[92:95], v[148:151], v[204:207], v[92:95]
	v_mfma_f32_16x16x32_bf16 v[88:91], v[164:167], v[204:207], v[88:91]
	v_mfma_f32_16x16x32_bf16 v[76:79], v[148:151], v[212:215], v[76:79]
	v_mfma_f32_16x16x32_bf16 v[72:75], v[164:167], v[212:215], v[72:75]
	v_mfma_f32_16x16x32_bf16 v[124:127], v[160:163], v[192:195], v[124:127]
	v_mfma_f32_16x16x32_bf16 v[120:123], v[168:171], v[192:195], v[120:123]
	v_mfma_f32_16x16x32_bf16 v[108:111], v[160:163], v[200:203], v[108:111]
	v_mfma_f32_16x16x32_bf16 v[104:107], v[168:171], v[200:203], v[104:107]
	v_mfma_f32_16x16x32_bf16 v[92:95], v[160:163], v[208:211], v[92:95]
	v_mfma_f32_16x16x32_bf16 v[88:91], v[168:171], v[208:211], v[88:91]
	v_mfma_f32_16x16x32_bf16 v[76:79], v[160:163], v[216:219], v[76:79]
	v_mfma_f32_16x16x32_bf16 v[72:75], v[168:171], v[216:219], v[72:75]
	s_setprio 0
	s_setprio 1
	v_mfma_f32_16x16x32_bf16 v[116:119], v[172:175], v[188:191], v[116:119]
	v_mfma_f32_16x16x32_bf16 v[112:115], v[180:183], v[188:191], v[112:115]
	v_mfma_f32_16x16x32_bf16 v[100:103], v[172:175], v[196:199], v[100:103]
	v_mfma_f32_16x16x32_bf16 v[96:99], v[180:183], v[196:199], v[96:99]
	v_mfma_f32_16x16x32_bf16 v[84:87], v[172:175], v[204:207], v[84:87]
	v_mfma_f32_16x16x32_bf16 v[80:83], v[180:183], v[204:207], v[80:83]
	v_mfma_f32_16x16x32_bf16 v[68:71], v[172:175], v[212:215], v[68:71]
	v_mfma_f32_16x16x32_bf16 v[64:67], v[180:183], v[212:215], v[64:67]
	v_mfma_f32_16x16x32_bf16 v[116:119], v[176:179], v[192:195], v[116:119]
	v_mfma_f32_16x16x32_bf16 v[112:115], v[184:187], v[192:195], v[112:115]
	v_mfma_f32_16x16x32_bf16 v[100:103], v[176:179], v[200:203], v[100:103]
	v_mfma_f32_16x16x32_bf16 v[96:99], v[184:187], v[200:203], v[96:99]
	v_mfma_f32_16x16x32_bf16 v[84:87], v[176:179], v[208:211], v[84:87]
	v_mfma_f32_16x16x32_bf16 v[80:83], v[184:187], v[208:211], v[80:83]
	v_mfma_f32_16x16x32_bf16 v[68:71], v[176:179], v[216:219], v[68:71]
	v_mfma_f32_16x16x32_bf16 v[64:67], v[184:187], v[216:219], v[64:67]
	s_setprio 0
	s_barrier
	s_add_i32 s34, s86, s57
	v_lshl_add_u64 v[220:221], v[220:221], 0, s[10:11]
	s_mov_b32 m0, s34
	ds_read_b128 v[188:191], v157 offset:49152
	ds_read_b128 v[192:195], v157 offset:50176
	ds_read_b128 v[196:199], v157 offset:51200
	ds_read_b128 v[200:203], v157 offset:52224
	ds_read_b128 v[204:207], v157 offset:53248
	ds_read_b128 v[208:211], v157 offset:54272
	ds_read_b128 v[212:215], v157 offset:55296
	ds_read_b128 v[216:219], v157 offset:56320
	global_load_lds_dwordx4 v[220:221], off
	s_add_i32 m0, s34, 0x2000
	s_add_u32 s34, s52, 0x40080
	v_lshl_add_u64 v[220:221], v[222:223], 0, s[10:11]
	s_addc_u32 s35, s53, 0
	s_add_i32 s52, s87, s57
	global_load_lds_dwordx4 v[220:221], off
	v_lshl_add_u64 v[220:221], s[34:35], 0, v[134:135]
	s_mov_b32 m0, s52
	s_nop 0
	global_load_lds_dwordx4 v[220:221], off
	v_lshl_add_u64 v[220:221], s[34:35], 0, v[138:139]
	s_add_i32 m0, s52, 0x2000
	s_nop 0
	global_load_lds_dwordx4 v[220:221], off
	v_lshl_add_u64 v[220:221], v[224:225], 0, s[10:11]
	s_mov_b32 m0, s65
	s_nop 0
	global_load_lds_dwordx4 v[220:221], off
	v_lshl_add_u64 v[220:221], v[226:227], 0, s[10:11]
	s_mov_b32 m0, s66
	s_nop 0
	global_load_lds_dwordx4 v[220:221], off
	s_waitcnt vmcnt(8)
	s_waitcnt lgkmcnt(0)
	s_barrier
	s_add_u32 s50, s50, 0x100
	s_addc_u32 s51, s51, 0
	s_add_u32 s49, s49, 0x100
	s_addc_u32 s77, s77, 0
	s_setprio 1
	s_waitcnt lgkmcnt(0)
	v_mfma_f32_16x16x32_bf16 v[60:63], v[148:151], v[188:191], v[60:63]
	v_mfma_f32_16x16x32_bf16 v[56:59], v[164:167], v[188:191], v[56:59]
	v_mfma_f32_16x16x32_bf16 v[44:47], v[148:151], v[196:199], v[44:47]
	v_mfma_f32_16x16x32_bf16 v[40:43], v[164:167], v[196:199], v[40:43]
	v_mfma_f32_16x16x32_bf16 v[28:31], v[148:151], v[204:207], v[28:31]
	v_mfma_f32_16x16x32_bf16 v[24:27], v[164:167], v[204:207], v[24:27]
	v_mfma_f32_16x16x32_bf16 v[12:15], v[148:151], v[212:215], v[12:15]
	v_mfma_f32_16x16x32_bf16 v[8:11], v[164:167], v[212:215], v[8:11]
	v_mfma_f32_16x16x32_bf16 v[60:63], v[160:163], v[192:195], v[60:63]
	v_mfma_f32_16x16x32_bf16 v[56:59], v[168:171], v[192:195], v[56:59]
	v_mfma_f32_16x16x32_bf16 v[44:47], v[160:163], v[200:203], v[44:47]
	v_mfma_f32_16x16x32_bf16 v[40:43], v[168:171], v[200:203], v[40:43]
	v_mfma_f32_16x16x32_bf16 v[28:31], v[160:163], v[208:211], v[28:31]
	v_mfma_f32_16x16x32_bf16 v[24:27], v[168:171], v[208:211], v[24:27]
	v_mfma_f32_16x16x32_bf16 v[12:15], v[160:163], v[216:219], v[12:15]
	v_mfma_f32_16x16x32_bf16 v[8:11], v[168:171], v[216:219], v[8:11]
	s_setprio 0
	s_setprio 1
	v_mfma_f32_16x16x32_bf16 v[52:55], v[172:175], v[188:191], v[52:55]
	v_mfma_f32_16x16x32_bf16 v[48:51], v[180:183], v[188:191], v[48:51]
	v_mfma_f32_16x16x32_bf16 v[36:39], v[172:175], v[196:199], v[36:39]
	v_mfma_f32_16x16x32_bf16 v[32:35], v[180:183], v[196:199], v[32:35]
	v_mfma_f32_16x16x32_bf16 v[20:23], v[172:175], v[204:207], v[20:23]
	v_mfma_f32_16x16x32_bf16 v[16:19], v[180:183], v[204:207], v[16:19]
	v_mfma_f32_16x16x32_bf16 v[4:7], v[172:175], v[212:215], v[4:7]
	v_mfma_f32_16x16x32_bf16 v[0:3], v[180:183], v[212:215], v[0:3]
	v_mfma_f32_16x16x32_bf16 v[52:55], v[176:179], v[192:195], v[52:55]
	v_mfma_f32_16x16x32_bf16 v[48:51], v[184:187], v[192:195], v[48:51]
	v_mfma_f32_16x16x32_bf16 v[36:39], v[176:179], v[200:203], v[36:39]
	v_mfma_f32_16x16x32_bf16 v[32:35], v[184:187], v[200:203], v[32:35]
	v_mfma_f32_16x16x32_bf16 v[20:23], v[176:179], v[208:211], v[20:23]
	v_mfma_f32_16x16x32_bf16 v[16:19], v[184:187], v[208:211], v[16:19]
	v_mfma_f32_16x16x32_bf16 v[4:7], v[176:179], v[216:219], v[4:7]
	v_mfma_f32_16x16x32_bf16 v[0:3], v[184:187], v[216:219], v[0:3]
	s_setprio 0
	s_cmp_eq_u32 s85, s98
	s_cbranch_scc1 .Lmy_nobar_4
	s_barrier
.Lmy_nobar_4:
	s_add_i32 s85, s85, 2
	s_cmp_gt_u32 s85, 13
	s_cbranch_scc0 .LBB0_386
	s_and_b64 vcc, exec, s[22:23]
	s_cbranch_vccz .LBB0_389
	s_nop 0

.Lmy_nobar2_5:
	ds_read_b128 v[148:151], v155
	ds_read_b128 v[160:163], v155 offset:1024
	ds_read_b128 v[164:167], v155 offset:2048
	ds_read_b128 v[168:171], v155 offset:3072
	ds_read_b128 v[172:175], v157
	ds_read_b128 v[176:179], v157 offset:1024
	ds_read_b128 v[180:183], v157 offset:2048
	ds_read_b128 v[184:187], v157 offset:3072
	s_add_u32 s34, s42, 0xfffc0080
	s_addc_u32 s35, s43, -1
	s_cmp_eq_u32 s85, 12
	s_cselect_b32 s51, s23, s35
	s_cselect_b32 s50, s81, s34
	s_cselect_b32 s49, s11, s84
	s_cselect_b32 s48, s82, s83
	v_lshl_add_u64 v[220:221], s[42:43], 0, v[140:141]
	s_add_i32 m0, s41, 0xc000
	ds_read_b128 v[188:191], v158
	ds_read_b128 v[192:195], v158 offset:1024
	ds_read_b128 v[196:199], v158 offset:2048
	ds_read_b128 v[200:203], v158 offset:3072
	ds_read_b128 v[204:207], v158 offset:4096
	ds_read_b128 v[208:211], v158 offset:5120
	ds_read_b128 v[212:215], v158 offset:6144
	ds_read_b128 v[216:219], v158 offset:7168
	global_load_lds_dwordx4 v[220:221], off
	v_lshl_add_u64 v[220:221], s[42:43], 0, v[142:143]
	s_add_i32 m0, s41, 0xe000
	s_nop 0
	global_load_lds_dwordx4 v[220:221], off
	s_waitcnt vmcnt(8)
	s_waitcnt lgkmcnt(0)
	s_barrier
	s_setprio 1
	s_waitcnt lgkmcnt(0)
	v_mfma_f32_16x16x32_bf16 v[124:127], v[148:151], v[188:191], 0
	v_mfma_f32_16x16x32_bf16 v[120:123], v[164:167], v[188:191], 0
	v_mfma_f32_16x16x32_bf16 v[108:111], v[148:151], v[196:199], 0
	v_mfma_f32_16x16x32_bf16 v[104:107], v[164:167], v[196:199], 0
	v_mfma_f32_16x16x32_bf16 v[92:95], v[148:151], v[204:207], 0
	v_mfma_f32_16x16x32_bf16 v[88:91], v[164:167], v[204:207], 0
	v_mfma_f32_16x16x32_bf16 v[76:79], v[148:151], v[212:215], 0
	v_mfma_f32_16x16x32_bf16 v[72:75], v[164:167], v[212:215], 0
	v_mfma_f32_16x16x32_bf16 v[124:127], v[160:163], v[192:195], v[124:127]
	v_mfma_f32_16x16x32_bf16 v[120:123], v[168:171], v[192:195], v[120:123]
	v_mfma_f32_16x16x32_bf16 v[108:111], v[160:163], v[200:203], v[108:111]
	v_mfma_f32_16x16x32_bf16 v[104:107], v[168:171], v[200:203], v[104:107]
	v_mfma_f32_16x16x32_bf16 v[92:95], v[160:163], v[208:211], v[92:95]
	v_mfma_f32_16x16x32_bf16 v[88:91], v[168:171], v[208:211], v[88:91]
	v_mfma_f32_16x16x32_bf16 v[76:79], v[160:163], v[216:219], v[76:79]
	v_mfma_f32_16x16x32_bf16 v[72:75], v[168:171], v[216:219], v[72:75]
	s_setprio 0
	s_setprio 1
	v_mfma_f32_16x16x32_bf16 v[116:119], v[172:175], v[188:191], 0
	v_mfma_f32_16x16x32_bf16 v[112:115], v[180:183], v[188:191], 0
	v_mfma_f32_16x16x32_bf16 v[100:103], v[172:175], v[196:199], 0
	v_mfma_f32_16x16x32_bf16 v[96:99], v[180:183], v[196:199], 0
	v_mfma_f32_16x16x32_bf16 v[84:87], v[172:175], v[204:207], 0
	v_mfma_f32_16x16x32_bf16 v[80:83], v[180:183], v[204:207], 0
	v_mfma_f32_16x16x32_bf16 v[68:71], v[172:175], v[212:215], 0
	v_mfma_f32_16x16x32_bf16 v[64:67], v[180:183], v[212:215], 0
	v_mfma_f32_16x16x32_bf16 v[116:119], v[176:179], v[192:195], v[116:119]
	v_mfma_f32_16x16x32_bf16 v[112:115], v[184:187], v[192:195], v[112:115]
	v_mfma_f32_16x16x32_bf16 v[100:103], v[176:179], v[200:203], v[100:103]
	v_mfma_f32_16x16x32_bf16 v[96:99], v[184:187], v[200:203], v[96:99]
	v_mfma_f32_16x16x32_bf16 v[84:87], v[176:179], v[208:211], v[84:87]
	v_mfma_f32_16x16x32_bf16 v[80:83], v[184:187], v[208:211], v[80:83]
	v_mfma_f32_16x16x32_bf16 v[68:71], v[176:179], v[216:219], v[68:71]
	v_mfma_f32_16x16x32_bf16 v[64:67], v[184:187], v[216:219], v[64:67]
	s_setprio 0
	s_barrier
	s_add_i32 s34, s65, s54
	v_lshl_add_u64 v[220:221], s[48:49], 0, v[136:137]
	s_mov_b32 m0, s34
	ds_read_b128 v[188:191], v158 offset:16384
	ds_read_b128 v[192:195], v158 offset:17408
	ds_read_b128 v[196:199], v158 offset:18432
	ds_read_b128 v[200:203], v158 offset:19456
	ds_read_b128 v[204:207], v158 offset:20480
	ds_read_b128 v[208:211], v158 offset:21504
	ds_read_b128 v[212:215], v158 offset:22528
	ds_read_b128 v[216:219], v158 offset:23552
	global_load_lds_dwordx4 v[220:221], off
	s_add_i32 m0, s34, 0x2000
	s_add_u32 s34, s48, 0x40000
	v_lshl_add_u64 v[222:223], s[48:49], 0, v[132:133]
	s_addc_u32 s35, s49, 0
	s_add_i32 s86, s66, s54
	global_load_lds_dwordx4 v[222:223], off
	v_lshl_add_u64 v[224:225], s[34:35], 0, v[136:137]
	s_mov_b32 m0, s86
	v_lshl_add_u64 v[226:227], s[50:51], 0, v[134:135]
	global_load_lds_dwordx4 v[224:225], off
	v_lshl_add_u64 v[224:225], s[34:35], 0, v[132:133]
	s_add_i32 m0, s86, 0x2000
	s_nop 0
	global_load_lds_dwordx4 v[224:225], off
	v_lshl_add_u64 v[224:225], s[50:51], 0, v[138:139]
	s_mov_b32 m0, s41
	s_nop 0
	global_load_lds_dwordx4 v[224:225], off
	s_mov_b32 m0, s58
	s_nop 0
	global_load_lds_dwordx4 v[226:227], off
	s_waitcnt vmcnt(8)
	s_waitcnt lgkmcnt(0)
	s_barrier
	s_setprio 1
	s_waitcnt lgkmcnt(0)
	v_mfma_f32_16x16x32_bf16 v[60:63], v[148:151], v[188:191], 0
	v_mfma_f32_16x16x32_bf16 v[56:59], v[164:167], v[188:191], 0
	v_mfma_f32_16x16x32_bf16 v[44:47], v[148:151], v[196:199], 0
	v_mfma_f32_16x16x32_bf16 v[40:43], v[164:167], v[196:199], 0
	v_mfma_f32_16x16x32_bf16 v[28:31], v[148:151], v[204:207], 0
	v_mfma_f32_16x16x32_bf16 v[24:27], v[164:167], v[204:207], 0
	v_mfma_f32_16x16x32_bf16 v[12:15], v[148:151], v[212:215], 0
	v_mfma_f32_16x16x32_bf16 v[8:11], v[164:167], v[212:215], 0
	v_mfma_f32_16x16x32_bf16 v[60:63], v[160:163], v[192:195], v[60:63]
	v_mfma_f32_16x16x32_bf16 v[56:59], v[168:171], v[192:195], v[56:59]
	v_mfma_f32_16x16x32_bf16 v[44:47], v[160:163], v[200:203], v[44:47]
	v_mfma_f32_16x16x32_bf16 v[40:43], v[168:171], v[200:203], v[40:43]
	v_mfma_f32_16x16x32_bf16 v[28:31], v[160:163], v[208:211], v[28:31]
	v_mfma_f32_16x16x32_bf16 v[24:27], v[168:171], v[208:211], v[24:27]
	v_mfma_f32_16x16x32_bf16 v[12:15], v[160:163], v[216:219], v[12:15]
	v_mfma_f32_16x16x32_bf16 v[8:11], v[168:171], v[216:219], v[8:11]
	s_setprio 0
	s_setprio 1
	v_mfma_f32_16x16x32_bf16 v[52:55], v[172:175], v[188:191], 0
	v_mfma_f32_16x16x32_bf16 v[48:51], v[180:183], v[188:191], 0
	v_mfma_f32_16x16x32_bf16 v[36:39], v[172:175], v[196:199], 0
	v_mfma_f32_16x16x32_bf16 v[32:35], v[180:183], v[196:199], 0
	v_mfma_f32_16x16x32_bf16 v[20:23], v[172:175], v[204:207], 0
	v_mfma_f32_16x16x32_bf16 v[16:19], v[180:183], v[204:207], 0
	v_mfma_f32_16x16x32_bf16 v[4:7], v[172:175], v[212:215], 0
	v_mfma_f32_16x16x32_bf16 v[0:3], v[180:183], v[212:215], 0
	v_mfma_f32_16x16x32_bf16 v[52:55], v[176:179], v[192:195], v[52:55]
	v_mfma_f32_16x16x32_bf16 v[48:51], v[184:187], v[192:195], v[48:51]
	v_mfma_f32_16x16x32_bf16 v[36:39], v[176:179], v[200:203], v[36:39]
	v_mfma_f32_16x16x32_bf16 v[32:35], v[184:187], v[200:203], v[32:35]
	v_mfma_f32_16x16x32_bf16 v[20:23], v[176:179], v[208:211], v[20:23]
	v_mfma_f32_16x16x32_bf16 v[16:19], v[184:187], v[208:211], v[16:19]
	v_mfma_f32_16x16x32_bf16 v[4:7], v[176:179], v[216:219], v[4:7]
	v_mfma_f32_16x16x32_bf16 v[0:3], v[184:187], v[216:219], v[0:3]
	s_setprio 0
	s_barrier
	s_add_i32 s86, 0, 0x18000
	v_add_u32_e32 v159, s86, v152
	s_add_i32 s87, 0, 0x1c000
	ds_read_b128 v[148:151], v159
	ds_read_b128 v[160:163], v159 offset:1024
	ds_read_b128 v[164:167], v159 offset:2048
	ds_read_b128 v[168:171], v159 offset:3072
	v_add_u32_e32 v159, s87, v152
	ds_read_b128 v[172:175], v159
	ds_read_b128 v[176:179], v159 offset:1024
	ds_read_b128 v[180:183], v159 offset:2048
	ds_read_b128 v[184:187], v159 offset:3072
	s_add_u32 s34, s50, 0x40000
	s_addc_u32 s35, s51, 0
	s_mov_b32 m0, s59
	v_lshl_add_u64 v[228:229], s[34:35], 0, v[138:139]
	ds_read_b128 v[188:191], v158 offset:32768
	ds_read_b128 v[192:195], v158 offset:33792
	ds_read_b128 v[196:199], v158 offset:34816
	ds_read_b128 v[200:203], v158 offset:35840
	ds_read_b128 v[204:207], v158 offset:36864
	ds_read_b128 v[208:211], v158 offset:37888
	ds_read_b128 v[212:215], v158 offset:38912
	ds_read_b128 v[216:219], v158 offset:39936
	global_load_lds_dwordx4 v[228:229], off
	v_lshl_add_u64 v[228:229], s[34:35], 0, v[134:135]
	s_mov_b32 m0, s62
	s_nop 0
	global_load_lds_dwordx4 v[228:229], off
	s_waitcnt vmcnt(8)
	s_waitcnt lgkmcnt(0)
	s_barrier
	s_setprio 1
	s_waitcnt lgkmcnt(0)
	v_mfma_f32_16x16x32_bf16 v[124:127], v[148:151], v[188:191], v[124:127]
	v_mfma_f32_16x16x32_bf16 v[120:123], v[164:167], v[188:191], v[120:123]
	v_mfma_f32_16x16x32_bf16 v[108:111], v[148:151], v[196:199], v[108:111]
	v_mfma_f32_16x16x32_bf16 v[104:107], v[164:167], v[196:199], v[104:107]
	v_mfma_f32_16x16x32_bf16 v[92:95], v[148:151], v[204:207], v[92:95]
	v_mfma_f32_16x16x32_bf16 v[88:91], v[164:167], v[204:207], v[88:91]
	v_mfma_f32_16x16x32_bf16 v[76:79], v[148:151], v[212:215], v[76:79]
	v_mfma_f32_16x16x32_bf16 v[72:75], v[164:167], v[212:215], v[72:75]
	v_mfma_f32_16x16x32_bf16 v[124:127], v[160:163], v[192:195], v[124:127]
	v_mfma_f32_16x16x32_bf16 v[120:123], v[168:171], v[192:195], v[120:123]
	v_mfma_f32_16x16x32_bf16 v[108:111], v[160:163], v[200:203], v[108:111]
	v_mfma_f32_16x16x32_bf16 v[104:107], v[168:171], v[200:203], v[104:107]
	v_mfma_f32_16x16x32_bf16 v[92:95], v[160:163], v[208:211], v[92:95]
	v_mfma_f32_16x16x32_bf16 v[88:91], v[168:171], v[208:211], v[88:91]
	v_mfma_f32_16x16x32_bf16 v[76:79], v[160:163], v[216:219], v[76:79]
	v_mfma_f32_16x16x32_bf16 v[72:75], v[168:171], v[216:219], v[72:75]
	s_setprio 0
	s_setprio 1
	v_mfma_f32_16x16x32_bf16 v[116:119], v[172:175], v[188:191], v[116:119]
	v_mfma_f32_16x16x32_bf16 v[112:115], v[180:183], v[188:191], v[112:115]
	v_mfma_f32_16x16x32_bf16 v[100:103], v[172:175], v[196:199], v[100:103]
	v_mfma_f32_16x16x32_bf16 v[96:99], v[180:183], v[196:199], v[96:99]
	v_mfma_f32_16x16x32_bf16 v[84:87], v[172:175], v[204:207], v[84:87]
	v_mfma_f32_16x16x32_bf16 v[80:83], v[180:183], v[204:207], v[80:83]
	v_mfma_f32_16x16x32_bf16 v[68:71], v[172:175], v[212:215], v[68:71]
	v_mfma_f32_16x16x32_bf16 v[64:67], v[180:183], v[212:215], v[64:67]
	v_mfma_f32_16x16x32_bf16 v[116:119], v[176:179], v[192:195], v[116:119]
	v_mfma_f32_16x16x32_bf16 v[112:115], v[184:187], v[192:195], v[112:115]
	v_mfma_f32_16x16x32_bf16 v[100:103], v[176:179], v[200:203], v[100:103]
	v_mfma_f32_16x16x32_bf16 v[96:99], v[184:187], v[200:203], v[96:99]
	v_mfma_f32_16x16x32_bf16 v[84:87], v[176:179], v[208:211], v[84:87]
	v_mfma_f32_16x16x32_bf16 v[80:83], v[184:187], v[208:211], v[80:83]
	v_mfma_f32_16x16x32_bf16 v[68:71], v[176:179], v[216:219], v[68:71]
	v_mfma_f32_16x16x32_bf16 v[64:67], v[184:187], v[216:219], v[64:67]
	s_setprio 0
	s_barrier
	s_add_i32 s34, s86, s54
	v_lshl_add_u64 v[220:221], v[220:221], 0, s[6:7]
	s_mov_b32 m0, s34
	ds_read_b128 v[188:191], v158 offset:49152
	ds_read_b128 v[192:195], v158 offset:50176
	ds_read_b128 v[196:199], v158 offset:51200
	ds_read_b128 v[200:203], v158 offset:52224
	ds_read_b128 v[204:207], v158 offset:53248
	ds_read_b128 v[208:211], v158 offset:54272
	ds_read_b128 v[212:215], v158 offset:55296
	ds_read_b128 v[216:219], v158 offset:56320
	global_load_lds_dwordx4 v[220:221], off
	s_add_i32 m0, s34, 0x2000
	s_add_u32 s34, s48, 0x40080
	v_lshl_add_u64 v[220:221], v[222:223], 0, s[6:7]
	s_addc_u32 s35, s49, 0
	s_add_i32 s48, s87, s54
	global_load_lds_dwordx4 v[220:221], off
	v_lshl_add_u64 v[220:221], s[34:35], 0, v[136:137]
	s_mov_b32 m0, s48
	s_nop 0
	global_load_lds_dwordx4 v[220:221], off
	v_lshl_add_u64 v[220:221], s[34:35], 0, v[132:133]
	s_add_i32 m0, s48, 0x2000
	s_nop 0
	global_load_lds_dwordx4 v[220:221], off
	v_lshl_add_u64 v[220:221], v[224:225], 0, s[6:7]
	s_mov_b32 m0, s63
	s_nop 0
	global_load_lds_dwordx4 v[220:221], off
	v_lshl_add_u64 v[220:221], v[226:227], 0, s[6:7]
	s_mov_b32 m0, s64
	s_nop 0
	global_load_lds_dwordx4 v[220:221], off
	s_waitcnt vmcnt(8)
	s_waitcnt lgkmcnt(0)
	s_barrier
	s_add_u32 s42, s42, 0x100
	s_addc_u32 s43, s43, 0
	s_add_u32 s83, s83, 0x100
	s_addc_u32 s84, s84, 0
	s_setprio 1
	s_waitcnt lgkmcnt(0)
	v_mfma_f32_16x16x32_bf16 v[60:63], v[148:151], v[188:191], v[60:63]
	v_mfma_f32_16x16x32_bf16 v[56:59], v[164:167], v[188:191], v[56:59]
	v_mfma_f32_16x16x32_bf16 v[44:47], v[148:151], v[196:199], v[44:47]
	v_mfma_f32_16x16x32_bf16 v[40:43], v[164:167], v[196:199], v[40:43]
	v_mfma_f32_16x16x32_bf16 v[28:31], v[148:151], v[204:207], v[28:31]
	v_mfma_f32_16x16x32_bf16 v[24:27], v[164:167], v[204:207], v[24:27]
	v_mfma_f32_16x16x32_bf16 v[12:15], v[148:151], v[212:215], v[12:15]
	v_mfma_f32_16x16x32_bf16 v[8:11], v[164:167], v[212:215], v[8:11]
	v_mfma_f32_16x16x32_bf16 v[60:63], v[160:163], v[192:195], v[60:63]
	v_mfma_f32_16x16x32_bf16 v[56:59], v[168:171], v[192:195], v[56:59]
	v_mfma_f32_16x16x32_bf16 v[44:47], v[160:163], v[200:203], v[44:47]
	v_mfma_f32_16x16x32_bf16 v[40:43], v[168:171], v[200:203], v[40:43]
	v_mfma_f32_16x16x32_bf16 v[28:31], v[160:163], v[208:211], v[28:31]
	v_mfma_f32_16x16x32_bf16 v[24:27], v[168:171], v[208:211], v[24:27]
	v_mfma_f32_16x16x32_bf16 v[12:15], v[160:163], v[216:219], v[12:15]
	v_mfma_f32_16x16x32_bf16 v[8:11], v[168:171], v[216:219], v[8:11]
	s_setprio 0
	s_setprio 1
	v_mfma_f32_16x16x32_bf16 v[52:55], v[172:175], v[188:191], v[52:55]
	v_mfma_f32_16x16x32_bf16 v[48:51], v[180:183], v[188:191], v[48:51]
	v_mfma_f32_16x16x32_bf16 v[36:39], v[172:175], v[196:199], v[36:39]
	v_mfma_f32_16x16x32_bf16 v[32:35], v[180:183], v[196:199], v[32:35]
	v_mfma_f32_16x16x32_bf16 v[20:23], v[172:175], v[204:207], v[20:23]
	v_mfma_f32_16x16x32_bf16 v[16:19], v[180:183], v[204:207], v[16:19]
	v_mfma_f32_16x16x32_bf16 v[4:7], v[172:175], v[212:215], v[4:7]
	v_mfma_f32_16x16x32_bf16 v[0:3], v[180:183], v[212:215], v[0:3]
	v_mfma_f32_16x16x32_bf16 v[52:55], v[176:179], v[192:195], v[52:55]
	v_mfma_f32_16x16x32_bf16 v[48:51], v[184:187], v[192:195], v[48:51]
	v_mfma_f32_16x16x32_bf16 v[36:39], v[176:179], v[200:203], v[36:39]
	v_mfma_f32_16x16x32_bf16 v[32:35], v[184:187], v[200:203], v[32:35]
	v_mfma_f32_16x16x32_bf16 v[20:23], v[176:179], v[208:211], v[20:23]
	v_mfma_f32_16x16x32_bf16 v[16:19], v[184:187], v[208:211], v[16:19]
	v_mfma_f32_16x16x32_bf16 v[4:7], v[176:179], v[216:219], v[4:7]
	v_mfma_f32_16x16x32_bf16 v[0:3], v[184:187], v[216:219], v[0:3]
	s_setprio 0
	s_barrier
	s_add_i32 s85, s85, 2
.LBB0_476:
	ds_read_b128 v[148:151], v155
	ds_read_b128 v[160:163], v155 offset:1024
	ds_read_b128 v[164:167], v155 offset:2048
	ds_read_b128 v[168:171], v155 offset:3072
	ds_read_b128 v[172:175], v157
	ds_read_b128 v[176:179], v157 offset:1024
	ds_read_b128 v[180:183], v157 offset:2048
	ds_read_b128 v[184:187], v157 offset:3072
	s_add_u32 s34, s42, 0xfffc0080
	s_addc_u32 s35, s43, -1
	s_cmp_eq_u32 s85, 12
	s_cselect_b32 s51, s23, s35
	s_cselect_b32 s50, s81, s34
	s_cselect_b32 s49, s11, s84
	s_cselect_b32 s48, s82, s83
	v_lshl_add_u64 v[220:221], s[42:43], 0, v[140:141]
	s_add_i32 m0, s41, 0xc000
	ds_read_b128 v[188:191], v158
	ds_read_b128 v[192:195], v158 offset:1024
	ds_read_b128 v[196:199], v158 offset:2048
	ds_read_b128 v[200:203], v158 offset:3072
	ds_read_b128 v[204:207], v158 offset:4096
	ds_read_b128 v[208:211], v158 offset:5120
	ds_read_b128 v[212:215], v158 offset:6144
	ds_read_b128 v[216:219], v158 offset:7168
	global_load_lds_dwordx4 v[220:221], off
	v_lshl_add_u64 v[220:221], s[42:43], 0, v[142:143]
	s_add_i32 m0, s41, 0xe000
	s_nop 0
	global_load_lds_dwordx4 v[220:221], off
	s_waitcnt vmcnt(8)
	s_waitcnt lgkmcnt(0)
	s_barrier
	s_setprio 1
	s_waitcnt lgkmcnt(0)
	v_mfma_f32_16x16x32_bf16 v[124:127], v[148:151], v[188:191], v[124:127]
	v_mfma_f32_16x16x32_bf16 v[120:123], v[164:167], v[188:191], v[120:123]
	v_mfma_f32_16x16x32_bf16 v[108:111], v[148:151], v[196:199], v[108:111]
	v_mfma_f32_16x16x32_bf16 v[104:107], v[164:167], v[196:199], v[104:107]
	v_mfma_f32_16x16x32_bf16 v[92:95], v[148:151], v[204:207], v[92:95]
	v_mfma_f32_16x16x32_bf16 v[88:91], v[164:167], v[204:207], v[88:91]
	v_mfma_f32_16x16x32_bf16 v[76:79], v[148:151], v[212:215], v[76:79]
	v_mfma_f32_16x16x32_bf16 v[72:75], v[164:167], v[212:215], v[72:75]
	v_mfma_f32_16x16x32_bf16 v[124:127], v[160:163], v[192:195], v[124:127]
	v_mfma_f32_16x16x32_bf16 v[120:123], v[168:171], v[192:195], v[120:123]
	v_mfma_f32_16x16x32_bf16 v[108:111], v[160:163], v[200:203], v[108:111]
	v_mfma_f32_16x16x32_bf16 v[104:107], v[168:171], v[200:203], v[104:107]
	v_mfma_f32_16x16x32_bf16 v[92:95], v[160:163], v[208:211], v[92:95]
	v_mfma_f32_16x16x32_bf16 v[88:91], v[168:171], v[208:211], v[88:91]
	v_mfma_f32_16x16x32_bf16 v[76:79], v[160:163], v[216:219], v[76:79]
	v_mfma_f32_16x16x32_bf16 v[72:75], v[168:171], v[216:219], v[72:75]
	s_setprio 0
	s_setprio 1
	v_mfma_f32_16x16x32_bf16 v[116:119], v[172:175], v[188:191], v[116:119]
	v_mfma_f32_16x16x32_bf16 v[112:115], v[180:183], v[188:191], v[112:115]
	v_mfma_f32_16x16x32_bf16 v[100:103], v[172:175], v[196:199], v[100:103]
	v_mfma_f32_16x16x32_bf16 v[96:99], v[180:183], v[196:199], v[96:99]
	v_mfma_f32_16x16x32_bf16 v[84:87], v[172:175], v[204:207], v[84:87]
	v_mfma_f32_16x16x32_bf16 v[80:83], v[180:183], v[204:207], v[80:83]
	v_mfma_f32_16x16x32_bf16 v[68:71], v[172:175], v[212:215], v[68:71]
	v_mfma_f32_16x16x32_bf16 v[64:67], v[180:183], v[212:215], v[64:67]
	v_mfma_f32_16x16x32_bf16 v[116:119], v[176:179], v[192:195], v[116:119]
	v_mfma_f32_16x16x32_bf16 v[112:115], v[184:187], v[192:195], v[112:115]
	v_mfma_f32_16x16x32_bf16 v[100:103], v[176:179], v[200:203], v[100:103]
	v_mfma_f32_16x16x32_bf16 v[96:99], v[184:187], v[200:203], v[96:99]
	v_mfma_f32_16x16x32_bf16 v[84:87], v[176:179], v[208:211], v[84:87]
	v_mfma_f32_16x16x32_bf16 v[80:83], v[184:187], v[208:211], v[80:83]
	v_mfma_f32_16x16x32_bf16 v[68:71], v[176:179], v[216:219], v[68:71]
	v_mfma_f32_16x16x32_bf16 v[64:67], v[184:187], v[216:219], v[64:67]
	s_setprio 0
	s_barrier
	s_add_i32 s34, s65, s54
	v_lshl_add_u64 v[220:221], s[48:49], 0, v[136:137]
	s_mov_b32 m0, s34
	ds_read_b128 v[188:191], v158 offset:16384
	ds_read_b128 v[192:195], v158 offset:17408
	ds_read_b128 v[196:199], v158 offset:18432
	ds_read_b128 v[200:203], v158 offset:19456
	ds_read_b128 v[204:207], v158 offset:20480
	ds_read_b128 v[208:211], v158 offset:21504
	ds_read_b128 v[212:215], v158 offset:22528
	ds_read_b128 v[216:219], v158 offset:23552
	global_load_lds_dwordx4 v[220:221], off
	s_add_i32 m0, s34, 0x2000
	s_add_u32 s34, s48, 0x40000
	v_lshl_add_u64 v[222:223], s[48:49], 0, v[132:133]
	s_addc_u32 s35, s49, 0
	s_add_i32 s86, s66, s54
	global_load_lds_dwordx4 v[222:223], off
	v_lshl_add_u64 v[224:225], s[34:35], 0, v[136:137]
	s_mov_b32 m0, s86
	v_lshl_add_u64 v[226:227], s[50:51], 0, v[134:135]
	global_load_lds_dwordx4 v[224:225], off
	v_lshl_add_u64 v[224:225], s[34:35], 0, v[132:133]
	s_add_i32 m0, s86, 0x2000
	s_nop 0
	global_load_lds_dwordx4 v[224:225], off
	v_lshl_add_u64 v[224:225], s[50:51], 0, v[138:139]
	s_mov_b32 m0, s41
	s_nop 0
	global_load_lds_dwordx4 v[224:225], off
	s_mov_b32 m0, s58
	s_nop 0
	global_load_lds_dwordx4 v[226:227], off
	s_waitcnt vmcnt(8)
	s_waitcnt lgkmcnt(0)
	s_barrier
	s_setprio 1
	s_waitcnt lgkmcnt(0)
	v_mfma_f32_16x16x32_bf16 v[60:63], v[148:151], v[188:191], v[60:63]
	v_mfma_f32_16x16x32_bf16 v[56:59], v[164:167], v[188:191], v[56:59]
	v_mfma_f32_16x16x32_bf16 v[44:47], v[148:151], v[196:199], v[44:47]
	v_mfma_f32_16x16x32_bf16 v[40:43], v[164:167], v[196:199], v[40:43]
	v_mfma_f32_16x16x32_bf16 v[28:31], v[148:151], v[204:207], v[28:31]
	v_mfma_f32_16x16x32_bf16 v[24:27], v[164:167], v[204:207], v[24:27]
	v_mfma_f32_16x16x32_bf16 v[12:15], v[148:151], v[212:215], v[12:15]
	v_mfma_f32_16x16x32_bf16 v[8:11], v[164:167], v[212:215], v[8:11]
	v_mfma_f32_16x16x32_bf16 v[60:63], v[160:163], v[192:195], v[60:63]
	v_mfma_f32_16x16x32_bf16 v[56:59], v[168:171], v[192:195], v[56:59]
	v_mfma_f32_16x16x32_bf16 v[44:47], v[160:163], v[200:203], v[44:47]
	v_mfma_f32_16x16x32_bf16 v[40:43], v[168:171], v[200:203], v[40:43]
	v_mfma_f32_16x16x32_bf16 v[28:31], v[160:163], v[208:211], v[28:31]
	v_mfma_f32_16x16x32_bf16 v[24:27], v[168:171], v[208:211], v[24:27]
	v_mfma_f32_16x16x32_bf16 v[12:15], v[160:163], v[216:219], v[12:15]
	v_mfma_f32_16x16x32_bf16 v[8:11], v[168:171], v[216:219], v[8:11]
	s_setprio 0
	s_setprio 1
	v_mfma_f32_16x16x32_bf16 v[52:55], v[172:175], v[188:191], v[52:55]
	v_mfma_f32_16x16x32_bf16 v[48:51], v[180:183], v[188:191], v[48:51]
	v_mfma_f32_16x16x32_bf16 v[36:39], v[172:175], v[196:199], v[36:39]
	v_mfma_f32_16x16x32_bf16 v[32:35], v[180:183], v[196:199], v[32:35]
	v_mfma_f32_16x16x32_bf16 v[20:23], v[172:175], v[204:207], v[20:23]
	v_mfma_f32_16x16x32_bf16 v[16:19], v[180:183], v[204:207], v[16:19]
	v_mfma_f32_16x16x32_bf16 v[4:7], v[172:175], v[212:215], v[4:7]
	v_mfma_f32_16x16x32_bf16 v[0:3], v[180:183], v[212:215], v[0:3]
	v_mfma_f32_16x16x32_bf16 v[52:55], v[176:179], v[192:195], v[52:55]
	v_mfma_f32_16x16x32_bf16 v[48:51], v[184:187], v[192:195], v[48:51]
	v_mfma_f32_16x16x32_bf16 v[36:39], v[176:179], v[200:203], v[36:39]
	v_mfma_f32_16x16x32_bf16 v[32:35], v[184:187], v[200:203], v[32:35]
	v_mfma_f32_16x16x32_bf16 v[20:23], v[176:179], v[208:211], v[20:23]
	v_mfma_f32_16x16x32_bf16 v[16:19], v[184:187], v[208:211], v[16:19]
	v_mfma_f32_16x16x32_bf16 v[4:7], v[176:179], v[216:219], v[4:7]
	v_mfma_f32_16x16x32_bf16 v[0:3], v[184:187], v[216:219], v[0:3]
	s_setprio 0
	s_barrier
	s_add_i32 s86, 0, 0x18000
	v_add_u32_e32 v159, s86, v152
	s_add_i32 s87, 0, 0x1c000
	ds_read_b128 v[148:151], v159
	ds_read_b128 v[160:163], v159 offset:1024
	ds_read_b128 v[164:167], v159 offset:2048
	ds_read_b128 v[168:171], v159 offset:3072
	v_add_u32_e32 v159, s87, v152
	ds_read_b128 v[172:175], v159
	ds_read_b128 v[176:179], v159 offset:1024
	ds_read_b128 v[180:183], v159 offset:2048
	ds_read_b128 v[184:187], v159 offset:3072
	s_add_u32 s34, s50, 0x40000
	s_addc_u32 s35, s51, 0
	s_mov_b32 m0, s59
	v_lshl_add_u64 v[228:229], s[34:35], 0, v[138:139]
	ds_read_b128 v[188:191], v158 offset:32768
	ds_read_b128 v[192:195], v158 offset:33792
	ds_read_b128 v[196:199], v158 offset:34816
	ds_read_b128 v[200:203], v158 offset:35840
	ds_read_b128 v[204:207], v158 offset:36864
	ds_read_b128 v[208:211], v158 offset:37888
	ds_read_b128 v[212:215], v158 offset:38912
	ds_read_b128 v[216:219], v158 offset:39936
	global_load_lds_dwordx4 v[228:229], off
	v_lshl_add_u64 v[228:229], s[34:35], 0, v[134:135]
	s_mov_b32 m0, s62
	s_nop 0
	global_load_lds_dwordx4 v[228:229], off
	s_waitcnt vmcnt(8)
	s_waitcnt lgkmcnt(0)
	s_barrier
	s_setprio 1
	s_waitcnt lgkmcnt(0)
	v_mfma_f32_16x16x32_bf16 v[124:127], v[148:151], v[188:191], v[124:127]
	v_mfma_f32_16x16x32_bf16 v[120:123], v[164:167], v[188:191], v[120:123]
	v_mfma_f32_16x16x32_bf16 v[108:111], v[148:151], v[196:199], v[108:111]
	v_mfma_f32_16x16x32_bf16 v[104:107], v[164:167], v[196:199], v[104:107]
	v_mfma_f32_16x16x32_bf16 v[92:95], v[148:151], v[204:207], v[92:95]
	v_mfma_f32_16x16x32_bf16 v[88:91], v[164:167], v[204:207], v[88:91]
	v_mfma_f32_16x16x32_bf16 v[76:79], v[148:151], v[212:215], v[76:79]
	v_mfma_f32_16x16x32_bf16 v[72:75], v[164:167], v[212:215], v[72:75]
	v_mfma_f32_16x16x32_bf16 v[124:127], v[160:163], v[192:195], v[124:127]
	v_mfma_f32_16x16x32_bf16 v[120:123], v[168:171], v[192:195], v[120:123]
	v_mfma_f32_16x16x32_bf16 v[108:111], v[160:163], v[200:203], v[108:111]
	v_mfma_f32_16x16x32_bf16 v[104:107], v[168:171], v[200:203], v[104:107]
	v_mfma_f32_16x16x32_bf16 v[92:95], v[160:163], v[208:211], v[92:95]
	v_mfma_f32_16x16x32_bf16 v[88:91], v[168:171], v[208:211], v[88:91]
	v_mfma_f32_16x16x32_bf16 v[76:79], v[160:163], v[216:219], v[76:79]
	v_mfma_f32_16x16x32_bf16 v[72:75], v[168:171], v[216:219], v[72:75]
	s_setprio 0
	s_setprio 1
	v_mfma_f32_16x16x32_bf16 v[116:119], v[172:175], v[188:191], v[116:119]
	v_mfma_f32_16x16x32_bf16 v[112:115], v[180:183], v[188:191], v[112:115]
	v_mfma_f32_16x16x32_bf16 v[100:103], v[172:175], v[196:199], v[100:103]
	v_mfma_f32_16x16x32_bf16 v[96:99], v[180:183], v[196:199], v[96:99]
	v_mfma_f32_16x16x32_bf16 v[84:87], v[172:175], v[204:207], v[84:87]
	v_mfma_f32_16x16x32_bf16 v[80:83], v[180:183], v[204:207], v[80:83]
	v_mfma_f32_16x16x32_bf16 v[68:71], v[172:175], v[212:215], v[68:71]
	v_mfma_f32_16x16x32_bf16 v[64:67], v[180:183], v[212:215], v[64:67]
	v_mfma_f32_16x16x32_bf16 v[116:119], v[176:179], v[192:195], v[116:119]
	v_mfma_f32_16x16x32_bf16 v[112:115], v[184:187], v[192:195], v[112:115]
	v_mfma_f32_16x16x32_bf16 v[100:103], v[176:179], v[200:203], v[100:103]
	v_mfma_f32_16x16x32_bf16 v[96:99], v[184:187], v[200:203], v[96:99]
	v_mfma_f32_16x16x32_bf16 v[84:87], v[176:179], v[208:211], v[84:87]
	v_mfma_f32_16x16x32_bf16 v[80:83], v[184:187], v[208:211], v[80:83]
	v_mfma_f32_16x16x32_bf16 v[68:71], v[176:179], v[216:219], v[68:71]
	v_mfma_f32_16x16x32_bf16 v[64:67], v[184:187], v[216:219], v[64:67]
	s_setprio 0
	s_barrier
	s_add_i32 s34, s86, s54
	v_lshl_add_u64 v[220:221], v[220:221], 0, s[6:7]
	s_mov_b32 m0, s34
	ds_read_b128 v[188:191], v158 offset:49152
	ds_read_b128 v[192:195], v158 offset:50176
	ds_read_b128 v[196:199], v158 offset:51200
	ds_read_b128 v[200:203], v158 offset:52224
	ds_read_b128 v[204:207], v158 offset:53248
	ds_read_b128 v[208:211], v158 offset:54272
	ds_read_b128 v[212:215], v158 offset:55296
	ds_read_b128 v[216:219], v158 offset:56320
	global_load_lds_dwordx4 v[220:221], off
	s_add_i32 m0, s34, 0x2000
	s_add_u32 s34, s48, 0x40080
	v_lshl_add_u64 v[220:221], v[222:223], 0, s[6:7]
	s_addc_u32 s35, s49, 0
	s_add_i32 s48, s87, s54
	global_load_lds_dwordx4 v[220:221], off
	v_lshl_add_u64 v[220:221], s[34:35], 0, v[136:137]
	s_mov_b32 m0, s48
	s_nop 0
	global_load_lds_dwordx4 v[220:221], off
	v_lshl_add_u64 v[220:221], s[34:35], 0, v[132:133]
	s_add_i32 m0, s48, 0x2000
	s_nop 0
	global_load_lds_dwordx4 v[220:221], off
	v_lshl_add_u64 v[220:221], v[224:225], 0, s[6:7]
	s_mov_b32 m0, s63
	s_nop 0
	global_load_lds_dwordx4 v[220:221], off
	v_lshl_add_u64 v[220:221], v[226:227], 0, s[6:7]
	s_mov_b32 m0, s64
	s_nop 0
	global_load_lds_dwordx4 v[220:221], off
	s_waitcnt vmcnt(8)
	s_waitcnt lgkmcnt(0)
	s_barrier
	s_add_u32 s42, s42, 0x100
	s_addc_u32 s43, s43, 0
	s_add_u32 s83, s83, 0x100
	s_addc_u32 s84, s84, 0
	s_setprio 1
	s_waitcnt lgkmcnt(0)
	v_mfma_f32_16x16x32_bf16 v[60:63], v[148:151], v[188:191], v[60:63]
	v_mfma_f32_16x16x32_bf16 v[56:59], v[164:167], v[188:191], v[56:59]
	v_mfma_f32_16x16x32_bf16 v[44:47], v[148:151], v[196:199], v[44:47]
	v_mfma_f32_16x16x32_bf16 v[40:43], v[164:167], v[196:199], v[40:43]
	v_mfma_f32_16x16x32_bf16 v[28:31], v[148:151], v[204:207], v[28:31]
	v_mfma_f32_16x16x32_bf16 v[24:27], v[164:167], v[204:207], v[24:27]
	v_mfma_f32_16x16x32_bf16 v[12:15], v[148:151], v[212:215], v[12:15]
	v_mfma_f32_16x16x32_bf16 v[8:11], v[164:167], v[212:215], v[8:11]
	v_mfma_f32_16x16x32_bf16 v[60:63], v[160:163], v[192:195], v[60:63]
	v_mfma_f32_16x16x32_bf16 v[56:59], v[168:171], v[192:195], v[56:59]
	v_mfma_f32_16x16x32_bf16 v[44:47], v[160:163], v[200:203], v[44:47]
	v_mfma_f32_16x16x32_bf16 v[40:43], v[168:171], v[200:203], v[40:43]
	v_mfma_f32_16x16x32_bf16 v[28:31], v[160:163], v[208:211], v[28:31]
	v_mfma_f32_16x16x32_bf16 v[24:27], v[168:171], v[208:211], v[24:27]
	v_mfma_f32_16x16x32_bf16 v[12:15], v[160:163], v[216:219], v[12:15]
	v_mfma_f32_16x16x32_bf16 v[8:11], v[168:171], v[216:219], v[8:11]
	s_setprio 0
	s_setprio 1
	v_mfma_f32_16x16x32_bf16 v[52:55], v[172:175], v[188:191], v[52:55]
	v_mfma_f32_16x16x32_bf16 v[48:51], v[180:183], v[188:191], v[48:51]
	v_mfma_f32_16x16x32_bf16 v[36:39], v[172:175], v[196:199], v[36:39]
	v_mfma_f32_16x16x32_bf16 v[32:35], v[180:183], v[196:199], v[32:35]
	v_mfma_f32_16x16x32_bf16 v[20:23], v[172:175], v[204:207], v[20:23]
	v_mfma_f32_16x16x32_bf16 v[16:19], v[180:183], v[204:207], v[16:19]
	v_mfma_f32_16x16x32_bf16 v[4:7], v[172:175], v[212:215], v[4:7]
	v_mfma_f32_16x16x32_bf16 v[0:3], v[180:183], v[212:215], v[0:3]
	v_mfma_f32_16x16x32_bf16 v[52:55], v[176:179], v[192:195], v[52:55]
	v_mfma_f32_16x16x32_bf16 v[48:51], v[184:187], v[192:195], v[48:51]
	v_mfma_f32_16x16x32_bf16 v[36:39], v[176:179], v[200:203], v[36:39]
	v_mfma_f32_16x16x32_bf16 v[32:35], v[184:187], v[200:203], v[32:35]
	v_mfma_f32_16x16x32_bf16 v[20:23], v[176:179], v[208:211], v[20:23]
	v_mfma_f32_16x16x32_bf16 v[16:19], v[184:187], v[208:211], v[16:19]
	v_mfma_f32_16x16x32_bf16 v[4:7], v[176:179], v[216:219], v[4:7]
	v_mfma_f32_16x16x32_bf16 v[0:3], v[184:187], v[216:219], v[0:3]
	s_setprio 0
	s_cmp_eq_u32 s85, s98
	s_cbranch_scc1 .Lmy_nobar_5
	s_barrier
.Lmy_nobar_5:
	s_add_i32 s85, s85, 2
	s_cmp_gt_u32 s85, 13
	s_cbranch_scc0 .LBB0_476
	s_and_b64 vcc, exec, s[8:9]
	s_cbranch_vccz .LBB0_479
	s_nop 0

.Lmy_nobar2_6:
	ds_read_b128 v[148:151], v154
	ds_read_b128 v[160:163], v154 offset:1024
	ds_read_b128 v[164:167], v154 offset:2048
	ds_read_b128 v[168:171], v154 offset:3072
	ds_read_b128 v[172:175], v155
	ds_read_b128 v[176:179], v155 offset:1024
	ds_read_b128 v[180:183], v155 offset:2048
	ds_read_b128 v[184:187], v155 offset:3072
	s_add_u32 s34, s40, 0xfff50080
	s_addc_u32 s35, s41, -1
	s_cmp_eq_u32 s81, 40
	s_cselect_b32 s49, s1, s35
	s_cselect_b32 s48, s0, s34
	s_cselect_b32 s43, s29, s77
	s_cselect_b32 s42, s28, s13
	v_lshl_add_u64 v[220:221], s[40:41], 0, v[140:141]
	s_add_i32 m0, s52, 0xc000
	ds_read_b128 v[188:191], v157
	ds_read_b128 v[192:195], v157 offset:1024
	ds_read_b128 v[196:199], v157 offset:2048
	ds_read_b128 v[200:203], v157 offset:3072
	ds_read_b128 v[204:207], v157 offset:4096
	ds_read_b128 v[208:211], v157 offset:5120
	ds_read_b128 v[212:215], v157 offset:6144
	ds_read_b128 v[216:219], v157 offset:7168
	global_load_lds_dwordx4 v[220:221], off
	v_lshl_add_u64 v[220:221], s[40:41], 0, v[142:143]
	s_add_i32 m0, s52, 0xe000
	s_nop 0
	global_load_lds_dwordx4 v[220:221], off
	s_waitcnt vmcnt(8)
	s_waitcnt lgkmcnt(0)
	s_barrier
	s_setprio 1
	s_waitcnt lgkmcnt(0)
	v_mfma_f32_16x16x32_bf16 v[124:127], v[148:151], v[188:191], 0
	v_mfma_f32_16x16x32_bf16 v[120:123], v[164:167], v[188:191], 0
	v_mfma_f32_16x16x32_bf16 v[108:111], v[148:151], v[196:199], 0
	v_mfma_f32_16x16x32_bf16 v[104:107], v[164:167], v[196:199], 0
	v_mfma_f32_16x16x32_bf16 v[92:95], v[148:151], v[204:207], 0
	v_mfma_f32_16x16x32_bf16 v[88:91], v[164:167], v[204:207], 0
	v_mfma_f32_16x16x32_bf16 v[76:79], v[148:151], v[212:215], 0
	v_mfma_f32_16x16x32_bf16 v[72:75], v[164:167], v[212:215], 0
	v_mfma_f32_16x16x32_bf16 v[124:127], v[160:163], v[192:195], v[124:127]
	v_mfma_f32_16x16x32_bf16 v[120:123], v[168:171], v[192:195], v[120:123]
	v_mfma_f32_16x16x32_bf16 v[108:111], v[160:163], v[200:203], v[108:111]
	v_mfma_f32_16x16x32_bf16 v[104:107], v[168:171], v[200:203], v[104:107]
	v_mfma_f32_16x16x32_bf16 v[92:95], v[160:163], v[208:211], v[92:95]
	v_mfma_f32_16x16x32_bf16 v[88:91], v[168:171], v[208:211], v[88:91]
	v_mfma_f32_16x16x32_bf16 v[76:79], v[160:163], v[216:219], v[76:79]
	v_mfma_f32_16x16x32_bf16 v[72:75], v[168:171], v[216:219], v[72:75]
	s_setprio 0
	s_setprio 1
	v_mfma_f32_16x16x32_bf16 v[116:119], v[172:175], v[188:191], 0
	v_mfma_f32_16x16x32_bf16 v[112:115], v[180:183], v[188:191], 0
	v_mfma_f32_16x16x32_bf16 v[100:103], v[172:175], v[196:199], 0
	v_mfma_f32_16x16x32_bf16 v[96:99], v[180:183], v[196:199], 0
	v_mfma_f32_16x16x32_bf16 v[84:87], v[172:175], v[204:207], 0
	v_mfma_f32_16x16x32_bf16 v[80:83], v[180:183], v[204:207], 0
	v_mfma_f32_16x16x32_bf16 v[68:71], v[172:175], v[212:215], 0
	v_mfma_f32_16x16x32_bf16 v[64:67], v[180:183], v[212:215], 0
	v_mfma_f32_16x16x32_bf16 v[116:119], v[176:179], v[192:195], v[116:119]
	v_mfma_f32_16x16x32_bf16 v[112:115], v[184:187], v[192:195], v[112:115]
	v_mfma_f32_16x16x32_bf16 v[100:103], v[176:179], v[200:203], v[100:103]
	v_mfma_f32_16x16x32_bf16 v[96:99], v[184:187], v[200:203], v[96:99]
	v_mfma_f32_16x16x32_bf16 v[84:87], v[176:179], v[208:211], v[84:87]
	v_mfma_f32_16x16x32_bf16 v[80:83], v[184:187], v[208:211], v[80:83]
	v_mfma_f32_16x16x32_bf16 v[68:71], v[176:179], v[216:219], v[68:71]
	v_mfma_f32_16x16x32_bf16 v[64:67], v[184:187], v[216:219], v[64:67]
	s_setprio 0
	s_barrier
	s_add_i32 s34, s64, s51
	v_lshl_add_u64 v[220:221], s[42:43], 0, v[134:135]
	s_mov_b32 m0, s34
	ds_read_b128 v[188:191], v157 offset:16384
	ds_read_b128 v[192:195], v157 offset:17408
	ds_read_b128 v[196:199], v157 offset:18432
	ds_read_b128 v[200:203], v157 offset:19456
	ds_read_b128 v[204:207], v157 offset:20480
	ds_read_b128 v[208:211], v157 offset:21504
	ds_read_b128 v[212:215], v157 offset:22528
	ds_read_b128 v[216:219], v157 offset:23552
	global_load_lds_dwordx4 v[220:221], off
	s_add_i32 m0, s34, 0x2000
	s_add_u32 s34, s42, 0xb0000
	v_lshl_add_u64 v[222:223], s[42:43], 0, v[138:139]
	s_addc_u32 s35, s43, 0
	s_add_i32 s82, s65, s51
	global_load_lds_dwordx4 v[222:223], off
	v_lshl_add_u64 v[224:225], s[34:35], 0, v[134:135]
	s_mov_b32 m0, s82
	v_lshl_add_u64 v[226:227], s[48:49], 0, v[136:137]
	global_load_lds_dwordx4 v[224:225], off
	v_lshl_add_u64 v[224:225], s[34:35], 0, v[138:139]
	s_add_i32 m0, s82, 0x2000
	s_nop 0
	global_load_lds_dwordx4 v[224:225], off
	v_lshl_add_u64 v[224:225], s[48:49], 0, v[132:133]
	s_mov_b32 m0, s52
	s_nop 0
	global_load_lds_dwordx4 v[224:225], off
	s_mov_b32 m0, s53
	s_nop 0
	global_load_lds_dwordx4 v[226:227], off
	s_waitcnt vmcnt(8)
	s_waitcnt lgkmcnt(0)
	s_barrier
	s_setprio 1
	s_waitcnt lgkmcnt(0)
	v_mfma_f32_16x16x32_bf16 v[60:63], v[148:151], v[188:191], 0
	v_mfma_f32_16x16x32_bf16 v[56:59], v[164:167], v[188:191], 0
	v_mfma_f32_16x16x32_bf16 v[44:47], v[148:151], v[196:199], 0
	v_mfma_f32_16x16x32_bf16 v[40:43], v[164:167], v[196:199], 0
	v_mfma_f32_16x16x32_bf16 v[28:31], v[148:151], v[204:207], 0
	v_mfma_f32_16x16x32_bf16 v[24:27], v[164:167], v[204:207], 0
	v_mfma_f32_16x16x32_bf16 v[12:15], v[148:151], v[212:215], 0
	v_mfma_f32_16x16x32_bf16 v[8:11], v[164:167], v[212:215], 0
	v_mfma_f32_16x16x32_bf16 v[60:63], v[160:163], v[192:195], v[60:63]
	v_mfma_f32_16x16x32_bf16 v[56:59], v[168:171], v[192:195], v[56:59]
	v_mfma_f32_16x16x32_bf16 v[44:47], v[160:163], v[200:203], v[44:47]
	v_mfma_f32_16x16x32_bf16 v[40:43], v[168:171], v[200:203], v[40:43]
	v_mfma_f32_16x16x32_bf16 v[28:31], v[160:163], v[208:211], v[28:31]
	v_mfma_f32_16x16x32_bf16 v[24:27], v[168:171], v[208:211], v[24:27]
	v_mfma_f32_16x16x32_bf16 v[12:15], v[160:163], v[216:219], v[12:15]
	v_mfma_f32_16x16x32_bf16 v[8:11], v[168:171], v[216:219], v[8:11]
	s_setprio 0
	s_setprio 1
	v_mfma_f32_16x16x32_bf16 v[52:55], v[172:175], v[188:191], 0
	v_mfma_f32_16x16x32_bf16 v[48:51], v[180:183], v[188:191], 0
	v_mfma_f32_16x16x32_bf16 v[36:39], v[172:175], v[196:199], 0
	v_mfma_f32_16x16x32_bf16 v[32:35], v[180:183], v[196:199], 0
	v_mfma_f32_16x16x32_bf16 v[20:23], v[172:175], v[204:207], 0
	v_mfma_f32_16x16x32_bf16 v[16:19], v[180:183], v[204:207], 0
	v_mfma_f32_16x16x32_bf16 v[4:7], v[172:175], v[212:215], 0
	v_mfma_f32_16x16x32_bf16 v[0:3], v[180:183], v[212:215], 0
	v_mfma_f32_16x16x32_bf16 v[52:55], v[176:179], v[192:195], v[52:55]
	v_mfma_f32_16x16x32_bf16 v[48:51], v[184:187], v[192:195], v[48:51]
	v_mfma_f32_16x16x32_bf16 v[36:39], v[176:179], v[200:203], v[36:39]
	v_mfma_f32_16x16x32_bf16 v[32:35], v[184:187], v[200:203], v[32:35]
	v_mfma_f32_16x16x32_bf16 v[20:23], v[176:179], v[208:211], v[20:23]
	v_mfma_f32_16x16x32_bf16 v[16:19], v[184:187], v[208:211], v[16:19]
	v_mfma_f32_16x16x32_bf16 v[4:7], v[176:179], v[216:219], v[4:7]
	v_mfma_f32_16x16x32_bf16 v[0:3], v[184:187], v[216:219], v[0:3]
	s_setprio 0
	s_barrier
	s_add_i32 s82, 0, 0x18000
	v_add_u32_e32 v159, s82, v152
	s_add_i32 s83, 0, 0x1c000
	ds_read_b128 v[148:151], v159
	ds_read_b128 v[160:163], v159 offset:1024
	ds_read_b128 v[164:167], v159 offset:2048
	ds_read_b128 v[168:171], v159 offset:3072
	v_add_u32_e32 v159, s83, v152
	ds_read_b128 v[172:175], v159
	ds_read_b128 v[176:179], v159 offset:1024
	ds_read_b128 v[180:183], v159 offset:2048
	ds_read_b128 v[184:187], v159 offset:3072
	s_add_u32 s34, s48, 0xb0000
	s_addc_u32 s35, s49, 0
	s_mov_b32 m0, s54
	v_lshl_add_u64 v[228:229], s[34:35], 0, v[132:133]
	ds_read_b128 v[188:191], v157 offset:32768
	ds_read_b128 v[192:195], v157 offset:33792
	ds_read_b128 v[196:199], v157 offset:34816
	ds_read_b128 v[200:203], v157 offset:35840
	ds_read_b128 v[204:207], v157 offset:36864
	ds_read_b128 v[208:211], v157 offset:37888
	ds_read_b128 v[212:215], v157 offset:38912
	ds_read_b128 v[216:219], v157 offset:39936
	global_load_lds_dwordx4 v[228:229], off
	v_lshl_add_u64 v[228:229], s[34:35], 0, v[136:137]
	s_mov_b32 m0, s55
	s_nop 0
	global_load_lds_dwordx4 v[228:229], off
	s_waitcnt vmcnt(8)
	s_waitcnt lgkmcnt(0)
	s_barrier
	s_setprio 1
	s_waitcnt lgkmcnt(0)
	v_mfma_f32_16x16x32_bf16 v[124:127], v[148:151], v[188:191], v[124:127]
	v_mfma_f32_16x16x32_bf16 v[120:123], v[164:167], v[188:191], v[120:123]
	v_mfma_f32_16x16x32_bf16 v[108:111], v[148:151], v[196:199], v[108:111]
	v_mfma_f32_16x16x32_bf16 v[104:107], v[164:167], v[196:199], v[104:107]
	v_mfma_f32_16x16x32_bf16 v[92:95], v[148:151], v[204:207], v[92:95]
	v_mfma_f32_16x16x32_bf16 v[88:91], v[164:167], v[204:207], v[88:91]
	v_mfma_f32_16x16x32_bf16 v[76:79], v[148:151], v[212:215], v[76:79]
	v_mfma_f32_16x16x32_bf16 v[72:75], v[164:167], v[212:215], v[72:75]
	v_mfma_f32_16x16x32_bf16 v[124:127], v[160:163], v[192:195], v[124:127]
	v_mfma_f32_16x16x32_bf16 v[120:123], v[168:171], v[192:195], v[120:123]
	v_mfma_f32_16x16x32_bf16 v[108:111], v[160:163], v[200:203], v[108:111]
	v_mfma_f32_16x16x32_bf16 v[104:107], v[168:171], v[200:203], v[104:107]
	v_mfma_f32_16x16x32_bf16 v[92:95], v[160:163], v[208:211], v[92:95]
	v_mfma_f32_16x16x32_bf16 v[88:91], v[168:171], v[208:211], v[88:91]
	v_mfma_f32_16x16x32_bf16 v[76:79], v[160:163], v[216:219], v[76:79]
	v_mfma_f32_16x16x32_bf16 v[72:75], v[168:171], v[216:219], v[72:75]
	s_setprio 0
	s_setprio 1
	v_mfma_f32_16x16x32_bf16 v[116:119], v[172:175], v[188:191], v[116:119]
	v_mfma_f32_16x16x32_bf16 v[112:115], v[180:183], v[188:191], v[112:115]
	v_mfma_f32_16x16x32_bf16 v[100:103], v[172:175], v[196:199], v[100:103]
	v_mfma_f32_16x16x32_bf16 v[96:99], v[180:183], v[196:199], v[96:99]
	v_mfma_f32_16x16x32_bf16 v[84:87], v[172:175], v[204:207], v[84:87]
	v_mfma_f32_16x16x32_bf16 v[80:83], v[180:183], v[204:207], v[80:83]
	v_mfma_f32_16x16x32_bf16 v[68:71], v[172:175], v[212:215], v[68:71]
	v_mfma_f32_16x16x32_bf16 v[64:67], v[180:183], v[212:215], v[64:67]
	v_mfma_f32_16x16x32_bf16 v[116:119], v[176:179], v[192:195], v[116:119]
	v_mfma_f32_16x16x32_bf16 v[112:115], v[184:187], v[192:195], v[112:115]
	v_mfma_f32_16x16x32_bf16 v[100:103], v[176:179], v[200:203], v[100:103]
	v_mfma_f32_16x16x32_bf16 v[96:99], v[184:187], v[200:203], v[96:99]
	v_mfma_f32_16x16x32_bf16 v[84:87], v[176:179], v[208:211], v[84:87]
	v_mfma_f32_16x16x32_bf16 v[80:83], v[184:187], v[208:211], v[80:83]
	v_mfma_f32_16x16x32_bf16 v[68:71], v[176:179], v[216:219], v[68:71]
	v_mfma_f32_16x16x32_bf16 v[64:67], v[184:187], v[216:219], v[64:67]
	s_setprio 0
	s_barrier
	s_add_i32 s34, s82, s51
	v_lshl_add_u64 v[220:221], v[220:221], 0, s[22:23]
	s_mov_b32 m0, s34
	ds_read_b128 v[188:191], v157 offset:49152
	ds_read_b128 v[192:195], v157 offset:50176
	ds_read_b128 v[196:199], v157 offset:51200
	ds_read_b128 v[200:203], v157 offset:52224
	ds_read_b128 v[204:207], v157 offset:53248
	ds_read_b128 v[208:211], v157 offset:54272
	ds_read_b128 v[212:215], v157 offset:55296
	ds_read_b128 v[216:219], v157 offset:56320
	global_load_lds_dwordx4 v[220:221], off
	s_add_i32 m0, s34, 0x2000
	s_add_u32 s34, s42, 0xb0080
	v_lshl_add_u64 v[220:221], v[222:223], 0, s[22:23]
	s_addc_u32 s35, s43, 0
	s_add_i32 s42, s83, s51
	global_load_lds_dwordx4 v[220:221], off
	v_lshl_add_u64 v[220:221], s[34:35], 0, v[134:135]
	s_mov_b32 m0, s42
	s_nop 0
	global_load_lds_dwordx4 v[220:221], off
	v_lshl_add_u64 v[220:221], s[34:35], 0, v[138:139]
	s_add_i32 m0, s42, 0x2000
	s_nop 0
	global_load_lds_dwordx4 v[220:221], off
	v_lshl_add_u64 v[220:221], v[224:225], 0, s[22:23]
	s_mov_b32 m0, s57
	s_nop 0
	global_load_lds_dwordx4 v[220:221], off
	v_lshl_add_u64 v[220:221], v[226:227], 0, s[22:23]
	s_mov_b32 m0, s58
	s_nop 0
	global_load_lds_dwordx4 v[220:221], off
	s_waitcnt vmcnt(8)
	s_waitcnt lgkmcnt(0)
	s_barrier
	s_add_u32 s40, s40, 0x100
	s_addc_u32 s41, s41, 0
	s_add_u32 s13, s13, 0x100
	s_addc_u32 s77, s77, 0
	s_setprio 1
	s_waitcnt lgkmcnt(0)
	v_mfma_f32_16x16x32_bf16 v[60:63], v[148:151], v[188:191], v[60:63]
	v_mfma_f32_16x16x32_bf16 v[56:59], v[164:167], v[188:191], v[56:59]
	v_mfma_f32_16x16x32_bf16 v[44:47], v[148:151], v[196:199], v[44:47]
	v_mfma_f32_16x16x32_bf16 v[40:43], v[164:167], v[196:199], v[40:43]
	v_mfma_f32_16x16x32_bf16 v[28:31], v[148:151], v[204:207], v[28:31]
	v_mfma_f32_16x16x32_bf16 v[24:27], v[164:167], v[204:207], v[24:27]
	v_mfma_f32_16x16x32_bf16 v[12:15], v[148:151], v[212:215], v[12:15]
	v_mfma_f32_16x16x32_bf16 v[8:11], v[164:167], v[212:215], v[8:11]
	v_mfma_f32_16x16x32_bf16 v[60:63], v[160:163], v[192:195], v[60:63]
	v_mfma_f32_16x16x32_bf16 v[56:59], v[168:171], v[192:195], v[56:59]
	v_mfma_f32_16x16x32_bf16 v[44:47], v[160:163], v[200:203], v[44:47]
	v_mfma_f32_16x16x32_bf16 v[40:43], v[168:171], v[200:203], v[40:43]
	v_mfma_f32_16x16x32_bf16 v[28:31], v[160:163], v[208:211], v[28:31]
	v_mfma_f32_16x16x32_bf16 v[24:27], v[168:171], v[208:211], v[24:27]
	v_mfma_f32_16x16x32_bf16 v[12:15], v[160:163], v[216:219], v[12:15]
	v_mfma_f32_16x16x32_bf16 v[8:11], v[168:171], v[216:219], v[8:11]
	s_setprio 0
	s_setprio 1
	v_mfma_f32_16x16x32_bf16 v[52:55], v[172:175], v[188:191], v[52:55]
	v_mfma_f32_16x16x32_bf16 v[48:51], v[180:183], v[188:191], v[48:51]
	v_mfma_f32_16x16x32_bf16 v[36:39], v[172:175], v[196:199], v[36:39]
	v_mfma_f32_16x16x32_bf16 v[32:35], v[180:183], v[196:199], v[32:35]
	v_mfma_f32_16x16x32_bf16 v[20:23], v[172:175], v[204:207], v[20:23]
	v_mfma_f32_16x16x32_bf16 v[16:19], v[180:183], v[204:207], v[16:19]
	v_mfma_f32_16x16x32_bf16 v[4:7], v[172:175], v[212:215], v[4:7]
	v_mfma_f32_16x16x32_bf16 v[0:3], v[180:183], v[212:215], v[0:3]
	v_mfma_f32_16x16x32_bf16 v[52:55], v[176:179], v[192:195], v[52:55]
	v_mfma_f32_16x16x32_bf16 v[48:51], v[184:187], v[192:195], v[48:51]
	v_mfma_f32_16x16x32_bf16 v[36:39], v[176:179], v[200:203], v[36:39]
	v_mfma_f32_16x16x32_bf16 v[32:35], v[184:187], v[200:203], v[32:35]
	v_mfma_f32_16x16x32_bf16 v[20:23], v[176:179], v[208:211], v[20:23]
	v_mfma_f32_16x16x32_bf16 v[16:19], v[184:187], v[208:211], v[16:19]
	v_mfma_f32_16x16x32_bf16 v[4:7], v[176:179], v[216:219], v[4:7]
	v_mfma_f32_16x16x32_bf16 v[0:3], v[184:187], v[216:219], v[0:3]
	s_setprio 0
	s_barrier
	s_add_i32 s81, s81, 2
.LBB0_562:
	ds_read_b128 v[148:151], v154
	ds_read_b128 v[160:163], v154 offset:1024
	ds_read_b128 v[164:167], v154 offset:2048
	ds_read_b128 v[168:171], v154 offset:3072
	ds_read_b128 v[172:175], v155
	ds_read_b128 v[176:179], v155 offset:1024
	ds_read_b128 v[180:183], v155 offset:2048
	ds_read_b128 v[184:187], v155 offset:3072
	s_add_u32 s34, s40, 0xfff50080
	s_addc_u32 s35, s41, -1
	s_cmp_eq_u32 s81, 40
	s_cselect_b32 s49, s1, s35
	s_cselect_b32 s48, s0, s34
	s_cselect_b32 s43, s29, s77
	s_cselect_b32 s42, s28, s13
	v_lshl_add_u64 v[220:221], s[40:41], 0, v[140:141]
	s_add_i32 m0, s52, 0xc000
	ds_read_b128 v[188:191], v157
	ds_read_b128 v[192:195], v157 offset:1024
	ds_read_b128 v[196:199], v157 offset:2048
	ds_read_b128 v[200:203], v157 offset:3072
	ds_read_b128 v[204:207], v157 offset:4096
	ds_read_b128 v[208:211], v157 offset:5120
	ds_read_b128 v[212:215], v157 offset:6144
	ds_read_b128 v[216:219], v157 offset:7168
	global_load_lds_dwordx4 v[220:221], off
	v_lshl_add_u64 v[220:221], s[40:41], 0, v[142:143]
	s_add_i32 m0, s52, 0xe000
	s_nop 0
	global_load_lds_dwordx4 v[220:221], off
	s_waitcnt vmcnt(8)
	s_waitcnt lgkmcnt(0)
	s_barrier
	s_setprio 1
	s_waitcnt lgkmcnt(0)
	v_mfma_f32_16x16x32_bf16 v[124:127], v[148:151], v[188:191], v[124:127]
	v_mfma_f32_16x16x32_bf16 v[120:123], v[164:167], v[188:191], v[120:123]
	v_mfma_f32_16x16x32_bf16 v[108:111], v[148:151], v[196:199], v[108:111]
	v_mfma_f32_16x16x32_bf16 v[104:107], v[164:167], v[196:199], v[104:107]
	v_mfma_f32_16x16x32_bf16 v[92:95], v[148:151], v[204:207], v[92:95]
	v_mfma_f32_16x16x32_bf16 v[88:91], v[164:167], v[204:207], v[88:91]
	v_mfma_f32_16x16x32_bf16 v[76:79], v[148:151], v[212:215], v[76:79]
	v_mfma_f32_16x16x32_bf16 v[72:75], v[164:167], v[212:215], v[72:75]
	v_mfma_f32_16x16x32_bf16 v[124:127], v[160:163], v[192:195], v[124:127]
	v_mfma_f32_16x16x32_bf16 v[120:123], v[168:171], v[192:195], v[120:123]
	v_mfma_f32_16x16x32_bf16 v[108:111], v[160:163], v[200:203], v[108:111]
	v_mfma_f32_16x16x32_bf16 v[104:107], v[168:171], v[200:203], v[104:107]
	v_mfma_f32_16x16x32_bf16 v[92:95], v[160:163], v[208:211], v[92:95]
	v_mfma_f32_16x16x32_bf16 v[88:91], v[168:171], v[208:211], v[88:91]
	v_mfma_f32_16x16x32_bf16 v[76:79], v[160:163], v[216:219], v[76:79]
	v_mfma_f32_16x16x32_bf16 v[72:75], v[168:171], v[216:219], v[72:75]
	s_setprio 0
	s_setprio 1
	v_mfma_f32_16x16x32_bf16 v[116:119], v[172:175], v[188:191], v[116:119]
	v_mfma_f32_16x16x32_bf16 v[112:115], v[180:183], v[188:191], v[112:115]
	v_mfma_f32_16x16x32_bf16 v[100:103], v[172:175], v[196:199], v[100:103]
	v_mfma_f32_16x16x32_bf16 v[96:99], v[180:183], v[196:199], v[96:99]
	v_mfma_f32_16x16x32_bf16 v[84:87], v[172:175], v[204:207], v[84:87]
	v_mfma_f32_16x16x32_bf16 v[80:83], v[180:183], v[204:207], v[80:83]
	v_mfma_f32_16x16x32_bf16 v[68:71], v[172:175], v[212:215], v[68:71]
	v_mfma_f32_16x16x32_bf16 v[64:67], v[180:183], v[212:215], v[64:67]
	v_mfma_f32_16x16x32_bf16 v[116:119], v[176:179], v[192:195], v[116:119]
	v_mfma_f32_16x16x32_bf16 v[112:115], v[184:187], v[192:195], v[112:115]
	v_mfma_f32_16x16x32_bf16 v[100:103], v[176:179], v[200:203], v[100:103]
	v_mfma_f32_16x16x32_bf16 v[96:99], v[184:187], v[200:203], v[96:99]
	v_mfma_f32_16x16x32_bf16 v[84:87], v[176:179], v[208:211], v[84:87]
	v_mfma_f32_16x16x32_bf16 v[80:83], v[184:187], v[208:211], v[80:83]
	v_mfma_f32_16x16x32_bf16 v[68:71], v[176:179], v[216:219], v[68:71]
	v_mfma_f32_16x16x32_bf16 v[64:67], v[184:187], v[216:219], v[64:67]
	s_setprio 0
	s_barrier
	s_add_i32 s34, s64, s51
	v_lshl_add_u64 v[220:221], s[42:43], 0, v[134:135]
	s_mov_b32 m0, s34
	ds_read_b128 v[188:191], v157 offset:16384
	ds_read_b128 v[192:195], v157 offset:17408
	ds_read_b128 v[196:199], v157 offset:18432
	ds_read_b128 v[200:203], v157 offset:19456
	ds_read_b128 v[204:207], v157 offset:20480
	ds_read_b128 v[208:211], v157 offset:21504
	ds_read_b128 v[212:215], v157 offset:22528
	ds_read_b128 v[216:219], v157 offset:23552
	global_load_lds_dwordx4 v[220:221], off
	s_add_i32 m0, s34, 0x2000
	s_add_u32 s34, s42, 0xb0000
	v_lshl_add_u64 v[222:223], s[42:43], 0, v[138:139]
	s_addc_u32 s35, s43, 0
	s_add_i32 s82, s65, s51
	global_load_lds_dwordx4 v[222:223], off
	v_lshl_add_u64 v[224:225], s[34:35], 0, v[134:135]
	s_mov_b32 m0, s82
	v_lshl_add_u64 v[226:227], s[48:49], 0, v[136:137]
	global_load_lds_dwordx4 v[224:225], off
	v_lshl_add_u64 v[224:225], s[34:35], 0, v[138:139]
	s_add_i32 m0, s82, 0x2000
	s_nop 0
	global_load_lds_dwordx4 v[224:225], off
	v_lshl_add_u64 v[224:225], s[48:49], 0, v[132:133]
	s_mov_b32 m0, s52
	s_nop 0
	global_load_lds_dwordx4 v[224:225], off
	s_mov_b32 m0, s53
	s_nop 0
	global_load_lds_dwordx4 v[226:227], off
	s_waitcnt vmcnt(8)
	s_waitcnt lgkmcnt(0)
	s_barrier
	s_setprio 1
	s_waitcnt lgkmcnt(0)
	v_mfma_f32_16x16x32_bf16 v[60:63], v[148:151], v[188:191], v[60:63]
	v_mfma_f32_16x16x32_bf16 v[56:59], v[164:167], v[188:191], v[56:59]
	v_mfma_f32_16x16x32_bf16 v[44:47], v[148:151], v[196:199], v[44:47]
	v_mfma_f32_16x16x32_bf16 v[40:43], v[164:167], v[196:199], v[40:43]
	v_mfma_f32_16x16x32_bf16 v[28:31], v[148:151], v[204:207], v[28:31]
	v_mfma_f32_16x16x32_bf16 v[24:27], v[164:167], v[204:207], v[24:27]
	v_mfma_f32_16x16x32_bf16 v[12:15], v[148:151], v[212:215], v[12:15]
	v_mfma_f32_16x16x32_bf16 v[8:11], v[164:167], v[212:215], v[8:11]
	v_mfma_f32_16x16x32_bf16 v[60:63], v[160:163], v[192:195], v[60:63]
	v_mfma_f32_16x16x32_bf16 v[56:59], v[168:171], v[192:195], v[56:59]
	v_mfma_f32_16x16x32_bf16 v[44:47], v[160:163], v[200:203], v[44:47]
	v_mfma_f32_16x16x32_bf16 v[40:43], v[168:171], v[200:203], v[40:43]
	v_mfma_f32_16x16x32_bf16 v[28:31], v[160:163], v[208:211], v[28:31]
	v_mfma_f32_16x16x32_bf16 v[24:27], v[168:171], v[208:211], v[24:27]
	v_mfma_f32_16x16x32_bf16 v[12:15], v[160:163], v[216:219], v[12:15]
	v_mfma_f32_16x16x32_bf16 v[8:11], v[168:171], v[216:219], v[8:11]
	s_setprio 0
	s_setprio 1
	v_mfma_f32_16x16x32_bf16 v[52:55], v[172:175], v[188:191], v[52:55]
	v_mfma_f32_16x16x32_bf16 v[48:51], v[180:183], v[188:191], v[48:51]
	v_mfma_f32_16x16x32_bf16 v[36:39], v[172:175], v[196:199], v[36:39]
	v_mfma_f32_16x16x32_bf16 v[32:35], v[180:183], v[196:199], v[32:35]
	v_mfma_f32_16x16x32_bf16 v[20:23], v[172:175], v[204:207], v[20:23]
	v_mfma_f32_16x16x32_bf16 v[16:19], v[180:183], v[204:207], v[16:19]
	v_mfma_f32_16x16x32_bf16 v[4:7], v[172:175], v[212:215], v[4:7]
	v_mfma_f32_16x16x32_bf16 v[0:3], v[180:183], v[212:215], v[0:3]
	v_mfma_f32_16x16x32_bf16 v[52:55], v[176:179], v[192:195], v[52:55]
	v_mfma_f32_16x16x32_bf16 v[48:51], v[184:187], v[192:195], v[48:51]
	v_mfma_f32_16x16x32_bf16 v[36:39], v[176:179], v[200:203], v[36:39]
	v_mfma_f32_16x16x32_bf16 v[32:35], v[184:187], v[200:203], v[32:35]
	v_mfma_f32_16x16x32_bf16 v[20:23], v[176:179], v[208:211], v[20:23]
	v_mfma_f32_16x16x32_bf16 v[16:19], v[184:187], v[208:211], v[16:19]
	v_mfma_f32_16x16x32_bf16 v[4:7], v[176:179], v[216:219], v[4:7]
	v_mfma_f32_16x16x32_bf16 v[0:3], v[184:187], v[216:219], v[0:3]
	s_setprio 0
	s_barrier
	s_add_i32 s82, 0, 0x18000
	v_add_u32_e32 v159, s82, v152
	s_add_i32 s83, 0, 0x1c000
	ds_read_b128 v[148:151], v159
	ds_read_b128 v[160:163], v159 offset:1024
	ds_read_b128 v[164:167], v159 offset:2048
	ds_read_b128 v[168:171], v159 offset:3072
	v_add_u32_e32 v159, s83, v152
	ds_read_b128 v[172:175], v159
	ds_read_b128 v[176:179], v159 offset:1024
	ds_read_b128 v[180:183], v159 offset:2048
	ds_read_b128 v[184:187], v159 offset:3072
	s_add_u32 s34, s48, 0xb0000
	s_addc_u32 s35, s49, 0
	s_mov_b32 m0, s54
	v_lshl_add_u64 v[228:229], s[34:35], 0, v[132:133]
	ds_read_b128 v[188:191], v157 offset:32768
	ds_read_b128 v[192:195], v157 offset:33792
	ds_read_b128 v[196:199], v157 offset:34816
	ds_read_b128 v[200:203], v157 offset:35840
	ds_read_b128 v[204:207], v157 offset:36864
	ds_read_b128 v[208:211], v157 offset:37888
	ds_read_b128 v[212:215], v157 offset:38912
	ds_read_b128 v[216:219], v157 offset:39936
	global_load_lds_dwordx4 v[228:229], off
	v_lshl_add_u64 v[228:229], s[34:35], 0, v[136:137]
	s_mov_b32 m0, s55
	s_nop 0
	global_load_lds_dwordx4 v[228:229], off
	s_waitcnt vmcnt(8)
	s_waitcnt lgkmcnt(0)
	s_barrier
	s_setprio 1
	s_waitcnt lgkmcnt(0)
	v_mfma_f32_16x16x32_bf16 v[124:127], v[148:151], v[188:191], v[124:127]
	v_mfma_f32_16x16x32_bf16 v[120:123], v[164:167], v[188:191], v[120:123]
	v_mfma_f32_16x16x32_bf16 v[108:111], v[148:151], v[196:199], v[108:111]
	v_mfma_f32_16x16x32_bf16 v[104:107], v[164:167], v[196:199], v[104:107]
	v_mfma_f32_16x16x32_bf16 v[92:95], v[148:151], v[204:207], v[92:95]
	v_mfma_f32_16x16x32_bf16 v[88:91], v[164:167], v[204:207], v[88:91]
	v_mfma_f32_16x16x32_bf16 v[76:79], v[148:151], v[212:215], v[76:79]
	v_mfma_f32_16x16x32_bf16 v[72:75], v[164:167], v[212:215], v[72:75]
	v_mfma_f32_16x16x32_bf16 v[124:127], v[160:163], v[192:195], v[124:127]
	v_mfma_f32_16x16x32_bf16 v[120:123], v[168:171], v[192:195], v[120:123]
	v_mfma_f32_16x16x32_bf16 v[108:111], v[160:163], v[200:203], v[108:111]
	v_mfma_f32_16x16x32_bf16 v[104:107], v[168:171], v[200:203], v[104:107]
	v_mfma_f32_16x16x32_bf16 v[92:95], v[160:163], v[208:211], v[92:95]
	v_mfma_f32_16x16x32_bf16 v[88:91], v[168:171], v[208:211], v[88:91]
	v_mfma_f32_16x16x32_bf16 v[76:79], v[160:163], v[216:219], v[76:79]
	v_mfma_f32_16x16x32_bf16 v[72:75], v[168:171], v[216:219], v[72:75]
	s_setprio 0
	s_setprio 1
	v_mfma_f32_16x16x32_bf16 v[116:119], v[172:175], v[188:191], v[116:119]
	v_mfma_f32_16x16x32_bf16 v[112:115], v[180:183], v[188:191], v[112:115]
	v_mfma_f32_16x16x32_bf16 v[100:103], v[172:175], v[196:199], v[100:103]
	v_mfma_f32_16x16x32_bf16 v[96:99], v[180:183], v[196:199], v[96:99]
	v_mfma_f32_16x16x32_bf16 v[84:87], v[172:175], v[204:207], v[84:87]
	v_mfma_f32_16x16x32_bf16 v[80:83], v[180:183], v[204:207], v[80:83]
	v_mfma_f32_16x16x32_bf16 v[68:71], v[172:175], v[212:215], v[68:71]
	v_mfma_f32_16x16x32_bf16 v[64:67], v[180:183], v[212:215], v[64:67]
	v_mfma_f32_16x16x32_bf16 v[116:119], v[176:179], v[192:195], v[116:119]
	v_mfma_f32_16x16x32_bf16 v[112:115], v[184:187], v[192:195], v[112:115]
	v_mfma_f32_16x16x32_bf16 v[100:103], v[176:179], v[200:203], v[100:103]
	v_mfma_f32_16x16x32_bf16 v[96:99], v[184:187], v[200:203], v[96:99]
	v_mfma_f32_16x16x32_bf16 v[84:87], v[176:179], v[208:211], v[84:87]
	v_mfma_f32_16x16x32_bf16 v[80:83], v[184:187], v[208:211], v[80:83]
	v_mfma_f32_16x16x32_bf16 v[68:71], v[176:179], v[216:219], v[68:71]
	v_mfma_f32_16x16x32_bf16 v[64:67], v[184:187], v[216:219], v[64:67]
	s_setprio 0
	s_barrier
	s_add_i32 s34, s82, s51
	v_lshl_add_u64 v[220:221], v[220:221], 0, s[22:23]
	s_mov_b32 m0, s34
	ds_read_b128 v[188:191], v157 offset:49152
	ds_read_b128 v[192:195], v157 offset:50176
	ds_read_b128 v[196:199], v157 offset:51200
	ds_read_b128 v[200:203], v157 offset:52224
	ds_read_b128 v[204:207], v157 offset:53248
	ds_read_b128 v[208:211], v157 offset:54272
	ds_read_b128 v[212:215], v157 offset:55296
	ds_read_b128 v[216:219], v157 offset:56320
	global_load_lds_dwordx4 v[220:221], off
	s_add_i32 m0, s34, 0x2000
	s_add_u32 s34, s42, 0xb0080
	v_lshl_add_u64 v[220:221], v[222:223], 0, s[22:23]
	s_addc_u32 s35, s43, 0
	s_add_i32 s42, s83, s51
	global_load_lds_dwordx4 v[220:221], off
	v_lshl_add_u64 v[220:221], s[34:35], 0, v[134:135]
	s_mov_b32 m0, s42
	s_nop 0
	global_load_lds_dwordx4 v[220:221], off
	v_lshl_add_u64 v[220:221], s[34:35], 0, v[138:139]
	s_add_i32 m0, s42, 0x2000
	s_nop 0
	global_load_lds_dwordx4 v[220:221], off
	v_lshl_add_u64 v[220:221], v[224:225], 0, s[22:23]
	s_mov_b32 m0, s57
	s_nop 0
	global_load_lds_dwordx4 v[220:221], off
	v_lshl_add_u64 v[220:221], v[226:227], 0, s[22:23]
	s_mov_b32 m0, s58
	s_nop 0
	global_load_lds_dwordx4 v[220:221], off
	s_waitcnt vmcnt(8)
	s_waitcnt lgkmcnt(0)
	s_barrier
	s_add_u32 s40, s40, 0x100
	s_addc_u32 s41, s41, 0
	s_add_u32 s13, s13, 0x100
	s_addc_u32 s77, s77, 0
	s_setprio 1
	s_waitcnt lgkmcnt(0)
	v_mfma_f32_16x16x32_bf16 v[60:63], v[148:151], v[188:191], v[60:63]
	v_mfma_f32_16x16x32_bf16 v[56:59], v[164:167], v[188:191], v[56:59]
	v_mfma_f32_16x16x32_bf16 v[44:47], v[148:151], v[196:199], v[44:47]
	v_mfma_f32_16x16x32_bf16 v[40:43], v[164:167], v[196:199], v[40:43]
	v_mfma_f32_16x16x32_bf16 v[28:31], v[148:151], v[204:207], v[28:31]
	v_mfma_f32_16x16x32_bf16 v[24:27], v[164:167], v[204:207], v[24:27]
	v_mfma_f32_16x16x32_bf16 v[12:15], v[148:151], v[212:215], v[12:15]
	v_mfma_f32_16x16x32_bf16 v[8:11], v[164:167], v[212:215], v[8:11]
	v_mfma_f32_16x16x32_bf16 v[60:63], v[160:163], v[192:195], v[60:63]
	v_mfma_f32_16x16x32_bf16 v[56:59], v[168:171], v[192:195], v[56:59]
	v_mfma_f32_16x16x32_bf16 v[44:47], v[160:163], v[200:203], v[44:47]
	v_mfma_f32_16x16x32_bf16 v[40:43], v[168:171], v[200:203], v[40:43]
	v_mfma_f32_16x16x32_bf16 v[28:31], v[160:163], v[208:211], v[28:31]
	v_mfma_f32_16x16x32_bf16 v[24:27], v[168:171], v[208:211], v[24:27]
	v_mfma_f32_16x16x32_bf16 v[12:15], v[160:163], v[216:219], v[12:15]
	v_mfma_f32_16x16x32_bf16 v[8:11], v[168:171], v[216:219], v[8:11]
	s_setprio 0
	s_setprio 1
	v_mfma_f32_16x16x32_bf16 v[52:55], v[172:175], v[188:191], v[52:55]
	v_mfma_f32_16x16x32_bf16 v[48:51], v[180:183], v[188:191], v[48:51]
	v_mfma_f32_16x16x32_bf16 v[36:39], v[172:175], v[196:199], v[36:39]
	v_mfma_f32_16x16x32_bf16 v[32:35], v[180:183], v[196:199], v[32:35]
	v_mfma_f32_16x16x32_bf16 v[20:23], v[172:175], v[204:207], v[20:23]
	v_mfma_f32_16x16x32_bf16 v[16:19], v[180:183], v[204:207], v[16:19]
	v_mfma_f32_16x16x32_bf16 v[4:7], v[172:175], v[212:215], v[4:7]
	v_mfma_f32_16x16x32_bf16 v[0:3], v[180:183], v[212:215], v[0:3]
	v_mfma_f32_16x16x32_bf16 v[52:55], v[176:179], v[192:195], v[52:55]
	v_mfma_f32_16x16x32_bf16 v[48:51], v[184:187], v[192:195], v[48:51]
	v_mfma_f32_16x16x32_bf16 v[36:39], v[176:179], v[200:203], v[36:39]
	v_mfma_f32_16x16x32_bf16 v[32:35], v[184:187], v[200:203], v[32:35]
	v_mfma_f32_16x16x32_bf16 v[20:23], v[176:179], v[208:211], v[20:23]
	v_mfma_f32_16x16x32_bf16 v[16:19], v[184:187], v[208:211], v[16:19]
	v_mfma_f32_16x16x32_bf16 v[4:7], v[176:179], v[216:219], v[4:7]
	v_mfma_f32_16x16x32_bf16 v[0:3], v[184:187], v[216:219], v[0:3]
	s_setprio 0
	s_cmp_eq_u32 s81, s98
	s_cbranch_scc1 .Lmy_nobar_6
	s_barrier
.Lmy_nobar_6:
	s_add_i32 s81, s81, 2
	s_cmp_gt_u32 s81, 41
	s_cbranch_scc0 .LBB0_562
	s_and_b64 vcc, exec, s[26:27]
	s_cbranch_vccz .LBB0_565
	s_nop 0

.Lmy_nobar2_7:
	ds_read_b128 v[148:151], v160
	ds_read_b128 v[152:155], v160 offset:1024
	ds_read_b128 v[164:167], v160 offset:2048
	ds_read_b128 v[168:171], v160 offset:3072
	ds_read_b128 v[172:175], v161
	ds_read_b128 v[176:179], v161 offset:1024
	ds_read_b128 v[180:183], v161 offset:2048
	ds_read_b128 v[184:187], v161 offset:3072
	s_add_u32 s34, s52, 0xfffc0080
	s_addc_u32 s35, s53, -1
	s_cmp_eq_u32 s77, 12
	s_cselect_b32 s57, s9, s35
	s_cselect_b32 s56, s10, s34
	s_cselect_b32 s55, s12, s43
	s_cselect_b32 s54, s13, s41
	v_lshl_add_u64 v[220:221], s[52:53], 0, v[140:141]
	s_add_i32 m0, s65, 0xc000
	ds_read_b128 v[188:191], v162
	ds_read_b128 v[192:195], v162 offset:1024
	ds_read_b128 v[196:199], v162 offset:2048
	ds_read_b128 v[200:203], v162 offset:3072
	ds_read_b128 v[204:207], v162 offset:4096
	ds_read_b128 v[208:211], v162 offset:5120
	ds_read_b128 v[212:215], v162 offset:6144
	ds_read_b128 v[216:219], v162 offset:7168
	global_load_lds_dwordx4 v[220:221], off
	v_lshl_add_u64 v[220:221], s[52:53], 0, v[142:143]
	s_add_i32 m0, s65, 0xe000
	s_nop 0
	global_load_lds_dwordx4 v[220:221], off
	s_waitcnt vmcnt(8)
	s_waitcnt lgkmcnt(0)
	s_barrier
	s_setprio 1
	s_waitcnt lgkmcnt(0)
	v_mfma_f32_16x16x32_bf16 v[124:127], v[148:151], v[188:191], 0
	v_mfma_f32_16x16x32_bf16 v[120:123], v[164:167], v[188:191], 0
	v_mfma_f32_16x16x32_bf16 v[108:111], v[148:151], v[196:199], 0
	v_mfma_f32_16x16x32_bf16 v[104:107], v[164:167], v[196:199], 0
	v_mfma_f32_16x16x32_bf16 v[92:95], v[148:151], v[204:207], 0
	v_mfma_f32_16x16x32_bf16 v[88:91], v[164:167], v[204:207], 0
	v_mfma_f32_16x16x32_bf16 v[76:79], v[148:151], v[212:215], 0
	v_mfma_f32_16x16x32_bf16 v[72:75], v[164:167], v[212:215], 0
	v_mfma_f32_16x16x32_bf16 v[124:127], v[152:155], v[192:195], v[124:127]
	v_mfma_f32_16x16x32_bf16 v[120:123], v[168:171], v[192:195], v[120:123]
	v_mfma_f32_16x16x32_bf16 v[108:111], v[152:155], v[200:203], v[108:111]
	v_mfma_f32_16x16x32_bf16 v[104:107], v[168:171], v[200:203], v[104:107]
	v_mfma_f32_16x16x32_bf16 v[92:95], v[152:155], v[208:211], v[92:95]
	v_mfma_f32_16x16x32_bf16 v[88:91], v[168:171], v[208:211], v[88:91]
	v_mfma_f32_16x16x32_bf16 v[76:79], v[152:155], v[216:219], v[76:79]
	v_mfma_f32_16x16x32_bf16 v[72:75], v[168:171], v[216:219], v[72:75]
	s_setprio 0
	s_setprio 1
	v_mfma_f32_16x16x32_bf16 v[116:119], v[172:175], v[188:191], 0
	v_mfma_f32_16x16x32_bf16 v[112:115], v[180:183], v[188:191], 0
	v_mfma_f32_16x16x32_bf16 v[100:103], v[172:175], v[196:199], 0
	v_mfma_f32_16x16x32_bf16 v[96:99], v[180:183], v[196:199], 0
	v_mfma_f32_16x16x32_bf16 v[84:87], v[172:175], v[204:207], 0
	v_mfma_f32_16x16x32_bf16 v[80:83], v[180:183], v[204:207], 0
	v_mfma_f32_16x16x32_bf16 v[68:71], v[172:175], v[212:215], 0
	v_mfma_f32_16x16x32_bf16 v[64:67], v[180:183], v[212:215], 0
	v_mfma_f32_16x16x32_bf16 v[116:119], v[176:179], v[192:195], v[116:119]
	v_mfma_f32_16x16x32_bf16 v[112:115], v[184:187], v[192:195], v[112:115]
	v_mfma_f32_16x16x32_bf16 v[100:103], v[176:179], v[200:203], v[100:103]
	v_mfma_f32_16x16x32_bf16 v[96:99], v[184:187], v[200:203], v[96:99]
	v_mfma_f32_16x16x32_bf16 v[84:87], v[176:179], v[208:211], v[84:87]
	v_mfma_f32_16x16x32_bf16 v[80:83], v[184:187], v[208:211], v[80:83]
	v_mfma_f32_16x16x32_bf16 v[68:71], v[176:179], v[216:219], v[68:71]
	v_mfma_f32_16x16x32_bf16 v[64:67], v[184:187], v[216:219], v[64:67]
	s_setprio 0
	s_barrier
	s_add_i32 s34, s88, s62
	v_lshl_add_u64 v[220:221], s[54:55], 0, v[134:135]
	s_mov_b32 m0, s34
	ds_read_b128 v[188:191], v162 offset:16384
	ds_read_b128 v[192:195], v162 offset:17408
	ds_read_b128 v[196:199], v162 offset:18432
	ds_read_b128 v[200:203], v162 offset:19456
	ds_read_b128 v[204:207], v162 offset:20480
	ds_read_b128 v[208:211], v162 offset:21504
	ds_read_b128 v[212:215], v162 offset:22528
	ds_read_b128 v[216:219], v162 offset:23552
	global_load_lds_dwordx4 v[220:221], off
	s_add_i32 m0, s34, 0x2000
	s_add_u32 s34, s54, 0x40000
	v_lshl_add_u64 v[222:223], s[54:55], 0, v[138:139]
	s_addc_u32 s35, s55, 0
	s_add_i32 s90, s89, s62
	global_load_lds_dwordx4 v[222:223], off
	v_lshl_add_u64 v[224:225], s[34:35], 0, v[134:135]
	s_mov_b32 m0, s90
	v_lshl_add_u64 v[226:227], s[56:57], 0, v[136:137]
	global_load_lds_dwordx4 v[224:225], off
	v_lshl_add_u64 v[224:225], s[34:35], 0, v[138:139]
	s_add_i32 m0, s90, 0x2000
	s_nop 0
	global_load_lds_dwordx4 v[224:225], off
	v_lshl_add_u64 v[224:225], s[56:57], 0, v[132:133]
	s_mov_b32 m0, s65
	s_nop 0
	global_load_lds_dwordx4 v[224:225], off
	s_mov_b32 m0, s66
	s_nop 0
	global_load_lds_dwordx4 v[226:227], off
	s_waitcnt vmcnt(8)
	s_waitcnt lgkmcnt(0)
	s_barrier
	s_setprio 1
	s_waitcnt lgkmcnt(0)
	v_mfma_f32_16x16x32_bf16 v[60:63], v[148:151], v[188:191], 0
	v_mfma_f32_16x16x32_bf16 v[56:59], v[164:167], v[188:191], 0
	v_mfma_f32_16x16x32_bf16 v[44:47], v[148:151], v[196:199], 0
	v_mfma_f32_16x16x32_bf16 v[40:43], v[164:167], v[196:199], 0
	v_mfma_f32_16x16x32_bf16 v[28:31], v[148:151], v[204:207], 0
	v_mfma_f32_16x16x32_bf16 v[24:27], v[164:167], v[204:207], 0
	v_mfma_f32_16x16x32_bf16 v[12:15], v[148:151], v[212:215], 0
	v_mfma_f32_16x16x32_bf16 v[8:11], v[164:167], v[212:215], 0
	v_mfma_f32_16x16x32_bf16 v[60:63], v[152:155], v[192:195], v[60:63]
	v_mfma_f32_16x16x32_bf16 v[56:59], v[168:171], v[192:195], v[56:59]
	v_mfma_f32_16x16x32_bf16 v[44:47], v[152:155], v[200:203], v[44:47]
	v_mfma_f32_16x16x32_bf16 v[40:43], v[168:171], v[200:203], v[40:43]
	v_mfma_f32_16x16x32_bf16 v[28:31], v[152:155], v[208:211], v[28:31]
	v_mfma_f32_16x16x32_bf16 v[24:27], v[168:171], v[208:211], v[24:27]
	v_mfma_f32_16x16x32_bf16 v[12:15], v[152:155], v[216:219], v[12:15]
	v_mfma_f32_16x16x32_bf16 v[8:11], v[168:171], v[216:219], v[8:11]
	s_setprio 0
	s_setprio 1
	v_mfma_f32_16x16x32_bf16 v[52:55], v[172:175], v[188:191], 0
	v_mfma_f32_16x16x32_bf16 v[48:51], v[180:183], v[188:191], 0
	v_mfma_f32_16x16x32_bf16 v[36:39], v[172:175], v[196:199], 0
	v_mfma_f32_16x16x32_bf16 v[32:35], v[180:183], v[196:199], 0
	v_mfma_f32_16x16x32_bf16 v[20:23], v[172:175], v[204:207], 0
	v_mfma_f32_16x16x32_bf16 v[16:19], v[180:183], v[204:207], 0
	v_mfma_f32_16x16x32_bf16 v[4:7], v[172:175], v[212:215], 0
	v_mfma_f32_16x16x32_bf16 v[0:3], v[180:183], v[212:215], 0
	v_mfma_f32_16x16x32_bf16 v[52:55], v[176:179], v[192:195], v[52:55]
	v_mfma_f32_16x16x32_bf16 v[48:51], v[184:187], v[192:195], v[48:51]
	v_mfma_f32_16x16x32_bf16 v[36:39], v[176:179], v[200:203], v[36:39]
	v_mfma_f32_16x16x32_bf16 v[32:35], v[184:187], v[200:203], v[32:35]
	v_mfma_f32_16x16x32_bf16 v[20:23], v[176:179], v[208:211], v[20:23]
	v_mfma_f32_16x16x32_bf16 v[16:19], v[184:187], v[208:211], v[16:19]
	v_mfma_f32_16x16x32_bf16 v[4:7], v[176:179], v[216:219], v[4:7]
	v_mfma_f32_16x16x32_bf16 v[0:3], v[184:187], v[216:219], v[0:3]
	s_setprio 0
	s_barrier
	s_add_i32 s90, 0, 0x18000
	s_add_i32 s95, 0, 0x1c000
	v_add_u32_e32 v168, s90, v157
	v_add_u32_e32 v184, s95, v157
	ds_read_b128 v[148:151], v168
	ds_read_b128 v[152:155], v168 offset:1024
	ds_read_b128 v[164:167], v168 offset:2048
	ds_read_b128 v[168:171], v168 offset:3072
	ds_read_b128 v[172:175], v184
	ds_read_b128 v[176:179], v184 offset:1024
	ds_read_b128 v[180:183], v184 offset:2048
	ds_read_b128 v[184:187], v184 offset:3072
	s_add_u32 s34, s56, 0x40000
	s_addc_u32 s35, s57, 0
	s_mov_b32 m0, s67
	v_lshl_add_u64 v[228:229], s[34:35], 0, v[132:133]
	ds_read_b128 v[188:191], v162 offset:32768
	ds_read_b128 v[192:195], v162 offset:33792
	ds_read_b128 v[196:199], v162 offset:34816
	ds_read_b128 v[200:203], v162 offset:35840
	ds_read_b128 v[204:207], v162 offset:36864
	ds_read_b128 v[208:211], v162 offset:37888
	ds_read_b128 v[212:215], v162 offset:38912
	ds_read_b128 v[216:219], v162 offset:39936
	global_load_lds_dwordx4 v[228:229], off
	v_lshl_add_u64 v[228:229], s[34:35], 0, v[136:137]
	s_mov_b32 m0, s79
	s_nop 0
	global_load_lds_dwordx4 v[228:229], off
	s_waitcnt vmcnt(8)
	s_waitcnt lgkmcnt(0)
	s_barrier
	s_setprio 1
	s_waitcnt lgkmcnt(0)
	v_mfma_f32_16x16x32_bf16 v[124:127], v[148:151], v[188:191], v[124:127]
	v_mfma_f32_16x16x32_bf16 v[120:123], v[164:167], v[188:191], v[120:123]
	v_mfma_f32_16x16x32_bf16 v[108:111], v[148:151], v[196:199], v[108:111]
	v_mfma_f32_16x16x32_bf16 v[104:107], v[164:167], v[196:199], v[104:107]
	v_mfma_f32_16x16x32_bf16 v[92:95], v[148:151], v[204:207], v[92:95]
	v_mfma_f32_16x16x32_bf16 v[88:91], v[164:167], v[204:207], v[88:91]
	v_mfma_f32_16x16x32_bf16 v[76:79], v[148:151], v[212:215], v[76:79]
	v_mfma_f32_16x16x32_bf16 v[72:75], v[164:167], v[212:215], v[72:75]
	v_mfma_f32_16x16x32_bf16 v[124:127], v[152:155], v[192:195], v[124:127]
	v_mfma_f32_16x16x32_bf16 v[120:123], v[168:171], v[192:195], v[120:123]
	v_mfma_f32_16x16x32_bf16 v[108:111], v[152:155], v[200:203], v[108:111]
	v_mfma_f32_16x16x32_bf16 v[104:107], v[168:171], v[200:203], v[104:107]
	v_mfma_f32_16x16x32_bf16 v[92:95], v[152:155], v[208:211], v[92:95]
	v_mfma_f32_16x16x32_bf16 v[88:91], v[168:171], v[208:211], v[88:91]
	v_mfma_f32_16x16x32_bf16 v[76:79], v[152:155], v[216:219], v[76:79]
	v_mfma_f32_16x16x32_bf16 v[72:75], v[168:171], v[216:219], v[72:75]
	s_setprio 0
	s_setprio 1
	v_mfma_f32_16x16x32_bf16 v[116:119], v[172:175], v[188:191], v[116:119]
	v_mfma_f32_16x16x32_bf16 v[112:115], v[180:183], v[188:191], v[112:115]
	v_mfma_f32_16x16x32_bf16 v[100:103], v[172:175], v[196:199], v[100:103]
	v_mfma_f32_16x16x32_bf16 v[96:99], v[180:183], v[196:199], v[96:99]
	v_mfma_f32_16x16x32_bf16 v[84:87], v[172:175], v[204:207], v[84:87]
	v_mfma_f32_16x16x32_bf16 v[80:83], v[180:183], v[204:207], v[80:83]
	v_mfma_f32_16x16x32_bf16 v[68:71], v[172:175], v[212:215], v[68:71]
	v_mfma_f32_16x16x32_bf16 v[64:67], v[180:183], v[212:215], v[64:67]
	v_mfma_f32_16x16x32_bf16 v[116:119], v[176:179], v[192:195], v[116:119]
	v_mfma_f32_16x16x32_bf16 v[112:115], v[184:187], v[192:195], v[112:115]
	v_mfma_f32_16x16x32_bf16 v[100:103], v[176:179], v[200:203], v[100:103]
	v_mfma_f32_16x16x32_bf16 v[96:99], v[184:187], v[200:203], v[96:99]
	v_mfma_f32_16x16x32_bf16 v[84:87], v[176:179], v[208:211], v[84:87]
	v_mfma_f32_16x16x32_bf16 v[80:83], v[184:187], v[208:211], v[80:83]
	v_mfma_f32_16x16x32_bf16 v[68:71], v[176:179], v[216:219], v[68:71]
	v_mfma_f32_16x16x32_bf16 v[64:67], v[184:187], v[216:219], v[64:67]
	s_setprio 0
	s_barrier
	s_add_i32 s34, s90, s62
	v_lshl_add_u64 v[220:221], v[220:221], 0, s[26:27]
	s_mov_b32 m0, s34
	ds_read_b128 v[188:191], v162 offset:49152
	ds_read_b128 v[192:195], v162 offset:50176
	ds_read_b128 v[196:199], v162 offset:51200
	ds_read_b128 v[200:203], v162 offset:52224
	ds_read_b128 v[204:207], v162 offset:53248
	ds_read_b128 v[208:211], v162 offset:54272
	ds_read_b128 v[212:215], v162 offset:55296
	ds_read_b128 v[216:219], v162 offset:56320
	global_load_lds_dwordx4 v[220:221], off
	s_add_i32 m0, s34, 0x2000
	s_add_u32 s34, s54, 0x40080
	v_lshl_add_u64 v[220:221], v[222:223], 0, s[26:27]
	s_addc_u32 s35, s55, 0
	s_add_i32 s54, s95, s62
	global_load_lds_dwordx4 v[220:221], off
	v_lshl_add_u64 v[220:221], s[34:35], 0, v[134:135]
	s_mov_b32 m0, s54
	s_nop 0
	global_load_lds_dwordx4 v[220:221], off
	v_lshl_add_u64 v[220:221], s[34:35], 0, v[138:139]
	s_add_i32 m0, s54, 0x2000
	s_nop 0
	global_load_lds_dwordx4 v[220:221], off
	v_lshl_add_u64 v[220:221], v[224:225], 0, s[26:27]
	s_mov_b32 m0, s83
	s_nop 0
	global_load_lds_dwordx4 v[220:221], off
	v_lshl_add_u64 v[220:221], v[226:227], 0, s[26:27]
	s_mov_b32 m0, s84
	s_nop 0
	global_load_lds_dwordx4 v[220:221], off
	s_waitcnt vmcnt(8)
	s_waitcnt lgkmcnt(0)
	s_barrier
	s_add_u32 s52, s52, 0x100
	s_addc_u32 s53, s53, 0
	s_add_u32 s41, s41, 0x100
	s_addc_u32 s43, s43, 0
	s_setprio 1
	s_waitcnt lgkmcnt(0)
	v_mfma_f32_16x16x32_bf16 v[60:63], v[148:151], v[188:191], v[60:63]
	v_mfma_f32_16x16x32_bf16 v[56:59], v[164:167], v[188:191], v[56:59]
	v_mfma_f32_16x16x32_bf16 v[44:47], v[148:151], v[196:199], v[44:47]
	v_mfma_f32_16x16x32_bf16 v[40:43], v[164:167], v[196:199], v[40:43]
	v_mfma_f32_16x16x32_bf16 v[28:31], v[148:151], v[204:207], v[28:31]
	v_mfma_f32_16x16x32_bf16 v[24:27], v[164:167], v[204:207], v[24:27]
	v_mfma_f32_16x16x32_bf16 v[12:15], v[148:151], v[212:215], v[12:15]
	v_mfma_f32_16x16x32_bf16 v[8:11], v[164:167], v[212:215], v[8:11]
	v_mfma_f32_16x16x32_bf16 v[60:63], v[152:155], v[192:195], v[60:63]
	v_mfma_f32_16x16x32_bf16 v[56:59], v[168:171], v[192:195], v[56:59]
	v_mfma_f32_16x16x32_bf16 v[44:47], v[152:155], v[200:203], v[44:47]
	v_mfma_f32_16x16x32_bf16 v[40:43], v[168:171], v[200:203], v[40:43]
	v_mfma_f32_16x16x32_bf16 v[28:31], v[152:155], v[208:211], v[28:31]
	v_mfma_f32_16x16x32_bf16 v[24:27], v[168:171], v[208:211], v[24:27]
	v_mfma_f32_16x16x32_bf16 v[12:15], v[152:155], v[216:219], v[12:15]
	v_mfma_f32_16x16x32_bf16 v[8:11], v[168:171], v[216:219], v[8:11]
	s_setprio 0
	s_setprio 1
	v_mfma_f32_16x16x32_bf16 v[52:55], v[172:175], v[188:191], v[52:55]
	v_mfma_f32_16x16x32_bf16 v[48:51], v[180:183], v[188:191], v[48:51]
	v_mfma_f32_16x16x32_bf16 v[36:39], v[172:175], v[196:199], v[36:39]
	v_mfma_f32_16x16x32_bf16 v[32:35], v[180:183], v[196:199], v[32:35]
	v_mfma_f32_16x16x32_bf16 v[20:23], v[172:175], v[204:207], v[20:23]
	v_mfma_f32_16x16x32_bf16 v[16:19], v[180:183], v[204:207], v[16:19]
	v_mfma_f32_16x16x32_bf16 v[4:7], v[172:175], v[212:215], v[4:7]
	v_mfma_f32_16x16x32_bf16 v[0:3], v[180:183], v[212:215], v[0:3]
	v_mfma_f32_16x16x32_bf16 v[52:55], v[176:179], v[192:195], v[52:55]
	v_mfma_f32_16x16x32_bf16 v[48:51], v[184:187], v[192:195], v[48:51]
	v_mfma_f32_16x16x32_bf16 v[36:39], v[176:179], v[200:203], v[36:39]
	v_mfma_f32_16x16x32_bf16 v[32:35], v[184:187], v[200:203], v[32:35]
	v_mfma_f32_16x16x32_bf16 v[20:23], v[176:179], v[208:211], v[20:23]
	v_mfma_f32_16x16x32_bf16 v[16:19], v[184:187], v[208:211], v[16:19]
	v_mfma_f32_16x16x32_bf16 v[4:7], v[176:179], v[216:219], v[4:7]
	v_mfma_f32_16x16x32_bf16 v[0:3], v[184:187], v[216:219], v[0:3]
	s_setprio 0
	s_barrier
	s_add_i32 s77, s77, 2
.LBB0_655:
	ds_read_b128 v[148:151], v160
	ds_read_b128 v[152:155], v160 offset:1024
	ds_read_b128 v[164:167], v160 offset:2048
	ds_read_b128 v[168:171], v160 offset:3072
	ds_read_b128 v[172:175], v161
	ds_read_b128 v[176:179], v161 offset:1024
	ds_read_b128 v[180:183], v161 offset:2048
	ds_read_b128 v[184:187], v161 offset:3072
	s_add_u32 s34, s52, 0xfffc0080
	s_addc_u32 s35, s53, -1
	s_cmp_eq_u32 s77, 12
	s_cselect_b32 s57, s9, s35
	s_cselect_b32 s56, s10, s34
	s_cselect_b32 s55, s12, s43
	s_cselect_b32 s54, s13, s41
	v_lshl_add_u64 v[220:221], s[52:53], 0, v[140:141]
	s_add_i32 m0, s65, 0xc000
	ds_read_b128 v[188:191], v162
	ds_read_b128 v[192:195], v162 offset:1024
	ds_read_b128 v[196:199], v162 offset:2048
	ds_read_b128 v[200:203], v162 offset:3072
	ds_read_b128 v[204:207], v162 offset:4096
	ds_read_b128 v[208:211], v162 offset:5120
	ds_read_b128 v[212:215], v162 offset:6144
	ds_read_b128 v[216:219], v162 offset:7168
	global_load_lds_dwordx4 v[220:221], off
	v_lshl_add_u64 v[220:221], s[52:53], 0, v[142:143]
	s_add_i32 m0, s65, 0xe000
	s_nop 0
	global_load_lds_dwordx4 v[220:221], off
	s_waitcnt vmcnt(8)
	s_waitcnt lgkmcnt(0)
	s_barrier
	s_setprio 1
	s_waitcnt lgkmcnt(0)
	v_mfma_f32_16x16x32_bf16 v[124:127], v[148:151], v[188:191], v[124:127]
	v_mfma_f32_16x16x32_bf16 v[120:123], v[164:167], v[188:191], v[120:123]
	v_mfma_f32_16x16x32_bf16 v[108:111], v[148:151], v[196:199], v[108:111]
	v_mfma_f32_16x16x32_bf16 v[104:107], v[164:167], v[196:199], v[104:107]
	v_mfma_f32_16x16x32_bf16 v[92:95], v[148:151], v[204:207], v[92:95]
	v_mfma_f32_16x16x32_bf16 v[88:91], v[164:167], v[204:207], v[88:91]
	v_mfma_f32_16x16x32_bf16 v[76:79], v[148:151], v[212:215], v[76:79]
	v_mfma_f32_16x16x32_bf16 v[72:75], v[164:167], v[212:215], v[72:75]
	v_mfma_f32_16x16x32_bf16 v[124:127], v[152:155], v[192:195], v[124:127]
	v_mfma_f32_16x16x32_bf16 v[120:123], v[168:171], v[192:195], v[120:123]
	v_mfma_f32_16x16x32_bf16 v[108:111], v[152:155], v[200:203], v[108:111]
	v_mfma_f32_16x16x32_bf16 v[104:107], v[168:171], v[200:203], v[104:107]
	v_mfma_f32_16x16x32_bf16 v[92:95], v[152:155], v[208:211], v[92:95]
	v_mfma_f32_16x16x32_bf16 v[88:91], v[168:171], v[208:211], v[88:91]
	v_mfma_f32_16x16x32_bf16 v[76:79], v[152:155], v[216:219], v[76:79]
	v_mfma_f32_16x16x32_bf16 v[72:75], v[168:171], v[216:219], v[72:75]
	s_setprio 0
	s_setprio 1
	v_mfma_f32_16x16x32_bf16 v[116:119], v[172:175], v[188:191], v[116:119]
	v_mfma_f32_16x16x32_bf16 v[112:115], v[180:183], v[188:191], v[112:115]
	v_mfma_f32_16x16x32_bf16 v[100:103], v[172:175], v[196:199], v[100:103]
	v_mfma_f32_16x16x32_bf16 v[96:99], v[180:183], v[196:199], v[96:99]
	v_mfma_f32_16x16x32_bf16 v[84:87], v[172:175], v[204:207], v[84:87]
	v_mfma_f32_16x16x32_bf16 v[80:83], v[180:183], v[204:207], v[80:83]
	v_mfma_f32_16x16x32_bf16 v[68:71], v[172:175], v[212:215], v[68:71]
	v_mfma_f32_16x16x32_bf16 v[64:67], v[180:183], v[212:215], v[64:67]
	v_mfma_f32_16x16x32_bf16 v[116:119], v[176:179], v[192:195], v[116:119]
	v_mfma_f32_16x16x32_bf16 v[112:115], v[184:187], v[192:195], v[112:115]
	v_mfma_f32_16x16x32_bf16 v[100:103], v[176:179], v[200:203], v[100:103]
	v_mfma_f32_16x16x32_bf16 v[96:99], v[184:187], v[200:203], v[96:99]
	v_mfma_f32_16x16x32_bf16 v[84:87], v[176:179], v[208:211], v[84:87]
	v_mfma_f32_16x16x32_bf16 v[80:83], v[184:187], v[208:211], v[80:83]
	v_mfma_f32_16x16x32_bf16 v[68:71], v[176:179], v[216:219], v[68:71]
	v_mfma_f32_16x16x32_bf16 v[64:67], v[184:187], v[216:219], v[64:67]
	s_setprio 0
	s_barrier
	s_add_i32 s34, s88, s62
	v_lshl_add_u64 v[220:221], s[54:55], 0, v[134:135]
	s_mov_b32 m0, s34
	ds_read_b128 v[188:191], v162 offset:16384
	ds_read_b128 v[192:195], v162 offset:17408
	ds_read_b128 v[196:199], v162 offset:18432
	ds_read_b128 v[200:203], v162 offset:19456
	ds_read_b128 v[204:207], v162 offset:20480
	ds_read_b128 v[208:211], v162 offset:21504
	ds_read_b128 v[212:215], v162 offset:22528
	ds_read_b128 v[216:219], v162 offset:23552
	global_load_lds_dwordx4 v[220:221], off
	s_add_i32 m0, s34, 0x2000
	s_add_u32 s34, s54, 0x40000
	v_lshl_add_u64 v[222:223], s[54:55], 0, v[138:139]
	s_addc_u32 s35, s55, 0
	s_add_i32 s90, s89, s62
	global_load_lds_dwordx4 v[222:223], off
	v_lshl_add_u64 v[224:225], s[34:35], 0, v[134:135]
	s_mov_b32 m0, s90
	v_lshl_add_u64 v[226:227], s[56:57], 0, v[136:137]
	global_load_lds_dwordx4 v[224:225], off
	v_lshl_add_u64 v[224:225], s[34:35], 0, v[138:139]
	s_add_i32 m0, s90, 0x2000
	s_nop 0
	global_load_lds_dwordx4 v[224:225], off
	v_lshl_add_u64 v[224:225], s[56:57], 0, v[132:133]
	s_mov_b32 m0, s65
	s_nop 0
	global_load_lds_dwordx4 v[224:225], off
	s_mov_b32 m0, s66
	s_nop 0
	global_load_lds_dwordx4 v[226:227], off
	s_waitcnt vmcnt(8)
	s_waitcnt lgkmcnt(0)
	s_barrier
	s_setprio 1
	s_waitcnt lgkmcnt(0)
	v_mfma_f32_16x16x32_bf16 v[60:63], v[148:151], v[188:191], v[60:63]
	v_mfma_f32_16x16x32_bf16 v[56:59], v[164:167], v[188:191], v[56:59]
	v_mfma_f32_16x16x32_bf16 v[44:47], v[148:151], v[196:199], v[44:47]
	v_mfma_f32_16x16x32_bf16 v[40:43], v[164:167], v[196:199], v[40:43]
	v_mfma_f32_16x16x32_bf16 v[28:31], v[148:151], v[204:207], v[28:31]
	v_mfma_f32_16x16x32_bf16 v[24:27], v[164:167], v[204:207], v[24:27]
	v_mfma_f32_16x16x32_bf16 v[12:15], v[148:151], v[212:215], v[12:15]
	v_mfma_f32_16x16x32_bf16 v[8:11], v[164:167], v[212:215], v[8:11]
	v_mfma_f32_16x16x32_bf16 v[60:63], v[152:155], v[192:195], v[60:63]
	v_mfma_f32_16x16x32_bf16 v[56:59], v[168:171], v[192:195], v[56:59]
	v_mfma_f32_16x16x32_bf16 v[44:47], v[152:155], v[200:203], v[44:47]
	v_mfma_f32_16x16x32_bf16 v[40:43], v[168:171], v[200:203], v[40:43]
	v_mfma_f32_16x16x32_bf16 v[28:31], v[152:155], v[208:211], v[28:31]
	v_mfma_f32_16x16x32_bf16 v[24:27], v[168:171], v[208:211], v[24:27]
	v_mfma_f32_16x16x32_bf16 v[12:15], v[152:155], v[216:219], v[12:15]
	v_mfma_f32_16x16x32_bf16 v[8:11], v[168:171], v[216:219], v[8:11]
	s_setprio 0
	s_setprio 1
	v_mfma_f32_16x16x32_bf16 v[52:55], v[172:175], v[188:191], v[52:55]
	v_mfma_f32_16x16x32_bf16 v[48:51], v[180:183], v[188:191], v[48:51]
	v_mfma_f32_16x16x32_bf16 v[36:39], v[172:175], v[196:199], v[36:39]
	v_mfma_f32_16x16x32_bf16 v[32:35], v[180:183], v[196:199], v[32:35]
	v_mfma_f32_16x16x32_bf16 v[20:23], v[172:175], v[204:207], v[20:23]
	v_mfma_f32_16x16x32_bf16 v[16:19], v[180:183], v[204:207], v[16:19]
	v_mfma_f32_16x16x32_bf16 v[4:7], v[172:175], v[212:215], v[4:7]
	v_mfma_f32_16x16x32_bf16 v[0:3], v[180:183], v[212:215], v[0:3]
	v_mfma_f32_16x16x32_bf16 v[52:55], v[176:179], v[192:195], v[52:55]
	v_mfma_f32_16x16x32_bf16 v[48:51], v[184:187], v[192:195], v[48:51]
	v_mfma_f32_16x16x32_bf16 v[36:39], v[176:179], v[200:203], v[36:39]
	v_mfma_f32_16x16x32_bf16 v[32:35], v[184:187], v[200:203], v[32:35]
	v_mfma_f32_16x16x32_bf16 v[20:23], v[176:179], v[208:211], v[20:23]
	v_mfma_f32_16x16x32_bf16 v[16:19], v[184:187], v[208:211], v[16:19]
	v_mfma_f32_16x16x32_bf16 v[4:7], v[176:179], v[216:219], v[4:7]
	v_mfma_f32_16x16x32_bf16 v[0:3], v[184:187], v[216:219], v[0:3]
	s_setprio 0
	s_barrier
	s_add_i32 s90, 0, 0x18000
	s_add_i32 s95, 0, 0x1c000
	v_add_u32_e32 v168, s90, v157
	v_add_u32_e32 v184, s95, v157
	ds_read_b128 v[148:151], v168
	ds_read_b128 v[152:155], v168 offset:1024
	ds_read_b128 v[164:167], v168 offset:2048
	ds_read_b128 v[168:171], v168 offset:3072
	ds_read_b128 v[172:175], v184
	ds_read_b128 v[176:179], v184 offset:1024
	ds_read_b128 v[180:183], v184 offset:2048
	ds_read_b128 v[184:187], v184 offset:3072
	s_add_u32 s34, s56, 0x40000
	s_addc_u32 s35, s57, 0
	s_mov_b32 m0, s67
	v_lshl_add_u64 v[228:229], s[34:35], 0, v[132:133]
	ds_read_b128 v[188:191], v162 offset:32768
	ds_read_b128 v[192:195], v162 offset:33792
	ds_read_b128 v[196:199], v162 offset:34816
	ds_read_b128 v[200:203], v162 offset:35840
	ds_read_b128 v[204:207], v162 offset:36864
	ds_read_b128 v[208:211], v162 offset:37888
	ds_read_b128 v[212:215], v162 offset:38912
	ds_read_b128 v[216:219], v162 offset:39936
	global_load_lds_dwordx4 v[228:229], off
	v_lshl_add_u64 v[228:229], s[34:35], 0, v[136:137]
	s_mov_b32 m0, s79
	s_nop 0
	global_load_lds_dwordx4 v[228:229], off
	s_waitcnt vmcnt(8)
	s_waitcnt lgkmcnt(0)
	s_barrier
	s_setprio 1
	s_waitcnt lgkmcnt(0)
	v_mfma_f32_16x16x32_bf16 v[124:127], v[148:151], v[188:191], v[124:127]
	v_mfma_f32_16x16x32_bf16 v[120:123], v[164:167], v[188:191], v[120:123]
	v_mfma_f32_16x16x32_bf16 v[108:111], v[148:151], v[196:199], v[108:111]
	v_mfma_f32_16x16x32_bf16 v[104:107], v[164:167], v[196:199], v[104:107]
	v_mfma_f32_16x16x32_bf16 v[92:95], v[148:151], v[204:207], v[92:95]
	v_mfma_f32_16x16x32_bf16 v[88:91], v[164:167], v[204:207], v[88:91]
	v_mfma_f32_16x16x32_bf16 v[76:79], v[148:151], v[212:215], v[76:79]
	v_mfma_f32_16x16x32_bf16 v[72:75], v[164:167], v[212:215], v[72:75]
	v_mfma_f32_16x16x32_bf16 v[124:127], v[152:155], v[192:195], v[124:127]
	v_mfma_f32_16x16x32_bf16 v[120:123], v[168:171], v[192:195], v[120:123]
	v_mfma_f32_16x16x32_bf16 v[108:111], v[152:155], v[200:203], v[108:111]
	v_mfma_f32_16x16x32_bf16 v[104:107], v[168:171], v[200:203], v[104:107]
	v_mfma_f32_16x16x32_bf16 v[92:95], v[152:155], v[208:211], v[92:95]
	v_mfma_f32_16x16x32_bf16 v[88:91], v[168:171], v[208:211], v[88:91]
	v_mfma_f32_16x16x32_bf16 v[76:79], v[152:155], v[216:219], v[76:79]
	v_mfma_f32_16x16x32_bf16 v[72:75], v[168:171], v[216:219], v[72:75]
	s_setprio 0
	s_setprio 1
	v_mfma_f32_16x16x32_bf16 v[116:119], v[172:175], v[188:191], v[116:119]
	v_mfma_f32_16x16x32_bf16 v[112:115], v[180:183], v[188:191], v[112:115]
	v_mfma_f32_16x16x32_bf16 v[100:103], v[172:175], v[196:199], v[100:103]
	v_mfma_f32_16x16x32_bf16 v[96:99], v[180:183], v[196:199], v[96:99]
	v_mfma_f32_16x16x32_bf16 v[84:87], v[172:175], v[204:207], v[84:87]
	v_mfma_f32_16x16x32_bf16 v[80:83], v[180:183], v[204:207], v[80:83]
	v_mfma_f32_16x16x32_bf16 v[68:71], v[172:175], v[212:215], v[68:71]
	v_mfma_f32_16x16x32_bf16 v[64:67], v[180:183], v[212:215], v[64:67]
	v_mfma_f32_16x16x32_bf16 v[116:119], v[176:179], v[192:195], v[116:119]
	v_mfma_f32_16x16x32_bf16 v[112:115], v[184:187], v[192:195], v[112:115]
	v_mfma_f32_16x16x32_bf16 v[100:103], v[176:179], v[200:203], v[100:103]
	v_mfma_f32_16x16x32_bf16 v[96:99], v[184:187], v[200:203], v[96:99]
	v_mfma_f32_16x16x32_bf16 v[84:87], v[176:179], v[208:211], v[84:87]
	v_mfma_f32_16x16x32_bf16 v[80:83], v[184:187], v[208:211], v[80:83]
	v_mfma_f32_16x16x32_bf16 v[68:71], v[176:179], v[216:219], v[68:71]
	v_mfma_f32_16x16x32_bf16 v[64:67], v[184:187], v[216:219], v[64:67]
	s_setprio 0
	s_barrier
	s_add_i32 s34, s90, s62
	v_lshl_add_u64 v[220:221], v[220:221], 0, s[26:27]
	s_mov_b32 m0, s34
	ds_read_b128 v[188:191], v162 offset:49152
	ds_read_b128 v[192:195], v162 offset:50176
	ds_read_b128 v[196:199], v162 offset:51200
	ds_read_b128 v[200:203], v162 offset:52224
	ds_read_b128 v[204:207], v162 offset:53248
	ds_read_b128 v[208:211], v162 offset:54272
	ds_read_b128 v[212:215], v162 offset:55296
	ds_read_b128 v[216:219], v162 offset:56320
	global_load_lds_dwordx4 v[220:221], off
	s_add_i32 m0, s34, 0x2000
	s_add_u32 s34, s54, 0x40080
	v_lshl_add_u64 v[220:221], v[222:223], 0, s[26:27]
	s_addc_u32 s35, s55, 0
	s_add_i32 s54, s95, s62
	global_load_lds_dwordx4 v[220:221], off
	v_lshl_add_u64 v[220:221], s[34:35], 0, v[134:135]
	s_mov_b32 m0, s54
	s_nop 0
	global_load_lds_dwordx4 v[220:221], off
	v_lshl_add_u64 v[220:221], s[34:35], 0, v[138:139]
	s_add_i32 m0, s54, 0x2000
	s_nop 0
	global_load_lds_dwordx4 v[220:221], off
	v_lshl_add_u64 v[220:221], v[224:225], 0, s[26:27]
	s_mov_b32 m0, s83
	s_nop 0
	global_load_lds_dwordx4 v[220:221], off
	v_lshl_add_u64 v[220:221], v[226:227], 0, s[26:27]
	s_mov_b32 m0, s84
	s_nop 0
	global_load_lds_dwordx4 v[220:221], off
	s_waitcnt vmcnt(8)
	s_waitcnt lgkmcnt(0)
	s_barrier
	s_add_u32 s52, s52, 0x100
	s_addc_u32 s53, s53, 0
	s_add_u32 s41, s41, 0x100
	s_addc_u32 s43, s43, 0
	s_setprio 1
	s_waitcnt lgkmcnt(0)
	v_mfma_f32_16x16x32_bf16 v[60:63], v[148:151], v[188:191], v[60:63]
	v_mfma_f32_16x16x32_bf16 v[56:59], v[164:167], v[188:191], v[56:59]
	v_mfma_f32_16x16x32_bf16 v[44:47], v[148:151], v[196:199], v[44:47]
	v_mfma_f32_16x16x32_bf16 v[40:43], v[164:167], v[196:199], v[40:43]
	v_mfma_f32_16x16x32_bf16 v[28:31], v[148:151], v[204:207], v[28:31]
	v_mfma_f32_16x16x32_bf16 v[24:27], v[164:167], v[204:207], v[24:27]
	v_mfma_f32_16x16x32_bf16 v[12:15], v[148:151], v[212:215], v[12:15]
	v_mfma_f32_16x16x32_bf16 v[8:11], v[164:167], v[212:215], v[8:11]
	v_mfma_f32_16x16x32_bf16 v[60:63], v[152:155], v[192:195], v[60:63]
	v_mfma_f32_16x16x32_bf16 v[56:59], v[168:171], v[192:195], v[56:59]
	v_mfma_f32_16x16x32_bf16 v[44:47], v[152:155], v[200:203], v[44:47]
	v_mfma_f32_16x16x32_bf16 v[40:43], v[168:171], v[200:203], v[40:43]
	v_mfma_f32_16x16x32_bf16 v[28:31], v[152:155], v[208:211], v[28:31]
	v_mfma_f32_16x16x32_bf16 v[24:27], v[168:171], v[208:211], v[24:27]
	v_mfma_f32_16x16x32_bf16 v[12:15], v[152:155], v[216:219], v[12:15]
	v_mfma_f32_16x16x32_bf16 v[8:11], v[168:171], v[216:219], v[8:11]
	s_setprio 0
	s_setprio 1
	v_mfma_f32_16x16x32_bf16 v[52:55], v[172:175], v[188:191], v[52:55]
	v_mfma_f32_16x16x32_bf16 v[48:51], v[180:183], v[188:191], v[48:51]
	v_mfma_f32_16x16x32_bf16 v[36:39], v[172:175], v[196:199], v[36:39]
	v_mfma_f32_16x16x32_bf16 v[32:35], v[180:183], v[196:199], v[32:35]
	v_mfma_f32_16x16x32_bf16 v[20:23], v[172:175], v[204:207], v[20:23]
	v_mfma_f32_16x16x32_bf16 v[16:19], v[180:183], v[204:207], v[16:19]
	v_mfma_f32_16x16x32_bf16 v[4:7], v[172:175], v[212:215], v[4:7]
	v_mfma_f32_16x16x32_bf16 v[0:3], v[180:183], v[212:215], v[0:3]
	v_mfma_f32_16x16x32_bf16 v[52:55], v[176:179], v[192:195], v[52:55]
	v_mfma_f32_16x16x32_bf16 v[48:51], v[184:187], v[192:195], v[48:51]
	v_mfma_f32_16x16x32_bf16 v[36:39], v[176:179], v[200:203], v[36:39]
	v_mfma_f32_16x16x32_bf16 v[32:35], v[184:187], v[200:203], v[32:35]
	v_mfma_f32_16x16x32_bf16 v[20:23], v[176:179], v[208:211], v[20:23]
	v_mfma_f32_16x16x32_bf16 v[16:19], v[184:187], v[208:211], v[16:19]
	v_mfma_f32_16x16x32_bf16 v[4:7], v[176:179], v[216:219], v[4:7]
	v_mfma_f32_16x16x32_bf16 v[0:3], v[184:187], v[216:219], v[0:3]
	s_setprio 0
	s_cmp_eq_u32 s77, s98
	s_cbranch_scc1 .Lmy_nobar_7
	s_barrier
.Lmy_nobar_7:
	s_add_i32 s77, s77, 2
	s_cmp_gt_u32 s77, 13
	s_cbranch_scc0 .LBB0_655
	s_and_b64 vcc, exec, s[28:29]
	s_cbranch_vccz .LBB0_658
	s_nop 0

.Lmy_nobar2_9:
	ds_read_b128 v[148:151], v154
	ds_read_b128 v[160:163], v154 offset:1024
	ds_read_b128 v[164:167], v154 offset:2048
	ds_read_b128 v[168:171], v154 offset:3072
	ds_read_b128 v[172:175], v155
	ds_read_b128 v[176:179], v155 offset:1024
	ds_read_b128 v[180:183], v155 offset:2048
	ds_read_b128 v[184:187], v155 offset:3072
	s_add_u32 s34, s40, 0xfffc0080
	s_addc_u32 s35, s41, -1
	s_cmp_eq_u32 s77, 12
	s_cselect_b32 s49, s12, s35
	s_cselect_b32 s48, s13, s34
	s_cselect_b32 s43, s27, s67
	s_cselect_b32 s42, s29, s39
	v_lshl_add_u64 v[220:221], s[40:41], 0, v[140:141]
	s_add_i32 m0, s52, 0xc000
	ds_read_b128 v[188:191], v157
	ds_read_b128 v[192:195], v157 offset:1024
	ds_read_b128 v[196:199], v157 offset:2048
	ds_read_b128 v[200:203], v157 offset:3072
	ds_read_b128 v[204:207], v157 offset:4096
	ds_read_b128 v[208:211], v157 offset:5120
	ds_read_b128 v[212:215], v157 offset:6144
	ds_read_b128 v[216:219], v157 offset:7168
	global_load_lds_dwordx4 v[220:221], off
	v_lshl_add_u64 v[220:221], s[40:41], 0, v[142:143]
	s_add_i32 m0, s52, 0xe000
	s_nop 0
	global_load_lds_dwordx4 v[220:221], off
	s_waitcnt vmcnt(8)
	s_waitcnt lgkmcnt(0)
	s_barrier
	s_setprio 1
	s_waitcnt lgkmcnt(0)
	v_mfma_f32_16x16x32_bf16 v[124:127], v[148:151], v[188:191], 0
	v_mfma_f32_16x16x32_bf16 v[120:123], v[164:167], v[188:191], 0
	v_mfma_f32_16x16x32_bf16 v[108:111], v[148:151], v[196:199], 0
	v_mfma_f32_16x16x32_bf16 v[104:107], v[164:167], v[196:199], 0
	v_mfma_f32_16x16x32_bf16 v[92:95], v[148:151], v[204:207], 0
	v_mfma_f32_16x16x32_bf16 v[88:91], v[164:167], v[204:207], 0
	v_mfma_f32_16x16x32_bf16 v[76:79], v[148:151], v[212:215], 0
	v_mfma_f32_16x16x32_bf16 v[72:75], v[164:167], v[212:215], 0
	v_mfma_f32_16x16x32_bf16 v[124:127], v[160:163], v[192:195], v[124:127]
	v_mfma_f32_16x16x32_bf16 v[120:123], v[168:171], v[192:195], v[120:123]
	v_mfma_f32_16x16x32_bf16 v[108:111], v[160:163], v[200:203], v[108:111]
	v_mfma_f32_16x16x32_bf16 v[104:107], v[168:171], v[200:203], v[104:107]
	v_mfma_f32_16x16x32_bf16 v[92:95], v[160:163], v[208:211], v[92:95]
	v_mfma_f32_16x16x32_bf16 v[88:91], v[168:171], v[208:211], v[88:91]
	v_mfma_f32_16x16x32_bf16 v[76:79], v[160:163], v[216:219], v[76:79]
	v_mfma_f32_16x16x32_bf16 v[72:75], v[168:171], v[216:219], v[72:75]
	s_setprio 0
	s_setprio 1
	v_mfma_f32_16x16x32_bf16 v[116:119], v[172:175], v[188:191], 0
	v_mfma_f32_16x16x32_bf16 v[112:115], v[180:183], v[188:191], 0
	v_mfma_f32_16x16x32_bf16 v[100:103], v[172:175], v[196:199], 0
	v_mfma_f32_16x16x32_bf16 v[96:99], v[180:183], v[196:199], 0
	v_mfma_f32_16x16x32_bf16 v[84:87], v[172:175], v[204:207], 0
	v_mfma_f32_16x16x32_bf16 v[80:83], v[180:183], v[204:207], 0
	v_mfma_f32_16x16x32_bf16 v[68:71], v[172:175], v[212:215], 0
	v_mfma_f32_16x16x32_bf16 v[64:67], v[180:183], v[212:215], 0
	v_mfma_f32_16x16x32_bf16 v[116:119], v[176:179], v[192:195], v[116:119]
	v_mfma_f32_16x16x32_bf16 v[112:115], v[184:187], v[192:195], v[112:115]
	v_mfma_f32_16x16x32_bf16 v[100:103], v[176:179], v[200:203], v[100:103]
	v_mfma_f32_16x16x32_bf16 v[96:99], v[184:187], v[200:203], v[96:99]
	v_mfma_f32_16x16x32_bf16 v[84:87], v[176:179], v[208:211], v[84:87]
	v_mfma_f32_16x16x32_bf16 v[80:83], v[184:187], v[208:211], v[80:83]
	v_mfma_f32_16x16x32_bf16 v[68:71], v[176:179], v[216:219], v[68:71]
	v_mfma_f32_16x16x32_bf16 v[64:67], v[184:187], v[216:219], v[64:67]
	s_setprio 0
	s_barrier
	s_add_i32 s34, s64, s51
	v_lshl_add_u64 v[220:221], s[42:43], 0, v[134:135]
	s_mov_b32 m0, s34
	ds_read_b128 v[188:191], v157 offset:16384
	ds_read_b128 v[192:195], v157 offset:17408
	ds_read_b128 v[196:199], v157 offset:18432
	ds_read_b128 v[200:203], v157 offset:19456
	ds_read_b128 v[204:207], v157 offset:20480
	ds_read_b128 v[208:211], v157 offset:21504
	ds_read_b128 v[212:215], v157 offset:22528
	ds_read_b128 v[216:219], v157 offset:23552
	global_load_lds_dwordx4 v[220:221], off
	s_add_i32 m0, s34, 0x2000
	s_add_u32 s34, s42, 0x40000
	v_lshl_add_u64 v[222:223], s[42:43], 0, v[138:139]
	s_addc_u32 s35, s43, 0
	s_add_i32 s79, s65, s51
	global_load_lds_dwordx4 v[222:223], off
	v_lshl_add_u64 v[224:225], s[34:35], 0, v[134:135]
	s_mov_b32 m0, s79
	v_lshl_add_u64 v[226:227], s[48:49], 0, v[136:137]
	global_load_lds_dwordx4 v[224:225], off
	v_lshl_add_u64 v[224:225], s[34:35], 0, v[138:139]
	s_add_i32 m0, s79, 0x2000
	s_nop 0
	global_load_lds_dwordx4 v[224:225], off
	v_lshl_add_u64 v[224:225], s[48:49], 0, v[132:133]
	s_mov_b32 m0, s52
	s_nop 0
	global_load_lds_dwordx4 v[224:225], off
	s_mov_b32 m0, s53
	s_nop 0
	global_load_lds_dwordx4 v[226:227], off
	s_waitcnt vmcnt(8)
	s_waitcnt lgkmcnt(0)
	s_barrier
	s_setprio 1
	s_waitcnt lgkmcnt(0)
	v_mfma_f32_16x16x32_bf16 v[60:63], v[148:151], v[188:191], 0
	v_mfma_f32_16x16x32_bf16 v[56:59], v[164:167], v[188:191], 0
	v_mfma_f32_16x16x32_bf16 v[44:47], v[148:151], v[196:199], 0
	v_mfma_f32_16x16x32_bf16 v[40:43], v[164:167], v[196:199], 0
	v_mfma_f32_16x16x32_bf16 v[28:31], v[148:151], v[204:207], 0
	v_mfma_f32_16x16x32_bf16 v[24:27], v[164:167], v[204:207], 0
	v_mfma_f32_16x16x32_bf16 v[12:15], v[148:151], v[212:215], 0
	v_mfma_f32_16x16x32_bf16 v[8:11], v[164:167], v[212:215], 0
	v_mfma_f32_16x16x32_bf16 v[60:63], v[160:163], v[192:195], v[60:63]
	v_mfma_f32_16x16x32_bf16 v[56:59], v[168:171], v[192:195], v[56:59]
	v_mfma_f32_16x16x32_bf16 v[44:47], v[160:163], v[200:203], v[44:47]
	v_mfma_f32_16x16x32_bf16 v[40:43], v[168:171], v[200:203], v[40:43]
	v_mfma_f32_16x16x32_bf16 v[28:31], v[160:163], v[208:211], v[28:31]
	v_mfma_f32_16x16x32_bf16 v[24:27], v[168:171], v[208:211], v[24:27]
	v_mfma_f32_16x16x32_bf16 v[12:15], v[160:163], v[216:219], v[12:15]
	v_mfma_f32_16x16x32_bf16 v[8:11], v[168:171], v[216:219], v[8:11]
	s_setprio 0
	s_setprio 1
	v_mfma_f32_16x16x32_bf16 v[52:55], v[172:175], v[188:191], 0
	v_mfma_f32_16x16x32_bf16 v[48:51], v[180:183], v[188:191], 0
	v_mfma_f32_16x16x32_bf16 v[36:39], v[172:175], v[196:199], 0
	v_mfma_f32_16x16x32_bf16 v[32:35], v[180:183], v[196:199], 0
	v_mfma_f32_16x16x32_bf16 v[20:23], v[172:175], v[204:207], 0
	v_mfma_f32_16x16x32_bf16 v[16:19], v[180:183], v[204:207], 0
	v_mfma_f32_16x16x32_bf16 v[4:7], v[172:175], v[212:215], 0
	v_mfma_f32_16x16x32_bf16 v[0:3], v[180:183], v[212:215], 0
	v_mfma_f32_16x16x32_bf16 v[52:55], v[176:179], v[192:195], v[52:55]
	v_mfma_f32_16x16x32_bf16 v[48:51], v[184:187], v[192:195], v[48:51]
	v_mfma_f32_16x16x32_bf16 v[36:39], v[176:179], v[200:203], v[36:39]
	v_mfma_f32_16x16x32_bf16 v[32:35], v[184:187], v[200:203], v[32:35]
	v_mfma_f32_16x16x32_bf16 v[20:23], v[176:179], v[208:211], v[20:23]
	v_mfma_f32_16x16x32_bf16 v[16:19], v[184:187], v[208:211], v[16:19]
	v_mfma_f32_16x16x32_bf16 v[4:7], v[176:179], v[216:219], v[4:7]
	v_mfma_f32_16x16x32_bf16 v[0:3], v[184:187], v[216:219], v[0:3]
	s_setprio 0
	s_barrier
	s_add_i32 s79, 0, 0x18000
	v_add_u32_e32 v159, s79, v152
	s_add_i32 s81, 0, 0x1c000
	ds_read_b128 v[148:151], v159
	ds_read_b128 v[160:163], v159 offset:1024
	ds_read_b128 v[164:167], v159 offset:2048
	ds_read_b128 v[168:171], v159 offset:3072
	v_add_u32_e32 v159, s81, v152
	ds_read_b128 v[172:175], v159
	ds_read_b128 v[176:179], v159 offset:1024
	ds_read_b128 v[180:183], v159 offset:2048
	ds_read_b128 v[184:187], v159 offset:3072
	s_add_u32 s34, s48, 0x40000
	s_addc_u32 s35, s49, 0
	s_mov_b32 m0, s54
	v_lshl_add_u64 v[228:229], s[34:35], 0, v[132:133]
	ds_read_b128 v[188:191], v157 offset:32768
	ds_read_b128 v[192:195], v157 offset:33792
	ds_read_b128 v[196:199], v157 offset:34816
	ds_read_b128 v[200:203], v157 offset:35840
	ds_read_b128 v[204:207], v157 offset:36864
	ds_read_b128 v[208:211], v157 offset:37888
	ds_read_b128 v[212:215], v157 offset:38912
	ds_read_b128 v[216:219], v157 offset:39936
	global_load_lds_dwordx4 v[228:229], off
	v_lshl_add_u64 v[228:229], s[34:35], 0, v[136:137]
	s_mov_b32 m0, s55
	s_nop 0
	global_load_lds_dwordx4 v[228:229], off
	s_waitcnt vmcnt(8)
	s_waitcnt lgkmcnt(0)
	s_barrier
	s_setprio 1
	s_waitcnt lgkmcnt(0)
	v_mfma_f32_16x16x32_bf16 v[124:127], v[148:151], v[188:191], v[124:127]
	v_mfma_f32_16x16x32_bf16 v[120:123], v[164:167], v[188:191], v[120:123]
	v_mfma_f32_16x16x32_bf16 v[108:111], v[148:151], v[196:199], v[108:111]
	v_mfma_f32_16x16x32_bf16 v[104:107], v[164:167], v[196:199], v[104:107]
	v_mfma_f32_16x16x32_bf16 v[92:95], v[148:151], v[204:207], v[92:95]
	v_mfma_f32_16x16x32_bf16 v[88:91], v[164:167], v[204:207], v[88:91]
	v_mfma_f32_16x16x32_bf16 v[76:79], v[148:151], v[212:215], v[76:79]
	v_mfma_f32_16x16x32_bf16 v[72:75], v[164:167], v[212:215], v[72:75]
	v_mfma_f32_16x16x32_bf16 v[124:127], v[160:163], v[192:195], v[124:127]
	v_mfma_f32_16x16x32_bf16 v[120:123], v[168:171], v[192:195], v[120:123]
	v_mfma_f32_16x16x32_bf16 v[108:111], v[160:163], v[200:203], v[108:111]
	v_mfma_f32_16x16x32_bf16 v[104:107], v[168:171], v[200:203], v[104:107]
	v_mfma_f32_16x16x32_bf16 v[92:95], v[160:163], v[208:211], v[92:95]
	v_mfma_f32_16x16x32_bf16 v[88:91], v[168:171], v[208:211], v[88:91]
	v_mfma_f32_16x16x32_bf16 v[76:79], v[160:163], v[216:219], v[76:79]
	v_mfma_f32_16x16x32_bf16 v[72:75], v[168:171], v[216:219], v[72:75]
	s_setprio 0
	s_setprio 1
	v_mfma_f32_16x16x32_bf16 v[116:119], v[172:175], v[188:191], v[116:119]
	v_mfma_f32_16x16x32_bf16 v[112:115], v[180:183], v[188:191], v[112:115]
	v_mfma_f32_16x16x32_bf16 v[100:103], v[172:175], v[196:199], v[100:103]
	v_mfma_f32_16x16x32_bf16 v[96:99], v[180:183], v[196:199], v[96:99]
	v_mfma_f32_16x16x32_bf16 v[84:87], v[172:175], v[204:207], v[84:87]
	v_mfma_f32_16x16x32_bf16 v[80:83], v[180:183], v[204:207], v[80:83]
	v_mfma_f32_16x16x32_bf16 v[68:71], v[172:175], v[212:215], v[68:71]
	v_mfma_f32_16x16x32_bf16 v[64:67], v[180:183], v[212:215], v[64:67]
	v_mfma_f32_16x16x32_bf16 v[116:119], v[176:179], v[192:195], v[116:119]
	v_mfma_f32_16x16x32_bf16 v[112:115], v[184:187], v[192:195], v[112:115]
	v_mfma_f32_16x16x32_bf16 v[100:103], v[176:179], v[200:203], v[100:103]
	v_mfma_f32_16x16x32_bf16 v[96:99], v[184:187], v[200:203], v[96:99]
	v_mfma_f32_16x16x32_bf16 v[84:87], v[176:179], v[208:211], v[84:87]
	v_mfma_f32_16x16x32_bf16 v[80:83], v[184:187], v[208:211], v[80:83]
	v_mfma_f32_16x16x32_bf16 v[68:71], v[176:179], v[216:219], v[68:71]
	v_mfma_f32_16x16x32_bf16 v[64:67], v[184:187], v[216:219], v[64:67]
	s_setprio 0
	s_barrier
	s_add_i32 s34, s79, s51
	v_lshl_add_u64 v[220:221], v[220:221], 0, s[10:11]
	s_mov_b32 m0, s34
	ds_read_b128 v[188:191], v157 offset:49152
	ds_read_b128 v[192:195], v157 offset:50176
	ds_read_b128 v[196:199], v157 offset:51200
	ds_read_b128 v[200:203], v157 offset:52224
	ds_read_b128 v[204:207], v157 offset:53248
	ds_read_b128 v[208:211], v157 offset:54272
	ds_read_b128 v[212:215], v157 offset:55296
	ds_read_b128 v[216:219], v157 offset:56320
	global_load_lds_dwordx4 v[220:221], off
	s_add_i32 m0, s34, 0x2000
	s_add_u32 s34, s42, 0x40080
	v_lshl_add_u64 v[220:221], v[222:223], 0, s[10:11]
	s_addc_u32 s35, s43, 0
	s_add_i32 s42, s81, s51
	global_load_lds_dwordx4 v[220:221], off
	v_lshl_add_u64 v[220:221], s[34:35], 0, v[134:135]
	s_mov_b32 m0, s42
	s_nop 0
	global_load_lds_dwordx4 v[220:221], off
	v_lshl_add_u64 v[220:221], s[34:35], 0, v[138:139]
	s_add_i32 m0, s42, 0x2000
	s_nop 0
	global_load_lds_dwordx4 v[220:221], off
	v_lshl_add_u64 v[220:221], v[224:225], 0, s[10:11]
	s_mov_b32 m0, s57
	s_nop 0
	global_load_lds_dwordx4 v[220:221], off
	v_lshl_add_u64 v[220:221], v[226:227], 0, s[10:11]
	s_mov_b32 m0, s58
	s_nop 0
	global_load_lds_dwordx4 v[220:221], off
	s_waitcnt vmcnt(8)
	s_waitcnt lgkmcnt(0)
	s_barrier
	s_add_u32 s40, s40, 0x100
	s_addc_u32 s41, s41, 0
	s_add_u32 s39, s39, 0x100
	s_addc_u32 s67, s67, 0
	s_setprio 1
	s_waitcnt lgkmcnt(0)
	v_mfma_f32_16x16x32_bf16 v[60:63], v[148:151], v[188:191], v[60:63]
	v_mfma_f32_16x16x32_bf16 v[56:59], v[164:167], v[188:191], v[56:59]
	v_mfma_f32_16x16x32_bf16 v[44:47], v[148:151], v[196:199], v[44:47]
	v_mfma_f32_16x16x32_bf16 v[40:43], v[164:167], v[196:199], v[40:43]
	v_mfma_f32_16x16x32_bf16 v[28:31], v[148:151], v[204:207], v[28:31]
	v_mfma_f32_16x16x32_bf16 v[24:27], v[164:167], v[204:207], v[24:27]
	v_mfma_f32_16x16x32_bf16 v[12:15], v[148:151], v[212:215], v[12:15]
	v_mfma_f32_16x16x32_bf16 v[8:11], v[164:167], v[212:215], v[8:11]
	v_mfma_f32_16x16x32_bf16 v[60:63], v[160:163], v[192:195], v[60:63]
	v_mfma_f32_16x16x32_bf16 v[56:59], v[168:171], v[192:195], v[56:59]
	v_mfma_f32_16x16x32_bf16 v[44:47], v[160:163], v[200:203], v[44:47]
	v_mfma_f32_16x16x32_bf16 v[40:43], v[168:171], v[200:203], v[40:43]
	v_mfma_f32_16x16x32_bf16 v[28:31], v[160:163], v[208:211], v[28:31]
	v_mfma_f32_16x16x32_bf16 v[24:27], v[168:171], v[208:211], v[24:27]
	v_mfma_f32_16x16x32_bf16 v[12:15], v[160:163], v[216:219], v[12:15]
	v_mfma_f32_16x16x32_bf16 v[8:11], v[168:171], v[216:219], v[8:11]
	s_setprio 0
	s_setprio 1
	v_mfma_f32_16x16x32_bf16 v[52:55], v[172:175], v[188:191], v[52:55]
	v_mfma_f32_16x16x32_bf16 v[48:51], v[180:183], v[188:191], v[48:51]
	v_mfma_f32_16x16x32_bf16 v[36:39], v[172:175], v[196:199], v[36:39]
	v_mfma_f32_16x16x32_bf16 v[32:35], v[180:183], v[196:199], v[32:35]
	v_mfma_f32_16x16x32_bf16 v[20:23], v[172:175], v[204:207], v[20:23]
	v_mfma_f32_16x16x32_bf16 v[16:19], v[180:183], v[204:207], v[16:19]
	v_mfma_f32_16x16x32_bf16 v[4:7], v[172:175], v[212:215], v[4:7]
	v_mfma_f32_16x16x32_bf16 v[0:3], v[180:183], v[212:215], v[0:3]
	v_mfma_f32_16x16x32_bf16 v[52:55], v[176:179], v[192:195], v[52:55]
	v_mfma_f32_16x16x32_bf16 v[48:51], v[184:187], v[192:195], v[48:51]
	v_mfma_f32_16x16x32_bf16 v[36:39], v[176:179], v[200:203], v[36:39]
	v_mfma_f32_16x16x32_bf16 v[32:35], v[184:187], v[200:203], v[32:35]
	v_mfma_f32_16x16x32_bf16 v[20:23], v[176:179], v[208:211], v[20:23]
	v_mfma_f32_16x16x32_bf16 v[16:19], v[184:187], v[208:211], v[16:19]
	v_mfma_f32_16x16x32_bf16 v[4:7], v[176:179], v[216:219], v[4:7]
	v_mfma_f32_16x16x32_bf16 v[0:3], v[184:187], v[216:219], v[0:3]
	s_setprio 0
	s_barrier
	s_add_i32 s77, s77, 2
.LBB0_969:
	ds_read_b128 v[148:151], v154
	ds_read_b128 v[160:163], v154 offset:1024
	ds_read_b128 v[164:167], v154 offset:2048
	ds_read_b128 v[168:171], v154 offset:3072
	ds_read_b128 v[172:175], v155
	ds_read_b128 v[176:179], v155 offset:1024
	ds_read_b128 v[180:183], v155 offset:2048
	ds_read_b128 v[184:187], v155 offset:3072
	s_add_u32 s34, s40, 0xfffc0080
	s_addc_u32 s35, s41, -1
	s_cmp_eq_u32 s77, 12
	s_cselect_b32 s49, s12, s35
	s_cselect_b32 s48, s13, s34
	s_cselect_b32 s43, s27, s67
	s_cselect_b32 s42, s29, s39
	v_lshl_add_u64 v[220:221], s[40:41], 0, v[140:141]
	s_add_i32 m0, s52, 0xc000
	ds_read_b128 v[188:191], v157
	ds_read_b128 v[192:195], v157 offset:1024
	ds_read_b128 v[196:199], v157 offset:2048
	ds_read_b128 v[200:203], v157 offset:3072
	ds_read_b128 v[204:207], v157 offset:4096
	ds_read_b128 v[208:211], v157 offset:5120
	ds_read_b128 v[212:215], v157 offset:6144
	ds_read_b128 v[216:219], v157 offset:7168
	global_load_lds_dwordx4 v[220:221], off
	v_lshl_add_u64 v[220:221], s[40:41], 0, v[142:143]
	s_add_i32 m0, s52, 0xe000
	s_nop 0
	global_load_lds_dwordx4 v[220:221], off
	s_waitcnt vmcnt(8)
	s_waitcnt lgkmcnt(0)
	s_barrier
	s_setprio 1
	s_waitcnt lgkmcnt(0)
	v_mfma_f32_16x16x32_bf16 v[124:127], v[148:151], v[188:191], v[124:127]
	v_mfma_f32_16x16x32_bf16 v[120:123], v[164:167], v[188:191], v[120:123]
	v_mfma_f32_16x16x32_bf16 v[108:111], v[148:151], v[196:199], v[108:111]
	v_mfma_f32_16x16x32_bf16 v[104:107], v[164:167], v[196:199], v[104:107]
	v_mfma_f32_16x16x32_bf16 v[92:95], v[148:151], v[204:207], v[92:95]
	v_mfma_f32_16x16x32_bf16 v[88:91], v[164:167], v[204:207], v[88:91]
	v_mfma_f32_16x16x32_bf16 v[76:79], v[148:151], v[212:215], v[76:79]
	v_mfma_f32_16x16x32_bf16 v[72:75], v[164:167], v[212:215], v[72:75]
	v_mfma_f32_16x16x32_bf16 v[124:127], v[160:163], v[192:195], v[124:127]
	v_mfma_f32_16x16x32_bf16 v[120:123], v[168:171], v[192:195], v[120:123]
	v_mfma_f32_16x16x32_bf16 v[108:111], v[160:163], v[200:203], v[108:111]
	v_mfma_f32_16x16x32_bf16 v[104:107], v[168:171], v[200:203], v[104:107]
	v_mfma_f32_16x16x32_bf16 v[92:95], v[160:163], v[208:211], v[92:95]
	v_mfma_f32_16x16x32_bf16 v[88:91], v[168:171], v[208:211], v[88:91]
	v_mfma_f32_16x16x32_bf16 v[76:79], v[160:163], v[216:219], v[76:79]
	v_mfma_f32_16x16x32_bf16 v[72:75], v[168:171], v[216:219], v[72:75]
	s_setprio 0
	s_setprio 1
	v_mfma_f32_16x16x32_bf16 v[116:119], v[172:175], v[188:191], v[116:119]
	v_mfma_f32_16x16x32_bf16 v[112:115], v[180:183], v[188:191], v[112:115]
	v_mfma_f32_16x16x32_bf16 v[100:103], v[172:175], v[196:199], v[100:103]
	v_mfma_f32_16x16x32_bf16 v[96:99], v[180:183], v[196:199], v[96:99]
	v_mfma_f32_16x16x32_bf16 v[84:87], v[172:175], v[204:207], v[84:87]
	v_mfma_f32_16x16x32_bf16 v[80:83], v[180:183], v[204:207], v[80:83]
	v_mfma_f32_16x16x32_bf16 v[68:71], v[172:175], v[212:215], v[68:71]
	v_mfma_f32_16x16x32_bf16 v[64:67], v[180:183], v[212:215], v[64:67]
	v_mfma_f32_16x16x32_bf16 v[116:119], v[176:179], v[192:195], v[116:119]
	v_mfma_f32_16x16x32_bf16 v[112:115], v[184:187], v[192:195], v[112:115]
	v_mfma_f32_16x16x32_bf16 v[100:103], v[176:179], v[200:203], v[100:103]
	v_mfma_f32_16x16x32_bf16 v[96:99], v[184:187], v[200:203], v[96:99]
	v_mfma_f32_16x16x32_bf16 v[84:87], v[176:179], v[208:211], v[84:87]
	v_mfma_f32_16x16x32_bf16 v[80:83], v[184:187], v[208:211], v[80:83]
	v_mfma_f32_16x16x32_bf16 v[68:71], v[176:179], v[216:219], v[68:71]
	v_mfma_f32_16x16x32_bf16 v[64:67], v[184:187], v[216:219], v[64:67]
	s_setprio 0
	s_barrier
	s_add_i32 s34, s64, s51
	v_lshl_add_u64 v[220:221], s[42:43], 0, v[134:135]
	s_mov_b32 m0, s34
	ds_read_b128 v[188:191], v157 offset:16384
	ds_read_b128 v[192:195], v157 offset:17408
	ds_read_b128 v[196:199], v157 offset:18432
	ds_read_b128 v[200:203], v157 offset:19456
	ds_read_b128 v[204:207], v157 offset:20480
	ds_read_b128 v[208:211], v157 offset:21504
	ds_read_b128 v[212:215], v157 offset:22528
	ds_read_b128 v[216:219], v157 offset:23552
	global_load_lds_dwordx4 v[220:221], off
	s_add_i32 m0, s34, 0x2000
	s_add_u32 s34, s42, 0x40000
	v_lshl_add_u64 v[222:223], s[42:43], 0, v[138:139]
	s_addc_u32 s35, s43, 0
	s_add_i32 s79, s65, s51
	global_load_lds_dwordx4 v[222:223], off
	v_lshl_add_u64 v[224:225], s[34:35], 0, v[134:135]
	s_mov_b32 m0, s79
	v_lshl_add_u64 v[226:227], s[48:49], 0, v[136:137]
	global_load_lds_dwordx4 v[224:225], off
	v_lshl_add_u64 v[224:225], s[34:35], 0, v[138:139]
	s_add_i32 m0, s79, 0x2000
	s_nop 0
	global_load_lds_dwordx4 v[224:225], off
	v_lshl_add_u64 v[224:225], s[48:49], 0, v[132:133]
	s_mov_b32 m0, s52
	s_nop 0
	global_load_lds_dwordx4 v[224:225], off
	s_mov_b32 m0, s53
	s_nop 0
	global_load_lds_dwordx4 v[226:227], off
	s_waitcnt vmcnt(8)
	s_waitcnt lgkmcnt(0)
	s_barrier
	s_setprio 1
	s_waitcnt lgkmcnt(0)
	v_mfma_f32_16x16x32_bf16 v[60:63], v[148:151], v[188:191], v[60:63]
	v_mfma_f32_16x16x32_bf16 v[56:59], v[164:167], v[188:191], v[56:59]
	v_mfma_f32_16x16x32_bf16 v[44:47], v[148:151], v[196:199], v[44:47]
	v_mfma_f32_16x16x32_bf16 v[40:43], v[164:167], v[196:199], v[40:43]
	v_mfma_f32_16x16x32_bf16 v[28:31], v[148:151], v[204:207], v[28:31]
	v_mfma_f32_16x16x32_bf16 v[24:27], v[164:167], v[204:207], v[24:27]
	v_mfma_f32_16x16x32_bf16 v[12:15], v[148:151], v[212:215], v[12:15]
	v_mfma_f32_16x16x32_bf16 v[8:11], v[164:167], v[212:215], v[8:11]
	v_mfma_f32_16x16x32_bf16 v[60:63], v[160:163], v[192:195], v[60:63]
	v_mfma_f32_16x16x32_bf16 v[56:59], v[168:171], v[192:195], v[56:59]
	v_mfma_f32_16x16x32_bf16 v[44:47], v[160:163], v[200:203], v[44:47]
	v_mfma_f32_16x16x32_bf16 v[40:43], v[168:171], v[200:203], v[40:43]
	v_mfma_f32_16x16x32_bf16 v[28:31], v[160:163], v[208:211], v[28:31]
	v_mfma_f32_16x16x32_bf16 v[24:27], v[168:171], v[208:211], v[24:27]
	v_mfma_f32_16x16x32_bf16 v[12:15], v[160:163], v[216:219], v[12:15]
	v_mfma_f32_16x16x32_bf16 v[8:11], v[168:171], v[216:219], v[8:11]
	s_setprio 0
	s_setprio 1
	v_mfma_f32_16x16x32_bf16 v[52:55], v[172:175], v[188:191], v[52:55]
	v_mfma_f32_16x16x32_bf16 v[48:51], v[180:183], v[188:191], v[48:51]
	v_mfma_f32_16x16x32_bf16 v[36:39], v[172:175], v[196:199], v[36:39]
	v_mfma_f32_16x16x32_bf16 v[32:35], v[180:183], v[196:199], v[32:35]
	v_mfma_f32_16x16x32_bf16 v[20:23], v[172:175], v[204:207], v[20:23]
	v_mfma_f32_16x16x32_bf16 v[16:19], v[180:183], v[204:207], v[16:19]
	v_mfma_f32_16x16x32_bf16 v[4:7], v[172:175], v[212:215], v[4:7]
	v_mfma_f32_16x16x32_bf16 v[0:3], v[180:183], v[212:215], v[0:3]
	v_mfma_f32_16x16x32_bf16 v[52:55], v[176:179], v[192:195], v[52:55]
	v_mfma_f32_16x16x32_bf16 v[48:51], v[184:187], v[192:195], v[48:51]
	v_mfma_f32_16x16x32_bf16 v[36:39], v[176:179], v[200:203], v[36:39]
	v_mfma_f32_16x16x32_bf16 v[32:35], v[184:187], v[200:203], v[32:35]
	v_mfma_f32_16x16x32_bf16 v[20:23], v[176:179], v[208:211], v[20:23]
	v_mfma_f32_16x16x32_bf16 v[16:19], v[184:187], v[208:211], v[16:19]
	v_mfma_f32_16x16x32_bf16 v[4:7], v[176:179], v[216:219], v[4:7]
	v_mfma_f32_16x16x32_bf16 v[0:3], v[184:187], v[216:219], v[0:3]
	s_setprio 0
	s_barrier
	s_add_i32 s79, 0, 0x18000
	v_add_u32_e32 v159, s79, v152
	s_add_i32 s81, 0, 0x1c000
	ds_read_b128 v[148:151], v159
	ds_read_b128 v[160:163], v159 offset:1024
	ds_read_b128 v[164:167], v159 offset:2048
	ds_read_b128 v[168:171], v159 offset:3072
	v_add_u32_e32 v159, s81, v152
	ds_read_b128 v[172:175], v159
	ds_read_b128 v[176:179], v159 offset:1024
	ds_read_b128 v[180:183], v159 offset:2048
	ds_read_b128 v[184:187], v159 offset:3072
	s_add_u32 s34, s48, 0x40000
	s_addc_u32 s35, s49, 0
	s_mov_b32 m0, s54
	v_lshl_add_u64 v[228:229], s[34:35], 0, v[132:133]
	ds_read_b128 v[188:191], v157 offset:32768
	ds_read_b128 v[192:195], v157 offset:33792
	ds_read_b128 v[196:199], v157 offset:34816
	ds_read_b128 v[200:203], v157 offset:35840
	ds_read_b128 v[204:207], v157 offset:36864
	ds_read_b128 v[208:211], v157 offset:37888
	ds_read_b128 v[212:215], v157 offset:38912
	ds_read_b128 v[216:219], v157 offset:39936
	global_load_lds_dwordx4 v[228:229], off
	v_lshl_add_u64 v[228:229], s[34:35], 0, v[136:137]
	s_mov_b32 m0, s55
	s_nop 0
	global_load_lds_dwordx4 v[228:229], off
	s_waitcnt vmcnt(8)
	s_waitcnt lgkmcnt(0)
	s_barrier
	s_setprio 1
	s_waitcnt lgkmcnt(0)
	v_mfma_f32_16x16x32_bf16 v[124:127], v[148:151], v[188:191], v[124:127]
	v_mfma_f32_16x16x32_bf16 v[120:123], v[164:167], v[188:191], v[120:123]
	v_mfma_f32_16x16x32_bf16 v[108:111], v[148:151], v[196:199], v[108:111]
	v_mfma_f32_16x16x32_bf16 v[104:107], v[164:167], v[196:199], v[104:107]
	v_mfma_f32_16x16x32_bf16 v[92:95], v[148:151], v[204:207], v[92:95]
	v_mfma_f32_16x16x32_bf16 v[88:91], v[164:167], v[204:207], v[88:91]
	v_mfma_f32_16x16x32_bf16 v[76:79], v[148:151], v[212:215], v[76:79]
	v_mfma_f32_16x16x32_bf16 v[72:75], v[164:167], v[212:215], v[72:75]
	v_mfma_f32_16x16x32_bf16 v[124:127], v[160:163], v[192:195], v[124:127]
	v_mfma_f32_16x16x32_bf16 v[120:123], v[168:171], v[192:195], v[120:123]
	v_mfma_f32_16x16x32_bf16 v[108:111], v[160:163], v[200:203], v[108:111]
	v_mfma_f32_16x16x32_bf16 v[104:107], v[168:171], v[200:203], v[104:107]
	v_mfma_f32_16x16x32_bf16 v[92:95], v[160:163], v[208:211], v[92:95]
	v_mfma_f32_16x16x32_bf16 v[88:91], v[168:171], v[208:211], v[88:91]
	v_mfma_f32_16x16x32_bf16 v[76:79], v[160:163], v[216:219], v[76:79]
	v_mfma_f32_16x16x32_bf16 v[72:75], v[168:171], v[216:219], v[72:75]
	s_setprio 0
	s_setprio 1
	v_mfma_f32_16x16x32_bf16 v[116:119], v[172:175], v[188:191], v[116:119]
	v_mfma_f32_16x16x32_bf16 v[112:115], v[180:183], v[188:191], v[112:115]
	v_mfma_f32_16x16x32_bf16 v[100:103], v[172:175], v[196:199], v[100:103]
	v_mfma_f32_16x16x32_bf16 v[96:99], v[180:183], v[196:199], v[96:99]
	v_mfma_f32_16x16x32_bf16 v[84:87], v[172:175], v[204:207], v[84:87]
	v_mfma_f32_16x16x32_bf16 v[80:83], v[180:183], v[204:207], v[80:83]
	v_mfma_f32_16x16x32_bf16 v[68:71], v[172:175], v[212:215], v[68:71]
	v_mfma_f32_16x16x32_bf16 v[64:67], v[180:183], v[212:215], v[64:67]
	v_mfma_f32_16x16x32_bf16 v[116:119], v[176:179], v[192:195], v[116:119]
	v_mfma_f32_16x16x32_bf16 v[112:115], v[184:187], v[192:195], v[112:115]
	v_mfma_f32_16x16x32_bf16 v[100:103], v[176:179], v[200:203], v[100:103]
	v_mfma_f32_16x16x32_bf16 v[96:99], v[184:187], v[200:203], v[96:99]
	v_mfma_f32_16x16x32_bf16 v[84:87], v[176:179], v[208:211], v[84:87]
	v_mfma_f32_16x16x32_bf16 v[80:83], v[184:187], v[208:211], v[80:83]
	v_mfma_f32_16x16x32_bf16 v[68:71], v[176:179], v[216:219], v[68:71]
	v_mfma_f32_16x16x32_bf16 v[64:67], v[184:187], v[216:219], v[64:67]
	s_setprio 0
	s_barrier
	s_add_i32 s34, s79, s51
	v_lshl_add_u64 v[220:221], v[220:221], 0, s[10:11]
	s_mov_b32 m0, s34
	ds_read_b128 v[188:191], v157 offset:49152
	ds_read_b128 v[192:195], v157 offset:50176
	ds_read_b128 v[196:199], v157 offset:51200
	ds_read_b128 v[200:203], v157 offset:52224
	ds_read_b128 v[204:207], v157 offset:53248
	ds_read_b128 v[208:211], v157 offset:54272
	ds_read_b128 v[212:215], v157 offset:55296
	ds_read_b128 v[216:219], v157 offset:56320
	global_load_lds_dwordx4 v[220:221], off
	s_add_i32 m0, s34, 0x2000
	s_add_u32 s34, s42, 0x40080
	v_lshl_add_u64 v[220:221], v[222:223], 0, s[10:11]
	s_addc_u32 s35, s43, 0
	s_add_i32 s42, s81, s51
	global_load_lds_dwordx4 v[220:221], off
	v_lshl_add_u64 v[220:221], s[34:35], 0, v[134:135]
	s_mov_b32 m0, s42
	s_nop 0
	global_load_lds_dwordx4 v[220:221], off
	v_lshl_add_u64 v[220:221], s[34:35], 0, v[138:139]
	s_add_i32 m0, s42, 0x2000
	s_nop 0
	global_load_lds_dwordx4 v[220:221], off
	v_lshl_add_u64 v[220:221], v[224:225], 0, s[10:11]
	s_mov_b32 m0, s57
	s_nop 0
	global_load_lds_dwordx4 v[220:221], off
	v_lshl_add_u64 v[220:221], v[226:227], 0, s[10:11]
	s_mov_b32 m0, s58
	s_nop 0
	global_load_lds_dwordx4 v[220:221], off
	s_waitcnt vmcnt(8)
	s_waitcnt lgkmcnt(0)
	s_barrier
	s_add_u32 s40, s40, 0x100
	s_addc_u32 s41, s41, 0
	s_add_u32 s39, s39, 0x100
	s_addc_u32 s67, s67, 0
	s_setprio 1
	s_waitcnt lgkmcnt(0)
	v_mfma_f32_16x16x32_bf16 v[60:63], v[148:151], v[188:191], v[60:63]
	v_mfma_f32_16x16x32_bf16 v[56:59], v[164:167], v[188:191], v[56:59]
	v_mfma_f32_16x16x32_bf16 v[44:47], v[148:151], v[196:199], v[44:47]
	v_mfma_f32_16x16x32_bf16 v[40:43], v[164:167], v[196:199], v[40:43]
	v_mfma_f32_16x16x32_bf16 v[28:31], v[148:151], v[204:207], v[28:31]
	v_mfma_f32_16x16x32_bf16 v[24:27], v[164:167], v[204:207], v[24:27]
	v_mfma_f32_16x16x32_bf16 v[12:15], v[148:151], v[212:215], v[12:15]
	v_mfma_f32_16x16x32_bf16 v[8:11], v[164:167], v[212:215], v[8:11]
	v_mfma_f32_16x16x32_bf16 v[60:63], v[160:163], v[192:195], v[60:63]
	v_mfma_f32_16x16x32_bf16 v[56:59], v[168:171], v[192:195], v[56:59]
	v_mfma_f32_16x16x32_bf16 v[44:47], v[160:163], v[200:203], v[44:47]
	v_mfma_f32_16x16x32_bf16 v[40:43], v[168:171], v[200:203], v[40:43]
	v_mfma_f32_16x16x32_bf16 v[28:31], v[160:163], v[208:211], v[28:31]
	v_mfma_f32_16x16x32_bf16 v[24:27], v[168:171], v[208:211], v[24:27]
	v_mfma_f32_16x16x32_bf16 v[12:15], v[160:163], v[216:219], v[12:15]
	v_mfma_f32_16x16x32_bf16 v[8:11], v[168:171], v[216:219], v[8:11]
	s_setprio 0
	s_setprio 1
	v_mfma_f32_16x16x32_bf16 v[52:55], v[172:175], v[188:191], v[52:55]
	v_mfma_f32_16x16x32_bf16 v[48:51], v[180:183], v[188:191], v[48:51]
	v_mfma_f32_16x16x32_bf16 v[36:39], v[172:175], v[196:199], v[36:39]
	v_mfma_f32_16x16x32_bf16 v[32:35], v[180:183], v[196:199], v[32:35]
	v_mfma_f32_16x16x32_bf16 v[20:23], v[172:175], v[204:207], v[20:23]
	v_mfma_f32_16x16x32_bf16 v[16:19], v[180:183], v[204:207], v[16:19]
	v_mfma_f32_16x16x32_bf16 v[4:7], v[172:175], v[212:215], v[4:7]
	v_mfma_f32_16x16x32_bf16 v[0:3], v[180:183], v[212:215], v[0:3]
	v_mfma_f32_16x16x32_bf16 v[52:55], v[176:179], v[192:195], v[52:55]
	v_mfma_f32_16x16x32_bf16 v[48:51], v[184:187], v[192:195], v[48:51]
	v_mfma_f32_16x16x32_bf16 v[36:39], v[176:179], v[200:203], v[36:39]
	v_mfma_f32_16x16x32_bf16 v[32:35], v[184:187], v[200:203], v[32:35]
	v_mfma_f32_16x16x32_bf16 v[20:23], v[176:179], v[208:211], v[20:23]
	v_mfma_f32_16x16x32_bf16 v[16:19], v[184:187], v[208:211], v[16:19]
	v_mfma_f32_16x16x32_bf16 v[4:7], v[176:179], v[216:219], v[4:7]
	v_mfma_f32_16x16x32_bf16 v[0:3], v[184:187], v[216:219], v[0:3]
	s_setprio 0
	s_cmp_eq_u32 s77, s98
	s_cbranch_scc1 .Lmy_nobar_9
	s_barrier
.Lmy_nobar_9:
	s_add_i32 s77, s77, 2
	s_cmp_gt_u32 s77, 13
	s_cbranch_scc0 .LBB0_969
	s_and_b64 vcc, exec, s[22:23]
	s_cbranch_vccz .LBB0_972
	s_nop 0

.Lmy_nobar2_10:
	ds_read_b128 v[148:151], v155
	ds_read_b128 v[160:163], v155 offset:1024
	ds_read_b128 v[164:167], v155 offset:2048
	ds_read_b128 v[168:171], v155 offset:3072
	ds_read_b128 v[172:175], v157
	ds_read_b128 v[176:179], v157 offset:1024
	ds_read_b128 v[180:183], v157 offset:2048
	ds_read_b128 v[184:187], v157 offset:3072
	s_add_u32 s34, s36, 0xfffc0080
	s_addc_u32 s35, s37, -1
	s_cmp_eq_u32 s77, 12
	s_cselect_b32 s41, s23, s35
	s_cselect_b32 s40, s64, s34
	s_cselect_b32 s39, s11, s67
	s_cselect_b32 s38, s65, s66
	v_lshl_add_u64 v[220:221], s[36:37], 0, v[140:141]
	s_add_i32 m0, s31, 0xc000
	ds_read_b128 v[188:191], v158
	ds_read_b128 v[192:195], v158 offset:1024
	ds_read_b128 v[196:199], v158 offset:2048
	ds_read_b128 v[200:203], v158 offset:3072
	ds_read_b128 v[204:207], v158 offset:4096
	ds_read_b128 v[208:211], v158 offset:5120
	ds_read_b128 v[212:215], v158 offset:6144
	ds_read_b128 v[216:219], v158 offset:7168
	global_load_lds_dwordx4 v[220:221], off
	v_lshl_add_u64 v[220:221], s[36:37], 0, v[142:143]
	s_add_i32 m0, s31, 0xe000
	s_nop 0
	global_load_lds_dwordx4 v[220:221], off
	s_waitcnt vmcnt(8)
	s_waitcnt lgkmcnt(0)
	s_barrier
	s_setprio 1
	s_waitcnt lgkmcnt(0)
	v_mfma_f32_16x16x32_bf16 v[124:127], v[148:151], v[188:191], 0
	v_mfma_f32_16x16x32_bf16 v[120:123], v[164:167], v[188:191], 0
	v_mfma_f32_16x16x32_bf16 v[108:111], v[148:151], v[196:199], 0
	v_mfma_f32_16x16x32_bf16 v[104:107], v[164:167], v[196:199], 0
	v_mfma_f32_16x16x32_bf16 v[92:95], v[148:151], v[204:207], 0
	v_mfma_f32_16x16x32_bf16 v[88:91], v[164:167], v[204:207], 0
	v_mfma_f32_16x16x32_bf16 v[76:79], v[148:151], v[212:215], 0
	v_mfma_f32_16x16x32_bf16 v[72:75], v[164:167], v[212:215], 0
	v_mfma_f32_16x16x32_bf16 v[124:127], v[160:163], v[192:195], v[124:127]
	v_mfma_f32_16x16x32_bf16 v[120:123], v[168:171], v[192:195], v[120:123]
	v_mfma_f32_16x16x32_bf16 v[108:111], v[160:163], v[200:203], v[108:111]
	v_mfma_f32_16x16x32_bf16 v[104:107], v[168:171], v[200:203], v[104:107]
	v_mfma_f32_16x16x32_bf16 v[92:95], v[160:163], v[208:211], v[92:95]
	v_mfma_f32_16x16x32_bf16 v[88:91], v[168:171], v[208:211], v[88:91]
	v_mfma_f32_16x16x32_bf16 v[76:79], v[160:163], v[216:219], v[76:79]
	v_mfma_f32_16x16x32_bf16 v[72:75], v[168:171], v[216:219], v[72:75]
	s_setprio 0
	s_setprio 1
	v_mfma_f32_16x16x32_bf16 v[116:119], v[172:175], v[188:191], 0
	v_mfma_f32_16x16x32_bf16 v[112:115], v[180:183], v[188:191], 0
	v_mfma_f32_16x16x32_bf16 v[100:103], v[172:175], v[196:199], 0
	v_mfma_f32_16x16x32_bf16 v[96:99], v[180:183], v[196:199], 0
	v_mfma_f32_16x16x32_bf16 v[84:87], v[172:175], v[204:207], 0
	v_mfma_f32_16x16x32_bf16 v[80:83], v[180:183], v[204:207], 0
	v_mfma_f32_16x16x32_bf16 v[68:71], v[172:175], v[212:215], 0
	v_mfma_f32_16x16x32_bf16 v[64:67], v[180:183], v[212:215], 0
	v_mfma_f32_16x16x32_bf16 v[116:119], v[176:179], v[192:195], v[116:119]
	v_mfma_f32_16x16x32_bf16 v[112:115], v[184:187], v[192:195], v[112:115]
	v_mfma_f32_16x16x32_bf16 v[100:103], v[176:179], v[200:203], v[100:103]
	v_mfma_f32_16x16x32_bf16 v[96:99], v[184:187], v[200:203], v[96:99]
	v_mfma_f32_16x16x32_bf16 v[84:87], v[176:179], v[208:211], v[84:87]
	v_mfma_f32_16x16x32_bf16 v[80:83], v[184:187], v[208:211], v[80:83]
	v_mfma_f32_16x16x32_bf16 v[68:71], v[176:179], v[216:219], v[68:71]
	v_mfma_f32_16x16x32_bf16 v[64:67], v[184:187], v[216:219], v[64:67]
	s_setprio 0
	s_barrier
	s_add_i32 s34, s57, s48
	v_lshl_add_u64 v[220:221], s[38:39], 0, v[136:137]
	s_mov_b32 m0, s34
	ds_read_b128 v[188:191], v158 offset:16384
	ds_read_b128 v[192:195], v158 offset:17408
	ds_read_b128 v[196:199], v158 offset:18432
	ds_read_b128 v[200:203], v158 offset:19456
	ds_read_b128 v[204:207], v158 offset:20480
	ds_read_b128 v[208:211], v158 offset:21504
	ds_read_b128 v[212:215], v158 offset:22528
	ds_read_b128 v[216:219], v158 offset:23552
	global_load_lds_dwordx4 v[220:221], off
	s_add_i32 m0, s34, 0x2000
	s_add_u32 s34, s38, 0x40000
	v_lshl_add_u64 v[222:223], s[38:39], 0, v[132:133]
	s_addc_u32 s35, s39, 0
	s_add_i32 s79, s58, s48
	global_load_lds_dwordx4 v[222:223], off
	v_lshl_add_u64 v[224:225], s[34:35], 0, v[136:137]
	s_mov_b32 m0, s79
	v_lshl_add_u64 v[226:227], s[40:41], 0, v[134:135]
	global_load_lds_dwordx4 v[224:225], off
	v_lshl_add_u64 v[224:225], s[34:35], 0, v[132:133]
	s_add_i32 m0, s79, 0x2000
	s_nop 0
	global_load_lds_dwordx4 v[224:225], off
	v_lshl_add_u64 v[224:225], s[40:41], 0, v[138:139]
	s_mov_b32 m0, s31
	s_nop 0
	global_load_lds_dwordx4 v[224:225], off
	s_mov_b32 m0, s52
	s_nop 0
	global_load_lds_dwordx4 v[226:227], off
	s_waitcnt vmcnt(8)
	s_waitcnt lgkmcnt(0)
	s_barrier
	s_setprio 1
	s_waitcnt lgkmcnt(0)
	v_mfma_f32_16x16x32_bf16 v[60:63], v[148:151], v[188:191], 0
	v_mfma_f32_16x16x32_bf16 v[56:59], v[164:167], v[188:191], 0
	v_mfma_f32_16x16x32_bf16 v[44:47], v[148:151], v[196:199], 0
	v_mfma_f32_16x16x32_bf16 v[40:43], v[164:167], v[196:199], 0
	v_mfma_f32_16x16x32_bf16 v[28:31], v[148:151], v[204:207], 0
	v_mfma_f32_16x16x32_bf16 v[24:27], v[164:167], v[204:207], 0
	v_mfma_f32_16x16x32_bf16 v[12:15], v[148:151], v[212:215], 0
	v_mfma_f32_16x16x32_bf16 v[8:11], v[164:167], v[212:215], 0
	v_mfma_f32_16x16x32_bf16 v[60:63], v[160:163], v[192:195], v[60:63]
	v_mfma_f32_16x16x32_bf16 v[56:59], v[168:171], v[192:195], v[56:59]
	v_mfma_f32_16x16x32_bf16 v[44:47], v[160:163], v[200:203], v[44:47]
	v_mfma_f32_16x16x32_bf16 v[40:43], v[168:171], v[200:203], v[40:43]
	v_mfma_f32_16x16x32_bf16 v[28:31], v[160:163], v[208:211], v[28:31]
	v_mfma_f32_16x16x32_bf16 v[24:27], v[168:171], v[208:211], v[24:27]
	v_mfma_f32_16x16x32_bf16 v[12:15], v[160:163], v[216:219], v[12:15]
	v_mfma_f32_16x16x32_bf16 v[8:11], v[168:171], v[216:219], v[8:11]
	s_setprio 0
	s_setprio 1
	v_mfma_f32_16x16x32_bf16 v[52:55], v[172:175], v[188:191], 0
	v_mfma_f32_16x16x32_bf16 v[48:51], v[180:183], v[188:191], 0
	v_mfma_f32_16x16x32_bf16 v[36:39], v[172:175], v[196:199], 0
	v_mfma_f32_16x16x32_bf16 v[32:35], v[180:183], v[196:199], 0
	v_mfma_f32_16x16x32_bf16 v[20:23], v[172:175], v[204:207], 0
	v_mfma_f32_16x16x32_bf16 v[16:19], v[180:183], v[204:207], 0
	v_mfma_f32_16x16x32_bf16 v[4:7], v[172:175], v[212:215], 0
	v_mfma_f32_16x16x32_bf16 v[0:3], v[180:183], v[212:215], 0
	v_mfma_f32_16x16x32_bf16 v[52:55], v[176:179], v[192:195], v[52:55]
	v_mfma_f32_16x16x32_bf16 v[48:51], v[184:187], v[192:195], v[48:51]
	v_mfma_f32_16x16x32_bf16 v[36:39], v[176:179], v[200:203], v[36:39]
	v_mfma_f32_16x16x32_bf16 v[32:35], v[184:187], v[200:203], v[32:35]
	v_mfma_f32_16x16x32_bf16 v[20:23], v[176:179], v[208:211], v[20:23]
	v_mfma_f32_16x16x32_bf16 v[16:19], v[184:187], v[208:211], v[16:19]
	v_mfma_f32_16x16x32_bf16 v[4:7], v[176:179], v[216:219], v[4:7]
	v_mfma_f32_16x16x32_bf16 v[0:3], v[184:187], v[216:219], v[0:3]
	s_setprio 0
	s_barrier
	s_add_i32 s79, 0, 0x18000
	v_add_u32_e32 v159, s79, v152
	s_add_i32 s81, 0, 0x1c000
	ds_read_b128 v[148:151], v159
	ds_read_b128 v[160:163], v159 offset:1024
	ds_read_b128 v[164:167], v159 offset:2048
	ds_read_b128 v[168:171], v159 offset:3072
	v_add_u32_e32 v159, s81, v152
	ds_read_b128 v[172:175], v159
	ds_read_b128 v[176:179], v159 offset:1024
	ds_read_b128 v[180:183], v159 offset:2048
	ds_read_b128 v[184:187], v159 offset:3072
	s_add_u32 s34, s40, 0x40000
	s_addc_u32 s35, s41, 0
	s_mov_b32 m0, s53
	v_lshl_add_u64 v[228:229], s[34:35], 0, v[138:139]
	ds_read_b128 v[188:191], v158 offset:32768
	ds_read_b128 v[192:195], v158 offset:33792
	ds_read_b128 v[196:199], v158 offset:34816
	ds_read_b128 v[200:203], v158 offset:35840
	ds_read_b128 v[204:207], v158 offset:36864
	ds_read_b128 v[208:211], v158 offset:37888
	ds_read_b128 v[212:215], v158 offset:38912
	ds_read_b128 v[216:219], v158 offset:39936
	global_load_lds_dwordx4 v[228:229], off
	v_lshl_add_u64 v[228:229], s[34:35], 0, v[134:135]
	s_mov_b32 m0, s54
	s_nop 0
	global_load_lds_dwordx4 v[228:229], off
	s_waitcnt vmcnt(8)
	s_waitcnt lgkmcnt(0)
	s_barrier
	s_setprio 1
	s_waitcnt lgkmcnt(0)
	v_mfma_f32_16x16x32_bf16 v[124:127], v[148:151], v[188:191], v[124:127]
	v_mfma_f32_16x16x32_bf16 v[120:123], v[164:167], v[188:191], v[120:123]
	v_mfma_f32_16x16x32_bf16 v[108:111], v[148:151], v[196:199], v[108:111]
	v_mfma_f32_16x16x32_bf16 v[104:107], v[164:167], v[196:199], v[104:107]
	v_mfma_f32_16x16x32_bf16 v[92:95], v[148:151], v[204:207], v[92:95]
	v_mfma_f32_16x16x32_bf16 v[88:91], v[164:167], v[204:207], v[88:91]
	v_mfma_f32_16x16x32_bf16 v[76:79], v[148:151], v[212:215], v[76:79]
	v_mfma_f32_16x16x32_bf16 v[72:75], v[164:167], v[212:215], v[72:75]
	v_mfma_f32_16x16x32_bf16 v[124:127], v[160:163], v[192:195], v[124:127]
	v_mfma_f32_16x16x32_bf16 v[120:123], v[168:171], v[192:195], v[120:123]
	v_mfma_f32_16x16x32_bf16 v[108:111], v[160:163], v[200:203], v[108:111]
	v_mfma_f32_16x16x32_bf16 v[104:107], v[168:171], v[200:203], v[104:107]
	v_mfma_f32_16x16x32_bf16 v[92:95], v[160:163], v[208:211], v[92:95]
	v_mfma_f32_16x16x32_bf16 v[88:91], v[168:171], v[208:211], v[88:91]
	v_mfma_f32_16x16x32_bf16 v[76:79], v[160:163], v[216:219], v[76:79]
	v_mfma_f32_16x16x32_bf16 v[72:75], v[168:171], v[216:219], v[72:75]
	s_setprio 0
	s_setprio 1
	v_mfma_f32_16x16x32_bf16 v[116:119], v[172:175], v[188:191], v[116:119]
	v_mfma_f32_16x16x32_bf16 v[112:115], v[180:183], v[188:191], v[112:115]
	v_mfma_f32_16x16x32_bf16 v[100:103], v[172:175], v[196:199], v[100:103]
	v_mfma_f32_16x16x32_bf16 v[96:99], v[180:183], v[196:199], v[96:99]
	v_mfma_f32_16x16x32_bf16 v[84:87], v[172:175], v[204:207], v[84:87]
	v_mfma_f32_16x16x32_bf16 v[80:83], v[180:183], v[204:207], v[80:83]
	v_mfma_f32_16x16x32_bf16 v[68:71], v[172:175], v[212:215], v[68:71]
	v_mfma_f32_16x16x32_bf16 v[64:67], v[180:183], v[212:215], v[64:67]
	v_mfma_f32_16x16x32_bf16 v[116:119], v[176:179], v[192:195], v[116:119]
	v_mfma_f32_16x16x32_bf16 v[112:115], v[184:187], v[192:195], v[112:115]
	v_mfma_f32_16x16x32_bf16 v[100:103], v[176:179], v[200:203], v[100:103]
	v_mfma_f32_16x16x32_bf16 v[96:99], v[184:187], v[200:203], v[96:99]
	v_mfma_f32_16x16x32_bf16 v[84:87], v[176:179], v[208:211], v[84:87]
	v_mfma_f32_16x16x32_bf16 v[80:83], v[184:187], v[208:211], v[80:83]
	v_mfma_f32_16x16x32_bf16 v[68:71], v[176:179], v[216:219], v[68:71]
	v_mfma_f32_16x16x32_bf16 v[64:67], v[184:187], v[216:219], v[64:67]
	s_setprio 0
	s_barrier
	s_add_i32 s34, s79, s48
	v_lshl_add_u64 v[220:221], v[220:221], 0, s[6:7]
	s_mov_b32 m0, s34
	ds_read_b128 v[188:191], v158 offset:49152
	ds_read_b128 v[192:195], v158 offset:50176
	ds_read_b128 v[196:199], v158 offset:51200
	ds_read_b128 v[200:203], v158 offset:52224
	ds_read_b128 v[204:207], v158 offset:53248
	ds_read_b128 v[208:211], v158 offset:54272
	ds_read_b128 v[212:215], v158 offset:55296
	ds_read_b128 v[216:219], v158 offset:56320
	global_load_lds_dwordx4 v[220:221], off
	s_add_i32 m0, s34, 0x2000
	s_add_u32 s34, s38, 0x40080
	v_lshl_add_u64 v[220:221], v[222:223], 0, s[6:7]
	s_addc_u32 s35, s39, 0
	s_add_i32 s38, s81, s48
	global_load_lds_dwordx4 v[220:221], off
	v_lshl_add_u64 v[220:221], s[34:35], 0, v[136:137]
	s_mov_b32 m0, s38
	s_nop 0
	global_load_lds_dwordx4 v[220:221], off
	v_lshl_add_u64 v[220:221], s[34:35], 0, v[132:133]
	s_add_i32 m0, s38, 0x2000
	s_nop 0
	global_load_lds_dwordx4 v[220:221], off
	v_lshl_add_u64 v[220:221], v[224:225], 0, s[6:7]
	s_mov_b32 m0, s55
	s_nop 0
	global_load_lds_dwordx4 v[220:221], off
	v_lshl_add_u64 v[220:221], v[226:227], 0, s[6:7]
	s_mov_b32 m0, s56
	s_nop 0
	global_load_lds_dwordx4 v[220:221], off
	s_waitcnt vmcnt(8)
	s_waitcnt lgkmcnt(0)
	s_barrier
	s_add_u32 s36, s36, 0x100
	s_addc_u32 s37, s37, 0
	s_add_u32 s66, s66, 0x100
	s_addc_u32 s67, s67, 0
	s_setprio 1
	s_waitcnt lgkmcnt(0)
	v_mfma_f32_16x16x32_bf16 v[60:63], v[148:151], v[188:191], v[60:63]
	v_mfma_f32_16x16x32_bf16 v[56:59], v[164:167], v[188:191], v[56:59]
	v_mfma_f32_16x16x32_bf16 v[44:47], v[148:151], v[196:199], v[44:47]
	v_mfma_f32_16x16x32_bf16 v[40:43], v[164:167], v[196:199], v[40:43]
	v_mfma_f32_16x16x32_bf16 v[28:31], v[148:151], v[204:207], v[28:31]
	v_mfma_f32_16x16x32_bf16 v[24:27], v[164:167], v[204:207], v[24:27]
	v_mfma_f32_16x16x32_bf16 v[12:15], v[148:151], v[212:215], v[12:15]
	v_mfma_f32_16x16x32_bf16 v[8:11], v[164:167], v[212:215], v[8:11]
	v_mfma_f32_16x16x32_bf16 v[60:63], v[160:163], v[192:195], v[60:63]
	v_mfma_f32_16x16x32_bf16 v[56:59], v[168:171], v[192:195], v[56:59]
	v_mfma_f32_16x16x32_bf16 v[44:47], v[160:163], v[200:203], v[44:47]
	v_mfma_f32_16x16x32_bf16 v[40:43], v[168:171], v[200:203], v[40:43]
	v_mfma_f32_16x16x32_bf16 v[28:31], v[160:163], v[208:211], v[28:31]
	v_mfma_f32_16x16x32_bf16 v[24:27], v[168:171], v[208:211], v[24:27]
	v_mfma_f32_16x16x32_bf16 v[12:15], v[160:163], v[216:219], v[12:15]
	v_mfma_f32_16x16x32_bf16 v[8:11], v[168:171], v[216:219], v[8:11]
	s_setprio 0
	s_setprio 1
	v_mfma_f32_16x16x32_bf16 v[52:55], v[172:175], v[188:191], v[52:55]
	v_mfma_f32_16x16x32_bf16 v[48:51], v[180:183], v[188:191], v[48:51]
	v_mfma_f32_16x16x32_bf16 v[36:39], v[172:175], v[196:199], v[36:39]
	v_mfma_f32_16x16x32_bf16 v[32:35], v[180:183], v[196:199], v[32:35]
	v_mfma_f32_16x16x32_bf16 v[20:23], v[172:175], v[204:207], v[20:23]
	v_mfma_f32_16x16x32_bf16 v[16:19], v[180:183], v[204:207], v[16:19]
	v_mfma_f32_16x16x32_bf16 v[4:7], v[172:175], v[212:215], v[4:7]
	v_mfma_f32_16x16x32_bf16 v[0:3], v[180:183], v[212:215], v[0:3]
	v_mfma_f32_16x16x32_bf16 v[52:55], v[176:179], v[192:195], v[52:55]
	v_mfma_f32_16x16x32_bf16 v[48:51], v[184:187], v[192:195], v[48:51]
	v_mfma_f32_16x16x32_bf16 v[36:39], v[176:179], v[200:203], v[36:39]
	v_mfma_f32_16x16x32_bf16 v[32:35], v[184:187], v[200:203], v[32:35]
	v_mfma_f32_16x16x32_bf16 v[20:23], v[176:179], v[208:211], v[20:23]
	v_mfma_f32_16x16x32_bf16 v[16:19], v[184:187], v[208:211], v[16:19]
	v_mfma_f32_16x16x32_bf16 v[4:7], v[176:179], v[216:219], v[4:7]
	v_mfma_f32_16x16x32_bf16 v[0:3], v[184:187], v[216:219], v[0:3]
	s_setprio 0
	s_barrier
	s_add_i32 s77, s77, 2
.LBB0_1059:
	ds_read_b128 v[148:151], v155
	ds_read_b128 v[160:163], v155 offset:1024
	ds_read_b128 v[164:167], v155 offset:2048
	ds_read_b128 v[168:171], v155 offset:3072
	ds_read_b128 v[172:175], v157
	ds_read_b128 v[176:179], v157 offset:1024
	ds_read_b128 v[180:183], v157 offset:2048
	ds_read_b128 v[184:187], v157 offset:3072
	s_add_u32 s34, s36, 0xfffc0080
	s_addc_u32 s35, s37, -1
	s_cmp_eq_u32 s77, 12
	s_cselect_b32 s41, s23, s35
	s_cselect_b32 s40, s64, s34
	s_cselect_b32 s39, s11, s67
	s_cselect_b32 s38, s65, s66
	v_lshl_add_u64 v[220:221], s[36:37], 0, v[140:141]
	s_add_i32 m0, s31, 0xc000
	ds_read_b128 v[188:191], v158
	ds_read_b128 v[192:195], v158 offset:1024
	ds_read_b128 v[196:199], v158 offset:2048
	ds_read_b128 v[200:203], v158 offset:3072
	ds_read_b128 v[204:207], v158 offset:4096
	ds_read_b128 v[208:211], v158 offset:5120
	ds_read_b128 v[212:215], v158 offset:6144
	ds_read_b128 v[216:219], v158 offset:7168
	global_load_lds_dwordx4 v[220:221], off
	v_lshl_add_u64 v[220:221], s[36:37], 0, v[142:143]
	s_add_i32 m0, s31, 0xe000
	s_nop 0
	global_load_lds_dwordx4 v[220:221], off
	s_waitcnt vmcnt(8)
	s_waitcnt lgkmcnt(0)
	s_barrier
	s_setprio 1
	s_waitcnt lgkmcnt(0)
	v_mfma_f32_16x16x32_bf16 v[124:127], v[148:151], v[188:191], v[124:127]
	v_mfma_f32_16x16x32_bf16 v[120:123], v[164:167], v[188:191], v[120:123]
	v_mfma_f32_16x16x32_bf16 v[108:111], v[148:151], v[196:199], v[108:111]
	v_mfma_f32_16x16x32_bf16 v[104:107], v[164:167], v[196:199], v[104:107]
	v_mfma_f32_16x16x32_bf16 v[92:95], v[148:151], v[204:207], v[92:95]
	v_mfma_f32_16x16x32_bf16 v[88:91], v[164:167], v[204:207], v[88:91]
	v_mfma_f32_16x16x32_bf16 v[76:79], v[148:151], v[212:215], v[76:79]
	v_mfma_f32_16x16x32_bf16 v[72:75], v[164:167], v[212:215], v[72:75]
	v_mfma_f32_16x16x32_bf16 v[124:127], v[160:163], v[192:195], v[124:127]
	v_mfma_f32_16x16x32_bf16 v[120:123], v[168:171], v[192:195], v[120:123]
	v_mfma_f32_16x16x32_bf16 v[108:111], v[160:163], v[200:203], v[108:111]
	v_mfma_f32_16x16x32_bf16 v[104:107], v[168:171], v[200:203], v[104:107]
	v_mfma_f32_16x16x32_bf16 v[92:95], v[160:163], v[208:211], v[92:95]
	v_mfma_f32_16x16x32_bf16 v[88:91], v[168:171], v[208:211], v[88:91]
	v_mfma_f32_16x16x32_bf16 v[76:79], v[160:163], v[216:219], v[76:79]
	v_mfma_f32_16x16x32_bf16 v[72:75], v[168:171], v[216:219], v[72:75]
	s_setprio 0
	s_setprio 1
	v_mfma_f32_16x16x32_bf16 v[116:119], v[172:175], v[188:191], v[116:119]
	v_mfma_f32_16x16x32_bf16 v[112:115], v[180:183], v[188:191], v[112:115]
	v_mfma_f32_16x16x32_bf16 v[100:103], v[172:175], v[196:199], v[100:103]
	v_mfma_f32_16x16x32_bf16 v[96:99], v[180:183], v[196:199], v[96:99]
	v_mfma_f32_16x16x32_bf16 v[84:87], v[172:175], v[204:207], v[84:87]
	v_mfma_f32_16x16x32_bf16 v[80:83], v[180:183], v[204:207], v[80:83]
	v_mfma_f32_16x16x32_bf16 v[68:71], v[172:175], v[212:215], v[68:71]
	v_mfma_f32_16x16x32_bf16 v[64:67], v[180:183], v[212:215], v[64:67]
	v_mfma_f32_16x16x32_bf16 v[116:119], v[176:179], v[192:195], v[116:119]
	v_mfma_f32_16x16x32_bf16 v[112:115], v[184:187], v[192:195], v[112:115]
	v_mfma_f32_16x16x32_bf16 v[100:103], v[176:179], v[200:203], v[100:103]
	v_mfma_f32_16x16x32_bf16 v[96:99], v[184:187], v[200:203], v[96:99]
	v_mfma_f32_16x16x32_bf16 v[84:87], v[176:179], v[208:211], v[84:87]
	v_mfma_f32_16x16x32_bf16 v[80:83], v[184:187], v[208:211], v[80:83]
	v_mfma_f32_16x16x32_bf16 v[68:71], v[176:179], v[216:219], v[68:71]
	v_mfma_f32_16x16x32_bf16 v[64:67], v[184:187], v[216:219], v[64:67]
	s_setprio 0
	s_barrier
	s_add_i32 s34, s57, s48
	v_lshl_add_u64 v[220:221], s[38:39], 0, v[136:137]
	s_mov_b32 m0, s34
	ds_read_b128 v[188:191], v158 offset:16384
	ds_read_b128 v[192:195], v158 offset:17408
	ds_read_b128 v[196:199], v158 offset:18432
	ds_read_b128 v[200:203], v158 offset:19456
	ds_read_b128 v[204:207], v158 offset:20480
	ds_read_b128 v[208:211], v158 offset:21504
	ds_read_b128 v[212:215], v158 offset:22528
	ds_read_b128 v[216:219], v158 offset:23552
	global_load_lds_dwordx4 v[220:221], off
	s_add_i32 m0, s34, 0x2000
	s_add_u32 s34, s38, 0x40000
	v_lshl_add_u64 v[222:223], s[38:39], 0, v[132:133]
	s_addc_u32 s35, s39, 0
	s_add_i32 s79, s58, s48
	global_load_lds_dwordx4 v[222:223], off
	v_lshl_add_u64 v[224:225], s[34:35], 0, v[136:137]
	s_mov_b32 m0, s79
	v_lshl_add_u64 v[226:227], s[40:41], 0, v[134:135]
	global_load_lds_dwordx4 v[224:225], off
	v_lshl_add_u64 v[224:225], s[34:35], 0, v[132:133]
	s_add_i32 m0, s79, 0x2000
	s_nop 0
	global_load_lds_dwordx4 v[224:225], off
	v_lshl_add_u64 v[224:225], s[40:41], 0, v[138:139]
	s_mov_b32 m0, s31
	s_nop 0
	global_load_lds_dwordx4 v[224:225], off
	s_mov_b32 m0, s52
	s_nop 0
	global_load_lds_dwordx4 v[226:227], off
	s_waitcnt vmcnt(8)
	s_waitcnt lgkmcnt(0)
	s_barrier
	s_setprio 1
	s_waitcnt lgkmcnt(0)
	v_mfma_f32_16x16x32_bf16 v[60:63], v[148:151], v[188:191], v[60:63]
	v_mfma_f32_16x16x32_bf16 v[56:59], v[164:167], v[188:191], v[56:59]
	v_mfma_f32_16x16x32_bf16 v[44:47], v[148:151], v[196:199], v[44:47]
	v_mfma_f32_16x16x32_bf16 v[40:43], v[164:167], v[196:199], v[40:43]
	v_mfma_f32_16x16x32_bf16 v[28:31], v[148:151], v[204:207], v[28:31]
	v_mfma_f32_16x16x32_bf16 v[24:27], v[164:167], v[204:207], v[24:27]
	v_mfma_f32_16x16x32_bf16 v[12:15], v[148:151], v[212:215], v[12:15]
	v_mfma_f32_16x16x32_bf16 v[8:11], v[164:167], v[212:215], v[8:11]
	v_mfma_f32_16x16x32_bf16 v[60:63], v[160:163], v[192:195], v[60:63]
	v_mfma_f32_16x16x32_bf16 v[56:59], v[168:171], v[192:195], v[56:59]
	v_mfma_f32_16x16x32_bf16 v[44:47], v[160:163], v[200:203], v[44:47]
	v_mfma_f32_16x16x32_bf16 v[40:43], v[168:171], v[200:203], v[40:43]
	v_mfma_f32_16x16x32_bf16 v[28:31], v[160:163], v[208:211], v[28:31]
	v_mfma_f32_16x16x32_bf16 v[24:27], v[168:171], v[208:211], v[24:27]
	v_mfma_f32_16x16x32_bf16 v[12:15], v[160:163], v[216:219], v[12:15]
	v_mfma_f32_16x16x32_bf16 v[8:11], v[168:171], v[216:219], v[8:11]
	s_setprio 0
	s_setprio 1
	v_mfma_f32_16x16x32_bf16 v[52:55], v[172:175], v[188:191], v[52:55]
	v_mfma_f32_16x16x32_bf16 v[48:51], v[180:183], v[188:191], v[48:51]
	v_mfma_f32_16x16x32_bf16 v[36:39], v[172:175], v[196:199], v[36:39]
	v_mfma_f32_16x16x32_bf16 v[32:35], v[180:183], v[196:199], v[32:35]
	v_mfma_f32_16x16x32_bf16 v[20:23], v[172:175], v[204:207], v[20:23]
	v_mfma_f32_16x16x32_bf16 v[16:19], v[180:183], v[204:207], v[16:19]
	v_mfma_f32_16x16x32_bf16 v[4:7], v[172:175], v[212:215], v[4:7]
	v_mfma_f32_16x16x32_bf16 v[0:3], v[180:183], v[212:215], v[0:3]
	v_mfma_f32_16x16x32_bf16 v[52:55], v[176:179], v[192:195], v[52:55]
	v_mfma_f32_16x16x32_bf16 v[48:51], v[184:187], v[192:195], v[48:51]
	v_mfma_f32_16x16x32_bf16 v[36:39], v[176:179], v[200:203], v[36:39]
	v_mfma_f32_16x16x32_bf16 v[32:35], v[184:187], v[200:203], v[32:35]
	v_mfma_f32_16x16x32_bf16 v[20:23], v[176:179], v[208:211], v[20:23]
	v_mfma_f32_16x16x32_bf16 v[16:19], v[184:187], v[208:211], v[16:19]
	v_mfma_f32_16x16x32_bf16 v[4:7], v[176:179], v[216:219], v[4:7]
	v_mfma_f32_16x16x32_bf16 v[0:3], v[184:187], v[216:219], v[0:3]
	s_setprio 0
	s_barrier
	s_add_i32 s79, 0, 0x18000
	v_add_u32_e32 v159, s79, v152
	s_add_i32 s81, 0, 0x1c000
	ds_read_b128 v[148:151], v159
	ds_read_b128 v[160:163], v159 offset:1024
	ds_read_b128 v[164:167], v159 offset:2048
	ds_read_b128 v[168:171], v159 offset:3072
	v_add_u32_e32 v159, s81, v152
	ds_read_b128 v[172:175], v159
	ds_read_b128 v[176:179], v159 offset:1024
	ds_read_b128 v[180:183], v159 offset:2048
	ds_read_b128 v[184:187], v159 offset:3072
	s_add_u32 s34, s40, 0x40000
	s_addc_u32 s35, s41, 0
	s_mov_b32 m0, s53
	v_lshl_add_u64 v[228:229], s[34:35], 0, v[138:139]
	ds_read_b128 v[188:191], v158 offset:32768
	ds_read_b128 v[192:195], v158 offset:33792
	ds_read_b128 v[196:199], v158 offset:34816
	ds_read_b128 v[200:203], v158 offset:35840
	ds_read_b128 v[204:207], v158 offset:36864
	ds_read_b128 v[208:211], v158 offset:37888
	ds_read_b128 v[212:215], v158 offset:38912
	ds_read_b128 v[216:219], v158 offset:39936
	global_load_lds_dwordx4 v[228:229], off
	v_lshl_add_u64 v[228:229], s[34:35], 0, v[134:135]
	s_mov_b32 m0, s54
	s_nop 0
	global_load_lds_dwordx4 v[228:229], off
	s_waitcnt vmcnt(8)
	s_waitcnt lgkmcnt(0)
	s_barrier
	s_setprio 1
	s_waitcnt lgkmcnt(0)
	v_mfma_f32_16x16x32_bf16 v[124:127], v[148:151], v[188:191], v[124:127]
	v_mfma_f32_16x16x32_bf16 v[120:123], v[164:167], v[188:191], v[120:123]
	v_mfma_f32_16x16x32_bf16 v[108:111], v[148:151], v[196:199], v[108:111]
	v_mfma_f32_16x16x32_bf16 v[104:107], v[164:167], v[196:199], v[104:107]
	v_mfma_f32_16x16x32_bf16 v[92:95], v[148:151], v[204:207], v[92:95]
	v_mfma_f32_16x16x32_bf16 v[88:91], v[164:167], v[204:207], v[88:91]
	v_mfma_f32_16x16x32_bf16 v[76:79], v[148:151], v[212:215], v[76:79]
	v_mfma_f32_16x16x32_bf16 v[72:75], v[164:167], v[212:215], v[72:75]
	v_mfma_f32_16x16x32_bf16 v[124:127], v[160:163], v[192:195], v[124:127]
	v_mfma_f32_16x16x32_bf16 v[120:123], v[168:171], v[192:195], v[120:123]
	v_mfma_f32_16x16x32_bf16 v[108:111], v[160:163], v[200:203], v[108:111]
	v_mfma_f32_16x16x32_bf16 v[104:107], v[168:171], v[200:203], v[104:107]
	v_mfma_f32_16x16x32_bf16 v[92:95], v[160:163], v[208:211], v[92:95]
	v_mfma_f32_16x16x32_bf16 v[88:91], v[168:171], v[208:211], v[88:91]
	v_mfma_f32_16x16x32_bf16 v[76:79], v[160:163], v[216:219], v[76:79]
	v_mfma_f32_16x16x32_bf16 v[72:75], v[168:171], v[216:219], v[72:75]
	s_setprio 0
	s_setprio 1
	v_mfma_f32_16x16x32_bf16 v[116:119], v[172:175], v[188:191], v[116:119]
	v_mfma_f32_16x16x32_bf16 v[112:115], v[180:183], v[188:191], v[112:115]
	v_mfma_f32_16x16x32_bf16 v[100:103], v[172:175], v[196:199], v[100:103]
	v_mfma_f32_16x16x32_bf16 v[96:99], v[180:183], v[196:199], v[96:99]
	v_mfma_f32_16x16x32_bf16 v[84:87], v[172:175], v[204:207], v[84:87]
	v_mfma_f32_16x16x32_bf16 v[80:83], v[180:183], v[204:207], v[80:83]
	v_mfma_f32_16x16x32_bf16 v[68:71], v[172:175], v[212:215], v[68:71]
	v_mfma_f32_16x16x32_bf16 v[64:67], v[180:183], v[212:215], v[64:67]
	v_mfma_f32_16x16x32_bf16 v[116:119], v[176:179], v[192:195], v[116:119]
	v_mfma_f32_16x16x32_bf16 v[112:115], v[184:187], v[192:195], v[112:115]
	v_mfma_f32_16x16x32_bf16 v[100:103], v[176:179], v[200:203], v[100:103]
	v_mfma_f32_16x16x32_bf16 v[96:99], v[184:187], v[200:203], v[96:99]
	v_mfma_f32_16x16x32_bf16 v[84:87], v[176:179], v[208:211], v[84:87]
	v_mfma_f32_16x16x32_bf16 v[80:83], v[184:187], v[208:211], v[80:83]
	v_mfma_f32_16x16x32_bf16 v[68:71], v[176:179], v[216:219], v[68:71]
	v_mfma_f32_16x16x32_bf16 v[64:67], v[184:187], v[216:219], v[64:67]
	s_setprio 0
	s_barrier
	s_add_i32 s34, s79, s48
	v_lshl_add_u64 v[220:221], v[220:221], 0, s[6:7]
	s_mov_b32 m0, s34
	ds_read_b128 v[188:191], v158 offset:49152
	ds_read_b128 v[192:195], v158 offset:50176
	ds_read_b128 v[196:199], v158 offset:51200
	ds_read_b128 v[200:203], v158 offset:52224
	ds_read_b128 v[204:207], v158 offset:53248
	ds_read_b128 v[208:211], v158 offset:54272
	ds_read_b128 v[212:215], v158 offset:55296
	ds_read_b128 v[216:219], v158 offset:56320
	global_load_lds_dwordx4 v[220:221], off
	s_add_i32 m0, s34, 0x2000
	s_add_u32 s34, s38, 0x40080
	v_lshl_add_u64 v[220:221], v[222:223], 0, s[6:7]
	s_addc_u32 s35, s39, 0
	s_add_i32 s38, s81, s48
	global_load_lds_dwordx4 v[220:221], off
	v_lshl_add_u64 v[220:221], s[34:35], 0, v[136:137]
	s_mov_b32 m0, s38
	s_nop 0
	global_load_lds_dwordx4 v[220:221], off
	v_lshl_add_u64 v[220:221], s[34:35], 0, v[132:133]
	s_add_i32 m0, s38, 0x2000
	s_nop 0
	global_load_lds_dwordx4 v[220:221], off
	v_lshl_add_u64 v[220:221], v[224:225], 0, s[6:7]
	s_mov_b32 m0, s55
	s_nop 0
	global_load_lds_dwordx4 v[220:221], off
	v_lshl_add_u64 v[220:221], v[226:227], 0, s[6:7]
	s_mov_b32 m0, s56
	s_nop 0
	global_load_lds_dwordx4 v[220:221], off
	s_waitcnt vmcnt(8)
	s_waitcnt lgkmcnt(0)
	s_barrier
	s_add_u32 s36, s36, 0x100
	s_addc_u32 s37, s37, 0
	s_add_u32 s66, s66, 0x100
	s_addc_u32 s67, s67, 0
	s_setprio 1
	s_waitcnt lgkmcnt(0)
	v_mfma_f32_16x16x32_bf16 v[60:63], v[148:151], v[188:191], v[60:63]
	v_mfma_f32_16x16x32_bf16 v[56:59], v[164:167], v[188:191], v[56:59]
	v_mfma_f32_16x16x32_bf16 v[44:47], v[148:151], v[196:199], v[44:47]
	v_mfma_f32_16x16x32_bf16 v[40:43], v[164:167], v[196:199], v[40:43]
	v_mfma_f32_16x16x32_bf16 v[28:31], v[148:151], v[204:207], v[28:31]
	v_mfma_f32_16x16x32_bf16 v[24:27], v[164:167], v[204:207], v[24:27]
	v_mfma_f32_16x16x32_bf16 v[12:15], v[148:151], v[212:215], v[12:15]
	v_mfma_f32_16x16x32_bf16 v[8:11], v[164:167], v[212:215], v[8:11]
	v_mfma_f32_16x16x32_bf16 v[60:63], v[160:163], v[192:195], v[60:63]
	v_mfma_f32_16x16x32_bf16 v[56:59], v[168:171], v[192:195], v[56:59]
	v_mfma_f32_16x16x32_bf16 v[44:47], v[160:163], v[200:203], v[44:47]
	v_mfma_f32_16x16x32_bf16 v[40:43], v[168:171], v[200:203], v[40:43]
	v_mfma_f32_16x16x32_bf16 v[28:31], v[160:163], v[208:211], v[28:31]
	v_mfma_f32_16x16x32_bf16 v[24:27], v[168:171], v[208:211], v[24:27]
	v_mfma_f32_16x16x32_bf16 v[12:15], v[160:163], v[216:219], v[12:15]
	v_mfma_f32_16x16x32_bf16 v[8:11], v[168:171], v[216:219], v[8:11]
	s_setprio 0
	s_setprio 1
	v_mfma_f32_16x16x32_bf16 v[52:55], v[172:175], v[188:191], v[52:55]
	v_mfma_f32_16x16x32_bf16 v[48:51], v[180:183], v[188:191], v[48:51]
	v_mfma_f32_16x16x32_bf16 v[36:39], v[172:175], v[196:199], v[36:39]
	v_mfma_f32_16x16x32_bf16 v[32:35], v[180:183], v[196:199], v[32:35]
	v_mfma_f32_16x16x32_bf16 v[20:23], v[172:175], v[204:207], v[20:23]
	v_mfma_f32_16x16x32_bf16 v[16:19], v[180:183], v[204:207], v[16:19]
	v_mfma_f32_16x16x32_bf16 v[4:7], v[172:175], v[212:215], v[4:7]
	v_mfma_f32_16x16x32_bf16 v[0:3], v[180:183], v[212:215], v[0:3]
	v_mfma_f32_16x16x32_bf16 v[52:55], v[176:179], v[192:195], v[52:55]
	v_mfma_f32_16x16x32_bf16 v[48:51], v[184:187], v[192:195], v[48:51]
	v_mfma_f32_16x16x32_bf16 v[36:39], v[176:179], v[200:203], v[36:39]
	v_mfma_f32_16x16x32_bf16 v[32:35], v[184:187], v[200:203], v[32:35]
	v_mfma_f32_16x16x32_bf16 v[20:23], v[176:179], v[208:211], v[20:23]
	v_mfma_f32_16x16x32_bf16 v[16:19], v[184:187], v[208:211], v[16:19]
	v_mfma_f32_16x16x32_bf16 v[4:7], v[176:179], v[216:219], v[4:7]
	v_mfma_f32_16x16x32_bf16 v[0:3], v[184:187], v[216:219], v[0:3]
	s_setprio 0
	s_cmp_eq_u32 s77, s98
	s_cbranch_scc1 .Lmy_nobar_10
	s_barrier
.Lmy_nobar_10:
	s_add_i32 s77, s77, 2
	s_cmp_gt_u32 s77, 13
	s_cbranch_scc0 .LBB0_1059
	s_and_b64 vcc, exec, s[8:9]
	s_cbranch_vccz .LBB0_1062
	s_nop 0

.Lmy_nobar2_11:
	ds_read_b128 v[148:151], v154
	ds_read_b128 v[160:163], v154 offset:1024
	ds_read_b128 v[164:167], v154 offset:2048
	ds_read_b128 v[168:171], v154 offset:3072
	ds_read_b128 v[172:175], v155
	ds_read_b128 v[176:179], v155 offset:1024
	ds_read_b128 v[180:183], v155 offset:2048
	ds_read_b128 v[184:187], v155 offset:3072
	s_add_u32 s34, s30, 0xfff50080
	s_addc_u32 s35, s31, -1
	s_cmp_eq_u32 s64, 40
	s_cselect_b32 s39, s1, s35
	s_cselect_b32 s38, s0, s34
	s_cselect_b32 s37, s29, s63
	s_cselect_b32 s36, s28, s13
	v_lshl_add_u64 v[220:221], s[30:31], 0, v[140:141]
	s_add_i32 m0, s42, 0xc000
	ds_read_b128 v[188:191], v157
	ds_read_b128 v[192:195], v157 offset:1024
	ds_read_b128 v[196:199], v157 offset:2048
	ds_read_b128 v[200:203], v157 offset:3072
	ds_read_b128 v[204:207], v157 offset:4096
	ds_read_b128 v[208:211], v157 offset:5120
	ds_read_b128 v[212:215], v157 offset:6144
	ds_read_b128 v[216:219], v157 offset:7168
	global_load_lds_dwordx4 v[220:221], off
	v_lshl_add_u64 v[220:221], s[30:31], 0, v[142:143]
	s_add_i32 m0, s42, 0xe000
	s_nop 0
	global_load_lds_dwordx4 v[220:221], off
	s_waitcnt vmcnt(8)
	s_waitcnt lgkmcnt(0)
	s_barrier
	s_setprio 1
	s_waitcnt lgkmcnt(0)
	v_mfma_f32_16x16x32_bf16 v[124:127], v[148:151], v[188:191], 0
	v_mfma_f32_16x16x32_bf16 v[120:123], v[164:167], v[188:191], 0
	v_mfma_f32_16x16x32_bf16 v[108:111], v[148:151], v[196:199], 0
	v_mfma_f32_16x16x32_bf16 v[104:107], v[164:167], v[196:199], 0
	v_mfma_f32_16x16x32_bf16 v[92:95], v[148:151], v[204:207], 0
	v_mfma_f32_16x16x32_bf16 v[88:91], v[164:167], v[204:207], 0
	v_mfma_f32_16x16x32_bf16 v[76:79], v[148:151], v[212:215], 0
	v_mfma_f32_16x16x32_bf16 v[72:75], v[164:167], v[212:215], 0
	v_mfma_f32_16x16x32_bf16 v[124:127], v[160:163], v[192:195], v[124:127]
	v_mfma_f32_16x16x32_bf16 v[120:123], v[168:171], v[192:195], v[120:123]
	v_mfma_f32_16x16x32_bf16 v[108:111], v[160:163], v[200:203], v[108:111]
	v_mfma_f32_16x16x32_bf16 v[104:107], v[168:171], v[200:203], v[104:107]
	v_mfma_f32_16x16x32_bf16 v[92:95], v[160:163], v[208:211], v[92:95]
	v_mfma_f32_16x16x32_bf16 v[88:91], v[168:171], v[208:211], v[88:91]
	v_mfma_f32_16x16x32_bf16 v[76:79], v[160:163], v[216:219], v[76:79]
	v_mfma_f32_16x16x32_bf16 v[72:75], v[168:171], v[216:219], v[72:75]
	s_setprio 0
	s_setprio 1
	v_mfma_f32_16x16x32_bf16 v[116:119], v[172:175], v[188:191], 0
	v_mfma_f32_16x16x32_bf16 v[112:115], v[180:183], v[188:191], 0
	v_mfma_f32_16x16x32_bf16 v[100:103], v[172:175], v[196:199], 0
	v_mfma_f32_16x16x32_bf16 v[96:99], v[180:183], v[196:199], 0
	v_mfma_f32_16x16x32_bf16 v[84:87], v[172:175], v[204:207], 0
	v_mfma_f32_16x16x32_bf16 v[80:83], v[180:183], v[204:207], 0
	v_mfma_f32_16x16x32_bf16 v[68:71], v[172:175], v[212:215], 0
	v_mfma_f32_16x16x32_bf16 v[64:67], v[180:183], v[212:215], 0
	v_mfma_f32_16x16x32_bf16 v[116:119], v[176:179], v[192:195], v[116:119]
	v_mfma_f32_16x16x32_bf16 v[112:115], v[184:187], v[192:195], v[112:115]
	v_mfma_f32_16x16x32_bf16 v[100:103], v[176:179], v[200:203], v[100:103]
	v_mfma_f32_16x16x32_bf16 v[96:99], v[184:187], v[200:203], v[96:99]
	v_mfma_f32_16x16x32_bf16 v[84:87], v[176:179], v[208:211], v[84:87]
	v_mfma_f32_16x16x32_bf16 v[80:83], v[184:187], v[208:211], v[80:83]
	v_mfma_f32_16x16x32_bf16 v[68:71], v[176:179], v[216:219], v[68:71]
	v_mfma_f32_16x16x32_bf16 v[64:67], v[184:187], v[216:219], v[64:67]
	s_setprio 0
	s_barrier
	s_add_i32 s34, s56, s41
	v_lshl_add_u64 v[220:221], s[36:37], 0, v[134:135]
	s_mov_b32 m0, s34
	ds_read_b128 v[188:191], v157 offset:16384
	ds_read_b128 v[192:195], v157 offset:17408
	ds_read_b128 v[196:199], v157 offset:18432
	ds_read_b128 v[200:203], v157 offset:19456
	ds_read_b128 v[204:207], v157 offset:20480
	ds_read_b128 v[208:211], v157 offset:21504
	ds_read_b128 v[212:215], v157 offset:22528
	ds_read_b128 v[216:219], v157 offset:23552
	global_load_lds_dwordx4 v[220:221], off
	s_add_i32 m0, s34, 0x2000
	s_add_u32 s34, s36, 0xb0000
	v_lshl_add_u64 v[222:223], s[36:37], 0, v[138:139]
	s_addc_u32 s35, s37, 0
	s_add_i32 s65, s57, s41
	global_load_lds_dwordx4 v[222:223], off
	v_lshl_add_u64 v[224:225], s[34:35], 0, v[134:135]
	s_mov_b32 m0, s65
	v_lshl_add_u64 v[226:227], s[38:39], 0, v[136:137]
	global_load_lds_dwordx4 v[224:225], off
	v_lshl_add_u64 v[224:225], s[34:35], 0, v[138:139]
	s_add_i32 m0, s65, 0x2000
	s_nop 0
	global_load_lds_dwordx4 v[224:225], off
	v_lshl_add_u64 v[224:225], s[38:39], 0, v[132:133]
	s_mov_b32 m0, s42
	s_nop 0
	global_load_lds_dwordx4 v[224:225], off
	s_mov_b32 m0, s43
	s_nop 0
	global_load_lds_dwordx4 v[226:227], off
	s_waitcnt vmcnt(8)
	s_waitcnt lgkmcnt(0)
	s_barrier
	s_setprio 1
	s_waitcnt lgkmcnt(0)
	v_mfma_f32_16x16x32_bf16 v[60:63], v[148:151], v[188:191], 0
	v_mfma_f32_16x16x32_bf16 v[56:59], v[164:167], v[188:191], 0
	v_mfma_f32_16x16x32_bf16 v[44:47], v[148:151], v[196:199], 0
	v_mfma_f32_16x16x32_bf16 v[40:43], v[164:167], v[196:199], 0
	v_mfma_f32_16x16x32_bf16 v[28:31], v[148:151], v[204:207], 0
	v_mfma_f32_16x16x32_bf16 v[24:27], v[164:167], v[204:207], 0
	v_mfma_f32_16x16x32_bf16 v[12:15], v[148:151], v[212:215], 0
	v_mfma_f32_16x16x32_bf16 v[8:11], v[164:167], v[212:215], 0
	v_mfma_f32_16x16x32_bf16 v[60:63], v[160:163], v[192:195], v[60:63]
	v_mfma_f32_16x16x32_bf16 v[56:59], v[168:171], v[192:195], v[56:59]
	v_mfma_f32_16x16x32_bf16 v[44:47], v[160:163], v[200:203], v[44:47]
	v_mfma_f32_16x16x32_bf16 v[40:43], v[168:171], v[200:203], v[40:43]
	v_mfma_f32_16x16x32_bf16 v[28:31], v[160:163], v[208:211], v[28:31]
	v_mfma_f32_16x16x32_bf16 v[24:27], v[168:171], v[208:211], v[24:27]
	v_mfma_f32_16x16x32_bf16 v[12:15], v[160:163], v[216:219], v[12:15]
	v_mfma_f32_16x16x32_bf16 v[8:11], v[168:171], v[216:219], v[8:11]
	s_setprio 0
	s_setprio 1
	v_mfma_f32_16x16x32_bf16 v[52:55], v[172:175], v[188:191], 0
	v_mfma_f32_16x16x32_bf16 v[48:51], v[180:183], v[188:191], 0
	v_mfma_f32_16x16x32_bf16 v[36:39], v[172:175], v[196:199], 0
	v_mfma_f32_16x16x32_bf16 v[32:35], v[180:183], v[196:199], 0
	v_mfma_f32_16x16x32_bf16 v[20:23], v[172:175], v[204:207], 0
	v_mfma_f32_16x16x32_bf16 v[16:19], v[180:183], v[204:207], 0
	v_mfma_f32_16x16x32_bf16 v[4:7], v[172:175], v[212:215], 0
	v_mfma_f32_16x16x32_bf16 v[0:3], v[180:183], v[212:215], 0
	v_mfma_f32_16x16x32_bf16 v[52:55], v[176:179], v[192:195], v[52:55]
	v_mfma_f32_16x16x32_bf16 v[48:51], v[184:187], v[192:195], v[48:51]
	v_mfma_f32_16x16x32_bf16 v[36:39], v[176:179], v[200:203], v[36:39]
	v_mfma_f32_16x16x32_bf16 v[32:35], v[184:187], v[200:203], v[32:35]
	v_mfma_f32_16x16x32_bf16 v[20:23], v[176:179], v[208:211], v[20:23]
	v_mfma_f32_16x16x32_bf16 v[16:19], v[184:187], v[208:211], v[16:19]
	v_mfma_f32_16x16x32_bf16 v[4:7], v[176:179], v[216:219], v[4:7]
	v_mfma_f32_16x16x32_bf16 v[0:3], v[184:187], v[216:219], v[0:3]
	s_setprio 0
	s_barrier
	s_add_i32 s65, 0, 0x18000
	v_add_u32_e32 v159, s65, v152
	s_add_i32 s66, 0, 0x1c000
	ds_read_b128 v[148:151], v159
	ds_read_b128 v[160:163], v159 offset:1024
	ds_read_b128 v[164:167], v159 offset:2048
	ds_read_b128 v[168:171], v159 offset:3072
	v_add_u32_e32 v159, s66, v152
	ds_read_b128 v[172:175], v159
	ds_read_b128 v[176:179], v159 offset:1024
	ds_read_b128 v[180:183], v159 offset:2048
	ds_read_b128 v[184:187], v159 offset:3072
	s_add_u32 s34, s38, 0xb0000
	s_addc_u32 s35, s39, 0
	s_mov_b32 m0, s48
	v_lshl_add_u64 v[228:229], s[34:35], 0, v[132:133]
	ds_read_b128 v[188:191], v157 offset:32768
	ds_read_b128 v[192:195], v157 offset:33792
	ds_read_b128 v[196:199], v157 offset:34816
	ds_read_b128 v[200:203], v157 offset:35840
	ds_read_b128 v[204:207], v157 offset:36864
	ds_read_b128 v[208:211], v157 offset:37888
	ds_read_b128 v[212:215], v157 offset:38912
	ds_read_b128 v[216:219], v157 offset:39936
	global_load_lds_dwordx4 v[228:229], off
	v_lshl_add_u64 v[228:229], s[34:35], 0, v[136:137]
	s_mov_b32 m0, s49
	s_nop 0
	global_load_lds_dwordx4 v[228:229], off
	s_waitcnt vmcnt(8)
	s_waitcnt lgkmcnt(0)
	s_barrier
	s_setprio 1
	s_waitcnt lgkmcnt(0)
	v_mfma_f32_16x16x32_bf16 v[124:127], v[148:151], v[188:191], v[124:127]
	v_mfma_f32_16x16x32_bf16 v[120:123], v[164:167], v[188:191], v[120:123]
	v_mfma_f32_16x16x32_bf16 v[108:111], v[148:151], v[196:199], v[108:111]
	v_mfma_f32_16x16x32_bf16 v[104:107], v[164:167], v[196:199], v[104:107]
	v_mfma_f32_16x16x32_bf16 v[92:95], v[148:151], v[204:207], v[92:95]
	v_mfma_f32_16x16x32_bf16 v[88:91], v[164:167], v[204:207], v[88:91]
	v_mfma_f32_16x16x32_bf16 v[76:79], v[148:151], v[212:215], v[76:79]
	v_mfma_f32_16x16x32_bf16 v[72:75], v[164:167], v[212:215], v[72:75]
	v_mfma_f32_16x16x32_bf16 v[124:127], v[160:163], v[192:195], v[124:127]
	v_mfma_f32_16x16x32_bf16 v[120:123], v[168:171], v[192:195], v[120:123]
	v_mfma_f32_16x16x32_bf16 v[108:111], v[160:163], v[200:203], v[108:111]
	v_mfma_f32_16x16x32_bf16 v[104:107], v[168:171], v[200:203], v[104:107]
	v_mfma_f32_16x16x32_bf16 v[92:95], v[160:163], v[208:211], v[92:95]
	v_mfma_f32_16x16x32_bf16 v[88:91], v[168:171], v[208:211], v[88:91]
	v_mfma_f32_16x16x32_bf16 v[76:79], v[160:163], v[216:219], v[76:79]
	v_mfma_f32_16x16x32_bf16 v[72:75], v[168:171], v[216:219], v[72:75]
	s_setprio 0
	s_setprio 1
	v_mfma_f32_16x16x32_bf16 v[116:119], v[172:175], v[188:191], v[116:119]
	v_mfma_f32_16x16x32_bf16 v[112:115], v[180:183], v[188:191], v[112:115]
	v_mfma_f32_16x16x32_bf16 v[100:103], v[172:175], v[196:199], v[100:103]
	v_mfma_f32_16x16x32_bf16 v[96:99], v[180:183], v[196:199], v[96:99]
	v_mfma_f32_16x16x32_bf16 v[84:87], v[172:175], v[204:207], v[84:87]
	v_mfma_f32_16x16x32_bf16 v[80:83], v[180:183], v[204:207], v[80:83]
	v_mfma_f32_16x16x32_bf16 v[68:71], v[172:175], v[212:215], v[68:71]
	v_mfma_f32_16x16x32_bf16 v[64:67], v[180:183], v[212:215], v[64:67]
	v_mfma_f32_16x16x32_bf16 v[116:119], v[176:179], v[192:195], v[116:119]
	v_mfma_f32_16x16x32_bf16 v[112:115], v[184:187], v[192:195], v[112:115]
	v_mfma_f32_16x16x32_bf16 v[100:103], v[176:179], v[200:203], v[100:103]
	v_mfma_f32_16x16x32_bf16 v[96:99], v[184:187], v[200:203], v[96:99]
	v_mfma_f32_16x16x32_bf16 v[84:87], v[176:179], v[208:211], v[84:87]
	v_mfma_f32_16x16x32_bf16 v[80:83], v[184:187], v[208:211], v[80:83]
	v_mfma_f32_16x16x32_bf16 v[68:71], v[176:179], v[216:219], v[68:71]
	v_mfma_f32_16x16x32_bf16 v[64:67], v[184:187], v[216:219], v[64:67]
	s_setprio 0
	s_barrier
	s_add_i32 s34, s65, s41
	v_lshl_add_u64 v[220:221], v[220:221], 0, s[22:23]
	s_mov_b32 m0, s34
	ds_read_b128 v[188:191], v157 offset:49152
	ds_read_b128 v[192:195], v157 offset:50176
	ds_read_b128 v[196:199], v157 offset:51200
	ds_read_b128 v[200:203], v157 offset:52224
	ds_read_b128 v[204:207], v157 offset:53248
	ds_read_b128 v[208:211], v157 offset:54272
	ds_read_b128 v[212:215], v157 offset:55296
	ds_read_b128 v[216:219], v157 offset:56320
	global_load_lds_dwordx4 v[220:221], off
	s_add_i32 m0, s34, 0x2000
	s_add_u32 s34, s36, 0xb0080
	v_lshl_add_u64 v[220:221], v[222:223], 0, s[22:23]
	s_addc_u32 s35, s37, 0
	s_add_i32 s36, s66, s41
	global_load_lds_dwordx4 v[220:221], off
	v_lshl_add_u64 v[220:221], s[34:35], 0, v[134:135]
	s_mov_b32 m0, s36
	s_nop 0
	global_load_lds_dwordx4 v[220:221], off
	v_lshl_add_u64 v[220:221], s[34:35], 0, v[138:139]
	s_add_i32 m0, s36, 0x2000
	s_nop 0
	global_load_lds_dwordx4 v[220:221], off
	v_lshl_add_u64 v[220:221], v[224:225], 0, s[22:23]
	s_mov_b32 m0, s51
	s_nop 0
	global_load_lds_dwordx4 v[220:221], off
	v_lshl_add_u64 v[220:221], v[226:227], 0, s[22:23]
	s_mov_b32 m0, s52
	s_nop 0
	global_load_lds_dwordx4 v[220:221], off
	s_waitcnt vmcnt(8)
	s_waitcnt lgkmcnt(0)
	s_barrier
	s_add_u32 s30, s30, 0x100
	s_addc_u32 s31, s31, 0
	s_add_u32 s13, s13, 0x100
	s_addc_u32 s63, s63, 0
	s_setprio 1
	s_waitcnt lgkmcnt(0)
	v_mfma_f32_16x16x32_bf16 v[60:63], v[148:151], v[188:191], v[60:63]
	v_mfma_f32_16x16x32_bf16 v[56:59], v[164:167], v[188:191], v[56:59]
	v_mfma_f32_16x16x32_bf16 v[44:47], v[148:151], v[196:199], v[44:47]
	v_mfma_f32_16x16x32_bf16 v[40:43], v[164:167], v[196:199], v[40:43]
	v_mfma_f32_16x16x32_bf16 v[28:31], v[148:151], v[204:207], v[28:31]
	v_mfma_f32_16x16x32_bf16 v[24:27], v[164:167], v[204:207], v[24:27]
	v_mfma_f32_16x16x32_bf16 v[12:15], v[148:151], v[212:215], v[12:15]
	v_mfma_f32_16x16x32_bf16 v[8:11], v[164:167], v[212:215], v[8:11]
	v_mfma_f32_16x16x32_bf16 v[60:63], v[160:163], v[192:195], v[60:63]
	v_mfma_f32_16x16x32_bf16 v[56:59], v[168:171], v[192:195], v[56:59]
	v_mfma_f32_16x16x32_bf16 v[44:47], v[160:163], v[200:203], v[44:47]
	v_mfma_f32_16x16x32_bf16 v[40:43], v[168:171], v[200:203], v[40:43]
	v_mfma_f32_16x16x32_bf16 v[28:31], v[160:163], v[208:211], v[28:31]
	v_mfma_f32_16x16x32_bf16 v[24:27], v[168:171], v[208:211], v[24:27]
	v_mfma_f32_16x16x32_bf16 v[12:15], v[160:163], v[216:219], v[12:15]
	v_mfma_f32_16x16x32_bf16 v[8:11], v[168:171], v[216:219], v[8:11]
	s_setprio 0
	s_setprio 1
	v_mfma_f32_16x16x32_bf16 v[52:55], v[172:175], v[188:191], v[52:55]
	v_mfma_f32_16x16x32_bf16 v[48:51], v[180:183], v[188:191], v[48:51]
	v_mfma_f32_16x16x32_bf16 v[36:39], v[172:175], v[196:199], v[36:39]
	v_mfma_f32_16x16x32_bf16 v[32:35], v[180:183], v[196:199], v[32:35]
	v_mfma_f32_16x16x32_bf16 v[20:23], v[172:175], v[204:207], v[20:23]
	v_mfma_f32_16x16x32_bf16 v[16:19], v[180:183], v[204:207], v[16:19]
	v_mfma_f32_16x16x32_bf16 v[4:7], v[172:175], v[212:215], v[4:7]
	v_mfma_f32_16x16x32_bf16 v[0:3], v[180:183], v[212:215], v[0:3]
	v_mfma_f32_16x16x32_bf16 v[52:55], v[176:179], v[192:195], v[52:55]
	v_mfma_f32_16x16x32_bf16 v[48:51], v[184:187], v[192:195], v[48:51]
	v_mfma_f32_16x16x32_bf16 v[36:39], v[176:179], v[200:203], v[36:39]
	v_mfma_f32_16x16x32_bf16 v[32:35], v[184:187], v[200:203], v[32:35]
	v_mfma_f32_16x16x32_bf16 v[20:23], v[176:179], v[208:211], v[20:23]
	v_mfma_f32_16x16x32_bf16 v[16:19], v[184:187], v[208:211], v[16:19]
	v_mfma_f32_16x16x32_bf16 v[4:7], v[176:179], v[216:219], v[4:7]
	v_mfma_f32_16x16x32_bf16 v[0:3], v[184:187], v[216:219], v[0:3]
	s_setprio 0
	s_barrier
	s_add_i32 s64, s64, 2
.LBB0_1145:
	ds_read_b128 v[148:151], v154
	ds_read_b128 v[160:163], v154 offset:1024
	ds_read_b128 v[164:167], v154 offset:2048
	ds_read_b128 v[168:171], v154 offset:3072
	ds_read_b128 v[172:175], v155
	ds_read_b128 v[176:179], v155 offset:1024
	ds_read_b128 v[180:183], v155 offset:2048
	ds_read_b128 v[184:187], v155 offset:3072
	s_add_u32 s34, s30, 0xfff50080
	s_addc_u32 s35, s31, -1
	s_cmp_eq_u32 s64, 40
	s_cselect_b32 s39, s1, s35
	s_cselect_b32 s38, s0, s34
	s_cselect_b32 s37, s29, s63
	s_cselect_b32 s36, s28, s13
	v_lshl_add_u64 v[220:221], s[30:31], 0, v[140:141]
	s_add_i32 m0, s42, 0xc000
	ds_read_b128 v[188:191], v157
	ds_read_b128 v[192:195], v157 offset:1024
	ds_read_b128 v[196:199], v157 offset:2048
	ds_read_b128 v[200:203], v157 offset:3072
	ds_read_b128 v[204:207], v157 offset:4096
	ds_read_b128 v[208:211], v157 offset:5120
	ds_read_b128 v[212:215], v157 offset:6144
	ds_read_b128 v[216:219], v157 offset:7168
	global_load_lds_dwordx4 v[220:221], off
	v_lshl_add_u64 v[220:221], s[30:31], 0, v[142:143]
	s_add_i32 m0, s42, 0xe000
	s_nop 0
	global_load_lds_dwordx4 v[220:221], off
	s_waitcnt vmcnt(8)
	s_waitcnt lgkmcnt(0)
	s_barrier
	s_setprio 1
	s_waitcnt lgkmcnt(0)
	v_mfma_f32_16x16x32_bf16 v[124:127], v[148:151], v[188:191], v[124:127]
	v_mfma_f32_16x16x32_bf16 v[120:123], v[164:167], v[188:191], v[120:123]
	v_mfma_f32_16x16x32_bf16 v[108:111], v[148:151], v[196:199], v[108:111]
	v_mfma_f32_16x16x32_bf16 v[104:107], v[164:167], v[196:199], v[104:107]
	v_mfma_f32_16x16x32_bf16 v[92:95], v[148:151], v[204:207], v[92:95]
	v_mfma_f32_16x16x32_bf16 v[88:91], v[164:167], v[204:207], v[88:91]
	v_mfma_f32_16x16x32_bf16 v[76:79], v[148:151], v[212:215], v[76:79]
	v_mfma_f32_16x16x32_bf16 v[72:75], v[164:167], v[212:215], v[72:75]
	v_mfma_f32_16x16x32_bf16 v[124:127], v[160:163], v[192:195], v[124:127]
	v_mfma_f32_16x16x32_bf16 v[120:123], v[168:171], v[192:195], v[120:123]
	v_mfma_f32_16x16x32_bf16 v[108:111], v[160:163], v[200:203], v[108:111]
	v_mfma_f32_16x16x32_bf16 v[104:107], v[168:171], v[200:203], v[104:107]
	v_mfma_f32_16x16x32_bf16 v[92:95], v[160:163], v[208:211], v[92:95]
	v_mfma_f32_16x16x32_bf16 v[88:91], v[168:171], v[208:211], v[88:91]
	v_mfma_f32_16x16x32_bf16 v[76:79], v[160:163], v[216:219], v[76:79]
	v_mfma_f32_16x16x32_bf16 v[72:75], v[168:171], v[216:219], v[72:75]
	s_setprio 0
	s_setprio 1
	v_mfma_f32_16x16x32_bf16 v[116:119], v[172:175], v[188:191], v[116:119]
	v_mfma_f32_16x16x32_bf16 v[112:115], v[180:183], v[188:191], v[112:115]
	v_mfma_f32_16x16x32_bf16 v[100:103], v[172:175], v[196:199], v[100:103]
	v_mfma_f32_16x16x32_bf16 v[96:99], v[180:183], v[196:199], v[96:99]
	v_mfma_f32_16x16x32_bf16 v[84:87], v[172:175], v[204:207], v[84:87]
	v_mfma_f32_16x16x32_bf16 v[80:83], v[180:183], v[204:207], v[80:83]
	v_mfma_f32_16x16x32_bf16 v[68:71], v[172:175], v[212:215], v[68:71]
	v_mfma_f32_16x16x32_bf16 v[64:67], v[180:183], v[212:215], v[64:67]
	v_mfma_f32_16x16x32_bf16 v[116:119], v[176:179], v[192:195], v[116:119]
	v_mfma_f32_16x16x32_bf16 v[112:115], v[184:187], v[192:195], v[112:115]
	v_mfma_f32_16x16x32_bf16 v[100:103], v[176:179], v[200:203], v[100:103]
	v_mfma_f32_16x16x32_bf16 v[96:99], v[184:187], v[200:203], v[96:99]
	v_mfma_f32_16x16x32_bf16 v[84:87], v[176:179], v[208:211], v[84:87]
	v_mfma_f32_16x16x32_bf16 v[80:83], v[184:187], v[208:211], v[80:83]
	v_mfma_f32_16x16x32_bf16 v[68:71], v[176:179], v[216:219], v[68:71]
	v_mfma_f32_16x16x32_bf16 v[64:67], v[184:187], v[216:219], v[64:67]
	s_setprio 0
	s_barrier
	s_add_i32 s34, s56, s41
	v_lshl_add_u64 v[220:221], s[36:37], 0, v[134:135]
	s_mov_b32 m0, s34
	ds_read_b128 v[188:191], v157 offset:16384
	ds_read_b128 v[192:195], v157 offset:17408
	ds_read_b128 v[196:199], v157 offset:18432
	ds_read_b128 v[200:203], v157 offset:19456
	ds_read_b128 v[204:207], v157 offset:20480
	ds_read_b128 v[208:211], v157 offset:21504
	ds_read_b128 v[212:215], v157 offset:22528
	ds_read_b128 v[216:219], v157 offset:23552
	global_load_lds_dwordx4 v[220:221], off
	s_add_i32 m0, s34, 0x2000
	s_add_u32 s34, s36, 0xb0000
	v_lshl_add_u64 v[222:223], s[36:37], 0, v[138:139]
	s_addc_u32 s35, s37, 0
	s_add_i32 s65, s57, s41
	global_load_lds_dwordx4 v[222:223], off
	v_lshl_add_u64 v[224:225], s[34:35], 0, v[134:135]
	s_mov_b32 m0, s65
	v_lshl_add_u64 v[226:227], s[38:39], 0, v[136:137]
	global_load_lds_dwordx4 v[224:225], off
	v_lshl_add_u64 v[224:225], s[34:35], 0, v[138:139]
	s_add_i32 m0, s65, 0x2000
	s_nop 0
	global_load_lds_dwordx4 v[224:225], off
	v_lshl_add_u64 v[224:225], s[38:39], 0, v[132:133]
	s_mov_b32 m0, s42
	s_nop 0
	global_load_lds_dwordx4 v[224:225], off
	s_mov_b32 m0, s43
	s_nop 0
	global_load_lds_dwordx4 v[226:227], off
	s_waitcnt vmcnt(8)
	s_waitcnt lgkmcnt(0)
	s_barrier
	s_setprio 1
	s_waitcnt lgkmcnt(0)
	v_mfma_f32_16x16x32_bf16 v[60:63], v[148:151], v[188:191], v[60:63]
	v_mfma_f32_16x16x32_bf16 v[56:59], v[164:167], v[188:191], v[56:59]
	v_mfma_f32_16x16x32_bf16 v[44:47], v[148:151], v[196:199], v[44:47]
	v_mfma_f32_16x16x32_bf16 v[40:43], v[164:167], v[196:199], v[40:43]
	v_mfma_f32_16x16x32_bf16 v[28:31], v[148:151], v[204:207], v[28:31]
	v_mfma_f32_16x16x32_bf16 v[24:27], v[164:167], v[204:207], v[24:27]
	v_mfma_f32_16x16x32_bf16 v[12:15], v[148:151], v[212:215], v[12:15]
	v_mfma_f32_16x16x32_bf16 v[8:11], v[164:167], v[212:215], v[8:11]
	v_mfma_f32_16x16x32_bf16 v[60:63], v[160:163], v[192:195], v[60:63]
	v_mfma_f32_16x16x32_bf16 v[56:59], v[168:171], v[192:195], v[56:59]
	v_mfma_f32_16x16x32_bf16 v[44:47], v[160:163], v[200:203], v[44:47]
	v_mfma_f32_16x16x32_bf16 v[40:43], v[168:171], v[200:203], v[40:43]
	v_mfma_f32_16x16x32_bf16 v[28:31], v[160:163], v[208:211], v[28:31]
	v_mfma_f32_16x16x32_bf16 v[24:27], v[168:171], v[208:211], v[24:27]
	v_mfma_f32_16x16x32_bf16 v[12:15], v[160:163], v[216:219], v[12:15]
	v_mfma_f32_16x16x32_bf16 v[8:11], v[168:171], v[216:219], v[8:11]
	s_setprio 0
	s_setprio 1
	v_mfma_f32_16x16x32_bf16 v[52:55], v[172:175], v[188:191], v[52:55]
	v_mfma_f32_16x16x32_bf16 v[48:51], v[180:183], v[188:191], v[48:51]
	v_mfma_f32_16x16x32_bf16 v[36:39], v[172:175], v[196:199], v[36:39]
	v_mfma_f32_16x16x32_bf16 v[32:35], v[180:183], v[196:199], v[32:35]
	v_mfma_f32_16x16x32_bf16 v[20:23], v[172:175], v[204:207], v[20:23]
	v_mfma_f32_16x16x32_bf16 v[16:19], v[180:183], v[204:207], v[16:19]
	v_mfma_f32_16x16x32_bf16 v[4:7], v[172:175], v[212:215], v[4:7]
	v_mfma_f32_16x16x32_bf16 v[0:3], v[180:183], v[212:215], v[0:3]
	v_mfma_f32_16x16x32_bf16 v[52:55], v[176:179], v[192:195], v[52:55]
	v_mfma_f32_16x16x32_bf16 v[48:51], v[184:187], v[192:195], v[48:51]
	v_mfma_f32_16x16x32_bf16 v[36:39], v[176:179], v[200:203], v[36:39]
	v_mfma_f32_16x16x32_bf16 v[32:35], v[184:187], v[200:203], v[32:35]
	v_mfma_f32_16x16x32_bf16 v[20:23], v[176:179], v[208:211], v[20:23]
	v_mfma_f32_16x16x32_bf16 v[16:19], v[184:187], v[208:211], v[16:19]
	v_mfma_f32_16x16x32_bf16 v[4:7], v[176:179], v[216:219], v[4:7]
	v_mfma_f32_16x16x32_bf16 v[0:3], v[184:187], v[216:219], v[0:3]
	s_setprio 0
	s_barrier
	s_add_i32 s65, 0, 0x18000
	v_add_u32_e32 v159, s65, v152
	s_add_i32 s66, 0, 0x1c000
	ds_read_b128 v[148:151], v159
	ds_read_b128 v[160:163], v159 offset:1024
	ds_read_b128 v[164:167], v159 offset:2048
	ds_read_b128 v[168:171], v159 offset:3072
	v_add_u32_e32 v159, s66, v152
	ds_read_b128 v[172:175], v159
	ds_read_b128 v[176:179], v159 offset:1024
	ds_read_b128 v[180:183], v159 offset:2048
	ds_read_b128 v[184:187], v159 offset:3072
	s_add_u32 s34, s38, 0xb0000
	s_addc_u32 s35, s39, 0
	s_mov_b32 m0, s48
	v_lshl_add_u64 v[228:229], s[34:35], 0, v[132:133]
	ds_read_b128 v[188:191], v157 offset:32768
	ds_read_b128 v[192:195], v157 offset:33792
	ds_read_b128 v[196:199], v157 offset:34816
	ds_read_b128 v[200:203], v157 offset:35840
	ds_read_b128 v[204:207], v157 offset:36864
	ds_read_b128 v[208:211], v157 offset:37888
	ds_read_b128 v[212:215], v157 offset:38912
	ds_read_b128 v[216:219], v157 offset:39936
	global_load_lds_dwordx4 v[228:229], off
	v_lshl_add_u64 v[228:229], s[34:35], 0, v[136:137]
	s_mov_b32 m0, s49
	s_nop 0
	global_load_lds_dwordx4 v[228:229], off
	s_waitcnt vmcnt(8)
	s_waitcnt lgkmcnt(0)
	s_barrier
	s_setprio 1
	s_waitcnt lgkmcnt(0)
	v_mfma_f32_16x16x32_bf16 v[124:127], v[148:151], v[188:191], v[124:127]
	v_mfma_f32_16x16x32_bf16 v[120:123], v[164:167], v[188:191], v[120:123]
	v_mfma_f32_16x16x32_bf16 v[108:111], v[148:151], v[196:199], v[108:111]
	v_mfma_f32_16x16x32_bf16 v[104:107], v[164:167], v[196:199], v[104:107]
	v_mfma_f32_16x16x32_bf16 v[92:95], v[148:151], v[204:207], v[92:95]
	v_mfma_f32_16x16x32_bf16 v[88:91], v[164:167], v[204:207], v[88:91]
	v_mfma_f32_16x16x32_bf16 v[76:79], v[148:151], v[212:215], v[76:79]
	v_mfma_f32_16x16x32_bf16 v[72:75], v[164:167], v[212:215], v[72:75]
	v_mfma_f32_16x16x32_bf16 v[124:127], v[160:163], v[192:195], v[124:127]
	v_mfma_f32_16x16x32_bf16 v[120:123], v[168:171], v[192:195], v[120:123]
	v_mfma_f32_16x16x32_bf16 v[108:111], v[160:163], v[200:203], v[108:111]
	v_mfma_f32_16x16x32_bf16 v[104:107], v[168:171], v[200:203], v[104:107]
	v_mfma_f32_16x16x32_bf16 v[92:95], v[160:163], v[208:211], v[92:95]
	v_mfma_f32_16x16x32_bf16 v[88:91], v[168:171], v[208:211], v[88:91]
	v_mfma_f32_16x16x32_bf16 v[76:79], v[160:163], v[216:219], v[76:79]
	v_mfma_f32_16x16x32_bf16 v[72:75], v[168:171], v[216:219], v[72:75]
	s_setprio 0
	s_setprio 1
	v_mfma_f32_16x16x32_bf16 v[116:119], v[172:175], v[188:191], v[116:119]
	v_mfma_f32_16x16x32_bf16 v[112:115], v[180:183], v[188:191], v[112:115]
	v_mfma_f32_16x16x32_bf16 v[100:103], v[172:175], v[196:199], v[100:103]
	v_mfma_f32_16x16x32_bf16 v[96:99], v[180:183], v[196:199], v[96:99]
	v_mfma_f32_16x16x32_bf16 v[84:87], v[172:175], v[204:207], v[84:87]
	v_mfma_f32_16x16x32_bf16 v[80:83], v[180:183], v[204:207], v[80:83]
	v_mfma_f32_16x16x32_bf16 v[68:71], v[172:175], v[212:215], v[68:71]
	v_mfma_f32_16x16x32_bf16 v[64:67], v[180:183], v[212:215], v[64:67]
	v_mfma_f32_16x16x32_bf16 v[116:119], v[176:179], v[192:195], v[116:119]
	v_mfma_f32_16x16x32_bf16 v[112:115], v[184:187], v[192:195], v[112:115]
	v_mfma_f32_16x16x32_bf16 v[100:103], v[176:179], v[200:203], v[100:103]
	v_mfma_f32_16x16x32_bf16 v[96:99], v[184:187], v[200:203], v[96:99]
	v_mfma_f32_16x16x32_bf16 v[84:87], v[176:179], v[208:211], v[84:87]
	v_mfma_f32_16x16x32_bf16 v[80:83], v[184:187], v[208:211], v[80:83]
	v_mfma_f32_16x16x32_bf16 v[68:71], v[176:179], v[216:219], v[68:71]
	v_mfma_f32_16x16x32_bf16 v[64:67], v[184:187], v[216:219], v[64:67]
	s_setprio 0
	s_barrier
	s_add_i32 s34, s65, s41
	v_lshl_add_u64 v[220:221], v[220:221], 0, s[22:23]
	s_mov_b32 m0, s34
	ds_read_b128 v[188:191], v157 offset:49152
	ds_read_b128 v[192:195], v157 offset:50176
	ds_read_b128 v[196:199], v157 offset:51200
	ds_read_b128 v[200:203], v157 offset:52224
	ds_read_b128 v[204:207], v157 offset:53248
	ds_read_b128 v[208:211], v157 offset:54272
	ds_read_b128 v[212:215], v157 offset:55296
	ds_read_b128 v[216:219], v157 offset:56320
	global_load_lds_dwordx4 v[220:221], off
	s_add_i32 m0, s34, 0x2000
	s_add_u32 s34, s36, 0xb0080
	v_lshl_add_u64 v[220:221], v[222:223], 0, s[22:23]
	s_addc_u32 s35, s37, 0
	s_add_i32 s36, s66, s41
	global_load_lds_dwordx4 v[220:221], off
	v_lshl_add_u64 v[220:221], s[34:35], 0, v[134:135]
	s_mov_b32 m0, s36
	s_nop 0
	global_load_lds_dwordx4 v[220:221], off
	v_lshl_add_u64 v[220:221], s[34:35], 0, v[138:139]
	s_add_i32 m0, s36, 0x2000
	s_nop 0
	global_load_lds_dwordx4 v[220:221], off
	v_lshl_add_u64 v[220:221], v[224:225], 0, s[22:23]
	s_mov_b32 m0, s51
	s_nop 0
	global_load_lds_dwordx4 v[220:221], off
	v_lshl_add_u64 v[220:221], v[226:227], 0, s[22:23]
	s_mov_b32 m0, s52
	s_nop 0
	global_load_lds_dwordx4 v[220:221], off
	s_waitcnt vmcnt(8)
	s_waitcnt lgkmcnt(0)
	s_barrier
	s_add_u32 s30, s30, 0x100
	s_addc_u32 s31, s31, 0
	s_add_u32 s13, s13, 0x100
	s_addc_u32 s63, s63, 0
	s_setprio 1
	s_waitcnt lgkmcnt(0)
	v_mfma_f32_16x16x32_bf16 v[60:63], v[148:151], v[188:191], v[60:63]
	v_mfma_f32_16x16x32_bf16 v[56:59], v[164:167], v[188:191], v[56:59]
	v_mfma_f32_16x16x32_bf16 v[44:47], v[148:151], v[196:199], v[44:47]
	v_mfma_f32_16x16x32_bf16 v[40:43], v[164:167], v[196:199], v[40:43]
	v_mfma_f32_16x16x32_bf16 v[28:31], v[148:151], v[204:207], v[28:31]
	v_mfma_f32_16x16x32_bf16 v[24:27], v[164:167], v[204:207], v[24:27]
	v_mfma_f32_16x16x32_bf16 v[12:15], v[148:151], v[212:215], v[12:15]
	v_mfma_f32_16x16x32_bf16 v[8:11], v[164:167], v[212:215], v[8:11]
	v_mfma_f32_16x16x32_bf16 v[60:63], v[160:163], v[192:195], v[60:63]
	v_mfma_f32_16x16x32_bf16 v[56:59], v[168:171], v[192:195], v[56:59]
	v_mfma_f32_16x16x32_bf16 v[44:47], v[160:163], v[200:203], v[44:47]
	v_mfma_f32_16x16x32_bf16 v[40:43], v[168:171], v[200:203], v[40:43]
	v_mfma_f32_16x16x32_bf16 v[28:31], v[160:163], v[208:211], v[28:31]
	v_mfma_f32_16x16x32_bf16 v[24:27], v[168:171], v[208:211], v[24:27]
	v_mfma_f32_16x16x32_bf16 v[12:15], v[160:163], v[216:219], v[12:15]
	v_mfma_f32_16x16x32_bf16 v[8:11], v[168:171], v[216:219], v[8:11]
	s_setprio 0
	s_setprio 1
	v_mfma_f32_16x16x32_bf16 v[52:55], v[172:175], v[188:191], v[52:55]
	v_mfma_f32_16x16x32_bf16 v[48:51], v[180:183], v[188:191], v[48:51]
	v_mfma_f32_16x16x32_bf16 v[36:39], v[172:175], v[196:199], v[36:39]
	v_mfma_f32_16x16x32_bf16 v[32:35], v[180:183], v[196:199], v[32:35]
	v_mfma_f32_16x16x32_bf16 v[20:23], v[172:175], v[204:207], v[20:23]
	v_mfma_f32_16x16x32_bf16 v[16:19], v[180:183], v[204:207], v[16:19]
	v_mfma_f32_16x16x32_bf16 v[4:7], v[172:175], v[212:215], v[4:7]
	v_mfma_f32_16x16x32_bf16 v[0:3], v[180:183], v[212:215], v[0:3]
	v_mfma_f32_16x16x32_bf16 v[52:55], v[176:179], v[192:195], v[52:55]
	v_mfma_f32_16x16x32_bf16 v[48:51], v[184:187], v[192:195], v[48:51]
	v_mfma_f32_16x16x32_bf16 v[36:39], v[176:179], v[200:203], v[36:39]
	v_mfma_f32_16x16x32_bf16 v[32:35], v[184:187], v[200:203], v[32:35]
	v_mfma_f32_16x16x32_bf16 v[20:23], v[176:179], v[208:211], v[20:23]
	v_mfma_f32_16x16x32_bf16 v[16:19], v[184:187], v[208:211], v[16:19]
	v_mfma_f32_16x16x32_bf16 v[4:7], v[176:179], v[216:219], v[4:7]
	v_mfma_f32_16x16x32_bf16 v[0:3], v[184:187], v[216:219], v[0:3]
	s_setprio 0
	s_cmp_eq_u32 s64, s98
	s_cbranch_scc1 .Lmy_nobar_11
	s_barrier
.Lmy_nobar_11:
	s_add_i32 s64, s64, 2
	s_cmp_gt_u32 s64, 41
	s_cbranch_scc0 .LBB0_1145
	s_and_b64 vcc, exec, s[26:27]
	s_cbranch_vccz .LBB0_1148
	s_nop 0

.Lmy_nobar2_12:
	ds_read_b128 v[148:151], v155
	ds_read_b128 v[160:163], v155 offset:1024
	ds_read_b128 v[164:167], v155 offset:2048
	ds_read_b128 v[168:171], v155 offset:3072
	ds_read_b128 v[172:175], v157
	ds_read_b128 v[176:179], v157 offset:1024
	ds_read_b128 v[180:183], v157 offset:2048
	ds_read_b128 v[184:187], v157 offset:3072
	s_add_u32 s34, s36, 0xfffc0080
	s_addc_u32 s35, s37, -1
	s_cmp_eq_u32 s77, 12
	s_cselect_b32 s41, s23, s35
	s_cselect_b32 s40, s64, s34
	s_cselect_b32 s39, s11, s67
	s_cselect_b32 s38, s65, s66
	v_lshl_add_u64 v[220:221], s[36:37], 0, v[140:141]
	s_add_i32 m0, s31, 0xc000
	ds_read_b128 v[188:191], v158
	ds_read_b128 v[192:195], v158 offset:1024
	ds_read_b128 v[196:199], v158 offset:2048
	ds_read_b128 v[200:203], v158 offset:3072
	ds_read_b128 v[204:207], v158 offset:4096
	ds_read_b128 v[208:211], v158 offset:5120
	ds_read_b128 v[212:215], v158 offset:6144
	ds_read_b128 v[216:219], v158 offset:7168
	global_load_lds_dwordx4 v[220:221], off
	v_lshl_add_u64 v[220:221], s[36:37], 0, v[142:143]
	s_add_i32 m0, s31, 0xe000
	s_nop 0
	global_load_lds_dwordx4 v[220:221], off
	s_waitcnt vmcnt(8)
	s_waitcnt lgkmcnt(0)
	s_barrier
	s_setprio 1
	s_waitcnt lgkmcnt(0)
	v_mfma_f32_16x16x32_bf16 v[124:127], v[148:151], v[188:191], 0
	v_mfma_f32_16x16x32_bf16 v[120:123], v[164:167], v[188:191], 0
	v_mfma_f32_16x16x32_bf16 v[108:111], v[148:151], v[196:199], 0
	v_mfma_f32_16x16x32_bf16 v[104:107], v[164:167], v[196:199], 0
	v_mfma_f32_16x16x32_bf16 v[92:95], v[148:151], v[204:207], 0
	v_mfma_f32_16x16x32_bf16 v[88:91], v[164:167], v[204:207], 0
	v_mfma_f32_16x16x32_bf16 v[76:79], v[148:151], v[212:215], 0
	v_mfma_f32_16x16x32_bf16 v[72:75], v[164:167], v[212:215], 0
	v_mfma_f32_16x16x32_bf16 v[124:127], v[160:163], v[192:195], v[124:127]
	v_mfma_f32_16x16x32_bf16 v[120:123], v[168:171], v[192:195], v[120:123]
	v_mfma_f32_16x16x32_bf16 v[108:111], v[160:163], v[200:203], v[108:111]
	v_mfma_f32_16x16x32_bf16 v[104:107], v[168:171], v[200:203], v[104:107]
	v_mfma_f32_16x16x32_bf16 v[92:95], v[160:163], v[208:211], v[92:95]
	v_mfma_f32_16x16x32_bf16 v[88:91], v[168:171], v[208:211], v[88:91]
	v_mfma_f32_16x16x32_bf16 v[76:79], v[160:163], v[216:219], v[76:79]
	v_mfma_f32_16x16x32_bf16 v[72:75], v[168:171], v[216:219], v[72:75]
	s_setprio 0
	s_setprio 1
	v_mfma_f32_16x16x32_bf16 v[116:119], v[172:175], v[188:191], 0
	v_mfma_f32_16x16x32_bf16 v[112:115], v[180:183], v[188:191], 0
	v_mfma_f32_16x16x32_bf16 v[100:103], v[172:175], v[196:199], 0
	v_mfma_f32_16x16x32_bf16 v[96:99], v[180:183], v[196:199], 0
	v_mfma_f32_16x16x32_bf16 v[84:87], v[172:175], v[204:207], 0
	v_mfma_f32_16x16x32_bf16 v[80:83], v[180:183], v[204:207], 0
	v_mfma_f32_16x16x32_bf16 v[68:71], v[172:175], v[212:215], 0
	v_mfma_f32_16x16x32_bf16 v[64:67], v[180:183], v[212:215], 0
	v_mfma_f32_16x16x32_bf16 v[116:119], v[176:179], v[192:195], v[116:119]
	v_mfma_f32_16x16x32_bf16 v[112:115], v[184:187], v[192:195], v[112:115]
	v_mfma_f32_16x16x32_bf16 v[100:103], v[176:179], v[200:203], v[100:103]
	v_mfma_f32_16x16x32_bf16 v[96:99], v[184:187], v[200:203], v[96:99]
	v_mfma_f32_16x16x32_bf16 v[84:87], v[176:179], v[208:211], v[84:87]
	v_mfma_f32_16x16x32_bf16 v[80:83], v[184:187], v[208:211], v[80:83]
	v_mfma_f32_16x16x32_bf16 v[68:71], v[176:179], v[216:219], v[68:71]
	v_mfma_f32_16x16x32_bf16 v[64:67], v[184:187], v[216:219], v[64:67]
	s_setprio 0
	s_barrier
	s_add_i32 s34, s55, s48
	v_lshl_add_u64 v[220:221], s[38:39], 0, v[136:137]
	s_mov_b32 m0, s34
	ds_read_b128 v[188:191], v158 offset:16384
	ds_read_b128 v[192:195], v158 offset:17408
	ds_read_b128 v[196:199], v158 offset:18432
	ds_read_b128 v[200:203], v158 offset:19456
	ds_read_b128 v[204:207], v158 offset:20480
	ds_read_b128 v[208:211], v158 offset:21504
	ds_read_b128 v[212:215], v158 offset:22528
	ds_read_b128 v[216:219], v158 offset:23552
	global_load_lds_dwordx4 v[220:221], off
	s_add_i32 m0, s34, 0x2000
	s_add_u32 s34, s38, 0x40000
	v_lshl_add_u64 v[222:223], s[38:39], 0, v[132:133]
	s_addc_u32 s35, s39, 0
	s_add_i32 s79, s56, s48
	global_load_lds_dwordx4 v[222:223], off
	v_lshl_add_u64 v[224:225], s[34:35], 0, v[136:137]
	s_mov_b32 m0, s79
	v_lshl_add_u64 v[226:227], s[40:41], 0, v[134:135]
	global_load_lds_dwordx4 v[224:225], off
	v_lshl_add_u64 v[224:225], s[34:35], 0, v[132:133]
	s_add_i32 m0, s79, 0x2000
	s_nop 0
	global_load_lds_dwordx4 v[224:225], off
	v_lshl_add_u64 v[224:225], s[40:41], 0, v[138:139]
	s_mov_b32 m0, s31
	s_nop 0
	global_load_lds_dwordx4 v[224:225], off
	s_mov_b32 m0, s52
	s_nop 0
	global_load_lds_dwordx4 v[226:227], off
	s_waitcnt vmcnt(8)
	s_waitcnt lgkmcnt(0)
	s_barrier
	s_setprio 1
	s_waitcnt lgkmcnt(0)
	v_mfma_f32_16x16x32_bf16 v[60:63], v[148:151], v[188:191], 0
	v_mfma_f32_16x16x32_bf16 v[56:59], v[164:167], v[188:191], 0
	v_mfma_f32_16x16x32_bf16 v[44:47], v[148:151], v[196:199], 0
	v_mfma_f32_16x16x32_bf16 v[40:43], v[164:167], v[196:199], 0
	v_mfma_f32_16x16x32_bf16 v[28:31], v[148:151], v[204:207], 0
	v_mfma_f32_16x16x32_bf16 v[24:27], v[164:167], v[204:207], 0
	v_mfma_f32_16x16x32_bf16 v[12:15], v[148:151], v[212:215], 0
	v_mfma_f32_16x16x32_bf16 v[8:11], v[164:167], v[212:215], 0
	v_mfma_f32_16x16x32_bf16 v[60:63], v[160:163], v[192:195], v[60:63]
	v_mfma_f32_16x16x32_bf16 v[56:59], v[168:171], v[192:195], v[56:59]
	v_mfma_f32_16x16x32_bf16 v[44:47], v[160:163], v[200:203], v[44:47]
	v_mfma_f32_16x16x32_bf16 v[40:43], v[168:171], v[200:203], v[40:43]
	v_mfma_f32_16x16x32_bf16 v[28:31], v[160:163], v[208:211], v[28:31]
	v_mfma_f32_16x16x32_bf16 v[24:27], v[168:171], v[208:211], v[24:27]
	v_mfma_f32_16x16x32_bf16 v[12:15], v[160:163], v[216:219], v[12:15]
	v_mfma_f32_16x16x32_bf16 v[8:11], v[168:171], v[216:219], v[8:11]
	s_setprio 0
	s_setprio 1
	v_mfma_f32_16x16x32_bf16 v[52:55], v[172:175], v[188:191], 0
	v_mfma_f32_16x16x32_bf16 v[48:51], v[180:183], v[188:191], 0
	v_mfma_f32_16x16x32_bf16 v[36:39], v[172:175], v[196:199], 0
	v_mfma_f32_16x16x32_bf16 v[32:35], v[180:183], v[196:199], 0
	v_mfma_f32_16x16x32_bf16 v[20:23], v[172:175], v[204:207], 0
	v_mfma_f32_16x16x32_bf16 v[16:19], v[180:183], v[204:207], 0
	v_mfma_f32_16x16x32_bf16 v[4:7], v[172:175], v[212:215], 0
	v_mfma_f32_16x16x32_bf16 v[0:3], v[180:183], v[212:215], 0
	v_mfma_f32_16x16x32_bf16 v[52:55], v[176:179], v[192:195], v[52:55]
	v_mfma_f32_16x16x32_bf16 v[48:51], v[184:187], v[192:195], v[48:51]
	v_mfma_f32_16x16x32_bf16 v[36:39], v[176:179], v[200:203], v[36:39]
	v_mfma_f32_16x16x32_bf16 v[32:35], v[184:187], v[200:203], v[32:35]
	v_mfma_f32_16x16x32_bf16 v[20:23], v[176:179], v[208:211], v[20:23]
	v_mfma_f32_16x16x32_bf16 v[16:19], v[184:187], v[208:211], v[16:19]
	v_mfma_f32_16x16x32_bf16 v[4:7], v[176:179], v[216:219], v[4:7]
	v_mfma_f32_16x16x32_bf16 v[0:3], v[184:187], v[216:219], v[0:3]
	s_setprio 0
	s_barrier
	s_add_i32 s79, 0, 0x18000
	v_add_u32_e32 v159, s79, v152
	s_add_i32 s81, 0, 0x1c000
	ds_read_b128 v[148:151], v159
	ds_read_b128 v[160:163], v159 offset:1024
	ds_read_b128 v[164:167], v159 offset:2048
	ds_read_b128 v[168:171], v159 offset:3072
	v_add_u32_e32 v159, s81, v152
	ds_read_b128 v[172:175], v159
	ds_read_b128 v[176:179], v159 offset:1024
	ds_read_b128 v[180:183], v159 offset:2048
	ds_read_b128 v[184:187], v159 offset:3072
	s_add_u32 s34, s40, 0x40000
	s_addc_u32 s35, s41, 0
	s_mov_b32 m0, s53
	v_lshl_add_u64 v[228:229], s[34:35], 0, v[138:139]
	ds_read_b128 v[188:191], v158 offset:32768
	ds_read_b128 v[192:195], v158 offset:33792
	ds_read_b128 v[196:199], v158 offset:34816
	ds_read_b128 v[200:203], v158 offset:35840
	ds_read_b128 v[204:207], v158 offset:36864
	ds_read_b128 v[208:211], v158 offset:37888
	ds_read_b128 v[212:215], v158 offset:38912
	ds_read_b128 v[216:219], v158 offset:39936
	global_load_lds_dwordx4 v[228:229], off
	v_lshl_add_u64 v[228:229], s[34:35], 0, v[134:135]
	s_mov_b32 m0, s54
	s_nop 0
	global_load_lds_dwordx4 v[228:229], off
	s_waitcnt vmcnt(8)
	s_waitcnt lgkmcnt(0)
	s_barrier
	s_setprio 1
	s_waitcnt lgkmcnt(0)
	v_mfma_f32_16x16x32_bf16 v[124:127], v[148:151], v[188:191], v[124:127]
	v_mfma_f32_16x16x32_bf16 v[120:123], v[164:167], v[188:191], v[120:123]
	v_mfma_f32_16x16x32_bf16 v[108:111], v[148:151], v[196:199], v[108:111]
	v_mfma_f32_16x16x32_bf16 v[104:107], v[164:167], v[196:199], v[104:107]
	v_mfma_f32_16x16x32_bf16 v[92:95], v[148:151], v[204:207], v[92:95]
	v_mfma_f32_16x16x32_bf16 v[88:91], v[164:167], v[204:207], v[88:91]
	v_mfma_f32_16x16x32_bf16 v[76:79], v[148:151], v[212:215], v[76:79]
	v_mfma_f32_16x16x32_bf16 v[72:75], v[164:167], v[212:215], v[72:75]
	v_mfma_f32_16x16x32_bf16 v[124:127], v[160:163], v[192:195], v[124:127]
	v_mfma_f32_16x16x32_bf16 v[120:123], v[168:171], v[192:195], v[120:123]
	v_mfma_f32_16x16x32_bf16 v[108:111], v[160:163], v[200:203], v[108:111]
	v_mfma_f32_16x16x32_bf16 v[104:107], v[168:171], v[200:203], v[104:107]
	v_mfma_f32_16x16x32_bf16 v[92:95], v[160:163], v[208:211], v[92:95]
	v_mfma_f32_16x16x32_bf16 v[88:91], v[168:171], v[208:211], v[88:91]
	v_mfma_f32_16x16x32_bf16 v[76:79], v[160:163], v[216:219], v[76:79]
	v_mfma_f32_16x16x32_bf16 v[72:75], v[168:171], v[216:219], v[72:75]
	s_setprio 0
	s_setprio 1
	v_mfma_f32_16x16x32_bf16 v[116:119], v[172:175], v[188:191], v[116:119]
	v_mfma_f32_16x16x32_bf16 v[112:115], v[180:183], v[188:191], v[112:115]
	v_mfma_f32_16x16x32_bf16 v[100:103], v[172:175], v[196:199], v[100:103]
	v_mfma_f32_16x16x32_bf16 v[96:99], v[180:183], v[196:199], v[96:99]
	v_mfma_f32_16x16x32_bf16 v[84:87], v[172:175], v[204:207], v[84:87]
	v_mfma_f32_16x16x32_bf16 v[80:83], v[180:183], v[204:207], v[80:83]
	v_mfma_f32_16x16x32_bf16 v[68:71], v[172:175], v[212:215], v[68:71]
	v_mfma_f32_16x16x32_bf16 v[64:67], v[180:183], v[212:215], v[64:67]
	v_mfma_f32_16x16x32_bf16 v[116:119], v[176:179], v[192:195], v[116:119]
	v_mfma_f32_16x16x32_bf16 v[112:115], v[184:187], v[192:195], v[112:115]
	v_mfma_f32_16x16x32_bf16 v[100:103], v[176:179], v[200:203], v[100:103]
	v_mfma_f32_16x16x32_bf16 v[96:99], v[184:187], v[200:203], v[96:99]
	v_mfma_f32_16x16x32_bf16 v[84:87], v[176:179], v[208:211], v[84:87]
	v_mfma_f32_16x16x32_bf16 v[80:83], v[184:187], v[208:211], v[80:83]
	v_mfma_f32_16x16x32_bf16 v[68:71], v[176:179], v[216:219], v[68:71]
	v_mfma_f32_16x16x32_bf16 v[64:67], v[184:187], v[216:219], v[64:67]
	s_setprio 0
	s_barrier
	s_add_i32 s34, s79, s48
	v_lshl_add_u64 v[220:221], v[220:221], 0, s[6:7]
	s_mov_b32 m0, s34
	ds_read_b128 v[188:191], v158 offset:49152
	ds_read_b128 v[192:195], v158 offset:50176
	ds_read_b128 v[196:199], v158 offset:51200
	ds_read_b128 v[200:203], v158 offset:52224
	ds_read_b128 v[204:207], v158 offset:53248
	ds_read_b128 v[208:211], v158 offset:54272
	ds_read_b128 v[212:215], v158 offset:55296
	ds_read_b128 v[216:219], v158 offset:56320
	global_load_lds_dwordx4 v[220:221], off
	s_add_i32 m0, s34, 0x2000
	s_add_u32 s34, s38, 0x40080
	v_lshl_add_u64 v[220:221], v[222:223], 0, s[6:7]
	s_addc_u32 s35, s39, 0
	s_add_i32 s38, s81, s48
	global_load_lds_dwordx4 v[220:221], off
	v_lshl_add_u64 v[220:221], s[34:35], 0, v[136:137]
	s_mov_b32 m0, s38
	s_nop 0
	global_load_lds_dwordx4 v[220:221], off
	v_lshl_add_u64 v[220:221], s[34:35], 0, v[132:133]
	s_add_i32 m0, s38, 0x2000
	s_nop 0
	global_load_lds_dwordx4 v[220:221], off
	v_lshl_add_u64 v[220:221], v[224:225], 0, s[6:7]
	s_mov_b32 m0, s12
	s_nop 0
	global_load_lds_dwordx4 v[220:221], off
	v_lshl_add_u64 v[220:221], v[226:227], 0, s[6:7]
	s_mov_b32 m0, s13
	s_nop 0
	global_load_lds_dwordx4 v[220:221], off
	s_waitcnt vmcnt(8)
	s_waitcnt lgkmcnt(0)
	s_barrier
	s_add_u32 s36, s36, 0x100
	s_addc_u32 s37, s37, 0
	s_add_u32 s66, s66, 0x100
	s_addc_u32 s67, s67, 0
	s_setprio 1
	s_waitcnt lgkmcnt(0)
	v_mfma_f32_16x16x32_bf16 v[60:63], v[148:151], v[188:191], v[60:63]
	v_mfma_f32_16x16x32_bf16 v[56:59], v[164:167], v[188:191], v[56:59]
	v_mfma_f32_16x16x32_bf16 v[44:47], v[148:151], v[196:199], v[44:47]
	v_mfma_f32_16x16x32_bf16 v[40:43], v[164:167], v[196:199], v[40:43]
	v_mfma_f32_16x16x32_bf16 v[28:31], v[148:151], v[204:207], v[28:31]
	v_mfma_f32_16x16x32_bf16 v[24:27], v[164:167], v[204:207], v[24:27]
	v_mfma_f32_16x16x32_bf16 v[12:15], v[148:151], v[212:215], v[12:15]
	v_mfma_f32_16x16x32_bf16 v[8:11], v[164:167], v[212:215], v[8:11]
	v_mfma_f32_16x16x32_bf16 v[60:63], v[160:163], v[192:195], v[60:63]
	v_mfma_f32_16x16x32_bf16 v[56:59], v[168:171], v[192:195], v[56:59]
	v_mfma_f32_16x16x32_bf16 v[44:47], v[160:163], v[200:203], v[44:47]
	v_mfma_f32_16x16x32_bf16 v[40:43], v[168:171], v[200:203], v[40:43]
	v_mfma_f32_16x16x32_bf16 v[28:31], v[160:163], v[208:211], v[28:31]
	v_mfma_f32_16x16x32_bf16 v[24:27], v[168:171], v[208:211], v[24:27]
	v_mfma_f32_16x16x32_bf16 v[12:15], v[160:163], v[216:219], v[12:15]
	v_mfma_f32_16x16x32_bf16 v[8:11], v[168:171], v[216:219], v[8:11]
	s_setprio 0
	s_setprio 1
	v_mfma_f32_16x16x32_bf16 v[52:55], v[172:175], v[188:191], v[52:55]
	v_mfma_f32_16x16x32_bf16 v[48:51], v[180:183], v[188:191], v[48:51]
	v_mfma_f32_16x16x32_bf16 v[36:39], v[172:175], v[196:199], v[36:39]
	v_mfma_f32_16x16x32_bf16 v[32:35], v[180:183], v[196:199], v[32:35]
	v_mfma_f32_16x16x32_bf16 v[20:23], v[172:175], v[204:207], v[20:23]
	v_mfma_f32_16x16x32_bf16 v[16:19], v[180:183], v[204:207], v[16:19]
	v_mfma_f32_16x16x32_bf16 v[4:7], v[172:175], v[212:215], v[4:7]
	v_mfma_f32_16x16x32_bf16 v[0:3], v[180:183], v[212:215], v[0:3]
	v_mfma_f32_16x16x32_bf16 v[52:55], v[176:179], v[192:195], v[52:55]
	v_mfma_f32_16x16x32_bf16 v[48:51], v[184:187], v[192:195], v[48:51]
	v_mfma_f32_16x16x32_bf16 v[36:39], v[176:179], v[200:203], v[36:39]
	v_mfma_f32_16x16x32_bf16 v[32:35], v[184:187], v[200:203], v[32:35]
	v_mfma_f32_16x16x32_bf16 v[20:23], v[176:179], v[208:211], v[20:23]
	v_mfma_f32_16x16x32_bf16 v[16:19], v[184:187], v[208:211], v[16:19]
	v_mfma_f32_16x16x32_bf16 v[4:7], v[176:179], v[216:219], v[4:7]
	v_mfma_f32_16x16x32_bf16 v[0:3], v[184:187], v[216:219], v[0:3]
	s_setprio 0
	s_barrier
	s_add_i32 s77, s77, 2
.LBB0_1235:
	ds_read_b128 v[148:151], v155
	ds_read_b128 v[160:163], v155 offset:1024
	ds_read_b128 v[164:167], v155 offset:2048
	ds_read_b128 v[168:171], v155 offset:3072
	ds_read_b128 v[172:175], v157
	ds_read_b128 v[176:179], v157 offset:1024
	ds_read_b128 v[180:183], v157 offset:2048
	ds_read_b128 v[184:187], v157 offset:3072
	s_add_u32 s34, s36, 0xfffc0080
	s_addc_u32 s35, s37, -1
	s_cmp_eq_u32 s77, 12
	s_cselect_b32 s41, s23, s35
	s_cselect_b32 s40, s64, s34
	s_cselect_b32 s39, s11, s67
	s_cselect_b32 s38, s65, s66
	v_lshl_add_u64 v[220:221], s[36:37], 0, v[140:141]
	s_add_i32 m0, s31, 0xc000
	ds_read_b128 v[188:191], v158
	ds_read_b128 v[192:195], v158 offset:1024
	ds_read_b128 v[196:199], v158 offset:2048
	ds_read_b128 v[200:203], v158 offset:3072
	ds_read_b128 v[204:207], v158 offset:4096
	ds_read_b128 v[208:211], v158 offset:5120
	ds_read_b128 v[212:215], v158 offset:6144
	ds_read_b128 v[216:219], v158 offset:7168
	global_load_lds_dwordx4 v[220:221], off
	v_lshl_add_u64 v[220:221], s[36:37], 0, v[142:143]
	s_add_i32 m0, s31, 0xe000
	s_nop 0
	global_load_lds_dwordx4 v[220:221], off
	s_waitcnt vmcnt(8)
	s_waitcnt lgkmcnt(0)
	s_barrier
	s_setprio 1
	s_waitcnt lgkmcnt(0)
	v_mfma_f32_16x16x32_bf16 v[124:127], v[148:151], v[188:191], v[124:127]
	v_mfma_f32_16x16x32_bf16 v[120:123], v[164:167], v[188:191], v[120:123]
	v_mfma_f32_16x16x32_bf16 v[108:111], v[148:151], v[196:199], v[108:111]
	v_mfma_f32_16x16x32_bf16 v[104:107], v[164:167], v[196:199], v[104:107]
	v_mfma_f32_16x16x32_bf16 v[92:95], v[148:151], v[204:207], v[92:95]
	v_mfma_f32_16x16x32_bf16 v[88:91], v[164:167], v[204:207], v[88:91]
	v_mfma_f32_16x16x32_bf16 v[76:79], v[148:151], v[212:215], v[76:79]
	v_mfma_f32_16x16x32_bf16 v[72:75], v[164:167], v[212:215], v[72:75]
	v_mfma_f32_16x16x32_bf16 v[124:127], v[160:163], v[192:195], v[124:127]
	v_mfma_f32_16x16x32_bf16 v[120:123], v[168:171], v[192:195], v[120:123]
	v_mfma_f32_16x16x32_bf16 v[108:111], v[160:163], v[200:203], v[108:111]
	v_mfma_f32_16x16x32_bf16 v[104:107], v[168:171], v[200:203], v[104:107]
	v_mfma_f32_16x16x32_bf16 v[92:95], v[160:163], v[208:211], v[92:95]
	v_mfma_f32_16x16x32_bf16 v[88:91], v[168:171], v[208:211], v[88:91]
	v_mfma_f32_16x16x32_bf16 v[76:79], v[160:163], v[216:219], v[76:79]
	v_mfma_f32_16x16x32_bf16 v[72:75], v[168:171], v[216:219], v[72:75]
	s_setprio 0
	s_setprio 1
	v_mfma_f32_16x16x32_bf16 v[116:119], v[172:175], v[188:191], v[116:119]
	v_mfma_f32_16x16x32_bf16 v[112:115], v[180:183], v[188:191], v[112:115]
	v_mfma_f32_16x16x32_bf16 v[100:103], v[172:175], v[196:199], v[100:103]
	v_mfma_f32_16x16x32_bf16 v[96:99], v[180:183], v[196:199], v[96:99]
	v_mfma_f32_16x16x32_bf16 v[84:87], v[172:175], v[204:207], v[84:87]
	v_mfma_f32_16x16x32_bf16 v[80:83], v[180:183], v[204:207], v[80:83]
	v_mfma_f32_16x16x32_bf16 v[68:71], v[172:175], v[212:215], v[68:71]
	v_mfma_f32_16x16x32_bf16 v[64:67], v[180:183], v[212:215], v[64:67]
	v_mfma_f32_16x16x32_bf16 v[116:119], v[176:179], v[192:195], v[116:119]
	v_mfma_f32_16x16x32_bf16 v[112:115], v[184:187], v[192:195], v[112:115]
	v_mfma_f32_16x16x32_bf16 v[100:103], v[176:179], v[200:203], v[100:103]
	v_mfma_f32_16x16x32_bf16 v[96:99], v[184:187], v[200:203], v[96:99]
	v_mfma_f32_16x16x32_bf16 v[84:87], v[176:179], v[208:211], v[84:87]
	v_mfma_f32_16x16x32_bf16 v[80:83], v[184:187], v[208:211], v[80:83]
	v_mfma_f32_16x16x32_bf16 v[68:71], v[176:179], v[216:219], v[68:71]
	v_mfma_f32_16x16x32_bf16 v[64:67], v[184:187], v[216:219], v[64:67]
	s_setprio 0
	s_barrier
	s_add_i32 s34, s55, s48
	v_lshl_add_u64 v[220:221], s[38:39], 0, v[136:137]
	s_mov_b32 m0, s34
	ds_read_b128 v[188:191], v158 offset:16384
	ds_read_b128 v[192:195], v158 offset:17408
	ds_read_b128 v[196:199], v158 offset:18432
	ds_read_b128 v[200:203], v158 offset:19456
	ds_read_b128 v[204:207], v158 offset:20480
	ds_read_b128 v[208:211], v158 offset:21504
	ds_read_b128 v[212:215], v158 offset:22528
	ds_read_b128 v[216:219], v158 offset:23552
	global_load_lds_dwordx4 v[220:221], off
	s_add_i32 m0, s34, 0x2000
	s_add_u32 s34, s38, 0x40000
	v_lshl_add_u64 v[222:223], s[38:39], 0, v[132:133]
	s_addc_u32 s35, s39, 0
	s_add_i32 s79, s56, s48
	global_load_lds_dwordx4 v[222:223], off
	v_lshl_add_u64 v[224:225], s[34:35], 0, v[136:137]
	s_mov_b32 m0, s79
	v_lshl_add_u64 v[226:227], s[40:41], 0, v[134:135]
	global_load_lds_dwordx4 v[224:225], off
	v_lshl_add_u64 v[224:225], s[34:35], 0, v[132:133]
	s_add_i32 m0, s79, 0x2000
	s_nop 0
	global_load_lds_dwordx4 v[224:225], off
	v_lshl_add_u64 v[224:225], s[40:41], 0, v[138:139]
	s_mov_b32 m0, s31
	s_nop 0
	global_load_lds_dwordx4 v[224:225], off
	s_mov_b32 m0, s52
	s_nop 0
	global_load_lds_dwordx4 v[226:227], off
	s_waitcnt vmcnt(8)
	s_waitcnt lgkmcnt(0)
	s_barrier
	s_setprio 1
	s_waitcnt lgkmcnt(0)
	v_mfma_f32_16x16x32_bf16 v[60:63], v[148:151], v[188:191], v[60:63]
	v_mfma_f32_16x16x32_bf16 v[56:59], v[164:167], v[188:191], v[56:59]
	v_mfma_f32_16x16x32_bf16 v[44:47], v[148:151], v[196:199], v[44:47]
	v_mfma_f32_16x16x32_bf16 v[40:43], v[164:167], v[196:199], v[40:43]
	v_mfma_f32_16x16x32_bf16 v[28:31], v[148:151], v[204:207], v[28:31]
	v_mfma_f32_16x16x32_bf16 v[24:27], v[164:167], v[204:207], v[24:27]
	v_mfma_f32_16x16x32_bf16 v[12:15], v[148:151], v[212:215], v[12:15]
	v_mfma_f32_16x16x32_bf16 v[8:11], v[164:167], v[212:215], v[8:11]
	v_mfma_f32_16x16x32_bf16 v[60:63], v[160:163], v[192:195], v[60:63]
	v_mfma_f32_16x16x32_bf16 v[56:59], v[168:171], v[192:195], v[56:59]
	v_mfma_f32_16x16x32_bf16 v[44:47], v[160:163], v[200:203], v[44:47]
	v_mfma_f32_16x16x32_bf16 v[40:43], v[168:171], v[200:203], v[40:43]
	v_mfma_f32_16x16x32_bf16 v[28:31], v[160:163], v[208:211], v[28:31]
	v_mfma_f32_16x16x32_bf16 v[24:27], v[168:171], v[208:211], v[24:27]
	v_mfma_f32_16x16x32_bf16 v[12:15], v[160:163], v[216:219], v[12:15]
	v_mfma_f32_16x16x32_bf16 v[8:11], v[168:171], v[216:219], v[8:11]
	s_setprio 0
	s_setprio 1
	v_mfma_f32_16x16x32_bf16 v[52:55], v[172:175], v[188:191], v[52:55]
	v_mfma_f32_16x16x32_bf16 v[48:51], v[180:183], v[188:191], v[48:51]
	v_mfma_f32_16x16x32_bf16 v[36:39], v[172:175], v[196:199], v[36:39]
	v_mfma_f32_16x16x32_bf16 v[32:35], v[180:183], v[196:199], v[32:35]
	v_mfma_f32_16x16x32_bf16 v[20:23], v[172:175], v[204:207], v[20:23]
	v_mfma_f32_16x16x32_bf16 v[16:19], v[180:183], v[204:207], v[16:19]
	v_mfma_f32_16x16x32_bf16 v[4:7], v[172:175], v[212:215], v[4:7]
	v_mfma_f32_16x16x32_bf16 v[0:3], v[180:183], v[212:215], v[0:3]
	v_mfma_f32_16x16x32_bf16 v[52:55], v[176:179], v[192:195], v[52:55]
	v_mfma_f32_16x16x32_bf16 v[48:51], v[184:187], v[192:195], v[48:51]
	v_mfma_f32_16x16x32_bf16 v[36:39], v[176:179], v[200:203], v[36:39]
	v_mfma_f32_16x16x32_bf16 v[32:35], v[184:187], v[200:203], v[32:35]
	v_mfma_f32_16x16x32_bf16 v[20:23], v[176:179], v[208:211], v[20:23]
	v_mfma_f32_16x16x32_bf16 v[16:19], v[184:187], v[208:211], v[16:19]
	v_mfma_f32_16x16x32_bf16 v[4:7], v[176:179], v[216:219], v[4:7]
	v_mfma_f32_16x16x32_bf16 v[0:3], v[184:187], v[216:219], v[0:3]
	s_setprio 0
	s_barrier
	s_add_i32 s79, 0, 0x18000
	v_add_u32_e32 v159, s79, v152
	s_add_i32 s81, 0, 0x1c000
	ds_read_b128 v[148:151], v159
	ds_read_b128 v[160:163], v159 offset:1024
	ds_read_b128 v[164:167], v159 offset:2048
	ds_read_b128 v[168:171], v159 offset:3072
	v_add_u32_e32 v159, s81, v152
	ds_read_b128 v[172:175], v159
	ds_read_b128 v[176:179], v159 offset:1024
	ds_read_b128 v[180:183], v159 offset:2048
	ds_read_b128 v[184:187], v159 offset:3072
	s_add_u32 s34, s40, 0x40000
	s_addc_u32 s35, s41, 0
	s_mov_b32 m0, s53
	v_lshl_add_u64 v[228:229], s[34:35], 0, v[138:139]
	ds_read_b128 v[188:191], v158 offset:32768
	ds_read_b128 v[192:195], v158 offset:33792
	ds_read_b128 v[196:199], v158 offset:34816
	ds_read_b128 v[200:203], v158 offset:35840
	ds_read_b128 v[204:207], v158 offset:36864
	ds_read_b128 v[208:211], v158 offset:37888
	ds_read_b128 v[212:215], v158 offset:38912
	ds_read_b128 v[216:219], v158 offset:39936
	global_load_lds_dwordx4 v[228:229], off
	v_lshl_add_u64 v[228:229], s[34:35], 0, v[134:135]
	s_mov_b32 m0, s54
	s_nop 0
	global_load_lds_dwordx4 v[228:229], off
	s_waitcnt vmcnt(8)
	s_waitcnt lgkmcnt(0)
	s_barrier
	s_setprio 1
	s_waitcnt lgkmcnt(0)
	v_mfma_f32_16x16x32_bf16 v[124:127], v[148:151], v[188:191], v[124:127]
	v_mfma_f32_16x16x32_bf16 v[120:123], v[164:167], v[188:191], v[120:123]
	v_mfma_f32_16x16x32_bf16 v[108:111], v[148:151], v[196:199], v[108:111]
	v_mfma_f32_16x16x32_bf16 v[104:107], v[164:167], v[196:199], v[104:107]
	v_mfma_f32_16x16x32_bf16 v[92:95], v[148:151], v[204:207], v[92:95]
	v_mfma_f32_16x16x32_bf16 v[88:91], v[164:167], v[204:207], v[88:91]
	v_mfma_f32_16x16x32_bf16 v[76:79], v[148:151], v[212:215], v[76:79]
	v_mfma_f32_16x16x32_bf16 v[72:75], v[164:167], v[212:215], v[72:75]
	v_mfma_f32_16x16x32_bf16 v[124:127], v[160:163], v[192:195], v[124:127]
	v_mfma_f32_16x16x32_bf16 v[120:123], v[168:171], v[192:195], v[120:123]
	v_mfma_f32_16x16x32_bf16 v[108:111], v[160:163], v[200:203], v[108:111]
	v_mfma_f32_16x16x32_bf16 v[104:107], v[168:171], v[200:203], v[104:107]
	v_mfma_f32_16x16x32_bf16 v[92:95], v[160:163], v[208:211], v[92:95]
	v_mfma_f32_16x16x32_bf16 v[88:91], v[168:171], v[208:211], v[88:91]
	v_mfma_f32_16x16x32_bf16 v[76:79], v[160:163], v[216:219], v[76:79]
	v_mfma_f32_16x16x32_bf16 v[72:75], v[168:171], v[216:219], v[72:75]
	s_setprio 0
	s_setprio 1
	v_mfma_f32_16x16x32_bf16 v[116:119], v[172:175], v[188:191], v[116:119]
	v_mfma_f32_16x16x32_bf16 v[112:115], v[180:183], v[188:191], v[112:115]
	v_mfma_f32_16x16x32_bf16 v[100:103], v[172:175], v[196:199], v[100:103]
	v_mfma_f32_16x16x32_bf16 v[96:99], v[180:183], v[196:199], v[96:99]
	v_mfma_f32_16x16x32_bf16 v[84:87], v[172:175], v[204:207], v[84:87]
	v_mfma_f32_16x16x32_bf16 v[80:83], v[180:183], v[204:207], v[80:83]
	v_mfma_f32_16x16x32_bf16 v[68:71], v[172:175], v[212:215], v[68:71]
	v_mfma_f32_16x16x32_bf16 v[64:67], v[180:183], v[212:215], v[64:67]
	v_mfma_f32_16x16x32_bf16 v[116:119], v[176:179], v[192:195], v[116:119]
	v_mfma_f32_16x16x32_bf16 v[112:115], v[184:187], v[192:195], v[112:115]
	v_mfma_f32_16x16x32_bf16 v[100:103], v[176:179], v[200:203], v[100:103]
	v_mfma_f32_16x16x32_bf16 v[96:99], v[184:187], v[200:203], v[96:99]
	v_mfma_f32_16x16x32_bf16 v[84:87], v[176:179], v[208:211], v[84:87]
	v_mfma_f32_16x16x32_bf16 v[80:83], v[184:187], v[208:211], v[80:83]
	v_mfma_f32_16x16x32_bf16 v[68:71], v[176:179], v[216:219], v[68:71]
	v_mfma_f32_16x16x32_bf16 v[64:67], v[184:187], v[216:219], v[64:67]
	s_setprio 0
	s_barrier
	s_add_i32 s34, s79, s48
	v_lshl_add_u64 v[220:221], v[220:221], 0, s[6:7]
	s_mov_b32 m0, s34
	ds_read_b128 v[188:191], v158 offset:49152
	ds_read_b128 v[192:195], v158 offset:50176
	ds_read_b128 v[196:199], v158 offset:51200
	ds_read_b128 v[200:203], v158 offset:52224
	ds_read_b128 v[204:207], v158 offset:53248
	ds_read_b128 v[208:211], v158 offset:54272
	ds_read_b128 v[212:215], v158 offset:55296
	ds_read_b128 v[216:219], v158 offset:56320
	global_load_lds_dwordx4 v[220:221], off
	s_add_i32 m0, s34, 0x2000
	s_add_u32 s34, s38, 0x40080
	v_lshl_add_u64 v[220:221], v[222:223], 0, s[6:7]
	s_addc_u32 s35, s39, 0
	s_add_i32 s38, s81, s48
	global_load_lds_dwordx4 v[220:221], off
	v_lshl_add_u64 v[220:221], s[34:35], 0, v[136:137]
	s_mov_b32 m0, s38
	s_nop 0
	global_load_lds_dwordx4 v[220:221], off
	v_lshl_add_u64 v[220:221], s[34:35], 0, v[132:133]
	s_add_i32 m0, s38, 0x2000
	s_nop 0
	global_load_lds_dwordx4 v[220:221], off
	v_lshl_add_u64 v[220:221], v[224:225], 0, s[6:7]
	s_mov_b32 m0, s12
	s_nop 0
	global_load_lds_dwordx4 v[220:221], off
	v_lshl_add_u64 v[220:221], v[226:227], 0, s[6:7]
	s_mov_b32 m0, s13
	s_nop 0
	global_load_lds_dwordx4 v[220:221], off
	s_waitcnt vmcnt(8)
	s_waitcnt lgkmcnt(0)
	s_barrier
	s_add_u32 s36, s36, 0x100
	s_addc_u32 s37, s37, 0
	s_add_u32 s66, s66, 0x100
	s_addc_u32 s67, s67, 0
	s_setprio 1
	s_waitcnt lgkmcnt(0)
	v_mfma_f32_16x16x32_bf16 v[60:63], v[148:151], v[188:191], v[60:63]
	v_mfma_f32_16x16x32_bf16 v[56:59], v[164:167], v[188:191], v[56:59]
	v_mfma_f32_16x16x32_bf16 v[44:47], v[148:151], v[196:199], v[44:47]
	v_mfma_f32_16x16x32_bf16 v[40:43], v[164:167], v[196:199], v[40:43]
	v_mfma_f32_16x16x32_bf16 v[28:31], v[148:151], v[204:207], v[28:31]
	v_mfma_f32_16x16x32_bf16 v[24:27], v[164:167], v[204:207], v[24:27]
	v_mfma_f32_16x16x32_bf16 v[12:15], v[148:151], v[212:215], v[12:15]
	v_mfma_f32_16x16x32_bf16 v[8:11], v[164:167], v[212:215], v[8:11]
	v_mfma_f32_16x16x32_bf16 v[60:63], v[160:163], v[192:195], v[60:63]
	v_mfma_f32_16x16x32_bf16 v[56:59], v[168:171], v[192:195], v[56:59]
	v_mfma_f32_16x16x32_bf16 v[44:47], v[160:163], v[200:203], v[44:47]
	v_mfma_f32_16x16x32_bf16 v[40:43], v[168:171], v[200:203], v[40:43]
	v_mfma_f32_16x16x32_bf16 v[28:31], v[160:163], v[208:211], v[28:31]
	v_mfma_f32_16x16x32_bf16 v[24:27], v[168:171], v[208:211], v[24:27]
	v_mfma_f32_16x16x32_bf16 v[12:15], v[160:163], v[216:219], v[12:15]
	v_mfma_f32_16x16x32_bf16 v[8:11], v[168:171], v[216:219], v[8:11]
	s_setprio 0
	s_setprio 1
	v_mfma_f32_16x16x32_bf16 v[52:55], v[172:175], v[188:191], v[52:55]
	v_mfma_f32_16x16x32_bf16 v[48:51], v[180:183], v[188:191], v[48:51]
	v_mfma_f32_16x16x32_bf16 v[36:39], v[172:175], v[196:199], v[36:39]
	v_mfma_f32_16x16x32_bf16 v[32:35], v[180:183], v[196:199], v[32:35]
	v_mfma_f32_16x16x32_bf16 v[20:23], v[172:175], v[204:207], v[20:23]
	v_mfma_f32_16x16x32_bf16 v[16:19], v[180:183], v[204:207], v[16:19]
	v_mfma_f32_16x16x32_bf16 v[4:7], v[172:175], v[212:215], v[4:7]
	v_mfma_f32_16x16x32_bf16 v[0:3], v[180:183], v[212:215], v[0:3]
	v_mfma_f32_16x16x32_bf16 v[52:55], v[176:179], v[192:195], v[52:55]
	v_mfma_f32_16x16x32_bf16 v[48:51], v[184:187], v[192:195], v[48:51]
	v_mfma_f32_16x16x32_bf16 v[36:39], v[176:179], v[200:203], v[36:39]
	v_mfma_f32_16x16x32_bf16 v[32:35], v[184:187], v[200:203], v[32:35]
	v_mfma_f32_16x16x32_bf16 v[20:23], v[176:179], v[208:211], v[20:23]
	v_mfma_f32_16x16x32_bf16 v[16:19], v[184:187], v[208:211], v[16:19]
	v_mfma_f32_16x16x32_bf16 v[4:7], v[176:179], v[216:219], v[4:7]
	v_mfma_f32_16x16x32_bf16 v[0:3], v[184:187], v[216:219], v[0:3]
	s_setprio 0
	s_cmp_eq_u32 s77, s98
	s_cbranch_scc1 .Lmy_nobar_12
	s_barrier

.Lmy_nobar2_16:
	ds_read_b128 v[146:149], v153
	ds_read_b128 v[158:161], v153 offset:1024
	ds_read_b128 v[162:165], v153 offset:2048
	ds_read_b128 v[166:169], v153 offset:3072
	ds_read_b128 v[170:173], v154
	ds_read_b128 v[174:177], v154 offset:1024
	ds_read_b128 v[178:181], v154 offset:2048
	ds_read_b128 v[182:185], v154 offset:3072
	s_add_u32 s34, s40, 0xfffc0080
	s_addc_u32 s35, s41, -1
	s_cmp_eq_u32 s62, 12
	s_cselect_b32 s45, s12, s35
	s_cselect_b32 s44, s13, s34
	s_cselect_b32 s43, s27, s61
	s_cselect_b32 s42, s29, s39
	v_lshl_add_u64 v[218:219], s[40:41], 0, v[138:139]
	s_add_i32 m0, s48, 0xc000
	ds_read_b128 v[186:189], v155
	ds_read_b128 v[190:193], v155 offset:1024
	ds_read_b128 v[194:197], v155 offset:2048
	ds_read_b128 v[198:201], v155 offset:3072
	ds_read_b128 v[202:205], v155 offset:4096
	ds_read_b128 v[206:209], v155 offset:5120
	ds_read_b128 v[210:213], v155 offset:6144
	ds_read_b128 v[214:217], v155 offset:7168
	global_load_lds_dwordx4 v[218:219], off
	v_lshl_add_u64 v[218:219], s[40:41], 0, v[140:141]
	s_add_i32 m0, s48, 0xe000
	s_nop 0
	global_load_lds_dwordx4 v[218:219], off
	s_waitcnt vmcnt(8)
	s_waitcnt lgkmcnt(0)
	s_barrier
	s_setprio 1
	s_waitcnt lgkmcnt(0)
	v_mfma_f32_16x16x32_bf16 v[124:127], v[146:149], v[186:189], 0
	v_mfma_f32_16x16x32_bf16 v[120:123], v[162:165], v[186:189], 0
	v_mfma_f32_16x16x32_bf16 v[108:111], v[146:149], v[194:197], 0
	v_mfma_f32_16x16x32_bf16 v[104:107], v[162:165], v[194:197], 0
	v_mfma_f32_16x16x32_bf16 v[92:95], v[146:149], v[202:205], 0
	v_mfma_f32_16x16x32_bf16 v[88:91], v[162:165], v[202:205], 0
	v_mfma_f32_16x16x32_bf16 v[76:79], v[146:149], v[210:213], 0
	v_mfma_f32_16x16x32_bf16 v[72:75], v[162:165], v[210:213], 0
	v_mfma_f32_16x16x32_bf16 v[124:127], v[158:161], v[190:193], v[124:127]
	v_mfma_f32_16x16x32_bf16 v[120:123], v[166:169], v[190:193], v[120:123]
	v_mfma_f32_16x16x32_bf16 v[108:111], v[158:161], v[198:201], v[108:111]
	v_mfma_f32_16x16x32_bf16 v[104:107], v[166:169], v[198:201], v[104:107]
	v_mfma_f32_16x16x32_bf16 v[92:95], v[158:161], v[206:209], v[92:95]
	v_mfma_f32_16x16x32_bf16 v[88:91], v[166:169], v[206:209], v[88:91]
	v_mfma_f32_16x16x32_bf16 v[76:79], v[158:161], v[214:217], v[76:79]
	v_mfma_f32_16x16x32_bf16 v[72:75], v[166:169], v[214:217], v[72:75]
	s_setprio 0
	s_setprio 1
	v_mfma_f32_16x16x32_bf16 v[116:119], v[170:173], v[186:189], 0
	v_mfma_f32_16x16x32_bf16 v[112:115], v[178:181], v[186:189], 0
	v_mfma_f32_16x16x32_bf16 v[100:103], v[170:173], v[194:197], 0
	v_mfma_f32_16x16x32_bf16 v[96:99], v[178:181], v[194:197], 0
	v_mfma_f32_16x16x32_bf16 v[84:87], v[170:173], v[202:205], 0
	v_mfma_f32_16x16x32_bf16 v[80:83], v[178:181], v[202:205], 0
	v_mfma_f32_16x16x32_bf16 v[68:71], v[170:173], v[210:213], 0
	v_mfma_f32_16x16x32_bf16 v[64:67], v[178:181], v[210:213], 0
	v_mfma_f32_16x16x32_bf16 v[116:119], v[174:177], v[190:193], v[116:119]
	v_mfma_f32_16x16x32_bf16 v[112:115], v[182:185], v[190:193], v[112:115]
	v_mfma_f32_16x16x32_bf16 v[100:103], v[174:177], v[198:201], v[100:103]
	v_mfma_f32_16x16x32_bf16 v[96:99], v[182:185], v[198:201], v[96:99]
	v_mfma_f32_16x16x32_bf16 v[84:87], v[174:177], v[206:209], v[84:87]
	v_mfma_f32_16x16x32_bf16 v[80:83], v[182:185], v[206:209], v[80:83]
	v_mfma_f32_16x16x32_bf16 v[68:71], v[174:177], v[214:217], v[68:71]
	v_mfma_f32_16x16x32_bf16 v[64:67], v[182:185], v[214:217], v[64:67]
	s_setprio 0
	s_barrier
	s_add_i32 s34, s58, s47
	v_lshl_add_u64 v[218:219], s[42:43], 0, v[132:133]
	s_mov_b32 m0, s34
	ds_read_b128 v[186:189], v155 offset:16384
	ds_read_b128 v[190:193], v155 offset:17408
	ds_read_b128 v[194:197], v155 offset:18432
	ds_read_b128 v[198:201], v155 offset:19456
	ds_read_b128 v[202:205], v155 offset:20480
	ds_read_b128 v[206:209], v155 offset:21504
	ds_read_b128 v[210:213], v155 offset:22528
	ds_read_b128 v[214:217], v155 offset:23552
	global_load_lds_dwordx4 v[218:219], off
	s_add_i32 m0, s34, 0x2000
	s_add_u32 s34, s42, 0x40000
	v_lshl_add_u64 v[220:221], s[42:43], 0, v[136:137]
	s_addc_u32 s35, s43, 0
	s_add_i32 s63, s59, s47
	global_load_lds_dwordx4 v[220:221], off
	v_lshl_add_u64 v[222:223], s[34:35], 0, v[132:133]
	s_mov_b32 m0, s63
	v_lshl_add_u64 v[224:225], s[44:45], 0, v[134:135]
	global_load_lds_dwordx4 v[222:223], off
	v_lshl_add_u64 v[222:223], s[34:35], 0, v[136:137]
	s_add_i32 m0, s63, 0x2000
	s_nop 0
	global_load_lds_dwordx4 v[222:223], off
	v_lshl_add_u64 v[222:223], s[44:45], 0, v[130:131]
	s_mov_b32 m0, s48
	s_nop 0
	global_load_lds_dwordx4 v[222:223], off
	s_mov_b32 m0, s49
	s_nop 0
	global_load_lds_dwordx4 v[224:225], off
	s_waitcnt vmcnt(8)
	s_waitcnt lgkmcnt(0)
	s_barrier
	s_setprio 1
	s_waitcnt lgkmcnt(0)
	v_mfma_f32_16x16x32_bf16 v[60:63], v[146:149], v[186:189], 0
	v_mfma_f32_16x16x32_bf16 v[56:59], v[162:165], v[186:189], 0
	v_mfma_f32_16x16x32_bf16 v[44:47], v[146:149], v[194:197], 0
	v_mfma_f32_16x16x32_bf16 v[40:43], v[162:165], v[194:197], 0
	v_mfma_f32_16x16x32_bf16 v[28:31], v[146:149], v[202:205], 0
	v_mfma_f32_16x16x32_bf16 v[24:27], v[162:165], v[202:205], 0
	v_mfma_f32_16x16x32_bf16 v[12:15], v[146:149], v[210:213], 0
	v_mfma_f32_16x16x32_bf16 v[8:11], v[162:165], v[210:213], 0
	v_mfma_f32_16x16x32_bf16 v[60:63], v[158:161], v[190:193], v[60:63]
	v_mfma_f32_16x16x32_bf16 v[56:59], v[166:169], v[190:193], v[56:59]
	v_mfma_f32_16x16x32_bf16 v[44:47], v[158:161], v[198:201], v[44:47]
	v_mfma_f32_16x16x32_bf16 v[40:43], v[166:169], v[198:201], v[40:43]
	v_mfma_f32_16x16x32_bf16 v[28:31], v[158:161], v[206:209], v[28:31]
	v_mfma_f32_16x16x32_bf16 v[24:27], v[166:169], v[206:209], v[24:27]
	v_mfma_f32_16x16x32_bf16 v[12:15], v[158:161], v[214:217], v[12:15]
	v_mfma_f32_16x16x32_bf16 v[8:11], v[166:169], v[214:217], v[8:11]
	s_setprio 0
	s_setprio 1
	v_mfma_f32_16x16x32_bf16 v[52:55], v[170:173], v[186:189], 0
	v_mfma_f32_16x16x32_bf16 v[48:51], v[178:181], v[186:189], 0
	v_mfma_f32_16x16x32_bf16 v[36:39], v[170:173], v[194:197], 0
	v_mfma_f32_16x16x32_bf16 v[32:35], v[178:181], v[194:197], 0
	v_mfma_f32_16x16x32_bf16 v[20:23], v[170:173], v[202:205], 0
	v_mfma_f32_16x16x32_bf16 v[16:19], v[178:181], v[202:205], 0
	v_mfma_f32_16x16x32_bf16 v[4:7], v[170:173], v[210:213], 0
	v_mfma_f32_16x16x32_bf16 v[0:3], v[178:181], v[210:213], 0
	v_mfma_f32_16x16x32_bf16 v[52:55], v[174:177], v[190:193], v[52:55]
	v_mfma_f32_16x16x32_bf16 v[48:51], v[182:185], v[190:193], v[48:51]
	v_mfma_f32_16x16x32_bf16 v[36:39], v[174:177], v[198:201], v[36:39]
	v_mfma_f32_16x16x32_bf16 v[32:35], v[182:185], v[198:201], v[32:35]
	v_mfma_f32_16x16x32_bf16 v[20:23], v[174:177], v[206:209], v[20:23]
	v_mfma_f32_16x16x32_bf16 v[16:19], v[182:185], v[206:209], v[16:19]
	v_mfma_f32_16x16x32_bf16 v[4:7], v[174:177], v[214:217], v[4:7]
	v_mfma_f32_16x16x32_bf16 v[0:3], v[182:185], v[214:217], v[0:3]
	s_setprio 0
	s_barrier
	s_add_i32 s63, 0, 0x18000
	s_add_i32 s64, 0, 0x1c000
	v_add_u32_e32 v166, s63, v151
	v_add_u32_e32 v182, s64, v151
	ds_read_b128 v[146:149], v166
	ds_read_b128 v[158:161], v166 offset:1024
	ds_read_b128 v[162:165], v166 offset:2048
	ds_read_b128 v[166:169], v166 offset:3072
	ds_read_b128 v[170:173], v182
	ds_read_b128 v[174:177], v182 offset:1024
	ds_read_b128 v[178:181], v182 offset:2048
	ds_read_b128 v[182:185], v182 offset:3072
	s_add_u32 s34, s44, 0x40000
	s_addc_u32 s35, s45, 0
	s_mov_b32 m0, s50
	v_lshl_add_u64 v[226:227], s[34:35], 0, v[130:131]
	ds_read_b128 v[186:189], v155 offset:32768
	ds_read_b128 v[190:193], v155 offset:33792
	ds_read_b128 v[194:197], v155 offset:34816
	ds_read_b128 v[198:201], v155 offset:35840
	ds_read_b128 v[202:205], v155 offset:36864
	ds_read_b128 v[206:209], v155 offset:37888
	ds_read_b128 v[210:213], v155 offset:38912
	ds_read_b128 v[214:217], v155 offset:39936
	global_load_lds_dwordx4 v[226:227], off
	v_lshl_add_u64 v[226:227], s[34:35], 0, v[134:135]
	s_mov_b32 m0, s51
	s_nop 0
	global_load_lds_dwordx4 v[226:227], off
	s_waitcnt vmcnt(8)
	s_waitcnt lgkmcnt(0)
	s_barrier
	s_setprio 1
	s_waitcnt lgkmcnt(0)
	v_mfma_f32_16x16x32_bf16 v[124:127], v[146:149], v[186:189], v[124:127]
	v_mfma_f32_16x16x32_bf16 v[120:123], v[162:165], v[186:189], v[120:123]
	v_mfma_f32_16x16x32_bf16 v[108:111], v[146:149], v[194:197], v[108:111]
	v_mfma_f32_16x16x32_bf16 v[104:107], v[162:165], v[194:197], v[104:107]
	v_mfma_f32_16x16x32_bf16 v[92:95], v[146:149], v[202:205], v[92:95]
	v_mfma_f32_16x16x32_bf16 v[88:91], v[162:165], v[202:205], v[88:91]
	v_mfma_f32_16x16x32_bf16 v[76:79], v[146:149], v[210:213], v[76:79]
	v_mfma_f32_16x16x32_bf16 v[72:75], v[162:165], v[210:213], v[72:75]
	v_mfma_f32_16x16x32_bf16 v[124:127], v[158:161], v[190:193], v[124:127]
	v_mfma_f32_16x16x32_bf16 v[120:123], v[166:169], v[190:193], v[120:123]
	v_mfma_f32_16x16x32_bf16 v[108:111], v[158:161], v[198:201], v[108:111]
	v_mfma_f32_16x16x32_bf16 v[104:107], v[166:169], v[198:201], v[104:107]
	v_mfma_f32_16x16x32_bf16 v[92:95], v[158:161], v[206:209], v[92:95]
	v_mfma_f32_16x16x32_bf16 v[88:91], v[166:169], v[206:209], v[88:91]
	v_mfma_f32_16x16x32_bf16 v[76:79], v[158:161], v[214:217], v[76:79]
	v_mfma_f32_16x16x32_bf16 v[72:75], v[166:169], v[214:217], v[72:75]
	s_setprio 0
	s_setprio 1
	v_mfma_f32_16x16x32_bf16 v[116:119], v[170:173], v[186:189], v[116:119]
	v_mfma_f32_16x16x32_bf16 v[112:115], v[178:181], v[186:189], v[112:115]
	v_mfma_f32_16x16x32_bf16 v[100:103], v[170:173], v[194:197], v[100:103]
	v_mfma_f32_16x16x32_bf16 v[96:99], v[178:181], v[194:197], v[96:99]
	v_mfma_f32_16x16x32_bf16 v[84:87], v[170:173], v[202:205], v[84:87]
	v_mfma_f32_16x16x32_bf16 v[80:83], v[178:181], v[202:205], v[80:83]
	v_mfma_f32_16x16x32_bf16 v[68:71], v[170:173], v[210:213], v[68:71]
	v_mfma_f32_16x16x32_bf16 v[64:67], v[178:181], v[210:213], v[64:67]
	v_mfma_f32_16x16x32_bf16 v[116:119], v[174:177], v[190:193], v[116:119]
	v_mfma_f32_16x16x32_bf16 v[112:115], v[182:185], v[190:193], v[112:115]
	v_mfma_f32_16x16x32_bf16 v[100:103], v[174:177], v[198:201], v[100:103]
	v_mfma_f32_16x16x32_bf16 v[96:99], v[182:185], v[198:201], v[96:99]
	v_mfma_f32_16x16x32_bf16 v[84:87], v[174:177], v[206:209], v[84:87]
	v_mfma_f32_16x16x32_bf16 v[80:83], v[182:185], v[206:209], v[80:83]
	v_mfma_f32_16x16x32_bf16 v[68:71], v[174:177], v[214:217], v[68:71]
	v_mfma_f32_16x16x32_bf16 v[64:67], v[182:185], v[214:217], v[64:67]
	s_setprio 0
	s_barrier
	s_add_i32 s34, s63, s47
	v_lshl_add_u64 v[218:219], v[218:219], 0, s[10:11]
	s_mov_b32 m0, s34
	ds_read_b128 v[186:189], v155 offset:49152
	ds_read_b128 v[190:193], v155 offset:50176
	ds_read_b128 v[194:197], v155 offset:51200
	ds_read_b128 v[198:201], v155 offset:52224
	ds_read_b128 v[202:205], v155 offset:53248
	ds_read_b128 v[206:209], v155 offset:54272
	ds_read_b128 v[210:213], v155 offset:55296
	ds_read_b128 v[214:217], v155 offset:56320
	global_load_lds_dwordx4 v[218:219], off
	s_add_i32 m0, s34, 0x2000
	s_add_u32 s34, s42, 0x40080
	v_lshl_add_u64 v[218:219], v[220:221], 0, s[10:11]
	s_addc_u32 s35, s43, 0
	s_add_i32 s42, s64, s47
	global_load_lds_dwordx4 v[218:219], off
	v_lshl_add_u64 v[218:219], s[34:35], 0, v[132:133]
	s_mov_b32 m0, s42
	s_nop 0
	global_load_lds_dwordx4 v[218:219], off
	v_lshl_add_u64 v[218:219], s[34:35], 0, v[136:137]
	s_add_i32 m0, s42, 0x2000
	s_nop 0
	global_load_lds_dwordx4 v[218:219], off
	v_lshl_add_u64 v[218:219], v[222:223], 0, s[10:11]
	s_mov_b32 m0, s53
	s_nop 0
	global_load_lds_dwordx4 v[218:219], off
	v_lshl_add_u64 v[218:219], v[224:225], 0, s[10:11]
	s_mov_b32 m0, s54
	s_nop 0
	global_load_lds_dwordx4 v[218:219], off
	s_waitcnt vmcnt(8)
	s_waitcnt lgkmcnt(0)
	s_barrier
	s_add_u32 s40, s40, 0x100
	s_addc_u32 s41, s41, 0
	s_add_u32 s39, s39, 0x100
	s_addc_u32 s61, s61, 0
	s_setprio 1
	s_waitcnt lgkmcnt(0)
	v_mfma_f32_16x16x32_bf16 v[60:63], v[146:149], v[186:189], v[60:63]
	v_mfma_f32_16x16x32_bf16 v[56:59], v[162:165], v[186:189], v[56:59]
	v_mfma_f32_16x16x32_bf16 v[44:47], v[146:149], v[194:197], v[44:47]
	v_mfma_f32_16x16x32_bf16 v[40:43], v[162:165], v[194:197], v[40:43]
	v_mfma_f32_16x16x32_bf16 v[28:31], v[146:149], v[202:205], v[28:31]
	v_mfma_f32_16x16x32_bf16 v[24:27], v[162:165], v[202:205], v[24:27]
	v_mfma_f32_16x16x32_bf16 v[12:15], v[146:149], v[210:213], v[12:15]
	v_mfma_f32_16x16x32_bf16 v[8:11], v[162:165], v[210:213], v[8:11]
	v_mfma_f32_16x16x32_bf16 v[60:63], v[158:161], v[190:193], v[60:63]
	v_mfma_f32_16x16x32_bf16 v[56:59], v[166:169], v[190:193], v[56:59]
	v_mfma_f32_16x16x32_bf16 v[44:47], v[158:161], v[198:201], v[44:47]
	v_mfma_f32_16x16x32_bf16 v[40:43], v[166:169], v[198:201], v[40:43]
	v_mfma_f32_16x16x32_bf16 v[28:31], v[158:161], v[206:209], v[28:31]
	v_mfma_f32_16x16x32_bf16 v[24:27], v[166:169], v[206:209], v[24:27]
	v_mfma_f32_16x16x32_bf16 v[12:15], v[158:161], v[214:217], v[12:15]
	v_mfma_f32_16x16x32_bf16 v[8:11], v[166:169], v[214:217], v[8:11]
	s_setprio 0
	s_setprio 1
	v_mfma_f32_16x16x32_bf16 v[52:55], v[170:173], v[186:189], v[52:55]
	v_mfma_f32_16x16x32_bf16 v[48:51], v[178:181], v[186:189], v[48:51]
	v_mfma_f32_16x16x32_bf16 v[36:39], v[170:173], v[194:197], v[36:39]
	v_mfma_f32_16x16x32_bf16 v[32:35], v[178:181], v[194:197], v[32:35]
	v_mfma_f32_16x16x32_bf16 v[20:23], v[170:173], v[202:205], v[20:23]
	v_mfma_f32_16x16x32_bf16 v[16:19], v[178:181], v[202:205], v[16:19]
	v_mfma_f32_16x16x32_bf16 v[4:7], v[170:173], v[210:213], v[4:7]
	v_mfma_f32_16x16x32_bf16 v[0:3], v[178:181], v[210:213], v[0:3]
	v_mfma_f32_16x16x32_bf16 v[52:55], v[174:177], v[190:193], v[52:55]
	v_mfma_f32_16x16x32_bf16 v[48:51], v[182:185], v[190:193], v[48:51]
	v_mfma_f32_16x16x32_bf16 v[36:39], v[174:177], v[198:201], v[36:39]
	v_mfma_f32_16x16x32_bf16 v[32:35], v[182:185], v[198:201], v[32:35]
	v_mfma_f32_16x16x32_bf16 v[20:23], v[174:177], v[206:209], v[20:23]
	v_mfma_f32_16x16x32_bf16 v[16:19], v[182:185], v[206:209], v[16:19]
	v_mfma_f32_16x16x32_bf16 v[4:7], v[174:177], v[214:217], v[4:7]
	v_mfma_f32_16x16x32_bf16 v[0:3], v[182:185], v[214:217], v[0:3]
	s_setprio 0
	s_barrier
	s_add_i32 s62, s62, 2
.LBB0_1557:
	ds_read_b128 v[146:149], v153
	ds_read_b128 v[158:161], v153 offset:1024
	ds_read_b128 v[162:165], v153 offset:2048
	ds_read_b128 v[166:169], v153 offset:3072
	ds_read_b128 v[170:173], v154
	ds_read_b128 v[174:177], v154 offset:1024
	ds_read_b128 v[178:181], v154 offset:2048
	ds_read_b128 v[182:185], v154 offset:3072
	s_add_u32 s34, s40, 0xfffc0080
	s_addc_u32 s35, s41, -1
	s_cmp_eq_u32 s62, 12
	s_cselect_b32 s45, s12, s35
	s_cselect_b32 s44, s13, s34
	s_cselect_b32 s43, s27, s61
	s_cselect_b32 s42, s29, s39
	v_lshl_add_u64 v[218:219], s[40:41], 0, v[138:139]
	s_add_i32 m0, s48, 0xc000
	ds_read_b128 v[186:189], v155
	ds_read_b128 v[190:193], v155 offset:1024
	ds_read_b128 v[194:197], v155 offset:2048
	ds_read_b128 v[198:201], v155 offset:3072
	ds_read_b128 v[202:205], v155 offset:4096
	ds_read_b128 v[206:209], v155 offset:5120
	ds_read_b128 v[210:213], v155 offset:6144
	ds_read_b128 v[214:217], v155 offset:7168
	global_load_lds_dwordx4 v[218:219], off
	v_lshl_add_u64 v[218:219], s[40:41], 0, v[140:141]
	s_add_i32 m0, s48, 0xe000
	s_nop 0
	global_load_lds_dwordx4 v[218:219], off
	s_waitcnt vmcnt(8)
	s_waitcnt lgkmcnt(0)
	s_barrier
	s_setprio 1
	s_waitcnt lgkmcnt(0)
	v_mfma_f32_16x16x32_bf16 v[124:127], v[146:149], v[186:189], v[124:127]
	v_mfma_f32_16x16x32_bf16 v[120:123], v[162:165], v[186:189], v[120:123]
	v_mfma_f32_16x16x32_bf16 v[108:111], v[146:149], v[194:197], v[108:111]
	v_mfma_f32_16x16x32_bf16 v[104:107], v[162:165], v[194:197], v[104:107]
	v_mfma_f32_16x16x32_bf16 v[92:95], v[146:149], v[202:205], v[92:95]
	v_mfma_f32_16x16x32_bf16 v[88:91], v[162:165], v[202:205], v[88:91]
	v_mfma_f32_16x16x32_bf16 v[76:79], v[146:149], v[210:213], v[76:79]
	v_mfma_f32_16x16x32_bf16 v[72:75], v[162:165], v[210:213], v[72:75]
	v_mfma_f32_16x16x32_bf16 v[124:127], v[158:161], v[190:193], v[124:127]
	v_mfma_f32_16x16x32_bf16 v[120:123], v[166:169], v[190:193], v[120:123]
	v_mfma_f32_16x16x32_bf16 v[108:111], v[158:161], v[198:201], v[108:111]
	v_mfma_f32_16x16x32_bf16 v[104:107], v[166:169], v[198:201], v[104:107]
	v_mfma_f32_16x16x32_bf16 v[92:95], v[158:161], v[206:209], v[92:95]
	v_mfma_f32_16x16x32_bf16 v[88:91], v[166:169], v[206:209], v[88:91]
	v_mfma_f32_16x16x32_bf16 v[76:79], v[158:161], v[214:217], v[76:79]
	v_mfma_f32_16x16x32_bf16 v[72:75], v[166:169], v[214:217], v[72:75]
	s_setprio 0
	s_setprio 1
	v_mfma_f32_16x16x32_bf16 v[116:119], v[170:173], v[186:189], v[116:119]
	v_mfma_f32_16x16x32_bf16 v[112:115], v[178:181], v[186:189], v[112:115]
	v_mfma_f32_16x16x32_bf16 v[100:103], v[170:173], v[194:197], v[100:103]
	v_mfma_f32_16x16x32_bf16 v[96:99], v[178:181], v[194:197], v[96:99]
	v_mfma_f32_16x16x32_bf16 v[84:87], v[170:173], v[202:205], v[84:87]
	v_mfma_f32_16x16x32_bf16 v[80:83], v[178:181], v[202:205], v[80:83]
	v_mfma_f32_16x16x32_bf16 v[68:71], v[170:173], v[210:213], v[68:71]
	v_mfma_f32_16x16x32_bf16 v[64:67], v[178:181], v[210:213], v[64:67]
	v_mfma_f32_16x16x32_bf16 v[116:119], v[174:177], v[190:193], v[116:119]
	v_mfma_f32_16x16x32_bf16 v[112:115], v[182:185], v[190:193], v[112:115]
	v_mfma_f32_16x16x32_bf16 v[100:103], v[174:177], v[198:201], v[100:103]
	v_mfma_f32_16x16x32_bf16 v[96:99], v[182:185], v[198:201], v[96:99]
	v_mfma_f32_16x16x32_bf16 v[84:87], v[174:177], v[206:209], v[84:87]
	v_mfma_f32_16x16x32_bf16 v[80:83], v[182:185], v[206:209], v[80:83]
	v_mfma_f32_16x16x32_bf16 v[68:71], v[174:177], v[214:217], v[68:71]
	v_mfma_f32_16x16x32_bf16 v[64:67], v[182:185], v[214:217], v[64:67]
	s_setprio 0
	s_barrier
	s_add_i32 s34, s58, s47
	v_lshl_add_u64 v[218:219], s[42:43], 0, v[132:133]
	s_mov_b32 m0, s34
	ds_read_b128 v[186:189], v155 offset:16384
	ds_read_b128 v[190:193], v155 offset:17408
	ds_read_b128 v[194:197], v155 offset:18432
	ds_read_b128 v[198:201], v155 offset:19456
	ds_read_b128 v[202:205], v155 offset:20480
	ds_read_b128 v[206:209], v155 offset:21504
	ds_read_b128 v[210:213], v155 offset:22528
	ds_read_b128 v[214:217], v155 offset:23552
	global_load_lds_dwordx4 v[218:219], off
	s_add_i32 m0, s34, 0x2000
	s_add_u32 s34, s42, 0x40000
	v_lshl_add_u64 v[220:221], s[42:43], 0, v[136:137]
	s_addc_u32 s35, s43, 0
	s_add_i32 s63, s59, s47
	global_load_lds_dwordx4 v[220:221], off
	v_lshl_add_u64 v[222:223], s[34:35], 0, v[132:133]
	s_mov_b32 m0, s63
	v_lshl_add_u64 v[224:225], s[44:45], 0, v[134:135]
	global_load_lds_dwordx4 v[222:223], off
	v_lshl_add_u64 v[222:223], s[34:35], 0, v[136:137]
	s_add_i32 m0, s63, 0x2000
	s_nop 0
	global_load_lds_dwordx4 v[222:223], off
	v_lshl_add_u64 v[222:223], s[44:45], 0, v[130:131]
	s_mov_b32 m0, s48
	s_nop 0
	global_load_lds_dwordx4 v[222:223], off
	s_mov_b32 m0, s49
	s_nop 0
	global_load_lds_dwordx4 v[224:225], off
	s_waitcnt vmcnt(8)
	s_waitcnt lgkmcnt(0)
	s_barrier
	s_setprio 1
	s_waitcnt lgkmcnt(0)
	v_mfma_f32_16x16x32_bf16 v[60:63], v[146:149], v[186:189], v[60:63]
	v_mfma_f32_16x16x32_bf16 v[56:59], v[162:165], v[186:189], v[56:59]
	v_mfma_f32_16x16x32_bf16 v[44:47], v[146:149], v[194:197], v[44:47]
	v_mfma_f32_16x16x32_bf16 v[40:43], v[162:165], v[194:197], v[40:43]
	v_mfma_f32_16x16x32_bf16 v[28:31], v[146:149], v[202:205], v[28:31]
	v_mfma_f32_16x16x32_bf16 v[24:27], v[162:165], v[202:205], v[24:27]
	v_mfma_f32_16x16x32_bf16 v[12:15], v[146:149], v[210:213], v[12:15]
	v_mfma_f32_16x16x32_bf16 v[8:11], v[162:165], v[210:213], v[8:11]
	v_mfma_f32_16x16x32_bf16 v[60:63], v[158:161], v[190:193], v[60:63]
	v_mfma_f32_16x16x32_bf16 v[56:59], v[166:169], v[190:193], v[56:59]
	v_mfma_f32_16x16x32_bf16 v[44:47], v[158:161], v[198:201], v[44:47]
	v_mfma_f32_16x16x32_bf16 v[40:43], v[166:169], v[198:201], v[40:43]
	v_mfma_f32_16x16x32_bf16 v[28:31], v[158:161], v[206:209], v[28:31]
	v_mfma_f32_16x16x32_bf16 v[24:27], v[166:169], v[206:209], v[24:27]
	v_mfma_f32_16x16x32_bf16 v[12:15], v[158:161], v[214:217], v[12:15]
	v_mfma_f32_16x16x32_bf16 v[8:11], v[166:169], v[214:217], v[8:11]
	s_setprio 0
	s_setprio 1
	v_mfma_f32_16x16x32_bf16 v[52:55], v[170:173], v[186:189], v[52:55]
	v_mfma_f32_16x16x32_bf16 v[48:51], v[178:181], v[186:189], v[48:51]
	v_mfma_f32_16x16x32_bf16 v[36:39], v[170:173], v[194:197], v[36:39]
	v_mfma_f32_16x16x32_bf16 v[32:35], v[178:181], v[194:197], v[32:35]
	v_mfma_f32_16x16x32_bf16 v[20:23], v[170:173], v[202:205], v[20:23]
	v_mfma_f32_16x16x32_bf16 v[16:19], v[178:181], v[202:205], v[16:19]
	v_mfma_f32_16x16x32_bf16 v[4:7], v[170:173], v[210:213], v[4:7]
	v_mfma_f32_16x16x32_bf16 v[0:3], v[178:181], v[210:213], v[0:3]
	v_mfma_f32_16x16x32_bf16 v[52:55], v[174:177], v[190:193], v[52:55]
	v_mfma_f32_16x16x32_bf16 v[48:51], v[182:185], v[190:193], v[48:51]
	v_mfma_f32_16x16x32_bf16 v[36:39], v[174:177], v[198:201], v[36:39]
	v_mfma_f32_16x16x32_bf16 v[32:35], v[182:185], v[198:201], v[32:35]
	v_mfma_f32_16x16x32_bf16 v[20:23], v[174:177], v[206:209], v[20:23]
	v_mfma_f32_16x16x32_bf16 v[16:19], v[182:185], v[206:209], v[16:19]
	v_mfma_f32_16x16x32_bf16 v[4:7], v[174:177], v[214:217], v[4:7]
	v_mfma_f32_16x16x32_bf16 v[0:3], v[182:185], v[214:217], v[0:3]
	s_setprio 0
	s_barrier
	s_add_i32 s63, 0, 0x18000
	s_add_i32 s64, 0, 0x1c000
	v_add_u32_e32 v166, s63, v151
	v_add_u32_e32 v182, s64, v151
	ds_read_b128 v[146:149], v166
	ds_read_b128 v[158:161], v166 offset:1024
	ds_read_b128 v[162:165], v166 offset:2048
	ds_read_b128 v[166:169], v166 offset:3072
	ds_read_b128 v[170:173], v182
	ds_read_b128 v[174:177], v182 offset:1024
	ds_read_b128 v[178:181], v182 offset:2048
	ds_read_b128 v[182:185], v182 offset:3072
	s_add_u32 s34, s44, 0x40000
	s_addc_u32 s35, s45, 0
	s_mov_b32 m0, s50
	v_lshl_add_u64 v[226:227], s[34:35], 0, v[130:131]
	ds_read_b128 v[186:189], v155 offset:32768
	ds_read_b128 v[190:193], v155 offset:33792
	ds_read_b128 v[194:197], v155 offset:34816
	ds_read_b128 v[198:201], v155 offset:35840
	ds_read_b128 v[202:205], v155 offset:36864
	ds_read_b128 v[206:209], v155 offset:37888
	ds_read_b128 v[210:213], v155 offset:38912
	ds_read_b128 v[214:217], v155 offset:39936
	global_load_lds_dwordx4 v[226:227], off
	v_lshl_add_u64 v[226:227], s[34:35], 0, v[134:135]
	s_mov_b32 m0, s51
	s_nop 0
	global_load_lds_dwordx4 v[226:227], off
	s_waitcnt vmcnt(8)
	s_waitcnt lgkmcnt(0)
	s_barrier
	s_setprio 1
	s_waitcnt lgkmcnt(0)
	v_mfma_f32_16x16x32_bf16 v[124:127], v[146:149], v[186:189], v[124:127]
	v_mfma_f32_16x16x32_bf16 v[120:123], v[162:165], v[186:189], v[120:123]
	v_mfma_f32_16x16x32_bf16 v[108:111], v[146:149], v[194:197], v[108:111]
	v_mfma_f32_16x16x32_bf16 v[104:107], v[162:165], v[194:197], v[104:107]
	v_mfma_f32_16x16x32_bf16 v[92:95], v[146:149], v[202:205], v[92:95]
	v_mfma_f32_16x16x32_bf16 v[88:91], v[162:165], v[202:205], v[88:91]
	v_mfma_f32_16x16x32_bf16 v[76:79], v[146:149], v[210:213], v[76:79]
	v_mfma_f32_16x16x32_bf16 v[72:75], v[162:165], v[210:213], v[72:75]
	v_mfma_f32_16x16x32_bf16 v[124:127], v[158:161], v[190:193], v[124:127]
	v_mfma_f32_16x16x32_bf16 v[120:123], v[166:169], v[190:193], v[120:123]
	v_mfma_f32_16x16x32_bf16 v[108:111], v[158:161], v[198:201], v[108:111]
	v_mfma_f32_16x16x32_bf16 v[104:107], v[166:169], v[198:201], v[104:107]
	v_mfma_f32_16x16x32_bf16 v[92:95], v[158:161], v[206:209], v[92:95]
	v_mfma_f32_16x16x32_bf16 v[88:91], v[166:169], v[206:209], v[88:91]
	v_mfma_f32_16x16x32_bf16 v[76:79], v[158:161], v[214:217], v[76:79]
	v_mfma_f32_16x16x32_bf16 v[72:75], v[166:169], v[214:217], v[72:75]
	s_setprio 0
	s_setprio 1
	v_mfma_f32_16x16x32_bf16 v[116:119], v[170:173], v[186:189], v[116:119]
	v_mfma_f32_16x16x32_bf16 v[112:115], v[178:181], v[186:189], v[112:115]
	v_mfma_f32_16x16x32_bf16 v[100:103], v[170:173], v[194:197], v[100:103]
	v_mfma_f32_16x16x32_bf16 v[96:99], v[178:181], v[194:197], v[96:99]
	v_mfma_f32_16x16x32_bf16 v[84:87], v[170:173], v[202:205], v[84:87]
	v_mfma_f32_16x16x32_bf16 v[80:83], v[178:181], v[202:205], v[80:83]
	v_mfma_f32_16x16x32_bf16 v[68:71], v[170:173], v[210:213], v[68:71]
	v_mfma_f32_16x16x32_bf16 v[64:67], v[178:181], v[210:213], v[64:67]
	v_mfma_f32_16x16x32_bf16 v[116:119], v[174:177], v[190:193], v[116:119]
	v_mfma_f32_16x16x32_bf16 v[112:115], v[182:185], v[190:193], v[112:115]
	v_mfma_f32_16x16x32_bf16 v[100:103], v[174:177], v[198:201], v[100:103]
	v_mfma_f32_16x16x32_bf16 v[96:99], v[182:185], v[198:201], v[96:99]
	v_mfma_f32_16x16x32_bf16 v[84:87], v[174:177], v[206:209], v[84:87]
	v_mfma_f32_16x16x32_bf16 v[80:83], v[182:185], v[206:209], v[80:83]
	v_mfma_f32_16x16x32_bf16 v[68:71], v[174:177], v[214:217], v[68:71]
	v_mfma_f32_16x16x32_bf16 v[64:67], v[182:185], v[214:217], v[64:67]
	s_setprio 0
	s_barrier
	s_add_i32 s34, s63, s47
	v_lshl_add_u64 v[218:219], v[218:219], 0, s[10:11]
	s_mov_b32 m0, s34
	ds_read_b128 v[186:189], v155 offset:49152
	ds_read_b128 v[190:193], v155 offset:50176
	ds_read_b128 v[194:197], v155 offset:51200
	ds_read_b128 v[198:201], v155 offset:52224
	ds_read_b128 v[202:205], v155 offset:53248
	ds_read_b128 v[206:209], v155 offset:54272
	ds_read_b128 v[210:213], v155 offset:55296
	ds_read_b128 v[214:217], v155 offset:56320
	global_load_lds_dwordx4 v[218:219], off
	s_add_i32 m0, s34, 0x2000
	s_add_u32 s34, s42, 0x40080
	v_lshl_add_u64 v[218:219], v[220:221], 0, s[10:11]
	s_addc_u32 s35, s43, 0
	s_add_i32 s42, s64, s47
	global_load_lds_dwordx4 v[218:219], off
	v_lshl_add_u64 v[218:219], s[34:35], 0, v[132:133]
	s_mov_b32 m0, s42
	s_nop 0
	global_load_lds_dwordx4 v[218:219], off
	v_lshl_add_u64 v[218:219], s[34:35], 0, v[136:137]
	s_add_i32 m0, s42, 0x2000
	s_nop 0
	global_load_lds_dwordx4 v[218:219], off
	v_lshl_add_u64 v[218:219], v[222:223], 0, s[10:11]
	s_mov_b32 m0, s53
	s_nop 0
	global_load_lds_dwordx4 v[218:219], off
	v_lshl_add_u64 v[218:219], v[224:225], 0, s[10:11]
	s_mov_b32 m0, s54
	s_nop 0
	global_load_lds_dwordx4 v[218:219], off
	s_waitcnt vmcnt(8)
	s_waitcnt lgkmcnt(0)
	s_barrier
	s_add_u32 s40, s40, 0x100
	s_addc_u32 s41, s41, 0
	s_add_u32 s39, s39, 0x100
	s_addc_u32 s61, s61, 0
	s_setprio 1
	s_waitcnt lgkmcnt(0)
	v_mfma_f32_16x16x32_bf16 v[60:63], v[146:149], v[186:189], v[60:63]
	v_mfma_f32_16x16x32_bf16 v[56:59], v[162:165], v[186:189], v[56:59]
	v_mfma_f32_16x16x32_bf16 v[44:47], v[146:149], v[194:197], v[44:47]
	v_mfma_f32_16x16x32_bf16 v[40:43], v[162:165], v[194:197], v[40:43]
	v_mfma_f32_16x16x32_bf16 v[28:31], v[146:149], v[202:205], v[28:31]
	v_mfma_f32_16x16x32_bf16 v[24:27], v[162:165], v[202:205], v[24:27]
	v_mfma_f32_16x16x32_bf16 v[12:15], v[146:149], v[210:213], v[12:15]
	v_mfma_f32_16x16x32_bf16 v[8:11], v[162:165], v[210:213], v[8:11]
	v_mfma_f32_16x16x32_bf16 v[60:63], v[158:161], v[190:193], v[60:63]
	v_mfma_f32_16x16x32_bf16 v[56:59], v[166:169], v[190:193], v[56:59]
	v_mfma_f32_16x16x32_bf16 v[44:47], v[158:161], v[198:201], v[44:47]
	v_mfma_f32_16x16x32_bf16 v[40:43], v[166:169], v[198:201], v[40:43]
	v_mfma_f32_16x16x32_bf16 v[28:31], v[158:161], v[206:209], v[28:31]
	v_mfma_f32_16x16x32_bf16 v[24:27], v[166:169], v[206:209], v[24:27]
	v_mfma_f32_16x16x32_bf16 v[12:15], v[158:161], v[214:217], v[12:15]
	v_mfma_f32_16x16x32_bf16 v[8:11], v[166:169], v[214:217], v[8:11]
	s_setprio 0
	s_setprio 1
	v_mfma_f32_16x16x32_bf16 v[52:55], v[170:173], v[186:189], v[52:55]
	v_mfma_f32_16x16x32_bf16 v[48:51], v[178:181], v[186:189], v[48:51]
	v_mfma_f32_16x16x32_bf16 v[36:39], v[170:173], v[194:197], v[36:39]
	v_mfma_f32_16x16x32_bf16 v[32:35], v[178:181], v[194:197], v[32:35]
	v_mfma_f32_16x16x32_bf16 v[20:23], v[170:173], v[202:205], v[20:23]
	v_mfma_f32_16x16x32_bf16 v[16:19], v[178:181], v[202:205], v[16:19]
	v_mfma_f32_16x16x32_bf16 v[4:7], v[170:173], v[210:213], v[4:7]
	v_mfma_f32_16x16x32_bf16 v[0:3], v[178:181], v[210:213], v[0:3]
	v_mfma_f32_16x16x32_bf16 v[52:55], v[174:177], v[190:193], v[52:55]
	v_mfma_f32_16x16x32_bf16 v[48:51], v[182:185], v[190:193], v[48:51]
	v_mfma_f32_16x16x32_bf16 v[36:39], v[174:177], v[198:201], v[36:39]
	v_mfma_f32_16x16x32_bf16 v[32:35], v[182:185], v[198:201], v[32:35]
	v_mfma_f32_16x16x32_bf16 v[20:23], v[174:177], v[206:209], v[20:23]
	v_mfma_f32_16x16x32_bf16 v[16:19], v[182:185], v[206:209], v[16:19]
	v_mfma_f32_16x16x32_bf16 v[4:7], v[174:177], v[214:217], v[4:7]
	v_mfma_f32_16x16x32_bf16 v[0:3], v[182:185], v[214:217], v[0:3]
	s_setprio 0
	s_cmp_eq_u32 s62, s98
	s_cbranch_scc1 .Lmy_nobar_16
	s_barrier
.Lmy_nobar_16:
	s_add_i32 s62, s62, 2
	s_cmp_gt_u32 s62, 13
	s_cbranch_scc0 .LBB0_1557
	s_and_b64 vcc, exec, s[22:23]
	s_cbranch_vccz .LBB0_1560
	s_nop 0

.Lmy_nobar2_17:
	ds_read_b128 v[146:149], v154
	ds_read_b128 v[158:161], v154 offset:1024
	ds_read_b128 v[162:165], v154 offset:2048
	ds_read_b128 v[166:169], v154 offset:3072
	ds_read_b128 v[170:173], v155
	ds_read_b128 v[174:177], v155 offset:1024
	ds_read_b128 v[178:181], v155 offset:2048
	ds_read_b128 v[182:185], v155 offset:3072
	s_add_u32 s34, s36, 0xfffc0080
	s_addc_u32 s35, s37, -1
	s_cmp_eq_u32 s62, 12
	s_cselect_b32 s41, s23, s35
	s_cselect_b32 s40, s58, s34
	s_cselect_b32 s39, s11, s61
	s_cselect_b32 s38, s59, s60
	v_lshl_add_u64 v[218:219], s[36:37], 0, v[138:139]
	s_add_i32 m0, s31, 0xc000
	ds_read_b128 v[186:189], v157
	ds_read_b128 v[190:193], v157 offset:1024
	ds_read_b128 v[194:197], v157 offset:2048
	ds_read_b128 v[198:201], v157 offset:3072
	ds_read_b128 v[202:205], v157 offset:4096
	ds_read_b128 v[206:209], v157 offset:5120
	ds_read_b128 v[210:213], v157 offset:6144
	ds_read_b128 v[214:217], v157 offset:7168
	global_load_lds_dwordx4 v[218:219], off
	v_lshl_add_u64 v[218:219], s[36:37], 0, v[140:141]
	s_add_i32 m0, s31, 0xe000
	s_nop 0
	global_load_lds_dwordx4 v[218:219], off
	s_waitcnt vmcnt(8)
	s_waitcnt lgkmcnt(0)
	s_barrier
	s_setprio 1
	s_waitcnt lgkmcnt(0)
	v_mfma_f32_16x16x32_bf16 v[124:127], v[146:149], v[186:189], 0
	v_mfma_f32_16x16x32_bf16 v[120:123], v[162:165], v[186:189], 0
	v_mfma_f32_16x16x32_bf16 v[108:111], v[146:149], v[194:197], 0
	v_mfma_f32_16x16x32_bf16 v[104:107], v[162:165], v[194:197], 0
	v_mfma_f32_16x16x32_bf16 v[92:95], v[146:149], v[202:205], 0
	v_mfma_f32_16x16x32_bf16 v[88:91], v[162:165], v[202:205], 0
	v_mfma_f32_16x16x32_bf16 v[76:79], v[146:149], v[210:213], 0
	v_mfma_f32_16x16x32_bf16 v[72:75], v[162:165], v[210:213], 0
	v_mfma_f32_16x16x32_bf16 v[124:127], v[158:161], v[190:193], v[124:127]
	v_mfma_f32_16x16x32_bf16 v[120:123], v[166:169], v[190:193], v[120:123]
	v_mfma_f32_16x16x32_bf16 v[108:111], v[158:161], v[198:201], v[108:111]
	v_mfma_f32_16x16x32_bf16 v[104:107], v[166:169], v[198:201], v[104:107]
	v_mfma_f32_16x16x32_bf16 v[92:95], v[158:161], v[206:209], v[92:95]
	v_mfma_f32_16x16x32_bf16 v[88:91], v[166:169], v[206:209], v[88:91]
	v_mfma_f32_16x16x32_bf16 v[76:79], v[158:161], v[214:217], v[76:79]
	v_mfma_f32_16x16x32_bf16 v[72:75], v[166:169], v[214:217], v[72:75]
	s_setprio 0
	s_setprio 1
	v_mfma_f32_16x16x32_bf16 v[116:119], v[170:173], v[186:189], 0
	v_mfma_f32_16x16x32_bf16 v[112:115], v[178:181], v[186:189], 0
	v_mfma_f32_16x16x32_bf16 v[100:103], v[170:173], v[194:197], 0
	v_mfma_f32_16x16x32_bf16 v[96:99], v[178:181], v[194:197], 0
	v_mfma_f32_16x16x32_bf16 v[84:87], v[170:173], v[202:205], 0
	v_mfma_f32_16x16x32_bf16 v[80:83], v[178:181], v[202:205], 0
	v_mfma_f32_16x16x32_bf16 v[68:71], v[170:173], v[210:213], 0
	v_mfma_f32_16x16x32_bf16 v[64:67], v[178:181], v[210:213], 0
	v_mfma_f32_16x16x32_bf16 v[116:119], v[174:177], v[190:193], v[116:119]
	v_mfma_f32_16x16x32_bf16 v[112:115], v[182:185], v[190:193], v[112:115]
	v_mfma_f32_16x16x32_bf16 v[100:103], v[174:177], v[198:201], v[100:103]
	v_mfma_f32_16x16x32_bf16 v[96:99], v[182:185], v[198:201], v[96:99]
	v_mfma_f32_16x16x32_bf16 v[84:87], v[174:177], v[206:209], v[84:87]
	v_mfma_f32_16x16x32_bf16 v[80:83], v[182:185], v[206:209], v[80:83]
	v_mfma_f32_16x16x32_bf16 v[68:71], v[174:177], v[214:217], v[68:71]
	v_mfma_f32_16x16x32_bf16 v[64:67], v[182:185], v[214:217], v[64:67]
	s_setprio 0
	s_barrier
	s_add_i32 s34, s53, s44
	v_lshl_add_u64 v[218:219], s[38:39], 0, v[134:135]
	s_mov_b32 m0, s34
	ds_read_b128 v[186:189], v157 offset:16384
	ds_read_b128 v[190:193], v157 offset:17408
	ds_read_b128 v[194:197], v157 offset:18432
	ds_read_b128 v[198:201], v157 offset:19456
	ds_read_b128 v[202:205], v157 offset:20480
	ds_read_b128 v[206:209], v157 offset:21504
	ds_read_b128 v[210:213], v157 offset:22528
	ds_read_b128 v[214:217], v157 offset:23552
	global_load_lds_dwordx4 v[218:219], off
	s_add_i32 m0, s34, 0x2000
	s_add_u32 s34, s38, 0x40000
	v_lshl_add_u64 v[220:221], s[38:39], 0, v[130:131]
	s_addc_u32 s35, s39, 0
	s_add_i32 s63, s54, s44
	global_load_lds_dwordx4 v[220:221], off
	v_lshl_add_u64 v[222:223], s[34:35], 0, v[134:135]
	s_mov_b32 m0, s63
	v_lshl_add_u64 v[224:225], s[40:41], 0, v[132:133]
	global_load_lds_dwordx4 v[222:223], off
	v_lshl_add_u64 v[222:223], s[34:35], 0, v[130:131]
	s_add_i32 m0, s63, 0x2000
	s_nop 0
	global_load_lds_dwordx4 v[222:223], off
	v_lshl_add_u64 v[222:223], s[40:41], 0, v[136:137]
	s_mov_b32 m0, s31
	s_nop 0
	global_load_lds_dwordx4 v[222:223], off
	s_mov_b32 m0, s48
	s_nop 0
	global_load_lds_dwordx4 v[224:225], off
	s_waitcnt vmcnt(8)
	s_waitcnt lgkmcnt(0)
	s_barrier
	s_setprio 1
	s_waitcnt lgkmcnt(0)
	v_mfma_f32_16x16x32_bf16 v[60:63], v[146:149], v[186:189], 0
	v_mfma_f32_16x16x32_bf16 v[56:59], v[162:165], v[186:189], 0
	v_mfma_f32_16x16x32_bf16 v[44:47], v[146:149], v[194:197], 0
	v_mfma_f32_16x16x32_bf16 v[40:43], v[162:165], v[194:197], 0
	v_mfma_f32_16x16x32_bf16 v[28:31], v[146:149], v[202:205], 0
	v_mfma_f32_16x16x32_bf16 v[24:27], v[162:165], v[202:205], 0
	v_mfma_f32_16x16x32_bf16 v[12:15], v[146:149], v[210:213], 0
	v_mfma_f32_16x16x32_bf16 v[8:11], v[162:165], v[210:213], 0
	v_mfma_f32_16x16x32_bf16 v[60:63], v[158:161], v[190:193], v[60:63]
	v_mfma_f32_16x16x32_bf16 v[56:59], v[166:169], v[190:193], v[56:59]
	v_mfma_f32_16x16x32_bf16 v[44:47], v[158:161], v[198:201], v[44:47]
	v_mfma_f32_16x16x32_bf16 v[40:43], v[166:169], v[198:201], v[40:43]
	v_mfma_f32_16x16x32_bf16 v[28:31], v[158:161], v[206:209], v[28:31]
	v_mfma_f32_16x16x32_bf16 v[24:27], v[166:169], v[206:209], v[24:27]
	v_mfma_f32_16x16x32_bf16 v[12:15], v[158:161], v[214:217], v[12:15]
	v_mfma_f32_16x16x32_bf16 v[8:11], v[166:169], v[214:217], v[8:11]
	s_setprio 0
	s_setprio 1
	v_mfma_f32_16x16x32_bf16 v[52:55], v[170:173], v[186:189], 0
	v_mfma_f32_16x16x32_bf16 v[48:51], v[178:181], v[186:189], 0
	v_mfma_f32_16x16x32_bf16 v[36:39], v[170:173], v[194:197], 0
	v_mfma_f32_16x16x32_bf16 v[32:35], v[178:181], v[194:197], 0
	v_mfma_f32_16x16x32_bf16 v[20:23], v[170:173], v[202:205], 0
	v_mfma_f32_16x16x32_bf16 v[16:19], v[178:181], v[202:205], 0
	v_mfma_f32_16x16x32_bf16 v[4:7], v[170:173], v[210:213], 0
	v_mfma_f32_16x16x32_bf16 v[0:3], v[178:181], v[210:213], 0
	v_mfma_f32_16x16x32_bf16 v[52:55], v[174:177], v[190:193], v[52:55]
	v_mfma_f32_16x16x32_bf16 v[48:51], v[182:185], v[190:193], v[48:51]
	v_mfma_f32_16x16x32_bf16 v[36:39], v[174:177], v[198:201], v[36:39]
	v_mfma_f32_16x16x32_bf16 v[32:35], v[182:185], v[198:201], v[32:35]
	v_mfma_f32_16x16x32_bf16 v[20:23], v[174:177], v[206:209], v[20:23]
	v_mfma_f32_16x16x32_bf16 v[16:19], v[182:185], v[206:209], v[16:19]
	v_mfma_f32_16x16x32_bf16 v[4:7], v[174:177], v[214:217], v[4:7]
	v_mfma_f32_16x16x32_bf16 v[0:3], v[182:185], v[214:217], v[0:3]
	s_setprio 0
	s_barrier
	s_add_i32 s63, 0, 0x18000
	s_add_i32 s64, 0, 0x1c000
	v_add_u32_e32 v166, s63, v151
	v_add_u32_e32 v182, s64, v151
	ds_read_b128 v[146:149], v166
	ds_read_b128 v[158:161], v166 offset:1024
	ds_read_b128 v[162:165], v166 offset:2048
	ds_read_b128 v[166:169], v166 offset:3072
	ds_read_b128 v[170:173], v182
	ds_read_b128 v[174:177], v182 offset:1024
	ds_read_b128 v[178:181], v182 offset:2048
	ds_read_b128 v[182:185], v182 offset:3072
	s_add_u32 s34, s40, 0x40000
	s_addc_u32 s35, s41, 0
	s_mov_b32 m0, s49
	v_lshl_add_u64 v[226:227], s[34:35], 0, v[136:137]
	ds_read_b128 v[186:189], v157 offset:32768
	ds_read_b128 v[190:193], v157 offset:33792
	ds_read_b128 v[194:197], v157 offset:34816
	ds_read_b128 v[198:201], v157 offset:35840
	ds_read_b128 v[202:205], v157 offset:36864
	ds_read_b128 v[206:209], v157 offset:37888
	ds_read_b128 v[210:213], v157 offset:38912
	ds_read_b128 v[214:217], v157 offset:39936
	global_load_lds_dwordx4 v[226:227], off
	v_lshl_add_u64 v[226:227], s[34:35], 0, v[132:133]
	s_mov_b32 m0, s50
	s_nop 0
	global_load_lds_dwordx4 v[226:227], off
	s_waitcnt vmcnt(8)
	s_waitcnt lgkmcnt(0)
	s_barrier
	s_setprio 1
	s_waitcnt lgkmcnt(0)
	v_mfma_f32_16x16x32_bf16 v[124:127], v[146:149], v[186:189], v[124:127]
	v_mfma_f32_16x16x32_bf16 v[120:123], v[162:165], v[186:189], v[120:123]
	v_mfma_f32_16x16x32_bf16 v[108:111], v[146:149], v[194:197], v[108:111]
	v_mfma_f32_16x16x32_bf16 v[104:107], v[162:165], v[194:197], v[104:107]
	v_mfma_f32_16x16x32_bf16 v[92:95], v[146:149], v[202:205], v[92:95]
	v_mfma_f32_16x16x32_bf16 v[88:91], v[162:165], v[202:205], v[88:91]
	v_mfma_f32_16x16x32_bf16 v[76:79], v[146:149], v[210:213], v[76:79]
	v_mfma_f32_16x16x32_bf16 v[72:75], v[162:165], v[210:213], v[72:75]
	v_mfma_f32_16x16x32_bf16 v[124:127], v[158:161], v[190:193], v[124:127]
	v_mfma_f32_16x16x32_bf16 v[120:123], v[166:169], v[190:193], v[120:123]
	v_mfma_f32_16x16x32_bf16 v[108:111], v[158:161], v[198:201], v[108:111]
	v_mfma_f32_16x16x32_bf16 v[104:107], v[166:169], v[198:201], v[104:107]
	v_mfma_f32_16x16x32_bf16 v[92:95], v[158:161], v[206:209], v[92:95]
	v_mfma_f32_16x16x32_bf16 v[88:91], v[166:169], v[206:209], v[88:91]
	v_mfma_f32_16x16x32_bf16 v[76:79], v[158:161], v[214:217], v[76:79]
	v_mfma_f32_16x16x32_bf16 v[72:75], v[166:169], v[214:217], v[72:75]
	s_setprio 0
	s_setprio 1
	v_mfma_f32_16x16x32_bf16 v[116:119], v[170:173], v[186:189], v[116:119]
	v_mfma_f32_16x16x32_bf16 v[112:115], v[178:181], v[186:189], v[112:115]
	v_mfma_f32_16x16x32_bf16 v[100:103], v[170:173], v[194:197], v[100:103]
	v_mfma_f32_16x16x32_bf16 v[96:99], v[178:181], v[194:197], v[96:99]
	v_mfma_f32_16x16x32_bf16 v[84:87], v[170:173], v[202:205], v[84:87]
	v_mfma_f32_16x16x32_bf16 v[80:83], v[178:181], v[202:205], v[80:83]
	v_mfma_f32_16x16x32_bf16 v[68:71], v[170:173], v[210:213], v[68:71]
	v_mfma_f32_16x16x32_bf16 v[64:67], v[178:181], v[210:213], v[64:67]
	v_mfma_f32_16x16x32_bf16 v[116:119], v[174:177], v[190:193], v[116:119]
	v_mfma_f32_16x16x32_bf16 v[112:115], v[182:185], v[190:193], v[112:115]
	v_mfma_f32_16x16x32_bf16 v[100:103], v[174:177], v[198:201], v[100:103]
	v_mfma_f32_16x16x32_bf16 v[96:99], v[182:185], v[198:201], v[96:99]
	v_mfma_f32_16x16x32_bf16 v[84:87], v[174:177], v[206:209], v[84:87]
	v_mfma_f32_16x16x32_bf16 v[80:83], v[182:185], v[206:209], v[80:83]
	v_mfma_f32_16x16x32_bf16 v[68:71], v[174:177], v[214:217], v[68:71]
	v_mfma_f32_16x16x32_bf16 v[64:67], v[182:185], v[214:217], v[64:67]
	s_setprio 0
	s_barrier
	s_add_i32 s34, s63, s44
	v_lshl_add_u64 v[218:219], v[218:219], 0, s[6:7]
	s_mov_b32 m0, s34
	ds_read_b128 v[186:189], v157 offset:49152
	ds_read_b128 v[190:193], v157 offset:50176
	ds_read_b128 v[194:197], v157 offset:51200
	ds_read_b128 v[198:201], v157 offset:52224
	ds_read_b128 v[202:205], v157 offset:53248
	ds_read_b128 v[206:209], v157 offset:54272
	ds_read_b128 v[210:213], v157 offset:55296
	ds_read_b128 v[214:217], v157 offset:56320
	global_load_lds_dwordx4 v[218:219], off
	s_add_i32 m0, s34, 0x2000
	s_add_u32 s34, s38, 0x40080
	v_lshl_add_u64 v[218:219], v[220:221], 0, s[6:7]
	s_addc_u32 s35, s39, 0
	s_add_i32 s38, s64, s44
	global_load_lds_dwordx4 v[218:219], off
	v_lshl_add_u64 v[218:219], s[34:35], 0, v[134:135]
	s_mov_b32 m0, s38
	s_nop 0
	global_load_lds_dwordx4 v[218:219], off
	v_lshl_add_u64 v[218:219], s[34:35], 0, v[130:131]
	s_add_i32 m0, s38, 0x2000
	s_nop 0
	global_load_lds_dwordx4 v[218:219], off
	v_lshl_add_u64 v[218:219], v[222:223], 0, s[6:7]
	s_mov_b32 m0, s51
	s_nop 0
	global_load_lds_dwordx4 v[218:219], off
	v_lshl_add_u64 v[218:219], v[224:225], 0, s[6:7]
	s_mov_b32 m0, s52
	s_nop 0
	global_load_lds_dwordx4 v[218:219], off
	s_waitcnt vmcnt(8)
	s_waitcnt lgkmcnt(0)
	s_barrier
	s_add_u32 s36, s36, 0x100
	s_addc_u32 s37, s37, 0
	s_add_u32 s60, s60, 0x100
	s_addc_u32 s61, s61, 0
	s_setprio 1
	s_waitcnt lgkmcnt(0)
	v_mfma_f32_16x16x32_bf16 v[60:63], v[146:149], v[186:189], v[60:63]
	v_mfma_f32_16x16x32_bf16 v[56:59], v[162:165], v[186:189], v[56:59]
	v_mfma_f32_16x16x32_bf16 v[44:47], v[146:149], v[194:197], v[44:47]
	v_mfma_f32_16x16x32_bf16 v[40:43], v[162:165], v[194:197], v[40:43]
	v_mfma_f32_16x16x32_bf16 v[28:31], v[146:149], v[202:205], v[28:31]
	v_mfma_f32_16x16x32_bf16 v[24:27], v[162:165], v[202:205], v[24:27]
	v_mfma_f32_16x16x32_bf16 v[12:15], v[146:149], v[210:213], v[12:15]
	v_mfma_f32_16x16x32_bf16 v[8:11], v[162:165], v[210:213], v[8:11]
	v_mfma_f32_16x16x32_bf16 v[60:63], v[158:161], v[190:193], v[60:63]
	v_mfma_f32_16x16x32_bf16 v[56:59], v[166:169], v[190:193], v[56:59]
	v_mfma_f32_16x16x32_bf16 v[44:47], v[158:161], v[198:201], v[44:47]
	v_mfma_f32_16x16x32_bf16 v[40:43], v[166:169], v[198:201], v[40:43]
	v_mfma_f32_16x16x32_bf16 v[28:31], v[158:161], v[206:209], v[28:31]
	v_mfma_f32_16x16x32_bf16 v[24:27], v[166:169], v[206:209], v[24:27]
	v_mfma_f32_16x16x32_bf16 v[12:15], v[158:161], v[214:217], v[12:15]
	v_mfma_f32_16x16x32_bf16 v[8:11], v[166:169], v[214:217], v[8:11]
	s_setprio 0
	s_setprio 1
	v_mfma_f32_16x16x32_bf16 v[52:55], v[170:173], v[186:189], v[52:55]
	v_mfma_f32_16x16x32_bf16 v[48:51], v[178:181], v[186:189], v[48:51]
	v_mfma_f32_16x16x32_bf16 v[36:39], v[170:173], v[194:197], v[36:39]
	v_mfma_f32_16x16x32_bf16 v[32:35], v[178:181], v[194:197], v[32:35]
	v_mfma_f32_16x16x32_bf16 v[20:23], v[170:173], v[202:205], v[20:23]
	v_mfma_f32_16x16x32_bf16 v[16:19], v[178:181], v[202:205], v[16:19]
	v_mfma_f32_16x16x32_bf16 v[4:7], v[170:173], v[210:213], v[4:7]
	v_mfma_f32_16x16x32_bf16 v[0:3], v[178:181], v[210:213], v[0:3]
	v_mfma_f32_16x16x32_bf16 v[52:55], v[174:177], v[190:193], v[52:55]
	v_mfma_f32_16x16x32_bf16 v[48:51], v[182:185], v[190:193], v[48:51]
	v_mfma_f32_16x16x32_bf16 v[36:39], v[174:177], v[198:201], v[36:39]
	v_mfma_f32_16x16x32_bf16 v[32:35], v[182:185], v[198:201], v[32:35]
	v_mfma_f32_16x16x32_bf16 v[20:23], v[174:177], v[206:209], v[20:23]
	v_mfma_f32_16x16x32_bf16 v[16:19], v[182:185], v[206:209], v[16:19]
	v_mfma_f32_16x16x32_bf16 v[4:7], v[174:177], v[214:217], v[4:7]
	v_mfma_f32_16x16x32_bf16 v[0:3], v[182:185], v[214:217], v[0:3]
	s_setprio 0
	s_barrier
	s_add_i32 s62, s62, 2
.LBB0_1647:
	ds_read_b128 v[146:149], v154
	ds_read_b128 v[158:161], v154 offset:1024
	ds_read_b128 v[162:165], v154 offset:2048
	ds_read_b128 v[166:169], v154 offset:3072
	ds_read_b128 v[170:173], v155
	ds_read_b128 v[174:177], v155 offset:1024
	ds_read_b128 v[178:181], v155 offset:2048
	ds_read_b128 v[182:185], v155 offset:3072
	s_add_u32 s34, s36, 0xfffc0080
	s_addc_u32 s35, s37, -1
	s_cmp_eq_u32 s62, 12
	s_cselect_b32 s41, s23, s35
	s_cselect_b32 s40, s58, s34
	s_cselect_b32 s39, s11, s61
	s_cselect_b32 s38, s59, s60
	v_lshl_add_u64 v[218:219], s[36:37], 0, v[138:139]
	s_add_i32 m0, s31, 0xc000
	ds_read_b128 v[186:189], v157
	ds_read_b128 v[190:193], v157 offset:1024
	ds_read_b128 v[194:197], v157 offset:2048
	ds_read_b128 v[198:201], v157 offset:3072
	ds_read_b128 v[202:205], v157 offset:4096
	ds_read_b128 v[206:209], v157 offset:5120
	ds_read_b128 v[210:213], v157 offset:6144
	ds_read_b128 v[214:217], v157 offset:7168
	global_load_lds_dwordx4 v[218:219], off
	v_lshl_add_u64 v[218:219], s[36:37], 0, v[140:141]
	s_add_i32 m0, s31, 0xe000
	s_nop 0
	global_load_lds_dwordx4 v[218:219], off
	s_waitcnt vmcnt(8)
	s_waitcnt lgkmcnt(0)
	s_barrier
	s_setprio 1
	s_waitcnt lgkmcnt(0)
	v_mfma_f32_16x16x32_bf16 v[124:127], v[146:149], v[186:189], v[124:127]
	v_mfma_f32_16x16x32_bf16 v[120:123], v[162:165], v[186:189], v[120:123]
	v_mfma_f32_16x16x32_bf16 v[108:111], v[146:149], v[194:197], v[108:111]
	v_mfma_f32_16x16x32_bf16 v[104:107], v[162:165], v[194:197], v[104:107]
	v_mfma_f32_16x16x32_bf16 v[92:95], v[146:149], v[202:205], v[92:95]
	v_mfma_f32_16x16x32_bf16 v[88:91], v[162:165], v[202:205], v[88:91]
	v_mfma_f32_16x16x32_bf16 v[76:79], v[146:149], v[210:213], v[76:79]
	v_mfma_f32_16x16x32_bf16 v[72:75], v[162:165], v[210:213], v[72:75]
	v_mfma_f32_16x16x32_bf16 v[124:127], v[158:161], v[190:193], v[124:127]
	v_mfma_f32_16x16x32_bf16 v[120:123], v[166:169], v[190:193], v[120:123]
	v_mfma_f32_16x16x32_bf16 v[108:111], v[158:161], v[198:201], v[108:111]
	v_mfma_f32_16x16x32_bf16 v[104:107], v[166:169], v[198:201], v[104:107]
	v_mfma_f32_16x16x32_bf16 v[92:95], v[158:161], v[206:209], v[92:95]
	v_mfma_f32_16x16x32_bf16 v[88:91], v[166:169], v[206:209], v[88:91]
	v_mfma_f32_16x16x32_bf16 v[76:79], v[158:161], v[214:217], v[76:79]
	v_mfma_f32_16x16x32_bf16 v[72:75], v[166:169], v[214:217], v[72:75]
	s_setprio 0
	s_setprio 1
	v_mfma_f32_16x16x32_bf16 v[116:119], v[170:173], v[186:189], v[116:119]
	v_mfma_f32_16x16x32_bf16 v[112:115], v[178:181], v[186:189], v[112:115]
	v_mfma_f32_16x16x32_bf16 v[100:103], v[170:173], v[194:197], v[100:103]
	v_mfma_f32_16x16x32_bf16 v[96:99], v[178:181], v[194:197], v[96:99]
	v_mfma_f32_16x16x32_bf16 v[84:87], v[170:173], v[202:205], v[84:87]
	v_mfma_f32_16x16x32_bf16 v[80:83], v[178:181], v[202:205], v[80:83]
	v_mfma_f32_16x16x32_bf16 v[68:71], v[170:173], v[210:213], v[68:71]
	v_mfma_f32_16x16x32_bf16 v[64:67], v[178:181], v[210:213], v[64:67]
	v_mfma_f32_16x16x32_bf16 v[116:119], v[174:177], v[190:193], v[116:119]
	v_mfma_f32_16x16x32_bf16 v[112:115], v[182:185], v[190:193], v[112:115]
	v_mfma_f32_16x16x32_bf16 v[100:103], v[174:177], v[198:201], v[100:103]
	v_mfma_f32_16x16x32_bf16 v[96:99], v[182:185], v[198:201], v[96:99]
	v_mfma_f32_16x16x32_bf16 v[84:87], v[174:177], v[206:209], v[84:87]
	v_mfma_f32_16x16x32_bf16 v[80:83], v[182:185], v[206:209], v[80:83]
	v_mfma_f32_16x16x32_bf16 v[68:71], v[174:177], v[214:217], v[68:71]
	v_mfma_f32_16x16x32_bf16 v[64:67], v[182:185], v[214:217], v[64:67]
	s_setprio 0
	s_barrier
	s_add_i32 s34, s53, s44
	v_lshl_add_u64 v[218:219], s[38:39], 0, v[134:135]
	s_mov_b32 m0, s34
	ds_read_b128 v[186:189], v157 offset:16384
	ds_read_b128 v[190:193], v157 offset:17408
	ds_read_b128 v[194:197], v157 offset:18432
	ds_read_b128 v[198:201], v157 offset:19456
	ds_read_b128 v[202:205], v157 offset:20480
	ds_read_b128 v[206:209], v157 offset:21504
	ds_read_b128 v[210:213], v157 offset:22528
	ds_read_b128 v[214:217], v157 offset:23552
	global_load_lds_dwordx4 v[218:219], off
	s_add_i32 m0, s34, 0x2000
	s_add_u32 s34, s38, 0x40000
	v_lshl_add_u64 v[220:221], s[38:39], 0, v[130:131]
	s_addc_u32 s35, s39, 0
	s_add_i32 s63, s54, s44
	global_load_lds_dwordx4 v[220:221], off
	v_lshl_add_u64 v[222:223], s[34:35], 0, v[134:135]
	s_mov_b32 m0, s63
	v_lshl_add_u64 v[224:225], s[40:41], 0, v[132:133]
	global_load_lds_dwordx4 v[222:223], off
	v_lshl_add_u64 v[222:223], s[34:35], 0, v[130:131]
	s_add_i32 m0, s63, 0x2000
	s_nop 0
	global_load_lds_dwordx4 v[222:223], off
	v_lshl_add_u64 v[222:223], s[40:41], 0, v[136:137]
	s_mov_b32 m0, s31
	s_nop 0
	global_load_lds_dwordx4 v[222:223], off
	s_mov_b32 m0, s48
	s_nop 0
	global_load_lds_dwordx4 v[224:225], off
	s_waitcnt vmcnt(8)
	s_waitcnt lgkmcnt(0)
	s_barrier
	s_setprio 1
	s_waitcnt lgkmcnt(0)
	v_mfma_f32_16x16x32_bf16 v[60:63], v[146:149], v[186:189], v[60:63]
	v_mfma_f32_16x16x32_bf16 v[56:59], v[162:165], v[186:189], v[56:59]
	v_mfma_f32_16x16x32_bf16 v[44:47], v[146:149], v[194:197], v[44:47]
	v_mfma_f32_16x16x32_bf16 v[40:43], v[162:165], v[194:197], v[40:43]
	v_mfma_f32_16x16x32_bf16 v[28:31], v[146:149], v[202:205], v[28:31]
	v_mfma_f32_16x16x32_bf16 v[24:27], v[162:165], v[202:205], v[24:27]
	v_mfma_f32_16x16x32_bf16 v[12:15], v[146:149], v[210:213], v[12:15]
	v_mfma_f32_16x16x32_bf16 v[8:11], v[162:165], v[210:213], v[8:11]
	v_mfma_f32_16x16x32_bf16 v[60:63], v[158:161], v[190:193], v[60:63]
	v_mfma_f32_16x16x32_bf16 v[56:59], v[166:169], v[190:193], v[56:59]
	v_mfma_f32_16x16x32_bf16 v[44:47], v[158:161], v[198:201], v[44:47]
	v_mfma_f32_16x16x32_bf16 v[40:43], v[166:169], v[198:201], v[40:43]
	v_mfma_f32_16x16x32_bf16 v[28:31], v[158:161], v[206:209], v[28:31]
	v_mfma_f32_16x16x32_bf16 v[24:27], v[166:169], v[206:209], v[24:27]
	v_mfma_f32_16x16x32_bf16 v[12:15], v[158:161], v[214:217], v[12:15]
	v_mfma_f32_16x16x32_bf16 v[8:11], v[166:169], v[214:217], v[8:11]
	s_setprio 0
	s_setprio 1
	v_mfma_f32_16x16x32_bf16 v[52:55], v[170:173], v[186:189], v[52:55]
	v_mfma_f32_16x16x32_bf16 v[48:51], v[178:181], v[186:189], v[48:51]
	v_mfma_f32_16x16x32_bf16 v[36:39], v[170:173], v[194:197], v[36:39]
	v_mfma_f32_16x16x32_bf16 v[32:35], v[178:181], v[194:197], v[32:35]
	v_mfma_f32_16x16x32_bf16 v[20:23], v[170:173], v[202:205], v[20:23]
	v_mfma_f32_16x16x32_bf16 v[16:19], v[178:181], v[202:205], v[16:19]
	v_mfma_f32_16x16x32_bf16 v[4:7], v[170:173], v[210:213], v[4:7]
	v_mfma_f32_16x16x32_bf16 v[0:3], v[178:181], v[210:213], v[0:3]
	v_mfma_f32_16x16x32_bf16 v[52:55], v[174:177], v[190:193], v[52:55]
	v_mfma_f32_16x16x32_bf16 v[48:51], v[182:185], v[190:193], v[48:51]
	v_mfma_f32_16x16x32_bf16 v[36:39], v[174:177], v[198:201], v[36:39]
	v_mfma_f32_16x16x32_bf16 v[32:35], v[182:185], v[198:201], v[32:35]
	v_mfma_f32_16x16x32_bf16 v[20:23], v[174:177], v[206:209], v[20:23]
	v_mfma_f32_16x16x32_bf16 v[16:19], v[182:185], v[206:209], v[16:19]
	v_mfma_f32_16x16x32_bf16 v[4:7], v[174:177], v[214:217], v[4:7]
	v_mfma_f32_16x16x32_bf16 v[0:3], v[182:185], v[214:217], v[0:3]
	s_setprio 0
	s_barrier
	s_add_i32 s63, 0, 0x18000
	s_add_i32 s64, 0, 0x1c000
	v_add_u32_e32 v166, s63, v151
	v_add_u32_e32 v182, s64, v151
	ds_read_b128 v[146:149], v166
	ds_read_b128 v[158:161], v166 offset:1024
	ds_read_b128 v[162:165], v166 offset:2048
	ds_read_b128 v[166:169], v166 offset:3072
	ds_read_b128 v[170:173], v182
	ds_read_b128 v[174:177], v182 offset:1024
	ds_read_b128 v[178:181], v182 offset:2048
	ds_read_b128 v[182:185], v182 offset:3072
	s_add_u32 s34, s40, 0x40000
	s_addc_u32 s35, s41, 0
	s_mov_b32 m0, s49
	v_lshl_add_u64 v[226:227], s[34:35], 0, v[136:137]
	ds_read_b128 v[186:189], v157 offset:32768
	ds_read_b128 v[190:193], v157 offset:33792
	ds_read_b128 v[194:197], v157 offset:34816
	ds_read_b128 v[198:201], v157 offset:35840
	ds_read_b128 v[202:205], v157 offset:36864
	ds_read_b128 v[206:209], v157 offset:37888
	ds_read_b128 v[210:213], v157 offset:38912
	ds_read_b128 v[214:217], v157 offset:39936
	global_load_lds_dwordx4 v[226:227], off
	v_lshl_add_u64 v[226:227], s[34:35], 0, v[132:133]
	s_mov_b32 m0, s50
	s_nop 0
	global_load_lds_dwordx4 v[226:227], off
	s_waitcnt vmcnt(8)
	s_waitcnt lgkmcnt(0)
	s_barrier
	s_setprio 1
	s_waitcnt lgkmcnt(0)
	v_mfma_f32_16x16x32_bf16 v[124:127], v[146:149], v[186:189], v[124:127]
	v_mfma_f32_16x16x32_bf16 v[120:123], v[162:165], v[186:189], v[120:123]
	v_mfma_f32_16x16x32_bf16 v[108:111], v[146:149], v[194:197], v[108:111]
	v_mfma_f32_16x16x32_bf16 v[104:107], v[162:165], v[194:197], v[104:107]
	v_mfma_f32_16x16x32_bf16 v[92:95], v[146:149], v[202:205], v[92:95]
	v_mfma_f32_16x16x32_bf16 v[88:91], v[162:165], v[202:205], v[88:91]
	v_mfma_f32_16x16x32_bf16 v[76:79], v[146:149], v[210:213], v[76:79]
	v_mfma_f32_16x16x32_bf16 v[72:75], v[162:165], v[210:213], v[72:75]
	v_mfma_f32_16x16x32_bf16 v[124:127], v[158:161], v[190:193], v[124:127]
	v_mfma_f32_16x16x32_bf16 v[120:123], v[166:169], v[190:193], v[120:123]
	v_mfma_f32_16x16x32_bf16 v[108:111], v[158:161], v[198:201], v[108:111]
	v_mfma_f32_16x16x32_bf16 v[104:107], v[166:169], v[198:201], v[104:107]
	v_mfma_f32_16x16x32_bf16 v[92:95], v[158:161], v[206:209], v[92:95]
	v_mfma_f32_16x16x32_bf16 v[88:91], v[166:169], v[206:209], v[88:91]
	v_mfma_f32_16x16x32_bf16 v[76:79], v[158:161], v[214:217], v[76:79]
	v_mfma_f32_16x16x32_bf16 v[72:75], v[166:169], v[214:217], v[72:75]
	s_setprio 0
	s_setprio 1
	v_mfma_f32_16x16x32_bf16 v[116:119], v[170:173], v[186:189], v[116:119]
	v_mfma_f32_16x16x32_bf16 v[112:115], v[178:181], v[186:189], v[112:115]
	v_mfma_f32_16x16x32_bf16 v[100:103], v[170:173], v[194:197], v[100:103]
	v_mfma_f32_16x16x32_bf16 v[96:99], v[178:181], v[194:197], v[96:99]
	v_mfma_f32_16x16x32_bf16 v[84:87], v[170:173], v[202:205], v[84:87]
	v_mfma_f32_16x16x32_bf16 v[80:83], v[178:181], v[202:205], v[80:83]
	v_mfma_f32_16x16x32_bf16 v[68:71], v[170:173], v[210:213], v[68:71]
	v_mfma_f32_16x16x32_bf16 v[64:67], v[178:181], v[210:213], v[64:67]
	v_mfma_f32_16x16x32_bf16 v[116:119], v[174:177], v[190:193], v[116:119]
	v_mfma_f32_16x16x32_bf16 v[112:115], v[182:185], v[190:193], v[112:115]
	v_mfma_f32_16x16x32_bf16 v[100:103], v[174:177], v[198:201], v[100:103]
	v_mfma_f32_16x16x32_bf16 v[96:99], v[182:185], v[198:201], v[96:99]
	v_mfma_f32_16x16x32_bf16 v[84:87], v[174:177], v[206:209], v[84:87]
	v_mfma_f32_16x16x32_bf16 v[80:83], v[182:185], v[206:209], v[80:83]
	v_mfma_f32_16x16x32_bf16 v[68:71], v[174:177], v[214:217], v[68:71]
	v_mfma_f32_16x16x32_bf16 v[64:67], v[182:185], v[214:217], v[64:67]
	s_setprio 0
	s_barrier
	s_add_i32 s34, s63, s44
	v_lshl_add_u64 v[218:219], v[218:219], 0, s[6:7]
	s_mov_b32 m0, s34
	ds_read_b128 v[186:189], v157 offset:49152
	ds_read_b128 v[190:193], v157 offset:50176
	ds_read_b128 v[194:197], v157 offset:51200
	ds_read_b128 v[198:201], v157 offset:52224
	ds_read_b128 v[202:205], v157 offset:53248
	ds_read_b128 v[206:209], v157 offset:54272
	ds_read_b128 v[210:213], v157 offset:55296
	ds_read_b128 v[214:217], v157 offset:56320
	global_load_lds_dwordx4 v[218:219], off
	s_add_i32 m0, s34, 0x2000
	s_add_u32 s34, s38, 0x40080
	v_lshl_add_u64 v[218:219], v[220:221], 0, s[6:7]
	s_addc_u32 s35, s39, 0
	s_add_i32 s38, s64, s44
	global_load_lds_dwordx4 v[218:219], off
	v_lshl_add_u64 v[218:219], s[34:35], 0, v[134:135]
	s_mov_b32 m0, s38
	s_nop 0
	global_load_lds_dwordx4 v[218:219], off
	v_lshl_add_u64 v[218:219], s[34:35], 0, v[130:131]
	s_add_i32 m0, s38, 0x2000
	s_nop 0
	global_load_lds_dwordx4 v[218:219], off
	v_lshl_add_u64 v[218:219], v[222:223], 0, s[6:7]
	s_mov_b32 m0, s51
	s_nop 0
	global_load_lds_dwordx4 v[218:219], off
	v_lshl_add_u64 v[218:219], v[224:225], 0, s[6:7]
	s_mov_b32 m0, s52
	s_nop 0
	global_load_lds_dwordx4 v[218:219], off
	s_waitcnt vmcnt(8)
	s_waitcnt lgkmcnt(0)
	s_barrier
	s_add_u32 s36, s36, 0x100
	s_addc_u32 s37, s37, 0
	s_add_u32 s60, s60, 0x100
	s_addc_u32 s61, s61, 0
	s_setprio 1
	s_waitcnt lgkmcnt(0)
	v_mfma_f32_16x16x32_bf16 v[60:63], v[146:149], v[186:189], v[60:63]
	v_mfma_f32_16x16x32_bf16 v[56:59], v[162:165], v[186:189], v[56:59]
	v_mfma_f32_16x16x32_bf16 v[44:47], v[146:149], v[194:197], v[44:47]
	v_mfma_f32_16x16x32_bf16 v[40:43], v[162:165], v[194:197], v[40:43]
	v_mfma_f32_16x16x32_bf16 v[28:31], v[146:149], v[202:205], v[28:31]
	v_mfma_f32_16x16x32_bf16 v[24:27], v[162:165], v[202:205], v[24:27]
	v_mfma_f32_16x16x32_bf16 v[12:15], v[146:149], v[210:213], v[12:15]
	v_mfma_f32_16x16x32_bf16 v[8:11], v[162:165], v[210:213], v[8:11]
	v_mfma_f32_16x16x32_bf16 v[60:63], v[158:161], v[190:193], v[60:63]
	v_mfma_f32_16x16x32_bf16 v[56:59], v[166:169], v[190:193], v[56:59]
	v_mfma_f32_16x16x32_bf16 v[44:47], v[158:161], v[198:201], v[44:47]
	v_mfma_f32_16x16x32_bf16 v[40:43], v[166:169], v[198:201], v[40:43]
	v_mfma_f32_16x16x32_bf16 v[28:31], v[158:161], v[206:209], v[28:31]
	v_mfma_f32_16x16x32_bf16 v[24:27], v[166:169], v[206:209], v[24:27]
	v_mfma_f32_16x16x32_bf16 v[12:15], v[158:161], v[214:217], v[12:15]
	v_mfma_f32_16x16x32_bf16 v[8:11], v[166:169], v[214:217], v[8:11]
	s_setprio 0
	s_setprio 1
	v_mfma_f32_16x16x32_bf16 v[52:55], v[170:173], v[186:189], v[52:55]
	v_mfma_f32_16x16x32_bf16 v[48:51], v[178:181], v[186:189], v[48:51]
	v_mfma_f32_16x16x32_bf16 v[36:39], v[170:173], v[194:197], v[36:39]
	v_mfma_f32_16x16x32_bf16 v[32:35], v[178:181], v[194:197], v[32:35]
	v_mfma_f32_16x16x32_bf16 v[20:23], v[170:173], v[202:205], v[20:23]
	v_mfma_f32_16x16x32_bf16 v[16:19], v[178:181], v[202:205], v[16:19]
	v_mfma_f32_16x16x32_bf16 v[4:7], v[170:173], v[210:213], v[4:7]
	v_mfma_f32_16x16x32_bf16 v[0:3], v[178:181], v[210:213], v[0:3]
	v_mfma_f32_16x16x32_bf16 v[52:55], v[174:177], v[190:193], v[52:55]
	v_mfma_f32_16x16x32_bf16 v[48:51], v[182:185], v[190:193], v[48:51]
	v_mfma_f32_16x16x32_bf16 v[36:39], v[174:177], v[198:201], v[36:39]
	v_mfma_f32_16x16x32_bf16 v[32:35], v[182:185], v[198:201], v[32:35]
	v_mfma_f32_16x16x32_bf16 v[20:23], v[174:177], v[206:209], v[20:23]
	v_mfma_f32_16x16x32_bf16 v[16:19], v[182:185], v[206:209], v[16:19]
	v_mfma_f32_16x16x32_bf16 v[4:7], v[174:177], v[214:217], v[4:7]
	v_mfma_f32_16x16x32_bf16 v[0:3], v[182:185], v[214:217], v[0:3]
	s_setprio 0
	s_cmp_eq_u32 s62, s98
	s_cbranch_scc1 .Lmy_nobar_17
	s_barrier
.Lmy_nobar_17:
	s_add_i32 s62, s62, 2
	s_cmp_gt_u32 s62, 13
	s_cbranch_scc0 .LBB0_1647
	s_and_b64 vcc, exec, s[8:9]
	s_cbranch_vccz .LBB0_1650
	s_nop 0

.Lmy_nobar2_18:
	ds_read_b128 v[146:149], v153
	ds_read_b128 v[158:161], v153 offset:1024
	ds_read_b128 v[162:165], v153 offset:2048
	ds_read_b128 v[166:169], v153 offset:3072
	ds_read_b128 v[170:173], v154
	ds_read_b128 v[174:177], v154 offset:1024
	ds_read_b128 v[178:181], v154 offset:2048
	ds_read_b128 v[182:185], v154 offset:3072
	s_add_u32 s34, s30, 0xfff50080
	s_addc_u32 s35, s31, -1
	s_cmp_eq_u32 s58, 40
	s_cselect_b32 s39, s1, s35
	s_cselect_b32 s38, s0, s34
	s_cselect_b32 s37, s29, s57
	s_cselect_b32 s36, s28, s13
	v_lshl_add_u64 v[218:219], s[30:31], 0, v[138:139]
	s_add_i32 m0, s42, 0xc000
	ds_read_b128 v[186:189], v155
	ds_read_b128 v[190:193], v155 offset:1024
	ds_read_b128 v[194:197], v155 offset:2048
	ds_read_b128 v[198:201], v155 offset:3072
	ds_read_b128 v[202:205], v155 offset:4096
	ds_read_b128 v[206:209], v155 offset:5120
	ds_read_b128 v[210:213], v155 offset:6144
	ds_read_b128 v[214:217], v155 offset:7168
	global_load_lds_dwordx4 v[218:219], off
	v_lshl_add_u64 v[218:219], s[30:31], 0, v[140:141]
	s_add_i32 m0, s42, 0xe000
	s_nop 0
	global_load_lds_dwordx4 v[218:219], off
	s_waitcnt vmcnt(8)
	s_waitcnt lgkmcnt(0)
	s_barrier
	s_setprio 1
	s_waitcnt lgkmcnt(0)
	v_mfma_f32_16x16x32_bf16 v[124:127], v[146:149], v[186:189], 0
	v_mfma_f32_16x16x32_bf16 v[120:123], v[162:165], v[186:189], 0
	v_mfma_f32_16x16x32_bf16 v[108:111], v[146:149], v[194:197], 0
	v_mfma_f32_16x16x32_bf16 v[104:107], v[162:165], v[194:197], 0
	v_mfma_f32_16x16x32_bf16 v[92:95], v[146:149], v[202:205], 0
	v_mfma_f32_16x16x32_bf16 v[88:91], v[162:165], v[202:205], 0
	v_mfma_f32_16x16x32_bf16 v[76:79], v[146:149], v[210:213], 0
	v_mfma_f32_16x16x32_bf16 v[72:75], v[162:165], v[210:213], 0
	v_mfma_f32_16x16x32_bf16 v[124:127], v[158:161], v[190:193], v[124:127]
	v_mfma_f32_16x16x32_bf16 v[120:123], v[166:169], v[190:193], v[120:123]
	v_mfma_f32_16x16x32_bf16 v[108:111], v[158:161], v[198:201], v[108:111]
	v_mfma_f32_16x16x32_bf16 v[104:107], v[166:169], v[198:201], v[104:107]
	v_mfma_f32_16x16x32_bf16 v[92:95], v[158:161], v[206:209], v[92:95]
	v_mfma_f32_16x16x32_bf16 v[88:91], v[166:169], v[206:209], v[88:91]
	v_mfma_f32_16x16x32_bf16 v[76:79], v[158:161], v[214:217], v[76:79]
	v_mfma_f32_16x16x32_bf16 v[72:75], v[166:169], v[214:217], v[72:75]
	s_setprio 0
	s_setprio 1
	v_mfma_f32_16x16x32_bf16 v[116:119], v[170:173], v[186:189], 0
	v_mfma_f32_16x16x32_bf16 v[112:115], v[178:181], v[186:189], 0
	v_mfma_f32_16x16x32_bf16 v[100:103], v[170:173], v[194:197], 0
	v_mfma_f32_16x16x32_bf16 v[96:99], v[178:181], v[194:197], 0
	v_mfma_f32_16x16x32_bf16 v[84:87], v[170:173], v[202:205], 0
	v_mfma_f32_16x16x32_bf16 v[80:83], v[178:181], v[202:205], 0
	v_mfma_f32_16x16x32_bf16 v[68:71], v[170:173], v[210:213], 0
	v_mfma_f32_16x16x32_bf16 v[64:67], v[178:181], v[210:213], 0
	v_mfma_f32_16x16x32_bf16 v[116:119], v[174:177], v[190:193], v[116:119]
	v_mfma_f32_16x16x32_bf16 v[112:115], v[182:185], v[190:193], v[112:115]
	v_mfma_f32_16x16x32_bf16 v[100:103], v[174:177], v[198:201], v[100:103]
	v_mfma_f32_16x16x32_bf16 v[96:99], v[182:185], v[198:201], v[96:99]
	v_mfma_f32_16x16x32_bf16 v[84:87], v[174:177], v[206:209], v[84:87]
	v_mfma_f32_16x16x32_bf16 v[80:83], v[182:185], v[206:209], v[80:83]
	v_mfma_f32_16x16x32_bf16 v[68:71], v[174:177], v[214:217], v[68:71]
	v_mfma_f32_16x16x32_bf16 v[64:67], v[182:185], v[214:217], v[64:67]
	s_setprio 0
	s_barrier
	s_add_i32 s34, s52, s41
	v_lshl_add_u64 v[218:219], s[36:37], 0, v[132:133]
	s_mov_b32 m0, s34
	ds_read_b128 v[186:189], v155 offset:16384
	ds_read_b128 v[190:193], v155 offset:17408
	ds_read_b128 v[194:197], v155 offset:18432
	ds_read_b128 v[198:201], v155 offset:19456
	ds_read_b128 v[202:205], v155 offset:20480
	ds_read_b128 v[206:209], v155 offset:21504
	ds_read_b128 v[210:213], v155 offset:22528
	ds_read_b128 v[214:217], v155 offset:23552
	global_load_lds_dwordx4 v[218:219], off
	s_add_i32 m0, s34, 0x2000
	s_add_u32 s34, s36, 0xb0000
	v_lshl_add_u64 v[220:221], s[36:37], 0, v[136:137]
	s_addc_u32 s35, s37, 0
	s_add_i32 s59, s53, s41
	global_load_lds_dwordx4 v[220:221], off
	v_lshl_add_u64 v[222:223], s[34:35], 0, v[132:133]
	s_mov_b32 m0, s59
	v_lshl_add_u64 v[224:225], s[38:39], 0, v[134:135]
	global_load_lds_dwordx4 v[222:223], off
	v_lshl_add_u64 v[222:223], s[34:35], 0, v[136:137]
	s_add_i32 m0, s59, 0x2000
	s_nop 0
	global_load_lds_dwordx4 v[222:223], off
	v_lshl_add_u64 v[222:223], s[38:39], 0, v[130:131]
	s_mov_b32 m0, s42
	s_nop 0
	global_load_lds_dwordx4 v[222:223], off
	s_mov_b32 m0, s43
	s_nop 0
	global_load_lds_dwordx4 v[224:225], off
	s_waitcnt vmcnt(8)
	s_waitcnt lgkmcnt(0)
	s_barrier
	s_setprio 1
	s_waitcnt lgkmcnt(0)
	v_mfma_f32_16x16x32_bf16 v[60:63], v[146:149], v[186:189], 0
	v_mfma_f32_16x16x32_bf16 v[56:59], v[162:165], v[186:189], 0
	v_mfma_f32_16x16x32_bf16 v[44:47], v[146:149], v[194:197], 0
	v_mfma_f32_16x16x32_bf16 v[40:43], v[162:165], v[194:197], 0
	v_mfma_f32_16x16x32_bf16 v[28:31], v[146:149], v[202:205], 0
	v_mfma_f32_16x16x32_bf16 v[24:27], v[162:165], v[202:205], 0
	v_mfma_f32_16x16x32_bf16 v[12:15], v[146:149], v[210:213], 0
	v_mfma_f32_16x16x32_bf16 v[8:11], v[162:165], v[210:213], 0
	v_mfma_f32_16x16x32_bf16 v[60:63], v[158:161], v[190:193], v[60:63]
	v_mfma_f32_16x16x32_bf16 v[56:59], v[166:169], v[190:193], v[56:59]
	v_mfma_f32_16x16x32_bf16 v[44:47], v[158:161], v[198:201], v[44:47]
	v_mfma_f32_16x16x32_bf16 v[40:43], v[166:169], v[198:201], v[40:43]
	v_mfma_f32_16x16x32_bf16 v[28:31], v[158:161], v[206:209], v[28:31]
	v_mfma_f32_16x16x32_bf16 v[24:27], v[166:169], v[206:209], v[24:27]
	v_mfma_f32_16x16x32_bf16 v[12:15], v[158:161], v[214:217], v[12:15]
	v_mfma_f32_16x16x32_bf16 v[8:11], v[166:169], v[214:217], v[8:11]
	s_setprio 0
	s_setprio 1
	v_mfma_f32_16x16x32_bf16 v[52:55], v[170:173], v[186:189], 0
	v_mfma_f32_16x16x32_bf16 v[48:51], v[178:181], v[186:189], 0
	v_mfma_f32_16x16x32_bf16 v[36:39], v[170:173], v[194:197], 0
	v_mfma_f32_16x16x32_bf16 v[32:35], v[178:181], v[194:197], 0
	v_mfma_f32_16x16x32_bf16 v[20:23], v[170:173], v[202:205], 0
	v_mfma_f32_16x16x32_bf16 v[16:19], v[178:181], v[202:205], 0
	v_mfma_f32_16x16x32_bf16 v[4:7], v[170:173], v[210:213], 0
	v_mfma_f32_16x16x32_bf16 v[0:3], v[178:181], v[210:213], 0
	v_mfma_f32_16x16x32_bf16 v[52:55], v[174:177], v[190:193], v[52:55]
	v_mfma_f32_16x16x32_bf16 v[48:51], v[182:185], v[190:193], v[48:51]
	v_mfma_f32_16x16x32_bf16 v[36:39], v[174:177], v[198:201], v[36:39]
	v_mfma_f32_16x16x32_bf16 v[32:35], v[182:185], v[198:201], v[32:35]
	v_mfma_f32_16x16x32_bf16 v[20:23], v[174:177], v[206:209], v[20:23]
	v_mfma_f32_16x16x32_bf16 v[16:19], v[182:185], v[206:209], v[16:19]
	v_mfma_f32_16x16x32_bf16 v[4:7], v[174:177], v[214:217], v[4:7]
	v_mfma_f32_16x16x32_bf16 v[0:3], v[182:185], v[214:217], v[0:3]
	s_setprio 0
	s_barrier
	s_add_i32 s59, 0, 0x18000
	s_add_i32 s60, 0, 0x1c000
	v_add_u32_e32 v166, s59, v151
	v_add_u32_e32 v182, s60, v151
	ds_read_b128 v[146:149], v166
	ds_read_b128 v[158:161], v166 offset:1024
	ds_read_b128 v[162:165], v166 offset:2048
	ds_read_b128 v[166:169], v166 offset:3072
	ds_read_b128 v[170:173], v182
	ds_read_b128 v[174:177], v182 offset:1024
	ds_read_b128 v[178:181], v182 offset:2048
	ds_read_b128 v[182:185], v182 offset:3072
	s_add_u32 s34, s38, 0xb0000
	s_addc_u32 s35, s39, 0
	s_mov_b32 m0, s44
	v_lshl_add_u64 v[226:227], s[34:35], 0, v[130:131]
	ds_read_b128 v[186:189], v155 offset:32768
	ds_read_b128 v[190:193], v155 offset:33792
	ds_read_b128 v[194:197], v155 offset:34816
	ds_read_b128 v[198:201], v155 offset:35840
	ds_read_b128 v[202:205], v155 offset:36864
	ds_read_b128 v[206:209], v155 offset:37888
	ds_read_b128 v[210:213], v155 offset:38912
	ds_read_b128 v[214:217], v155 offset:39936
	global_load_lds_dwordx4 v[226:227], off
	v_lshl_add_u64 v[226:227], s[34:35], 0, v[134:135]
	s_mov_b32 m0, s45
	s_nop 0
	global_load_lds_dwordx4 v[226:227], off
	s_waitcnt vmcnt(8)
	s_waitcnt lgkmcnt(0)
	s_barrier
	s_setprio 1
	s_waitcnt lgkmcnt(0)
	v_mfma_f32_16x16x32_bf16 v[124:127], v[146:149], v[186:189], v[124:127]
	v_mfma_f32_16x16x32_bf16 v[120:123], v[162:165], v[186:189], v[120:123]
	v_mfma_f32_16x16x32_bf16 v[108:111], v[146:149], v[194:197], v[108:111]
	v_mfma_f32_16x16x32_bf16 v[104:107], v[162:165], v[194:197], v[104:107]
	v_mfma_f32_16x16x32_bf16 v[92:95], v[146:149], v[202:205], v[92:95]
	v_mfma_f32_16x16x32_bf16 v[88:91], v[162:165], v[202:205], v[88:91]
	v_mfma_f32_16x16x32_bf16 v[76:79], v[146:149], v[210:213], v[76:79]
	v_mfma_f32_16x16x32_bf16 v[72:75], v[162:165], v[210:213], v[72:75]
	v_mfma_f32_16x16x32_bf16 v[124:127], v[158:161], v[190:193], v[124:127]
	v_mfma_f32_16x16x32_bf16 v[120:123], v[166:169], v[190:193], v[120:123]
	v_mfma_f32_16x16x32_bf16 v[108:111], v[158:161], v[198:201], v[108:111]
	v_mfma_f32_16x16x32_bf16 v[104:107], v[166:169], v[198:201], v[104:107]
	v_mfma_f32_16x16x32_bf16 v[92:95], v[158:161], v[206:209], v[92:95]
	v_mfma_f32_16x16x32_bf16 v[88:91], v[166:169], v[206:209], v[88:91]
	v_mfma_f32_16x16x32_bf16 v[76:79], v[158:161], v[214:217], v[76:79]
	v_mfma_f32_16x16x32_bf16 v[72:75], v[166:169], v[214:217], v[72:75]
	s_setprio 0
	s_setprio 1
	v_mfma_f32_16x16x32_bf16 v[116:119], v[170:173], v[186:189], v[116:119]
	v_mfma_f32_16x16x32_bf16 v[112:115], v[178:181], v[186:189], v[112:115]
	v_mfma_f32_16x16x32_bf16 v[100:103], v[170:173], v[194:197], v[100:103]
	v_mfma_f32_16x16x32_bf16 v[96:99], v[178:181], v[194:197], v[96:99]
	v_mfma_f32_16x16x32_bf16 v[84:87], v[170:173], v[202:205], v[84:87]
	v_mfma_f32_16x16x32_bf16 v[80:83], v[178:181], v[202:205], v[80:83]
	v_mfma_f32_16x16x32_bf16 v[68:71], v[170:173], v[210:213], v[68:71]
	v_mfma_f32_16x16x32_bf16 v[64:67], v[178:181], v[210:213], v[64:67]
	v_mfma_f32_16x16x32_bf16 v[116:119], v[174:177], v[190:193], v[116:119]
	v_mfma_f32_16x16x32_bf16 v[112:115], v[182:185], v[190:193], v[112:115]
	v_mfma_f32_16x16x32_bf16 v[100:103], v[174:177], v[198:201], v[100:103]
	v_mfma_f32_16x16x32_bf16 v[96:99], v[182:185], v[198:201], v[96:99]
	v_mfma_f32_16x16x32_bf16 v[84:87], v[174:177], v[206:209], v[84:87]
	v_mfma_f32_16x16x32_bf16 v[80:83], v[182:185], v[206:209], v[80:83]
	v_mfma_f32_16x16x32_bf16 v[68:71], v[174:177], v[214:217], v[68:71]
	v_mfma_f32_16x16x32_bf16 v[64:67], v[182:185], v[214:217], v[64:67]
	s_setprio 0
	s_barrier
	s_add_i32 s34, s59, s41
	v_lshl_add_u64 v[218:219], v[218:219], 0, s[22:23]
	s_mov_b32 m0, s34
	ds_read_b128 v[186:189], v155 offset:49152
	ds_read_b128 v[190:193], v155 offset:50176
	ds_read_b128 v[194:197], v155 offset:51200
	ds_read_b128 v[198:201], v155 offset:52224
	ds_read_b128 v[202:205], v155 offset:53248
	ds_read_b128 v[206:209], v155 offset:54272
	ds_read_b128 v[210:213], v155 offset:55296
	ds_read_b128 v[214:217], v155 offset:56320
	global_load_lds_dwordx4 v[218:219], off
	s_add_i32 m0, s34, 0x2000
	s_add_u32 s34, s36, 0xb0080
	v_lshl_add_u64 v[218:219], v[220:221], 0, s[22:23]
	s_addc_u32 s35, s37, 0
	s_add_i32 s36, s60, s41
	global_load_lds_dwordx4 v[218:219], off
	v_lshl_add_u64 v[218:219], s[34:35], 0, v[132:133]
	s_mov_b32 m0, s36
	s_nop 0
	global_load_lds_dwordx4 v[218:219], off
	v_lshl_add_u64 v[218:219], s[34:35], 0, v[136:137]
	s_add_i32 m0, s36, 0x2000
	s_nop 0
	global_load_lds_dwordx4 v[218:219], off
	v_lshl_add_u64 v[218:219], v[222:223], 0, s[22:23]
	s_mov_b32 m0, s47
	s_nop 0
	global_load_lds_dwordx4 v[218:219], off
	v_lshl_add_u64 v[218:219], v[224:225], 0, s[22:23]
	s_mov_b32 m0, s48
	s_nop 0
	global_load_lds_dwordx4 v[218:219], off
	s_waitcnt vmcnt(8)
	s_waitcnt lgkmcnt(0)
	s_barrier
	s_add_u32 s30, s30, 0x100
	s_addc_u32 s31, s31, 0
	s_add_u32 s13, s13, 0x100
	s_addc_u32 s57, s57, 0
	s_setprio 1
	s_waitcnt lgkmcnt(0)
	v_mfma_f32_16x16x32_bf16 v[60:63], v[146:149], v[186:189], v[60:63]
	v_mfma_f32_16x16x32_bf16 v[56:59], v[162:165], v[186:189], v[56:59]
	v_mfma_f32_16x16x32_bf16 v[44:47], v[146:149], v[194:197], v[44:47]
	v_mfma_f32_16x16x32_bf16 v[40:43], v[162:165], v[194:197], v[40:43]
	v_mfma_f32_16x16x32_bf16 v[28:31], v[146:149], v[202:205], v[28:31]
	v_mfma_f32_16x16x32_bf16 v[24:27], v[162:165], v[202:205], v[24:27]
	v_mfma_f32_16x16x32_bf16 v[12:15], v[146:149], v[210:213], v[12:15]
	v_mfma_f32_16x16x32_bf16 v[8:11], v[162:165], v[210:213], v[8:11]
	v_mfma_f32_16x16x32_bf16 v[60:63], v[158:161], v[190:193], v[60:63]
	v_mfma_f32_16x16x32_bf16 v[56:59], v[166:169], v[190:193], v[56:59]
	v_mfma_f32_16x16x32_bf16 v[44:47], v[158:161], v[198:201], v[44:47]
	v_mfma_f32_16x16x32_bf16 v[40:43], v[166:169], v[198:201], v[40:43]
	v_mfma_f32_16x16x32_bf16 v[28:31], v[158:161], v[206:209], v[28:31]
	v_mfma_f32_16x16x32_bf16 v[24:27], v[166:169], v[206:209], v[24:27]
	v_mfma_f32_16x16x32_bf16 v[12:15], v[158:161], v[214:217], v[12:15]
	v_mfma_f32_16x16x32_bf16 v[8:11], v[166:169], v[214:217], v[8:11]
	s_setprio 0
	s_setprio 1
	v_mfma_f32_16x16x32_bf16 v[52:55], v[170:173], v[186:189], v[52:55]
	v_mfma_f32_16x16x32_bf16 v[48:51], v[178:181], v[186:189], v[48:51]
	v_mfma_f32_16x16x32_bf16 v[36:39], v[170:173], v[194:197], v[36:39]
	v_mfma_f32_16x16x32_bf16 v[32:35], v[178:181], v[194:197], v[32:35]
	v_mfma_f32_16x16x32_bf16 v[20:23], v[170:173], v[202:205], v[20:23]
	v_mfma_f32_16x16x32_bf16 v[16:19], v[178:181], v[202:205], v[16:19]
	v_mfma_f32_16x16x32_bf16 v[4:7], v[170:173], v[210:213], v[4:7]
	v_mfma_f32_16x16x32_bf16 v[0:3], v[178:181], v[210:213], v[0:3]
	v_mfma_f32_16x16x32_bf16 v[52:55], v[174:177], v[190:193], v[52:55]
	v_mfma_f32_16x16x32_bf16 v[48:51], v[182:185], v[190:193], v[48:51]
	v_mfma_f32_16x16x32_bf16 v[36:39], v[174:177], v[198:201], v[36:39]
	v_mfma_f32_16x16x32_bf16 v[32:35], v[182:185], v[198:201], v[32:35]
	v_mfma_f32_16x16x32_bf16 v[20:23], v[174:177], v[206:209], v[20:23]
	v_mfma_f32_16x16x32_bf16 v[16:19], v[182:185], v[206:209], v[16:19]
	v_mfma_f32_16x16x32_bf16 v[4:7], v[174:177], v[214:217], v[4:7]
	v_mfma_f32_16x16x32_bf16 v[0:3], v[182:185], v[214:217], v[0:3]
	s_setprio 0
	s_barrier
	s_add_i32 s58, s58, 2
.LBB0_1733:
	ds_read_b128 v[146:149], v153
	ds_read_b128 v[158:161], v153 offset:1024
	ds_read_b128 v[162:165], v153 offset:2048
	ds_read_b128 v[166:169], v153 offset:3072
	ds_read_b128 v[170:173], v154
	ds_read_b128 v[174:177], v154 offset:1024
	ds_read_b128 v[178:181], v154 offset:2048
	ds_read_b128 v[182:185], v154 offset:3072
	s_add_u32 s34, s30, 0xfff50080
	s_addc_u32 s35, s31, -1
	s_cmp_eq_u32 s58, 40
	s_cselect_b32 s39, s1, s35
	s_cselect_b32 s38, s0, s34
	s_cselect_b32 s37, s29, s57
	s_cselect_b32 s36, s28, s13
	v_lshl_add_u64 v[218:219], s[30:31], 0, v[138:139]
	s_add_i32 m0, s42, 0xc000
	ds_read_b128 v[186:189], v155
	ds_read_b128 v[190:193], v155 offset:1024
	ds_read_b128 v[194:197], v155 offset:2048
	ds_read_b128 v[198:201], v155 offset:3072
	ds_read_b128 v[202:205], v155 offset:4096
	ds_read_b128 v[206:209], v155 offset:5120
	ds_read_b128 v[210:213], v155 offset:6144
	ds_read_b128 v[214:217], v155 offset:7168
	global_load_lds_dwordx4 v[218:219], off
	v_lshl_add_u64 v[218:219], s[30:31], 0, v[140:141]
	s_add_i32 m0, s42, 0xe000
	s_nop 0
	global_load_lds_dwordx4 v[218:219], off
	s_waitcnt vmcnt(8)
	s_waitcnt lgkmcnt(0)
	s_barrier
	s_setprio 1
	s_waitcnt lgkmcnt(0)
	v_mfma_f32_16x16x32_bf16 v[124:127], v[146:149], v[186:189], v[124:127]
	v_mfma_f32_16x16x32_bf16 v[120:123], v[162:165], v[186:189], v[120:123]
	v_mfma_f32_16x16x32_bf16 v[108:111], v[146:149], v[194:197], v[108:111]
	v_mfma_f32_16x16x32_bf16 v[104:107], v[162:165], v[194:197], v[104:107]
	v_mfma_f32_16x16x32_bf16 v[92:95], v[146:149], v[202:205], v[92:95]
	v_mfma_f32_16x16x32_bf16 v[88:91], v[162:165], v[202:205], v[88:91]
	v_mfma_f32_16x16x32_bf16 v[76:79], v[146:149], v[210:213], v[76:79]
	v_mfma_f32_16x16x32_bf16 v[72:75], v[162:165], v[210:213], v[72:75]
	v_mfma_f32_16x16x32_bf16 v[124:127], v[158:161], v[190:193], v[124:127]
	v_mfma_f32_16x16x32_bf16 v[120:123], v[166:169], v[190:193], v[120:123]
	v_mfma_f32_16x16x32_bf16 v[108:111], v[158:161], v[198:201], v[108:111]
	v_mfma_f32_16x16x32_bf16 v[104:107], v[166:169], v[198:201], v[104:107]
	v_mfma_f32_16x16x32_bf16 v[92:95], v[158:161], v[206:209], v[92:95]
	v_mfma_f32_16x16x32_bf16 v[88:91], v[166:169], v[206:209], v[88:91]
	v_mfma_f32_16x16x32_bf16 v[76:79], v[158:161], v[214:217], v[76:79]
	v_mfma_f32_16x16x32_bf16 v[72:75], v[166:169], v[214:217], v[72:75]
	s_setprio 0
	s_setprio 1
	v_mfma_f32_16x16x32_bf16 v[116:119], v[170:173], v[186:189], v[116:119]
	v_mfma_f32_16x16x32_bf16 v[112:115], v[178:181], v[186:189], v[112:115]
	v_mfma_f32_16x16x32_bf16 v[100:103], v[170:173], v[194:197], v[100:103]
	v_mfma_f32_16x16x32_bf16 v[96:99], v[178:181], v[194:197], v[96:99]
	v_mfma_f32_16x16x32_bf16 v[84:87], v[170:173], v[202:205], v[84:87]
	v_mfma_f32_16x16x32_bf16 v[80:83], v[178:181], v[202:205], v[80:83]
	v_mfma_f32_16x16x32_bf16 v[68:71], v[170:173], v[210:213], v[68:71]
	v_mfma_f32_16x16x32_bf16 v[64:67], v[178:181], v[210:213], v[64:67]
	v_mfma_f32_16x16x32_bf16 v[116:119], v[174:177], v[190:193], v[116:119]
	v_mfma_f32_16x16x32_bf16 v[112:115], v[182:185], v[190:193], v[112:115]
	v_mfma_f32_16x16x32_bf16 v[100:103], v[174:177], v[198:201], v[100:103]
	v_mfma_f32_16x16x32_bf16 v[96:99], v[182:185], v[198:201], v[96:99]
	v_mfma_f32_16x16x32_bf16 v[84:87], v[174:177], v[206:209], v[84:87]
	v_mfma_f32_16x16x32_bf16 v[80:83], v[182:185], v[206:209], v[80:83]
	v_mfma_f32_16x16x32_bf16 v[68:71], v[174:177], v[214:217], v[68:71]
	v_mfma_f32_16x16x32_bf16 v[64:67], v[182:185], v[214:217], v[64:67]
	s_setprio 0
	s_barrier
	s_add_i32 s34, s52, s41
	v_lshl_add_u64 v[218:219], s[36:37], 0, v[132:133]
	s_mov_b32 m0, s34
	ds_read_b128 v[186:189], v155 offset:16384
	ds_read_b128 v[190:193], v155 offset:17408
	ds_read_b128 v[194:197], v155 offset:18432
	ds_read_b128 v[198:201], v155 offset:19456
	ds_read_b128 v[202:205], v155 offset:20480
	ds_read_b128 v[206:209], v155 offset:21504
	ds_read_b128 v[210:213], v155 offset:22528
	ds_read_b128 v[214:217], v155 offset:23552
	global_load_lds_dwordx4 v[218:219], off
	s_add_i32 m0, s34, 0x2000
	s_add_u32 s34, s36, 0xb0000
	v_lshl_add_u64 v[220:221], s[36:37], 0, v[136:137]
	s_addc_u32 s35, s37, 0
	s_add_i32 s59, s53, s41
	global_load_lds_dwordx4 v[220:221], off
	v_lshl_add_u64 v[222:223], s[34:35], 0, v[132:133]
	s_mov_b32 m0, s59
	v_lshl_add_u64 v[224:225], s[38:39], 0, v[134:135]
	global_load_lds_dwordx4 v[222:223], off
	v_lshl_add_u64 v[222:223], s[34:35], 0, v[136:137]
	s_add_i32 m0, s59, 0x2000
	s_nop 0
	global_load_lds_dwordx4 v[222:223], off
	v_lshl_add_u64 v[222:223], s[38:39], 0, v[130:131]
	s_mov_b32 m0, s42
	s_nop 0
	global_load_lds_dwordx4 v[222:223], off
	s_mov_b32 m0, s43
	s_nop 0
	global_load_lds_dwordx4 v[224:225], off
	s_waitcnt vmcnt(8)
	s_waitcnt lgkmcnt(0)
	s_barrier
	s_setprio 1
	s_waitcnt lgkmcnt(0)
	v_mfma_f32_16x16x32_bf16 v[60:63], v[146:149], v[186:189], v[60:63]
	v_mfma_f32_16x16x32_bf16 v[56:59], v[162:165], v[186:189], v[56:59]
	v_mfma_f32_16x16x32_bf16 v[44:47], v[146:149], v[194:197], v[44:47]
	v_mfma_f32_16x16x32_bf16 v[40:43], v[162:165], v[194:197], v[40:43]
	v_mfma_f32_16x16x32_bf16 v[28:31], v[146:149], v[202:205], v[28:31]
	v_mfma_f32_16x16x32_bf16 v[24:27], v[162:165], v[202:205], v[24:27]
	v_mfma_f32_16x16x32_bf16 v[12:15], v[146:149], v[210:213], v[12:15]
	v_mfma_f32_16x16x32_bf16 v[8:11], v[162:165], v[210:213], v[8:11]
	v_mfma_f32_16x16x32_bf16 v[60:63], v[158:161], v[190:193], v[60:63]
	v_mfma_f32_16x16x32_bf16 v[56:59], v[166:169], v[190:193], v[56:59]
	v_mfma_f32_16x16x32_bf16 v[44:47], v[158:161], v[198:201], v[44:47]
	v_mfma_f32_16x16x32_bf16 v[40:43], v[166:169], v[198:201], v[40:43]
	v_mfma_f32_16x16x32_bf16 v[28:31], v[158:161], v[206:209], v[28:31]
	v_mfma_f32_16x16x32_bf16 v[24:27], v[166:169], v[206:209], v[24:27]
	v_mfma_f32_16x16x32_bf16 v[12:15], v[158:161], v[214:217], v[12:15]
	v_mfma_f32_16x16x32_bf16 v[8:11], v[166:169], v[214:217], v[8:11]
	s_setprio 0
	s_setprio 1
	v_mfma_f32_16x16x32_bf16 v[52:55], v[170:173], v[186:189], v[52:55]
	v_mfma_f32_16x16x32_bf16 v[48:51], v[178:181], v[186:189], v[48:51]
	v_mfma_f32_16x16x32_bf16 v[36:39], v[170:173], v[194:197], v[36:39]
	v_mfma_f32_16x16x32_bf16 v[32:35], v[178:181], v[194:197], v[32:35]
	v_mfma_f32_16x16x32_bf16 v[20:23], v[170:173], v[202:205], v[20:23]
	v_mfma_f32_16x16x32_bf16 v[16:19], v[178:181], v[202:205], v[16:19]
	v_mfma_f32_16x16x32_bf16 v[4:7], v[170:173], v[210:213], v[4:7]
	v_mfma_f32_16x16x32_bf16 v[0:3], v[178:181], v[210:213], v[0:3]
	v_mfma_f32_16x16x32_bf16 v[52:55], v[174:177], v[190:193], v[52:55]
	v_mfma_f32_16x16x32_bf16 v[48:51], v[182:185], v[190:193], v[48:51]
	v_mfma_f32_16x16x32_bf16 v[36:39], v[174:177], v[198:201], v[36:39]
	v_mfma_f32_16x16x32_bf16 v[32:35], v[182:185], v[198:201], v[32:35]
	v_mfma_f32_16x16x32_bf16 v[20:23], v[174:177], v[206:209], v[20:23]
	v_mfma_f32_16x16x32_bf16 v[16:19], v[182:185], v[206:209], v[16:19]
	v_mfma_f32_16x16x32_bf16 v[4:7], v[174:177], v[214:217], v[4:7]
	v_mfma_f32_16x16x32_bf16 v[0:3], v[182:185], v[214:217], v[0:3]
	s_setprio 0
	s_barrier
	s_add_i32 s59, 0, 0x18000
	s_add_i32 s60, 0, 0x1c000
	v_add_u32_e32 v166, s59, v151
	v_add_u32_e32 v182, s60, v151
	ds_read_b128 v[146:149], v166
	ds_read_b128 v[158:161], v166 offset:1024
	ds_read_b128 v[162:165], v166 offset:2048
	ds_read_b128 v[166:169], v166 offset:3072
	ds_read_b128 v[170:173], v182
	ds_read_b128 v[174:177], v182 offset:1024
	ds_read_b128 v[178:181], v182 offset:2048
	ds_read_b128 v[182:185], v182 offset:3072
	s_add_u32 s34, s38, 0xb0000
	s_addc_u32 s35, s39, 0
	s_mov_b32 m0, s44
	v_lshl_add_u64 v[226:227], s[34:35], 0, v[130:131]
	ds_read_b128 v[186:189], v155 offset:32768
	ds_read_b128 v[190:193], v155 offset:33792
	ds_read_b128 v[194:197], v155 offset:34816
	ds_read_b128 v[198:201], v155 offset:35840
	ds_read_b128 v[202:205], v155 offset:36864
	ds_read_b128 v[206:209], v155 offset:37888
	ds_read_b128 v[210:213], v155 offset:38912
	ds_read_b128 v[214:217], v155 offset:39936
	global_load_lds_dwordx4 v[226:227], off
	v_lshl_add_u64 v[226:227], s[34:35], 0, v[134:135]
	s_mov_b32 m0, s45
	s_nop 0
	global_load_lds_dwordx4 v[226:227], off
	s_waitcnt vmcnt(8)
	s_waitcnt lgkmcnt(0)
	s_barrier
	s_setprio 1
	s_waitcnt lgkmcnt(0)
	v_mfma_f32_16x16x32_bf16 v[124:127], v[146:149], v[186:189], v[124:127]
	v_mfma_f32_16x16x32_bf16 v[120:123], v[162:165], v[186:189], v[120:123]
	v_mfma_f32_16x16x32_bf16 v[108:111], v[146:149], v[194:197], v[108:111]
	v_mfma_f32_16x16x32_bf16 v[104:107], v[162:165], v[194:197], v[104:107]
	v_mfma_f32_16x16x32_bf16 v[92:95], v[146:149], v[202:205], v[92:95]
	v_mfma_f32_16x16x32_bf16 v[88:91], v[162:165], v[202:205], v[88:91]
	v_mfma_f32_16x16x32_bf16 v[76:79], v[146:149], v[210:213], v[76:79]
	v_mfma_f32_16x16x32_bf16 v[72:75], v[162:165], v[210:213], v[72:75]
	v_mfma_f32_16x16x32_bf16 v[124:127], v[158:161], v[190:193], v[124:127]
	v_mfma_f32_16x16x32_bf16 v[120:123], v[166:169], v[190:193], v[120:123]
	v_mfma_f32_16x16x32_bf16 v[108:111], v[158:161], v[198:201], v[108:111]
	v_mfma_f32_16x16x32_bf16 v[104:107], v[166:169], v[198:201], v[104:107]
	v_mfma_f32_16x16x32_bf16 v[92:95], v[158:161], v[206:209], v[92:95]
	v_mfma_f32_16x16x32_bf16 v[88:91], v[166:169], v[206:209], v[88:91]
	v_mfma_f32_16x16x32_bf16 v[76:79], v[158:161], v[214:217], v[76:79]
	v_mfma_f32_16x16x32_bf16 v[72:75], v[166:169], v[214:217], v[72:75]
	s_setprio 0
	s_setprio 1
	v_mfma_f32_16x16x32_bf16 v[116:119], v[170:173], v[186:189], v[116:119]
	v_mfma_f32_16x16x32_bf16 v[112:115], v[178:181], v[186:189], v[112:115]
	v_mfma_f32_16x16x32_bf16 v[100:103], v[170:173], v[194:197], v[100:103]
	v_mfma_f32_16x16x32_bf16 v[96:99], v[178:181], v[194:197], v[96:99]
	v_mfma_f32_16x16x32_bf16 v[84:87], v[170:173], v[202:205], v[84:87]
	v_mfma_f32_16x16x32_bf16 v[80:83], v[178:181], v[202:205], v[80:83]
	v_mfma_f32_16x16x32_bf16 v[68:71], v[170:173], v[210:213], v[68:71]
	v_mfma_f32_16x16x32_bf16 v[64:67], v[178:181], v[210:213], v[64:67]
	v_mfma_f32_16x16x32_bf16 v[116:119], v[174:177], v[190:193], v[116:119]
	v_mfma_f32_16x16x32_bf16 v[112:115], v[182:185], v[190:193], v[112:115]
	v_mfma_f32_16x16x32_bf16 v[100:103], v[174:177], v[198:201], v[100:103]
	v_mfma_f32_16x16x32_bf16 v[96:99], v[182:185], v[198:201], v[96:99]
	v_mfma_f32_16x16x32_bf16 v[84:87], v[174:177], v[206:209], v[84:87]
	v_mfma_f32_16x16x32_bf16 v[80:83], v[182:185], v[206:209], v[80:83]
	v_mfma_f32_16x16x32_bf16 v[68:71], v[174:177], v[214:217], v[68:71]
	v_mfma_f32_16x16x32_bf16 v[64:67], v[182:185], v[214:217], v[64:67]
	s_setprio 0
	s_barrier
	s_add_i32 s34, s59, s41
	v_lshl_add_u64 v[218:219], v[218:219], 0, s[22:23]
	s_mov_b32 m0, s34
	ds_read_b128 v[186:189], v155 offset:49152
	ds_read_b128 v[190:193], v155 offset:50176
	ds_read_b128 v[194:197], v155 offset:51200
	ds_read_b128 v[198:201], v155 offset:52224
	ds_read_b128 v[202:205], v155 offset:53248
	ds_read_b128 v[206:209], v155 offset:54272
	ds_read_b128 v[210:213], v155 offset:55296
	ds_read_b128 v[214:217], v155 offset:56320
	global_load_lds_dwordx4 v[218:219], off
	s_add_i32 m0, s34, 0x2000
	s_add_u32 s34, s36, 0xb0080
	v_lshl_add_u64 v[218:219], v[220:221], 0, s[22:23]
	s_addc_u32 s35, s37, 0
	s_add_i32 s36, s60, s41
	global_load_lds_dwordx4 v[218:219], off
	v_lshl_add_u64 v[218:219], s[34:35], 0, v[132:133]
	s_mov_b32 m0, s36
	s_nop 0
	global_load_lds_dwordx4 v[218:219], off
	v_lshl_add_u64 v[218:219], s[34:35], 0, v[136:137]
	s_add_i32 m0, s36, 0x2000
	s_nop 0
	global_load_lds_dwordx4 v[218:219], off
	v_lshl_add_u64 v[218:219], v[222:223], 0, s[22:23]
	s_mov_b32 m0, s47
	s_nop 0
	global_load_lds_dwordx4 v[218:219], off
	v_lshl_add_u64 v[218:219], v[224:225], 0, s[22:23]
	s_mov_b32 m0, s48
	s_nop 0
	global_load_lds_dwordx4 v[218:219], off
	s_waitcnt vmcnt(8)
	s_waitcnt lgkmcnt(0)
	s_barrier
	s_add_u32 s30, s30, 0x100
	s_addc_u32 s31, s31, 0
	s_add_u32 s13, s13, 0x100
	s_addc_u32 s57, s57, 0
	s_setprio 1
	s_waitcnt lgkmcnt(0)
	v_mfma_f32_16x16x32_bf16 v[60:63], v[146:149], v[186:189], v[60:63]
	v_mfma_f32_16x16x32_bf16 v[56:59], v[162:165], v[186:189], v[56:59]
	v_mfma_f32_16x16x32_bf16 v[44:47], v[146:149], v[194:197], v[44:47]
	v_mfma_f32_16x16x32_bf16 v[40:43], v[162:165], v[194:197], v[40:43]
	v_mfma_f32_16x16x32_bf16 v[28:31], v[146:149], v[202:205], v[28:31]
	v_mfma_f32_16x16x32_bf16 v[24:27], v[162:165], v[202:205], v[24:27]
	v_mfma_f32_16x16x32_bf16 v[12:15], v[146:149], v[210:213], v[12:15]
	v_mfma_f32_16x16x32_bf16 v[8:11], v[162:165], v[210:213], v[8:11]
	v_mfma_f32_16x16x32_bf16 v[60:63], v[158:161], v[190:193], v[60:63]
	v_mfma_f32_16x16x32_bf16 v[56:59], v[166:169], v[190:193], v[56:59]
	v_mfma_f32_16x16x32_bf16 v[44:47], v[158:161], v[198:201], v[44:47]
	v_mfma_f32_16x16x32_bf16 v[40:43], v[166:169], v[198:201], v[40:43]
	v_mfma_f32_16x16x32_bf16 v[28:31], v[158:161], v[206:209], v[28:31]
	v_mfma_f32_16x16x32_bf16 v[24:27], v[166:169], v[206:209], v[24:27]
	v_mfma_f32_16x16x32_bf16 v[12:15], v[158:161], v[214:217], v[12:15]
	v_mfma_f32_16x16x32_bf16 v[8:11], v[166:169], v[214:217], v[8:11]
	s_setprio 0
	s_setprio 1
	v_mfma_f32_16x16x32_bf16 v[52:55], v[170:173], v[186:189], v[52:55]
	v_mfma_f32_16x16x32_bf16 v[48:51], v[178:181], v[186:189], v[48:51]
	v_mfma_f32_16x16x32_bf16 v[36:39], v[170:173], v[194:197], v[36:39]
	v_mfma_f32_16x16x32_bf16 v[32:35], v[178:181], v[194:197], v[32:35]
	v_mfma_f32_16x16x32_bf16 v[20:23], v[170:173], v[202:205], v[20:23]
	v_mfma_f32_16x16x32_bf16 v[16:19], v[178:181], v[202:205], v[16:19]
	v_mfma_f32_16x16x32_bf16 v[4:7], v[170:173], v[210:213], v[4:7]
	v_mfma_f32_16x16x32_bf16 v[0:3], v[178:181], v[210:213], v[0:3]
	v_mfma_f32_16x16x32_bf16 v[52:55], v[174:177], v[190:193], v[52:55]
	v_mfma_f32_16x16x32_bf16 v[48:51], v[182:185], v[190:193], v[48:51]
	v_mfma_f32_16x16x32_bf16 v[36:39], v[174:177], v[198:201], v[36:39]
	v_mfma_f32_16x16x32_bf16 v[32:35], v[182:185], v[198:201], v[32:35]
	v_mfma_f32_16x16x32_bf16 v[20:23], v[174:177], v[206:209], v[20:23]
	v_mfma_f32_16x16x32_bf16 v[16:19], v[182:185], v[206:209], v[16:19]
	v_mfma_f32_16x16x32_bf16 v[4:7], v[174:177], v[214:217], v[4:7]
	v_mfma_f32_16x16x32_bf16 v[0:3], v[182:185], v[214:217], v[0:3]
	s_setprio 0
	s_cmp_eq_u32 s58, s98
	s_cbranch_scc1 .Lmy_nobar_18
	s_barrier
.Lmy_nobar_18:
	s_add_i32 s58, s58, 2
	s_cmp_gt_u32 s58, 41
	s_cbranch_scc0 .LBB0_1733
	s_and_b64 vcc, exec, s[26:27]
	s_cbranch_vccz .LBB0_1736
	s_nop 0

.Lmy_nobar2_19:
	ds_read_b128 v[150:153], v157
	ds_read_b128 v[160:163], v157 offset:1024
	ds_read_b128 v[164:167], v157 offset:2048
	ds_read_b128 v[168:171], v157 offset:3072
	ds_read_b128 v[172:175], v158
	ds_read_b128 v[176:179], v158 offset:1024
	ds_read_b128 v[180:183], v158 offset:2048
	ds_read_b128 v[184:187], v158 offset:3072
	s_add_u32 s34, s42, 0xfffc0080
	s_addc_u32 s35, s43, -1
	s_cmp_eq_u32 s65, 12
	s_cselect_b32 s47, s7, s35
	s_cselect_b32 s46, s8, s34
	s_cselect_b32 s45, s12, s37
	s_cselect_b32 s44, s13, s31
	v_lshl_add_u64 v[220:221], s[42:43], 0, v[142:143]
	s_add_i32 m0, s53, 0xc000
	ds_read_b128 v[188:191], v159
	ds_read_b128 v[192:195], v159 offset:1024
	ds_read_b128 v[196:199], v159 offset:2048
	ds_read_b128 v[200:203], v159 offset:3072
	ds_read_b128 v[204:207], v159 offset:4096
	ds_read_b128 v[208:211], v159 offset:5120
	ds_read_b128 v[212:215], v159 offset:6144
	ds_read_b128 v[216:219], v159 offset:7168
	global_load_lds_dwordx4 v[220:221], off
	v_lshl_add_u64 v[220:221], s[42:43], 0, v[144:145]
	s_add_i32 m0, s53, 0xe000
	s_nop 0
	global_load_lds_dwordx4 v[220:221], off
	s_waitcnt vmcnt(8)
	s_waitcnt lgkmcnt(0)
	s_barrier
	s_setprio 1
	s_waitcnt lgkmcnt(0)
	v_mfma_f32_16x16x32_bf16 v[124:127], v[150:153], v[188:191], 0
	v_mfma_f32_16x16x32_bf16 v[120:123], v[164:167], v[188:191], 0
	v_mfma_f32_16x16x32_bf16 v[108:111], v[150:153], v[196:199], 0
	v_mfma_f32_16x16x32_bf16 v[104:107], v[164:167], v[196:199], 0
	v_mfma_f32_16x16x32_bf16 v[92:95], v[150:153], v[204:207], 0
	v_mfma_f32_16x16x32_bf16 v[88:91], v[164:167], v[204:207], 0
	v_mfma_f32_16x16x32_bf16 v[76:79], v[150:153], v[212:215], 0
	v_mfma_f32_16x16x32_bf16 v[72:75], v[164:167], v[212:215], 0
	v_mfma_f32_16x16x32_bf16 v[124:127], v[160:163], v[192:195], v[124:127]
	v_mfma_f32_16x16x32_bf16 v[120:123], v[168:171], v[192:195], v[120:123]
	v_mfma_f32_16x16x32_bf16 v[108:111], v[160:163], v[200:203], v[108:111]
	v_mfma_f32_16x16x32_bf16 v[104:107], v[168:171], v[200:203], v[104:107]
	v_mfma_f32_16x16x32_bf16 v[92:95], v[160:163], v[208:211], v[92:95]
	v_mfma_f32_16x16x32_bf16 v[88:91], v[168:171], v[208:211], v[88:91]
	v_mfma_f32_16x16x32_bf16 v[76:79], v[160:163], v[216:219], v[76:79]
	v_mfma_f32_16x16x32_bf16 v[72:75], v[168:171], v[216:219], v[72:75]
	s_setprio 0
	s_setprio 1
	v_mfma_f32_16x16x32_bf16 v[116:119], v[172:175], v[188:191], 0
	v_mfma_f32_16x16x32_bf16 v[112:115], v[180:183], v[188:191], 0
	v_mfma_f32_16x16x32_bf16 v[100:103], v[172:175], v[196:199], 0
	v_mfma_f32_16x16x32_bf16 v[96:99], v[180:183], v[196:199], 0
	v_mfma_f32_16x16x32_bf16 v[84:87], v[172:175], v[204:207], 0
	v_mfma_f32_16x16x32_bf16 v[80:83], v[180:183], v[204:207], 0
	v_mfma_f32_16x16x32_bf16 v[68:71], v[172:175], v[212:215], 0
	v_mfma_f32_16x16x32_bf16 v[64:67], v[180:183], v[212:215], 0
	v_mfma_f32_16x16x32_bf16 v[116:119], v[176:179], v[192:195], v[116:119]
	v_mfma_f32_16x16x32_bf16 v[112:115], v[184:187], v[192:195], v[112:115]
	v_mfma_f32_16x16x32_bf16 v[100:103], v[176:179], v[200:203], v[100:103]
	v_mfma_f32_16x16x32_bf16 v[96:99], v[184:187], v[200:203], v[96:99]
	v_mfma_f32_16x16x32_bf16 v[84:87], v[176:179], v[208:211], v[84:87]
	v_mfma_f32_16x16x32_bf16 v[80:83], v[184:187], v[208:211], v[80:83]
	v_mfma_f32_16x16x32_bf16 v[68:71], v[176:179], v[216:219], v[68:71]
	v_mfma_f32_16x16x32_bf16 v[64:67], v[184:187], v[216:219], v[64:67]
	s_setprio 0
	s_barrier
	s_add_i32 s34, s61, s50
	v_lshl_add_u64 v[220:221], s[44:45], 0, v[134:135]
	s_mov_b32 m0, s34
	ds_read_b128 v[188:191], v159 offset:16384
	ds_read_b128 v[192:195], v159 offset:17408
	ds_read_b128 v[196:199], v159 offset:18432
	ds_read_b128 v[200:203], v159 offset:19456
	ds_read_b128 v[204:207], v159 offset:20480
	ds_read_b128 v[208:211], v159 offset:21504
	ds_read_b128 v[212:215], v159 offset:22528
	ds_read_b128 v[216:219], v159 offset:23552
	global_load_lds_dwordx4 v[220:221], off
	s_add_i32 m0, s34, 0x2000
	s_add_u32 s34, s44, 0x40000
	v_lshl_add_u64 v[222:223], s[44:45], 0, v[138:139]
	s_addc_u32 s35, s45, 0
	s_add_i32 s66, s62, s50
	global_load_lds_dwordx4 v[222:223], off
	v_lshl_add_u64 v[224:225], s[34:35], 0, v[134:135]
	s_mov_b32 m0, s66
	v_lshl_add_u64 v[226:227], s[46:47], 0, v[136:137]
	global_load_lds_dwordx4 v[224:225], off
	v_lshl_add_u64 v[224:225], s[34:35], 0, v[138:139]
	s_add_i32 m0, s66, 0x2000
	s_nop 0
	global_load_lds_dwordx4 v[224:225], off
	v_lshl_add_u64 v[224:225], s[46:47], 0, v[132:133]
	s_mov_b32 m0, s53
	s_nop 0
	global_load_lds_dwordx4 v[224:225], off
	s_mov_b32 m0, s54
	s_nop 0
	global_load_lds_dwordx4 v[226:227], off
	s_waitcnt vmcnt(8)
	s_waitcnt lgkmcnt(0)
	s_barrier
	s_setprio 1
	s_waitcnt lgkmcnt(0)
	v_mfma_f32_16x16x32_bf16 v[60:63], v[150:153], v[188:191], 0
	v_mfma_f32_16x16x32_bf16 v[56:59], v[164:167], v[188:191], 0
	v_mfma_f32_16x16x32_bf16 v[44:47], v[150:153], v[196:199], 0
	v_mfma_f32_16x16x32_bf16 v[40:43], v[164:167], v[196:199], 0
	v_mfma_f32_16x16x32_bf16 v[28:31], v[150:153], v[204:207], 0
	v_mfma_f32_16x16x32_bf16 v[24:27], v[164:167], v[204:207], 0
	v_mfma_f32_16x16x32_bf16 v[12:15], v[150:153], v[212:215], 0
	v_mfma_f32_16x16x32_bf16 v[8:11], v[164:167], v[212:215], 0
	v_mfma_f32_16x16x32_bf16 v[60:63], v[160:163], v[192:195], v[60:63]
	v_mfma_f32_16x16x32_bf16 v[56:59], v[168:171], v[192:195], v[56:59]
	v_mfma_f32_16x16x32_bf16 v[44:47], v[160:163], v[200:203], v[44:47]
	v_mfma_f32_16x16x32_bf16 v[40:43], v[168:171], v[200:203], v[40:43]
	v_mfma_f32_16x16x32_bf16 v[28:31], v[160:163], v[208:211], v[28:31]
	v_mfma_f32_16x16x32_bf16 v[24:27], v[168:171], v[208:211], v[24:27]
	v_mfma_f32_16x16x32_bf16 v[12:15], v[160:163], v[216:219], v[12:15]
	v_mfma_f32_16x16x32_bf16 v[8:11], v[168:171], v[216:219], v[8:11]
	s_setprio 0
	s_setprio 1
	v_mfma_f32_16x16x32_bf16 v[52:55], v[172:175], v[188:191], 0
	v_mfma_f32_16x16x32_bf16 v[48:51], v[180:183], v[188:191], 0
	v_mfma_f32_16x16x32_bf16 v[36:39], v[172:175], v[196:199], 0
	v_mfma_f32_16x16x32_bf16 v[32:35], v[180:183], v[196:199], 0
	v_mfma_f32_16x16x32_bf16 v[20:23], v[172:175], v[204:207], 0
	v_mfma_f32_16x16x32_bf16 v[16:19], v[180:183], v[204:207], 0
	v_mfma_f32_16x16x32_bf16 v[4:7], v[172:175], v[212:215], 0
	v_mfma_f32_16x16x32_bf16 v[0:3], v[180:183], v[212:215], 0
	v_mfma_f32_16x16x32_bf16 v[52:55], v[176:179], v[192:195], v[52:55]
	v_mfma_f32_16x16x32_bf16 v[48:51], v[184:187], v[192:195], v[48:51]
	v_mfma_f32_16x16x32_bf16 v[36:39], v[176:179], v[200:203], v[36:39]
	v_mfma_f32_16x16x32_bf16 v[32:35], v[184:187], v[200:203], v[32:35]
	v_mfma_f32_16x16x32_bf16 v[20:23], v[176:179], v[208:211], v[20:23]
	v_mfma_f32_16x16x32_bf16 v[16:19], v[184:187], v[208:211], v[16:19]
	v_mfma_f32_16x16x32_bf16 v[4:7], v[176:179], v[216:219], v[4:7]
	v_mfma_f32_16x16x32_bf16 v[0:3], v[184:187], v[216:219], v[0:3]
	s_setprio 0
	s_barrier
	s_add_i32 s66, 0, 0x18000
	v_add_u32_e32 v140, s66, v154
	s_add_i32 s67, 0, 0x1c000
	ds_read_b128 v[150:153], v140
	ds_read_b128 v[160:163], v140 offset:1024
	ds_read_b128 v[164:167], v140 offset:2048
	ds_read_b128 v[168:171], v140 offset:3072
	v_add_u32_e32 v140, s67, v154
	ds_read_b128 v[172:175], v140
	ds_read_b128 v[176:179], v140 offset:1024
	ds_read_b128 v[180:183], v140 offset:2048
	ds_read_b128 v[184:187], v140 offset:3072
	s_add_u32 s34, s46, 0x40000
	s_addc_u32 s35, s47, 0
	s_mov_b32 m0, s55
	v_lshl_add_u64 v[228:229], s[34:35], 0, v[132:133]
	ds_read_b128 v[188:191], v159 offset:32768
	ds_read_b128 v[192:195], v159 offset:33792
	ds_read_b128 v[196:199], v159 offset:34816
	ds_read_b128 v[200:203], v159 offset:35840
	ds_read_b128 v[204:207], v159 offset:36864
	ds_read_b128 v[208:211], v159 offset:37888
	ds_read_b128 v[212:215], v159 offset:38912
	ds_read_b128 v[216:219], v159 offset:39936
	global_load_lds_dwordx4 v[228:229], off
	v_lshl_add_u64 v[228:229], s[34:35], 0, v[136:137]
	s_mov_b32 m0, s56
	s_nop 0
	global_load_lds_dwordx4 v[228:229], off
	s_waitcnt vmcnt(8)
	s_waitcnt lgkmcnt(0)
	s_barrier
	s_setprio 1
	s_waitcnt lgkmcnt(0)
	v_mfma_f32_16x16x32_bf16 v[124:127], v[150:153], v[188:191], v[124:127]
	v_mfma_f32_16x16x32_bf16 v[120:123], v[164:167], v[188:191], v[120:123]
	v_mfma_f32_16x16x32_bf16 v[108:111], v[150:153], v[196:199], v[108:111]
	v_mfma_f32_16x16x32_bf16 v[104:107], v[164:167], v[196:199], v[104:107]
	v_mfma_f32_16x16x32_bf16 v[92:95], v[150:153], v[204:207], v[92:95]
	v_mfma_f32_16x16x32_bf16 v[88:91], v[164:167], v[204:207], v[88:91]
	v_mfma_f32_16x16x32_bf16 v[76:79], v[150:153], v[212:215], v[76:79]
	v_mfma_f32_16x16x32_bf16 v[72:75], v[164:167], v[212:215], v[72:75]
	v_mfma_f32_16x16x32_bf16 v[124:127], v[160:163], v[192:195], v[124:127]
	v_mfma_f32_16x16x32_bf16 v[120:123], v[168:171], v[192:195], v[120:123]
	v_mfma_f32_16x16x32_bf16 v[108:111], v[160:163], v[200:203], v[108:111]
	v_mfma_f32_16x16x32_bf16 v[104:107], v[168:171], v[200:203], v[104:107]
	v_mfma_f32_16x16x32_bf16 v[92:95], v[160:163], v[208:211], v[92:95]
	v_mfma_f32_16x16x32_bf16 v[88:91], v[168:171], v[208:211], v[88:91]
	v_mfma_f32_16x16x32_bf16 v[76:79], v[160:163], v[216:219], v[76:79]
	v_mfma_f32_16x16x32_bf16 v[72:75], v[168:171], v[216:219], v[72:75]
	s_setprio 0
	s_setprio 1
	v_mfma_f32_16x16x32_bf16 v[116:119], v[172:175], v[188:191], v[116:119]
	v_mfma_f32_16x16x32_bf16 v[112:115], v[180:183], v[188:191], v[112:115]
	v_mfma_f32_16x16x32_bf16 v[100:103], v[172:175], v[196:199], v[100:103]
	v_mfma_f32_16x16x32_bf16 v[96:99], v[180:183], v[196:199], v[96:99]
	v_mfma_f32_16x16x32_bf16 v[84:87], v[172:175], v[204:207], v[84:87]
	v_mfma_f32_16x16x32_bf16 v[80:83], v[180:183], v[204:207], v[80:83]
	v_mfma_f32_16x16x32_bf16 v[68:71], v[172:175], v[212:215], v[68:71]
	v_mfma_f32_16x16x32_bf16 v[64:67], v[180:183], v[212:215], v[64:67]
	v_mfma_f32_16x16x32_bf16 v[116:119], v[176:179], v[192:195], v[116:119]
	v_mfma_f32_16x16x32_bf16 v[112:115], v[184:187], v[192:195], v[112:115]
	v_mfma_f32_16x16x32_bf16 v[100:103], v[176:179], v[200:203], v[100:103]
	v_mfma_f32_16x16x32_bf16 v[96:99], v[184:187], v[200:203], v[96:99]
	v_mfma_f32_16x16x32_bf16 v[84:87], v[176:179], v[208:211], v[84:87]
	v_mfma_f32_16x16x32_bf16 v[80:83], v[184:187], v[208:211], v[80:83]
	v_mfma_f32_16x16x32_bf16 v[68:71], v[176:179], v[216:219], v[68:71]
	v_mfma_f32_16x16x32_bf16 v[64:67], v[184:187], v[216:219], v[64:67]
	s_setprio 0
	s_barrier
	s_add_i32 s34, s66, s50
	v_lshl_add_u64 v[220:221], v[220:221], 0, s[26:27]
	s_mov_b32 m0, s34
	ds_read_b128 v[188:191], v159 offset:49152
	ds_read_b128 v[192:195], v159 offset:50176
	ds_read_b128 v[196:199], v159 offset:51200
	ds_read_b128 v[200:203], v159 offset:52224
	ds_read_b128 v[204:207], v159 offset:53248
	ds_read_b128 v[208:211], v159 offset:54272
	ds_read_b128 v[212:215], v159 offset:55296
	ds_read_b128 v[216:219], v159 offset:56320
	global_load_lds_dwordx4 v[220:221], off
	s_add_i32 m0, s34, 0x2000
	s_add_u32 s34, s44, 0x40080
	v_lshl_add_u64 v[220:221], v[222:223], 0, s[26:27]
	s_addc_u32 s35, s45, 0
	s_add_i32 s44, s67, s50
	global_load_lds_dwordx4 v[220:221], off
	v_lshl_add_u64 v[220:221], s[34:35], 0, v[134:135]
	s_mov_b32 m0, s44
	s_nop 0
	global_load_lds_dwordx4 v[220:221], off
	v_lshl_add_u64 v[220:221], s[34:35], 0, v[138:139]
	s_add_i32 m0, s44, 0x2000
	s_nop 0
	global_load_lds_dwordx4 v[220:221], off
	v_lshl_add_u64 v[220:221], v[224:225], 0, s[26:27]
	s_mov_b32 m0, s58
	s_nop 0
	global_load_lds_dwordx4 v[220:221], off
	v_lshl_add_u64 v[220:221], v[226:227], 0, s[26:27]
	s_mov_b32 m0, s59
	s_nop 0
	global_load_lds_dwordx4 v[220:221], off
	s_waitcnt vmcnt(8)
	s_waitcnt lgkmcnt(0)
	s_barrier
	s_add_u32 s42, s42, 0x100
	s_addc_u32 s43, s43, 0
	s_add_u32 s31, s31, 0x100
	s_addc_u32 s37, s37, 0
	s_setprio 1
	s_waitcnt lgkmcnt(0)
	v_mfma_f32_16x16x32_bf16 v[60:63], v[150:153], v[188:191], v[60:63]
	v_mfma_f32_16x16x32_bf16 v[56:59], v[164:167], v[188:191], v[56:59]
	v_mfma_f32_16x16x32_bf16 v[44:47], v[150:153], v[196:199], v[44:47]
	v_mfma_f32_16x16x32_bf16 v[40:43], v[164:167], v[196:199], v[40:43]
	v_mfma_f32_16x16x32_bf16 v[28:31], v[150:153], v[204:207], v[28:31]
	v_mfma_f32_16x16x32_bf16 v[24:27], v[164:167], v[204:207], v[24:27]
	v_mfma_f32_16x16x32_bf16 v[12:15], v[150:153], v[212:215], v[12:15]
	v_mfma_f32_16x16x32_bf16 v[8:11], v[164:167], v[212:215], v[8:11]
	v_mfma_f32_16x16x32_bf16 v[60:63], v[160:163], v[192:195], v[60:63]
	v_mfma_f32_16x16x32_bf16 v[56:59], v[168:171], v[192:195], v[56:59]
	v_mfma_f32_16x16x32_bf16 v[44:47], v[160:163], v[200:203], v[44:47]
	v_mfma_f32_16x16x32_bf16 v[40:43], v[168:171], v[200:203], v[40:43]
	v_mfma_f32_16x16x32_bf16 v[28:31], v[160:163], v[208:211], v[28:31]
	v_mfma_f32_16x16x32_bf16 v[24:27], v[168:171], v[208:211], v[24:27]
	v_mfma_f32_16x16x32_bf16 v[12:15], v[160:163], v[216:219], v[12:15]
	v_mfma_f32_16x16x32_bf16 v[8:11], v[168:171], v[216:219], v[8:11]
	s_setprio 0
	s_setprio 1
	v_mfma_f32_16x16x32_bf16 v[52:55], v[172:175], v[188:191], v[52:55]
	v_mfma_f32_16x16x32_bf16 v[48:51], v[180:183], v[188:191], v[48:51]
	v_mfma_f32_16x16x32_bf16 v[36:39], v[172:175], v[196:199], v[36:39]
	v_mfma_f32_16x16x32_bf16 v[32:35], v[180:183], v[196:199], v[32:35]
	v_mfma_f32_16x16x32_bf16 v[20:23], v[172:175], v[204:207], v[20:23]
	v_mfma_f32_16x16x32_bf16 v[16:19], v[180:183], v[204:207], v[16:19]
	v_mfma_f32_16x16x32_bf16 v[4:7], v[172:175], v[212:215], v[4:7]
	v_mfma_f32_16x16x32_bf16 v[0:3], v[180:183], v[212:215], v[0:3]
	v_mfma_f32_16x16x32_bf16 v[52:55], v[176:179], v[192:195], v[52:55]
	v_mfma_f32_16x16x32_bf16 v[48:51], v[184:187], v[192:195], v[48:51]
	v_mfma_f32_16x16x32_bf16 v[36:39], v[176:179], v[200:203], v[36:39]
	v_mfma_f32_16x16x32_bf16 v[32:35], v[184:187], v[200:203], v[32:35]
	v_mfma_f32_16x16x32_bf16 v[20:23], v[176:179], v[208:211], v[20:23]
	v_mfma_f32_16x16x32_bf16 v[16:19], v[184:187], v[208:211], v[16:19]
	v_mfma_f32_16x16x32_bf16 v[4:7], v[176:179], v[216:219], v[4:7]
	v_mfma_f32_16x16x32_bf16 v[0:3], v[184:187], v[216:219], v[0:3]
	s_setprio 0
	s_barrier
	s_add_i32 s65, s65, 2
.LBB0_1826:
	ds_read_b128 v[150:153], v157
	ds_read_b128 v[160:163], v157 offset:1024
	ds_read_b128 v[164:167], v157 offset:2048
	ds_read_b128 v[168:171], v157 offset:3072
	ds_read_b128 v[172:175], v158
	ds_read_b128 v[176:179], v158 offset:1024
	ds_read_b128 v[180:183], v158 offset:2048
	ds_read_b128 v[184:187], v158 offset:3072
	s_add_u32 s34, s42, 0xfffc0080
	s_addc_u32 s35, s43, -1
	s_cmp_eq_u32 s65, 12
	s_cselect_b32 s47, s7, s35
	s_cselect_b32 s46, s8, s34
	s_cselect_b32 s45, s12, s37
	s_cselect_b32 s44, s13, s31
	v_lshl_add_u64 v[220:221], s[42:43], 0, v[142:143]
	s_add_i32 m0, s53, 0xc000
	ds_read_b128 v[188:191], v159
	ds_read_b128 v[192:195], v159 offset:1024
	ds_read_b128 v[196:199], v159 offset:2048
	ds_read_b128 v[200:203], v159 offset:3072
	ds_read_b128 v[204:207], v159 offset:4096
	ds_read_b128 v[208:211], v159 offset:5120
	ds_read_b128 v[212:215], v159 offset:6144
	ds_read_b128 v[216:219], v159 offset:7168
	global_load_lds_dwordx4 v[220:221], off
	v_lshl_add_u64 v[220:221], s[42:43], 0, v[144:145]
	s_add_i32 m0, s53, 0xe000
	s_nop 0
	global_load_lds_dwordx4 v[220:221], off
	s_waitcnt vmcnt(8)
	s_waitcnt lgkmcnt(0)
	s_barrier
	s_setprio 1
	s_waitcnt lgkmcnt(0)
	v_mfma_f32_16x16x32_bf16 v[124:127], v[150:153], v[188:191], v[124:127]
	v_mfma_f32_16x16x32_bf16 v[120:123], v[164:167], v[188:191], v[120:123]
	v_mfma_f32_16x16x32_bf16 v[108:111], v[150:153], v[196:199], v[108:111]
	v_mfma_f32_16x16x32_bf16 v[104:107], v[164:167], v[196:199], v[104:107]
	v_mfma_f32_16x16x32_bf16 v[92:95], v[150:153], v[204:207], v[92:95]
	v_mfma_f32_16x16x32_bf16 v[88:91], v[164:167], v[204:207], v[88:91]
	v_mfma_f32_16x16x32_bf16 v[76:79], v[150:153], v[212:215], v[76:79]
	v_mfma_f32_16x16x32_bf16 v[72:75], v[164:167], v[212:215], v[72:75]
	v_mfma_f32_16x16x32_bf16 v[124:127], v[160:163], v[192:195], v[124:127]
	v_mfma_f32_16x16x32_bf16 v[120:123], v[168:171], v[192:195], v[120:123]
	v_mfma_f32_16x16x32_bf16 v[108:111], v[160:163], v[200:203], v[108:111]
	v_mfma_f32_16x16x32_bf16 v[104:107], v[168:171], v[200:203], v[104:107]
	v_mfma_f32_16x16x32_bf16 v[92:95], v[160:163], v[208:211], v[92:95]
	v_mfma_f32_16x16x32_bf16 v[88:91], v[168:171], v[208:211], v[88:91]
	v_mfma_f32_16x16x32_bf16 v[76:79], v[160:163], v[216:219], v[76:79]
	v_mfma_f32_16x16x32_bf16 v[72:75], v[168:171], v[216:219], v[72:75]
	s_setprio 0
	s_setprio 1
	v_mfma_f32_16x16x32_bf16 v[116:119], v[172:175], v[188:191], v[116:119]
	v_mfma_f32_16x16x32_bf16 v[112:115], v[180:183], v[188:191], v[112:115]
	v_mfma_f32_16x16x32_bf16 v[100:103], v[172:175], v[196:199], v[100:103]
	v_mfma_f32_16x16x32_bf16 v[96:99], v[180:183], v[196:199], v[96:99]
	v_mfma_f32_16x16x32_bf16 v[84:87], v[172:175], v[204:207], v[84:87]
	v_mfma_f32_16x16x32_bf16 v[80:83], v[180:183], v[204:207], v[80:83]
	v_mfma_f32_16x16x32_bf16 v[68:71], v[172:175], v[212:215], v[68:71]
	v_mfma_f32_16x16x32_bf16 v[64:67], v[180:183], v[212:215], v[64:67]
	v_mfma_f32_16x16x32_bf16 v[116:119], v[176:179], v[192:195], v[116:119]
	v_mfma_f32_16x16x32_bf16 v[112:115], v[184:187], v[192:195], v[112:115]
	v_mfma_f32_16x16x32_bf16 v[100:103], v[176:179], v[200:203], v[100:103]
	v_mfma_f32_16x16x32_bf16 v[96:99], v[184:187], v[200:203], v[96:99]
	v_mfma_f32_16x16x32_bf16 v[84:87], v[176:179], v[208:211], v[84:87]
	v_mfma_f32_16x16x32_bf16 v[80:83], v[184:187], v[208:211], v[80:83]
	v_mfma_f32_16x16x32_bf16 v[68:71], v[176:179], v[216:219], v[68:71]
	v_mfma_f32_16x16x32_bf16 v[64:67], v[184:187], v[216:219], v[64:67]
	s_setprio 0
	s_barrier
	s_add_i32 s34, s61, s50
	v_lshl_add_u64 v[220:221], s[44:45], 0, v[134:135]
	s_mov_b32 m0, s34
	ds_read_b128 v[188:191], v159 offset:16384
	ds_read_b128 v[192:195], v159 offset:17408
	ds_read_b128 v[196:199], v159 offset:18432
	ds_read_b128 v[200:203], v159 offset:19456
	ds_read_b128 v[204:207], v159 offset:20480
	ds_read_b128 v[208:211], v159 offset:21504
	ds_read_b128 v[212:215], v159 offset:22528
	ds_read_b128 v[216:219], v159 offset:23552
	global_load_lds_dwordx4 v[220:221], off
	s_add_i32 m0, s34, 0x2000
	s_add_u32 s34, s44, 0x40000
	v_lshl_add_u64 v[222:223], s[44:45], 0, v[138:139]
	s_addc_u32 s35, s45, 0
	s_add_i32 s66, s62, s50
	global_load_lds_dwordx4 v[222:223], off
	v_lshl_add_u64 v[224:225], s[34:35], 0, v[134:135]
	s_mov_b32 m0, s66
	v_lshl_add_u64 v[226:227], s[46:47], 0, v[136:137]
	global_load_lds_dwordx4 v[224:225], off
	v_lshl_add_u64 v[224:225], s[34:35], 0, v[138:139]
	s_add_i32 m0, s66, 0x2000
	s_nop 0
	global_load_lds_dwordx4 v[224:225], off
	v_lshl_add_u64 v[224:225], s[46:47], 0, v[132:133]
	s_mov_b32 m0, s53
	s_nop 0
	global_load_lds_dwordx4 v[224:225], off
	s_mov_b32 m0, s54
	s_nop 0
	global_load_lds_dwordx4 v[226:227], off
	s_waitcnt vmcnt(8)
	s_waitcnt lgkmcnt(0)
	s_barrier
	s_setprio 1
	s_waitcnt lgkmcnt(0)
	v_mfma_f32_16x16x32_bf16 v[60:63], v[150:153], v[188:191], v[60:63]
	v_mfma_f32_16x16x32_bf16 v[56:59], v[164:167], v[188:191], v[56:59]
	v_mfma_f32_16x16x32_bf16 v[44:47], v[150:153], v[196:199], v[44:47]
	v_mfma_f32_16x16x32_bf16 v[40:43], v[164:167], v[196:199], v[40:43]
	v_mfma_f32_16x16x32_bf16 v[28:31], v[150:153], v[204:207], v[28:31]
	v_mfma_f32_16x16x32_bf16 v[24:27], v[164:167], v[204:207], v[24:27]
	v_mfma_f32_16x16x32_bf16 v[12:15], v[150:153], v[212:215], v[12:15]
	v_mfma_f32_16x16x32_bf16 v[8:11], v[164:167], v[212:215], v[8:11]
	v_mfma_f32_16x16x32_bf16 v[60:63], v[160:163], v[192:195], v[60:63]
	v_mfma_f32_16x16x32_bf16 v[56:59], v[168:171], v[192:195], v[56:59]
	v_mfma_f32_16x16x32_bf16 v[44:47], v[160:163], v[200:203], v[44:47]
	v_mfma_f32_16x16x32_bf16 v[40:43], v[168:171], v[200:203], v[40:43]
	v_mfma_f32_16x16x32_bf16 v[28:31], v[160:163], v[208:211], v[28:31]
	v_mfma_f32_16x16x32_bf16 v[24:27], v[168:171], v[208:211], v[24:27]
	v_mfma_f32_16x16x32_bf16 v[12:15], v[160:163], v[216:219], v[12:15]
	v_mfma_f32_16x16x32_bf16 v[8:11], v[168:171], v[216:219], v[8:11]
	s_setprio 0
	s_setprio 1
	v_mfma_f32_16x16x32_bf16 v[52:55], v[172:175], v[188:191], v[52:55]
	v_mfma_f32_16x16x32_bf16 v[48:51], v[180:183], v[188:191], v[48:51]
	v_mfma_f32_16x16x32_bf16 v[36:39], v[172:175], v[196:199], v[36:39]
	v_mfma_f32_16x16x32_bf16 v[32:35], v[180:183], v[196:199], v[32:35]
	v_mfma_f32_16x16x32_bf16 v[20:23], v[172:175], v[204:207], v[20:23]
	v_mfma_f32_16x16x32_bf16 v[16:19], v[180:183], v[204:207], v[16:19]
	v_mfma_f32_16x16x32_bf16 v[4:7], v[172:175], v[212:215], v[4:7]
	v_mfma_f32_16x16x32_bf16 v[0:3], v[180:183], v[212:215], v[0:3]
	v_mfma_f32_16x16x32_bf16 v[52:55], v[176:179], v[192:195], v[52:55]
	v_mfma_f32_16x16x32_bf16 v[48:51], v[184:187], v[192:195], v[48:51]
	v_mfma_f32_16x16x32_bf16 v[36:39], v[176:179], v[200:203], v[36:39]
	v_mfma_f32_16x16x32_bf16 v[32:35], v[184:187], v[200:203], v[32:35]
	v_mfma_f32_16x16x32_bf16 v[20:23], v[176:179], v[208:211], v[20:23]
	v_mfma_f32_16x16x32_bf16 v[16:19], v[184:187], v[208:211], v[16:19]
	v_mfma_f32_16x16x32_bf16 v[4:7], v[176:179], v[216:219], v[4:7]
	v_mfma_f32_16x16x32_bf16 v[0:3], v[184:187], v[216:219], v[0:3]
	s_setprio 0
	s_barrier
	s_add_i32 s66, 0, 0x18000
	v_add_u32_e32 v140, s66, v154
	s_add_i32 s67, 0, 0x1c000
	ds_read_b128 v[150:153], v140
	ds_read_b128 v[160:163], v140 offset:1024
	ds_read_b128 v[164:167], v140 offset:2048
	ds_read_b128 v[168:171], v140 offset:3072
	v_add_u32_e32 v140, s67, v154
	ds_read_b128 v[172:175], v140
	ds_read_b128 v[176:179], v140 offset:1024
	ds_read_b128 v[180:183], v140 offset:2048
	ds_read_b128 v[184:187], v140 offset:3072
	s_add_u32 s34, s46, 0x40000
	s_addc_u32 s35, s47, 0
	s_mov_b32 m0, s55
	v_lshl_add_u64 v[228:229], s[34:35], 0, v[132:133]
	ds_read_b128 v[188:191], v159 offset:32768
	ds_read_b128 v[192:195], v159 offset:33792
	ds_read_b128 v[196:199], v159 offset:34816
	ds_read_b128 v[200:203], v159 offset:35840
	ds_read_b128 v[204:207], v159 offset:36864
	ds_read_b128 v[208:211], v159 offset:37888
	ds_read_b128 v[212:215], v159 offset:38912
	ds_read_b128 v[216:219], v159 offset:39936
	global_load_lds_dwordx4 v[228:229], off
	v_lshl_add_u64 v[228:229], s[34:35], 0, v[136:137]
	s_mov_b32 m0, s56
	s_nop 0
	global_load_lds_dwordx4 v[228:229], off
	s_waitcnt vmcnt(8)
	s_waitcnt lgkmcnt(0)
	s_barrier
	s_setprio 1
	s_waitcnt lgkmcnt(0)
	v_mfma_f32_16x16x32_bf16 v[124:127], v[150:153], v[188:191], v[124:127]
	v_mfma_f32_16x16x32_bf16 v[120:123], v[164:167], v[188:191], v[120:123]
	v_mfma_f32_16x16x32_bf16 v[108:111], v[150:153], v[196:199], v[108:111]
	v_mfma_f32_16x16x32_bf16 v[104:107], v[164:167], v[196:199], v[104:107]
	v_mfma_f32_16x16x32_bf16 v[92:95], v[150:153], v[204:207], v[92:95]
	v_mfma_f32_16x16x32_bf16 v[88:91], v[164:167], v[204:207], v[88:91]
	v_mfma_f32_16x16x32_bf16 v[76:79], v[150:153], v[212:215], v[76:79]
	v_mfma_f32_16x16x32_bf16 v[72:75], v[164:167], v[212:215], v[72:75]
	v_mfma_f32_16x16x32_bf16 v[124:127], v[160:163], v[192:195], v[124:127]
	v_mfma_f32_16x16x32_bf16 v[120:123], v[168:171], v[192:195], v[120:123]
	v_mfma_f32_16x16x32_bf16 v[108:111], v[160:163], v[200:203], v[108:111]
	v_mfma_f32_16x16x32_bf16 v[104:107], v[168:171], v[200:203], v[104:107]
	v_mfma_f32_16x16x32_bf16 v[92:95], v[160:163], v[208:211], v[92:95]
	v_mfma_f32_16x16x32_bf16 v[88:91], v[168:171], v[208:211], v[88:91]
	v_mfma_f32_16x16x32_bf16 v[76:79], v[160:163], v[216:219], v[76:79]
	v_mfma_f32_16x16x32_bf16 v[72:75], v[168:171], v[216:219], v[72:75]
	s_setprio 0
	s_setprio 1
	v_mfma_f32_16x16x32_bf16 v[116:119], v[172:175], v[188:191], v[116:119]
	v_mfma_f32_16x16x32_bf16 v[112:115], v[180:183], v[188:191], v[112:115]
	v_mfma_f32_16x16x32_bf16 v[100:103], v[172:175], v[196:199], v[100:103]
	v_mfma_f32_16x16x32_bf16 v[96:99], v[180:183], v[196:199], v[96:99]
	v_mfma_f32_16x16x32_bf16 v[84:87], v[172:175], v[204:207], v[84:87]
	v_mfma_f32_16x16x32_bf16 v[80:83], v[180:183], v[204:207], v[80:83]
	v_mfma_f32_16x16x32_bf16 v[68:71], v[172:175], v[212:215], v[68:71]
	v_mfma_f32_16x16x32_bf16 v[64:67], v[180:183], v[212:215], v[64:67]
	v_mfma_f32_16x16x32_bf16 v[116:119], v[176:179], v[192:195], v[116:119]
	v_mfma_f32_16x16x32_bf16 v[112:115], v[184:187], v[192:195], v[112:115]
	v_mfma_f32_16x16x32_bf16 v[100:103], v[176:179], v[200:203], v[100:103]
	v_mfma_f32_16x16x32_bf16 v[96:99], v[184:187], v[200:203], v[96:99]
	v_mfma_f32_16x16x32_bf16 v[84:87], v[176:179], v[208:211], v[84:87]
	v_mfma_f32_16x16x32_bf16 v[80:83], v[184:187], v[208:211], v[80:83]
	v_mfma_f32_16x16x32_bf16 v[68:71], v[176:179], v[216:219], v[68:71]
	v_mfma_f32_16x16x32_bf16 v[64:67], v[184:187], v[216:219], v[64:67]
	s_setprio 0
	s_barrier
	s_add_i32 s34, s66, s50
	v_lshl_add_u64 v[220:221], v[220:221], 0, s[26:27]
	s_mov_b32 m0, s34
	ds_read_b128 v[188:191], v159 offset:49152
	ds_read_b128 v[192:195], v159 offset:50176
	ds_read_b128 v[196:199], v159 offset:51200
	ds_read_b128 v[200:203], v159 offset:52224
	ds_read_b128 v[204:207], v159 offset:53248
	ds_read_b128 v[208:211], v159 offset:54272
	ds_read_b128 v[212:215], v159 offset:55296
	ds_read_b128 v[216:219], v159 offset:56320
	global_load_lds_dwordx4 v[220:221], off
	s_add_i32 m0, s34, 0x2000
	s_add_u32 s34, s44, 0x40080
	v_lshl_add_u64 v[220:221], v[222:223], 0, s[26:27]
	s_addc_u32 s35, s45, 0
	s_add_i32 s44, s67, s50
	global_load_lds_dwordx4 v[220:221], off
	v_lshl_add_u64 v[220:221], s[34:35], 0, v[134:135]
	s_mov_b32 m0, s44
	s_nop 0
	global_load_lds_dwordx4 v[220:221], off
	v_lshl_add_u64 v[220:221], s[34:35], 0, v[138:139]
	s_add_i32 m0, s44, 0x2000
	s_nop 0
	global_load_lds_dwordx4 v[220:221], off
	v_lshl_add_u64 v[220:221], v[224:225], 0, s[26:27]
	s_mov_b32 m0, s58
	s_nop 0
	global_load_lds_dwordx4 v[220:221], off
	v_lshl_add_u64 v[220:221], v[226:227], 0, s[26:27]
	s_mov_b32 m0, s59
	s_nop 0
	global_load_lds_dwordx4 v[220:221], off
	s_waitcnt vmcnt(8)
	s_waitcnt lgkmcnt(0)
	s_barrier
	s_add_u32 s42, s42, 0x100
	s_addc_u32 s43, s43, 0
	s_add_u32 s31, s31, 0x100
	s_addc_u32 s37, s37, 0
	s_setprio 1
	s_waitcnt lgkmcnt(0)
	v_mfma_f32_16x16x32_bf16 v[60:63], v[150:153], v[188:191], v[60:63]
	v_mfma_f32_16x16x32_bf16 v[56:59], v[164:167], v[188:191], v[56:59]
	v_mfma_f32_16x16x32_bf16 v[44:47], v[150:153], v[196:199], v[44:47]
	v_mfma_f32_16x16x32_bf16 v[40:43], v[164:167], v[196:199], v[40:43]
	v_mfma_f32_16x16x32_bf16 v[28:31], v[150:153], v[204:207], v[28:31]
	v_mfma_f32_16x16x32_bf16 v[24:27], v[164:167], v[204:207], v[24:27]
	v_mfma_f32_16x16x32_bf16 v[12:15], v[150:153], v[212:215], v[12:15]
	v_mfma_f32_16x16x32_bf16 v[8:11], v[164:167], v[212:215], v[8:11]
	v_mfma_f32_16x16x32_bf16 v[60:63], v[160:163], v[192:195], v[60:63]
	v_mfma_f32_16x16x32_bf16 v[56:59], v[168:171], v[192:195], v[56:59]
	v_mfma_f32_16x16x32_bf16 v[44:47], v[160:163], v[200:203], v[44:47]
	v_mfma_f32_16x16x32_bf16 v[40:43], v[168:171], v[200:203], v[40:43]
	v_mfma_f32_16x16x32_bf16 v[28:31], v[160:163], v[208:211], v[28:31]
	v_mfma_f32_16x16x32_bf16 v[24:27], v[168:171], v[208:211], v[24:27]
	v_mfma_f32_16x16x32_bf16 v[12:15], v[160:163], v[216:219], v[12:15]
	v_mfma_f32_16x16x32_bf16 v[8:11], v[168:171], v[216:219], v[8:11]
	s_setprio 0
	s_setprio 1
	v_mfma_f32_16x16x32_bf16 v[52:55], v[172:175], v[188:191], v[52:55]
	v_mfma_f32_16x16x32_bf16 v[48:51], v[180:183], v[188:191], v[48:51]
	v_mfma_f32_16x16x32_bf16 v[36:39], v[172:175], v[196:199], v[36:39]
	v_mfma_f32_16x16x32_bf16 v[32:35], v[180:183], v[196:199], v[32:35]
	v_mfma_f32_16x16x32_bf16 v[20:23], v[172:175], v[204:207], v[20:23]
	v_mfma_f32_16x16x32_bf16 v[16:19], v[180:183], v[204:207], v[16:19]
	v_mfma_f32_16x16x32_bf16 v[4:7], v[172:175], v[212:215], v[4:7]
	v_mfma_f32_16x16x32_bf16 v[0:3], v[180:183], v[212:215], v[0:3]
	v_mfma_f32_16x16x32_bf16 v[52:55], v[176:179], v[192:195], v[52:55]
	v_mfma_f32_16x16x32_bf16 v[48:51], v[184:187], v[192:195], v[48:51]
	v_mfma_f32_16x16x32_bf16 v[36:39], v[176:179], v[200:203], v[36:39]
	v_mfma_f32_16x16x32_bf16 v[32:35], v[184:187], v[200:203], v[32:35]
	v_mfma_f32_16x16x32_bf16 v[20:23], v[176:179], v[208:211], v[20:23]
	v_mfma_f32_16x16x32_bf16 v[16:19], v[184:187], v[208:211], v[16:19]
	v_mfma_f32_16x16x32_bf16 v[4:7], v[176:179], v[216:219], v[4:7]
	v_mfma_f32_16x16x32_bf16 v[0:3], v[184:187], v[216:219], v[0:3]
	s_setprio 0
	s_cmp_eq_u32 s65, s98
	s_cbranch_scc1 .Lmy_nobar_19
	s_barrier
.Lmy_nobar_19:
	s_add_i32 s65, s65, 2
	s_cmp_gt_u32 s65, 13
	s_cbranch_scc0 .LBB0_1826
	s_and_b64 vcc, exec, s[28:29]
	s_cbranch_vccz .LBB0_1829
	s_nop 0

.Lmy_nobar2_21:
	ds_read_b128 v[146:149], v153
	ds_read_b128 v[158:161], v153 offset:1024
	ds_read_b128 v[162:165], v153 offset:2048
	ds_read_b128 v[166:169], v153 offset:3072
	ds_read_b128 v[170:173], v154
	ds_read_b128 v[174:177], v154 offset:1024
	ds_read_b128 v[178:181], v154 offset:2048
	ds_read_b128 v[182:185], v154 offset:3072
	s_add_u32 s34, s38, 0xfffc0080
	s_addc_u32 s35, s39, -1
	s_cmp_eq_u32 s60, 12
	s_cselect_b32 s43, s12, s35
	s_cselect_b32 s42, s13, s34
	s_cselect_b32 s41, s25, s59
	s_cselect_b32 s40, s27, s37
	v_lshl_add_u64 v[218:219], s[38:39], 0, v[138:139]
	s_add_i32 m0, s46, 0xc000
	ds_read_b128 v[186:189], v155
	ds_read_b128 v[190:193], v155 offset:1024
	ds_read_b128 v[194:197], v155 offset:2048
	ds_read_b128 v[198:201], v155 offset:3072
	ds_read_b128 v[202:205], v155 offset:4096
	ds_read_b128 v[206:209], v155 offset:5120
	ds_read_b128 v[210:213], v155 offset:6144
	ds_read_b128 v[214:217], v155 offset:7168
	global_load_lds_dwordx4 v[218:219], off
	v_lshl_add_u64 v[218:219], s[38:39], 0, v[140:141]
	s_add_i32 m0, s46, 0xe000
	s_nop 0
	global_load_lds_dwordx4 v[218:219], off
	s_waitcnt vmcnt(8)
	s_waitcnt lgkmcnt(0)
	s_barrier
	s_setprio 1
	s_waitcnt lgkmcnt(0)
	v_mfma_f32_16x16x32_bf16 v[124:127], v[146:149], v[186:189], 0
	v_mfma_f32_16x16x32_bf16 v[120:123], v[162:165], v[186:189], 0
	v_mfma_f32_16x16x32_bf16 v[108:111], v[146:149], v[194:197], 0
	v_mfma_f32_16x16x32_bf16 v[104:107], v[162:165], v[194:197], 0
	v_mfma_f32_16x16x32_bf16 v[92:95], v[146:149], v[202:205], 0
	v_mfma_f32_16x16x32_bf16 v[88:91], v[162:165], v[202:205], 0
	v_mfma_f32_16x16x32_bf16 v[76:79], v[146:149], v[210:213], 0
	v_mfma_f32_16x16x32_bf16 v[72:75], v[162:165], v[210:213], 0
	v_mfma_f32_16x16x32_bf16 v[124:127], v[158:161], v[190:193], v[124:127]
	v_mfma_f32_16x16x32_bf16 v[120:123], v[166:169], v[190:193], v[120:123]
	v_mfma_f32_16x16x32_bf16 v[108:111], v[158:161], v[198:201], v[108:111]
	v_mfma_f32_16x16x32_bf16 v[104:107], v[166:169], v[198:201], v[104:107]
	v_mfma_f32_16x16x32_bf16 v[92:95], v[158:161], v[206:209], v[92:95]
	v_mfma_f32_16x16x32_bf16 v[88:91], v[166:169], v[206:209], v[88:91]
	v_mfma_f32_16x16x32_bf16 v[76:79], v[158:161], v[214:217], v[76:79]
	v_mfma_f32_16x16x32_bf16 v[72:75], v[166:169], v[214:217], v[72:75]
	s_setprio 0
	s_setprio 1
	v_mfma_f32_16x16x32_bf16 v[116:119], v[170:173], v[186:189], 0
	v_mfma_f32_16x16x32_bf16 v[112:115], v[178:181], v[186:189], 0
	v_mfma_f32_16x16x32_bf16 v[100:103], v[170:173], v[194:197], 0
	v_mfma_f32_16x16x32_bf16 v[96:99], v[178:181], v[194:197], 0
	v_mfma_f32_16x16x32_bf16 v[84:87], v[170:173], v[202:205], 0
	v_mfma_f32_16x16x32_bf16 v[80:83], v[178:181], v[202:205], 0
	v_mfma_f32_16x16x32_bf16 v[68:71], v[170:173], v[210:213], 0
	v_mfma_f32_16x16x32_bf16 v[64:67], v[178:181], v[210:213], 0
	v_mfma_f32_16x16x32_bf16 v[116:119], v[174:177], v[190:193], v[116:119]
	v_mfma_f32_16x16x32_bf16 v[112:115], v[182:185], v[190:193], v[112:115]
	v_mfma_f32_16x16x32_bf16 v[100:103], v[174:177], v[198:201], v[100:103]
	v_mfma_f32_16x16x32_bf16 v[96:99], v[182:185], v[198:201], v[96:99]
	v_mfma_f32_16x16x32_bf16 v[84:87], v[174:177], v[206:209], v[84:87]
	v_mfma_f32_16x16x32_bf16 v[80:83], v[182:185], v[206:209], v[80:83]
	v_mfma_f32_16x16x32_bf16 v[68:71], v[174:177], v[214:217], v[68:71]
	v_mfma_f32_16x16x32_bf16 v[64:67], v[182:185], v[214:217], v[64:67]
	s_setprio 0
	s_barrier
	s_add_i32 s34, s56, s45
	v_lshl_add_u64 v[218:219], s[40:41], 0, v[132:133]
	s_mov_b32 m0, s34
	ds_read_b128 v[186:189], v155 offset:16384
	ds_read_b128 v[190:193], v155 offset:17408
	ds_read_b128 v[194:197], v155 offset:18432
	ds_read_b128 v[198:201], v155 offset:19456
	ds_read_b128 v[202:205], v155 offset:20480
	ds_read_b128 v[206:209], v155 offset:21504
	ds_read_b128 v[210:213], v155 offset:22528
	ds_read_b128 v[214:217], v155 offset:23552
	global_load_lds_dwordx4 v[218:219], off
	s_add_i32 m0, s34, 0x2000
	s_add_u32 s34, s40, 0x40000
	v_lshl_add_u64 v[220:221], s[40:41], 0, v[136:137]
	s_addc_u32 s35, s41, 0
	s_add_i32 s61, s57, s45
	global_load_lds_dwordx4 v[220:221], off
	v_lshl_add_u64 v[222:223], s[34:35], 0, v[132:133]
	s_mov_b32 m0, s61
	v_lshl_add_u64 v[224:225], s[42:43], 0, v[134:135]
	global_load_lds_dwordx4 v[222:223], off
	v_lshl_add_u64 v[222:223], s[34:35], 0, v[136:137]
	s_add_i32 m0, s61, 0x2000
	s_nop 0
	global_load_lds_dwordx4 v[222:223], off
	v_lshl_add_u64 v[222:223], s[42:43], 0, v[130:131]
	s_mov_b32 m0, s46
	s_nop 0
	global_load_lds_dwordx4 v[222:223], off
	s_mov_b32 m0, s47
	s_nop 0
	global_load_lds_dwordx4 v[224:225], off
	s_waitcnt vmcnt(8)
	s_waitcnt lgkmcnt(0)
	s_barrier
	s_setprio 1
	s_waitcnt lgkmcnt(0)
	v_mfma_f32_16x16x32_bf16 v[60:63], v[146:149], v[186:189], 0
	v_mfma_f32_16x16x32_bf16 v[56:59], v[162:165], v[186:189], 0
	v_mfma_f32_16x16x32_bf16 v[44:47], v[146:149], v[194:197], 0
	v_mfma_f32_16x16x32_bf16 v[40:43], v[162:165], v[194:197], 0
	v_mfma_f32_16x16x32_bf16 v[28:31], v[146:149], v[202:205], 0
	v_mfma_f32_16x16x32_bf16 v[24:27], v[162:165], v[202:205], 0
	v_mfma_f32_16x16x32_bf16 v[12:15], v[146:149], v[210:213], 0
	v_mfma_f32_16x16x32_bf16 v[8:11], v[162:165], v[210:213], 0
	v_mfma_f32_16x16x32_bf16 v[60:63], v[158:161], v[190:193], v[60:63]
	v_mfma_f32_16x16x32_bf16 v[56:59], v[166:169], v[190:193], v[56:59]
	v_mfma_f32_16x16x32_bf16 v[44:47], v[158:161], v[198:201], v[44:47]
	v_mfma_f32_16x16x32_bf16 v[40:43], v[166:169], v[198:201], v[40:43]
	v_mfma_f32_16x16x32_bf16 v[28:31], v[158:161], v[206:209], v[28:31]
	v_mfma_f32_16x16x32_bf16 v[24:27], v[166:169], v[206:209], v[24:27]
	v_mfma_f32_16x16x32_bf16 v[12:15], v[158:161], v[214:217], v[12:15]
	v_mfma_f32_16x16x32_bf16 v[8:11], v[166:169], v[214:217], v[8:11]
	s_setprio 0
	s_setprio 1
	v_mfma_f32_16x16x32_bf16 v[52:55], v[170:173], v[186:189], 0
	v_mfma_f32_16x16x32_bf16 v[48:51], v[178:181], v[186:189], 0
	v_mfma_f32_16x16x32_bf16 v[36:39], v[170:173], v[194:197], 0
	v_mfma_f32_16x16x32_bf16 v[32:35], v[178:181], v[194:197], 0
	v_mfma_f32_16x16x32_bf16 v[20:23], v[170:173], v[202:205], 0
	v_mfma_f32_16x16x32_bf16 v[16:19], v[178:181], v[202:205], 0
	v_mfma_f32_16x16x32_bf16 v[4:7], v[170:173], v[210:213], 0
	v_mfma_f32_16x16x32_bf16 v[0:3], v[178:181], v[210:213], 0
	v_mfma_f32_16x16x32_bf16 v[52:55], v[174:177], v[190:193], v[52:55]
	v_mfma_f32_16x16x32_bf16 v[48:51], v[182:185], v[190:193], v[48:51]
	v_mfma_f32_16x16x32_bf16 v[36:39], v[174:177], v[198:201], v[36:39]
	v_mfma_f32_16x16x32_bf16 v[32:35], v[182:185], v[198:201], v[32:35]
	v_mfma_f32_16x16x32_bf16 v[20:23], v[174:177], v[206:209], v[20:23]
	v_mfma_f32_16x16x32_bf16 v[16:19], v[182:185], v[206:209], v[16:19]
	v_mfma_f32_16x16x32_bf16 v[4:7], v[174:177], v[214:217], v[4:7]
	v_mfma_f32_16x16x32_bf16 v[0:3], v[182:185], v[214:217], v[0:3]
	s_setprio 0
	s_barrier
	s_add_i32 s61, 0, 0x18000
	v_add_u32_e32 v157, s61, v151
	s_add_i32 s62, 0, 0x1c000
	ds_read_b128 v[146:149], v157
	ds_read_b128 v[158:161], v157 offset:1024
	ds_read_b128 v[162:165], v157 offset:2048
	ds_read_b128 v[166:169], v157 offset:3072
	v_add_u32_e32 v157, s62, v151
	ds_read_b128 v[170:173], v157
	ds_read_b128 v[174:177], v157 offset:1024
	ds_read_b128 v[178:181], v157 offset:2048
	ds_read_b128 v[182:185], v157 offset:3072
	s_add_u32 s34, s42, 0x40000
	s_addc_u32 s35, s43, 0
	s_mov_b32 m0, s48
	v_lshl_add_u64 v[226:227], s[34:35], 0, v[130:131]
	ds_read_b128 v[186:189], v155 offset:32768
	ds_read_b128 v[190:193], v155 offset:33792
	ds_read_b128 v[194:197], v155 offset:34816
	ds_read_b128 v[198:201], v155 offset:35840
	ds_read_b128 v[202:205], v155 offset:36864
	ds_read_b128 v[206:209], v155 offset:37888
	ds_read_b128 v[210:213], v155 offset:38912
	ds_read_b128 v[214:217], v155 offset:39936
	global_load_lds_dwordx4 v[226:227], off
	v_lshl_add_u64 v[226:227], s[34:35], 0, v[134:135]
	s_mov_b32 m0, s49
	s_nop 0
	global_load_lds_dwordx4 v[226:227], off
	s_waitcnt vmcnt(8)
	s_waitcnt lgkmcnt(0)
	s_barrier
	s_setprio 1
	s_waitcnt lgkmcnt(0)
	v_mfma_f32_16x16x32_bf16 v[124:127], v[146:149], v[186:189], v[124:127]
	v_mfma_f32_16x16x32_bf16 v[120:123], v[162:165], v[186:189], v[120:123]
	v_mfma_f32_16x16x32_bf16 v[108:111], v[146:149], v[194:197], v[108:111]
	v_mfma_f32_16x16x32_bf16 v[104:107], v[162:165], v[194:197], v[104:107]
	v_mfma_f32_16x16x32_bf16 v[92:95], v[146:149], v[202:205], v[92:95]
	v_mfma_f32_16x16x32_bf16 v[88:91], v[162:165], v[202:205], v[88:91]
	v_mfma_f32_16x16x32_bf16 v[76:79], v[146:149], v[210:213], v[76:79]
	v_mfma_f32_16x16x32_bf16 v[72:75], v[162:165], v[210:213], v[72:75]
	v_mfma_f32_16x16x32_bf16 v[124:127], v[158:161], v[190:193], v[124:127]
	v_mfma_f32_16x16x32_bf16 v[120:123], v[166:169], v[190:193], v[120:123]
	v_mfma_f32_16x16x32_bf16 v[108:111], v[158:161], v[198:201], v[108:111]
	v_mfma_f32_16x16x32_bf16 v[104:107], v[166:169], v[198:201], v[104:107]
	v_mfma_f32_16x16x32_bf16 v[92:95], v[158:161], v[206:209], v[92:95]
	v_mfma_f32_16x16x32_bf16 v[88:91], v[166:169], v[206:209], v[88:91]
	v_mfma_f32_16x16x32_bf16 v[76:79], v[158:161], v[214:217], v[76:79]
	v_mfma_f32_16x16x32_bf16 v[72:75], v[166:169], v[214:217], v[72:75]
	s_setprio 0
	s_setprio 1
	v_mfma_f32_16x16x32_bf16 v[116:119], v[170:173], v[186:189], v[116:119]
	v_mfma_f32_16x16x32_bf16 v[112:115], v[178:181], v[186:189], v[112:115]
	v_mfma_f32_16x16x32_bf16 v[100:103], v[170:173], v[194:197], v[100:103]
	v_mfma_f32_16x16x32_bf16 v[96:99], v[178:181], v[194:197], v[96:99]
	v_mfma_f32_16x16x32_bf16 v[84:87], v[170:173], v[202:205], v[84:87]
	v_mfma_f32_16x16x32_bf16 v[80:83], v[178:181], v[202:205], v[80:83]
	v_mfma_f32_16x16x32_bf16 v[68:71], v[170:173], v[210:213], v[68:71]
	v_mfma_f32_16x16x32_bf16 v[64:67], v[178:181], v[210:213], v[64:67]
	v_mfma_f32_16x16x32_bf16 v[116:119], v[174:177], v[190:193], v[116:119]
	v_mfma_f32_16x16x32_bf16 v[112:115], v[182:185], v[190:193], v[112:115]
	v_mfma_f32_16x16x32_bf16 v[100:103], v[174:177], v[198:201], v[100:103]
	v_mfma_f32_16x16x32_bf16 v[96:99], v[182:185], v[198:201], v[96:99]
	v_mfma_f32_16x16x32_bf16 v[84:87], v[174:177], v[206:209], v[84:87]
	v_mfma_f32_16x16x32_bf16 v[80:83], v[182:185], v[206:209], v[80:83]
	v_mfma_f32_16x16x32_bf16 v[68:71], v[174:177], v[214:217], v[68:71]
	v_mfma_f32_16x16x32_bf16 v[64:67], v[182:185], v[214:217], v[64:67]
	s_setprio 0
	s_barrier
	s_add_i32 s34, s61, s45
	v_lshl_add_u64 v[218:219], v[218:219], 0, s[10:11]
	s_mov_b32 m0, s34
	ds_read_b128 v[186:189], v155 offset:49152
	ds_read_b128 v[190:193], v155 offset:50176
	ds_read_b128 v[194:197], v155 offset:51200
	ds_read_b128 v[198:201], v155 offset:52224
	ds_read_b128 v[202:205], v155 offset:53248
	ds_read_b128 v[206:209], v155 offset:54272
	ds_read_b128 v[210:213], v155 offset:55296
	ds_read_b128 v[214:217], v155 offset:56320
	global_load_lds_dwordx4 v[218:219], off
	s_add_i32 m0, s34, 0x2000
	s_add_u32 s34, s40, 0x40080
	v_lshl_add_u64 v[218:219], v[220:221], 0, s[10:11]
	s_addc_u32 s35, s41, 0
	s_add_i32 s40, s62, s45
	global_load_lds_dwordx4 v[218:219], off
	v_lshl_add_u64 v[218:219], s[34:35], 0, v[132:133]
	s_mov_b32 m0, s40
	s_nop 0
	global_load_lds_dwordx4 v[218:219], off
	v_lshl_add_u64 v[218:219], s[34:35], 0, v[136:137]
	s_add_i32 m0, s40, 0x2000
	s_nop 0
	global_load_lds_dwordx4 v[218:219], off
	v_lshl_add_u64 v[218:219], v[222:223], 0, s[10:11]
	s_mov_b32 m0, s51
	s_nop 0
	global_load_lds_dwordx4 v[218:219], off
	v_lshl_add_u64 v[218:219], v[224:225], 0, s[10:11]
	s_mov_b32 m0, s52
	s_nop 0
	global_load_lds_dwordx4 v[218:219], off
	s_waitcnt vmcnt(8)
	s_waitcnt lgkmcnt(0)
	s_barrier
	s_add_u32 s38, s38, 0x100
	s_addc_u32 s39, s39, 0
	s_add_u32 s37, s37, 0x100
	s_addc_u32 s59, s59, 0
	s_setprio 1
	s_waitcnt lgkmcnt(0)
	v_mfma_f32_16x16x32_bf16 v[60:63], v[146:149], v[186:189], v[60:63]
	v_mfma_f32_16x16x32_bf16 v[56:59], v[162:165], v[186:189], v[56:59]
	v_mfma_f32_16x16x32_bf16 v[44:47], v[146:149], v[194:197], v[44:47]
	v_mfma_f32_16x16x32_bf16 v[40:43], v[162:165], v[194:197], v[40:43]
	v_mfma_f32_16x16x32_bf16 v[28:31], v[146:149], v[202:205], v[28:31]
	v_mfma_f32_16x16x32_bf16 v[24:27], v[162:165], v[202:205], v[24:27]
	v_mfma_f32_16x16x32_bf16 v[12:15], v[146:149], v[210:213], v[12:15]
	v_mfma_f32_16x16x32_bf16 v[8:11], v[162:165], v[210:213], v[8:11]
	v_mfma_f32_16x16x32_bf16 v[60:63], v[158:161], v[190:193], v[60:63]
	v_mfma_f32_16x16x32_bf16 v[56:59], v[166:169], v[190:193], v[56:59]
	v_mfma_f32_16x16x32_bf16 v[44:47], v[158:161], v[198:201], v[44:47]
	v_mfma_f32_16x16x32_bf16 v[40:43], v[166:169], v[198:201], v[40:43]
	v_mfma_f32_16x16x32_bf16 v[28:31], v[158:161], v[206:209], v[28:31]
	v_mfma_f32_16x16x32_bf16 v[24:27], v[166:169], v[206:209], v[24:27]
	v_mfma_f32_16x16x32_bf16 v[12:15], v[158:161], v[214:217], v[12:15]
	v_mfma_f32_16x16x32_bf16 v[8:11], v[166:169], v[214:217], v[8:11]
	s_setprio 0
	s_setprio 1
	v_mfma_f32_16x16x32_bf16 v[52:55], v[170:173], v[186:189], v[52:55]
	v_mfma_f32_16x16x32_bf16 v[48:51], v[178:181], v[186:189], v[48:51]
	v_mfma_f32_16x16x32_bf16 v[36:39], v[170:173], v[194:197], v[36:39]
	v_mfma_f32_16x16x32_bf16 v[32:35], v[178:181], v[194:197], v[32:35]
	v_mfma_f32_16x16x32_bf16 v[20:23], v[170:173], v[202:205], v[20:23]
	v_mfma_f32_16x16x32_bf16 v[16:19], v[178:181], v[202:205], v[16:19]
	v_mfma_f32_16x16x32_bf16 v[4:7], v[170:173], v[210:213], v[4:7]
	v_mfma_f32_16x16x32_bf16 v[0:3], v[178:181], v[210:213], v[0:3]
	v_mfma_f32_16x16x32_bf16 v[52:55], v[174:177], v[190:193], v[52:55]
	v_mfma_f32_16x16x32_bf16 v[48:51], v[182:185], v[190:193], v[48:51]
	v_mfma_f32_16x16x32_bf16 v[36:39], v[174:177], v[198:201], v[36:39]
	v_mfma_f32_16x16x32_bf16 v[32:35], v[182:185], v[198:201], v[32:35]
	v_mfma_f32_16x16x32_bf16 v[20:23], v[174:177], v[206:209], v[20:23]
	v_mfma_f32_16x16x32_bf16 v[16:19], v[182:185], v[206:209], v[16:19]
	v_mfma_f32_16x16x32_bf16 v[4:7], v[174:177], v[214:217], v[4:7]
	v_mfma_f32_16x16x32_bf16 v[0:3], v[182:185], v[214:217], v[0:3]
	s_setprio 0
	s_barrier
	s_add_i32 s60, s60, 2
.LBB0_2001:
	ds_read_b128 v[146:149], v153
	ds_read_b128 v[158:161], v153 offset:1024
	ds_read_b128 v[162:165], v153 offset:2048
	ds_read_b128 v[166:169], v153 offset:3072
	ds_read_b128 v[170:173], v154
	ds_read_b128 v[174:177], v154 offset:1024
	ds_read_b128 v[178:181], v154 offset:2048
	ds_read_b128 v[182:185], v154 offset:3072
	s_add_u32 s34, s38, 0xfffc0080
	s_addc_u32 s35, s39, -1
	s_cmp_eq_u32 s60, 12
	s_cselect_b32 s43, s12, s35
	s_cselect_b32 s42, s13, s34
	s_cselect_b32 s41, s25, s59
	s_cselect_b32 s40, s27, s37
	v_lshl_add_u64 v[218:219], s[38:39], 0, v[138:139]
	s_add_i32 m0, s46, 0xc000
	ds_read_b128 v[186:189], v155
	ds_read_b128 v[190:193], v155 offset:1024
	ds_read_b128 v[194:197], v155 offset:2048
	ds_read_b128 v[198:201], v155 offset:3072
	ds_read_b128 v[202:205], v155 offset:4096
	ds_read_b128 v[206:209], v155 offset:5120
	ds_read_b128 v[210:213], v155 offset:6144
	ds_read_b128 v[214:217], v155 offset:7168
	global_load_lds_dwordx4 v[218:219], off
	v_lshl_add_u64 v[218:219], s[38:39], 0, v[140:141]
	s_add_i32 m0, s46, 0xe000
	s_nop 0
	global_load_lds_dwordx4 v[218:219], off
	s_waitcnt vmcnt(8)
	s_waitcnt lgkmcnt(0)
	s_barrier
	s_setprio 1
	s_waitcnt lgkmcnt(0)
	v_mfma_f32_16x16x32_bf16 v[124:127], v[146:149], v[186:189], v[124:127]
	v_mfma_f32_16x16x32_bf16 v[120:123], v[162:165], v[186:189], v[120:123]
	v_mfma_f32_16x16x32_bf16 v[108:111], v[146:149], v[194:197], v[108:111]
	v_mfma_f32_16x16x32_bf16 v[104:107], v[162:165], v[194:197], v[104:107]
	v_mfma_f32_16x16x32_bf16 v[92:95], v[146:149], v[202:205], v[92:95]
	v_mfma_f32_16x16x32_bf16 v[88:91], v[162:165], v[202:205], v[88:91]
	v_mfma_f32_16x16x32_bf16 v[76:79], v[146:149], v[210:213], v[76:79]
	v_mfma_f32_16x16x32_bf16 v[72:75], v[162:165], v[210:213], v[72:75]
	v_mfma_f32_16x16x32_bf16 v[124:127], v[158:161], v[190:193], v[124:127]
	v_mfma_f32_16x16x32_bf16 v[120:123], v[166:169], v[190:193], v[120:123]
	v_mfma_f32_16x16x32_bf16 v[108:111], v[158:161], v[198:201], v[108:111]
	v_mfma_f32_16x16x32_bf16 v[104:107], v[166:169], v[198:201], v[104:107]
	v_mfma_f32_16x16x32_bf16 v[92:95], v[158:161], v[206:209], v[92:95]
	v_mfma_f32_16x16x32_bf16 v[88:91], v[166:169], v[206:209], v[88:91]
	v_mfma_f32_16x16x32_bf16 v[76:79], v[158:161], v[214:217], v[76:79]
	v_mfma_f32_16x16x32_bf16 v[72:75], v[166:169], v[214:217], v[72:75]
	s_setprio 0
	s_setprio 1
	v_mfma_f32_16x16x32_bf16 v[116:119], v[170:173], v[186:189], v[116:119]
	v_mfma_f32_16x16x32_bf16 v[112:115], v[178:181], v[186:189], v[112:115]
	v_mfma_f32_16x16x32_bf16 v[100:103], v[170:173], v[194:197], v[100:103]
	v_mfma_f32_16x16x32_bf16 v[96:99], v[178:181], v[194:197], v[96:99]
	v_mfma_f32_16x16x32_bf16 v[84:87], v[170:173], v[202:205], v[84:87]
	v_mfma_f32_16x16x32_bf16 v[80:83], v[178:181], v[202:205], v[80:83]
	v_mfma_f32_16x16x32_bf16 v[68:71], v[170:173], v[210:213], v[68:71]
	v_mfma_f32_16x16x32_bf16 v[64:67], v[178:181], v[210:213], v[64:67]
	v_mfma_f32_16x16x32_bf16 v[116:119], v[174:177], v[190:193], v[116:119]
	v_mfma_f32_16x16x32_bf16 v[112:115], v[182:185], v[190:193], v[112:115]
	v_mfma_f32_16x16x32_bf16 v[100:103], v[174:177], v[198:201], v[100:103]
	v_mfma_f32_16x16x32_bf16 v[96:99], v[182:185], v[198:201], v[96:99]
	v_mfma_f32_16x16x32_bf16 v[84:87], v[174:177], v[206:209], v[84:87]
	v_mfma_f32_16x16x32_bf16 v[80:83], v[182:185], v[206:209], v[80:83]
	v_mfma_f32_16x16x32_bf16 v[68:71], v[174:177], v[214:217], v[68:71]
	v_mfma_f32_16x16x32_bf16 v[64:67], v[182:185], v[214:217], v[64:67]
	s_setprio 0
	s_barrier
	s_add_i32 s34, s56, s45
	v_lshl_add_u64 v[218:219], s[40:41], 0, v[132:133]
	s_mov_b32 m0, s34
	ds_read_b128 v[186:189], v155 offset:16384
	ds_read_b128 v[190:193], v155 offset:17408
	ds_read_b128 v[194:197], v155 offset:18432
	ds_read_b128 v[198:201], v155 offset:19456
	ds_read_b128 v[202:205], v155 offset:20480
	ds_read_b128 v[206:209], v155 offset:21504
	ds_read_b128 v[210:213], v155 offset:22528
	ds_read_b128 v[214:217], v155 offset:23552
	global_load_lds_dwordx4 v[218:219], off
	s_add_i32 m0, s34, 0x2000
	s_add_u32 s34, s40, 0x40000
	v_lshl_add_u64 v[220:221], s[40:41], 0, v[136:137]
	s_addc_u32 s35, s41, 0
	s_add_i32 s61, s57, s45
	global_load_lds_dwordx4 v[220:221], off
	v_lshl_add_u64 v[222:223], s[34:35], 0, v[132:133]
	s_mov_b32 m0, s61
	v_lshl_add_u64 v[224:225], s[42:43], 0, v[134:135]
	global_load_lds_dwordx4 v[222:223], off
	v_lshl_add_u64 v[222:223], s[34:35], 0, v[136:137]
	s_add_i32 m0, s61, 0x2000
	s_nop 0
	global_load_lds_dwordx4 v[222:223], off
	v_lshl_add_u64 v[222:223], s[42:43], 0, v[130:131]
	s_mov_b32 m0, s46
	s_nop 0
	global_load_lds_dwordx4 v[222:223], off
	s_mov_b32 m0, s47
	s_nop 0
	global_load_lds_dwordx4 v[224:225], off
	s_waitcnt vmcnt(8)
	s_waitcnt lgkmcnt(0)
	s_barrier
	s_setprio 1
	s_waitcnt lgkmcnt(0)
	v_mfma_f32_16x16x32_bf16 v[60:63], v[146:149], v[186:189], v[60:63]
	v_mfma_f32_16x16x32_bf16 v[56:59], v[162:165], v[186:189], v[56:59]
	v_mfma_f32_16x16x32_bf16 v[44:47], v[146:149], v[194:197], v[44:47]
	v_mfma_f32_16x16x32_bf16 v[40:43], v[162:165], v[194:197], v[40:43]
	v_mfma_f32_16x16x32_bf16 v[28:31], v[146:149], v[202:205], v[28:31]
	v_mfma_f32_16x16x32_bf16 v[24:27], v[162:165], v[202:205], v[24:27]
	v_mfma_f32_16x16x32_bf16 v[12:15], v[146:149], v[210:213], v[12:15]
	v_mfma_f32_16x16x32_bf16 v[8:11], v[162:165], v[210:213], v[8:11]
	v_mfma_f32_16x16x32_bf16 v[60:63], v[158:161], v[190:193], v[60:63]
	v_mfma_f32_16x16x32_bf16 v[56:59], v[166:169], v[190:193], v[56:59]
	v_mfma_f32_16x16x32_bf16 v[44:47], v[158:161], v[198:201], v[44:47]
	v_mfma_f32_16x16x32_bf16 v[40:43], v[166:169], v[198:201], v[40:43]
	v_mfma_f32_16x16x32_bf16 v[28:31], v[158:161], v[206:209], v[28:31]
	v_mfma_f32_16x16x32_bf16 v[24:27], v[166:169], v[206:209], v[24:27]
	v_mfma_f32_16x16x32_bf16 v[12:15], v[158:161], v[214:217], v[12:15]
	v_mfma_f32_16x16x32_bf16 v[8:11], v[166:169], v[214:217], v[8:11]
	s_setprio 0
	s_setprio 1
	v_mfma_f32_16x16x32_bf16 v[52:55], v[170:173], v[186:189], v[52:55]
	v_mfma_f32_16x16x32_bf16 v[48:51], v[178:181], v[186:189], v[48:51]
	v_mfma_f32_16x16x32_bf16 v[36:39], v[170:173], v[194:197], v[36:39]
	v_mfma_f32_16x16x32_bf16 v[32:35], v[178:181], v[194:197], v[32:35]
	v_mfma_f32_16x16x32_bf16 v[20:23], v[170:173], v[202:205], v[20:23]
	v_mfma_f32_16x16x32_bf16 v[16:19], v[178:181], v[202:205], v[16:19]
	v_mfma_f32_16x16x32_bf16 v[4:7], v[170:173], v[210:213], v[4:7]
	v_mfma_f32_16x16x32_bf16 v[0:3], v[178:181], v[210:213], v[0:3]
	v_mfma_f32_16x16x32_bf16 v[52:55], v[174:177], v[190:193], v[52:55]
	v_mfma_f32_16x16x32_bf16 v[48:51], v[182:185], v[190:193], v[48:51]
	v_mfma_f32_16x16x32_bf16 v[36:39], v[174:177], v[198:201], v[36:39]
	v_mfma_f32_16x16x32_bf16 v[32:35], v[182:185], v[198:201], v[32:35]
	v_mfma_f32_16x16x32_bf16 v[20:23], v[174:177], v[206:209], v[20:23]
	v_mfma_f32_16x16x32_bf16 v[16:19], v[182:185], v[206:209], v[16:19]
	v_mfma_f32_16x16x32_bf16 v[4:7], v[174:177], v[214:217], v[4:7]
	v_mfma_f32_16x16x32_bf16 v[0:3], v[182:185], v[214:217], v[0:3]
	s_setprio 0
	s_barrier
	s_add_i32 s61, 0, 0x18000
	v_add_u32_e32 v157, s61, v151
	s_add_i32 s62, 0, 0x1c000
	ds_read_b128 v[146:149], v157
	ds_read_b128 v[158:161], v157 offset:1024
	ds_read_b128 v[162:165], v157 offset:2048
	ds_read_b128 v[166:169], v157 offset:3072
	v_add_u32_e32 v157, s62, v151
	ds_read_b128 v[170:173], v157
	ds_read_b128 v[174:177], v157 offset:1024
	ds_read_b128 v[178:181], v157 offset:2048
	ds_read_b128 v[182:185], v157 offset:3072
	s_add_u32 s34, s42, 0x40000
	s_addc_u32 s35, s43, 0
	s_mov_b32 m0, s48
	v_lshl_add_u64 v[226:227], s[34:35], 0, v[130:131]
	ds_read_b128 v[186:189], v155 offset:32768
	ds_read_b128 v[190:193], v155 offset:33792
	ds_read_b128 v[194:197], v155 offset:34816
	ds_read_b128 v[198:201], v155 offset:35840
	ds_read_b128 v[202:205], v155 offset:36864
	ds_read_b128 v[206:209], v155 offset:37888
	ds_read_b128 v[210:213], v155 offset:38912
	ds_read_b128 v[214:217], v155 offset:39936
	global_load_lds_dwordx4 v[226:227], off
	v_lshl_add_u64 v[226:227], s[34:35], 0, v[134:135]
	s_mov_b32 m0, s49
	s_nop 0
	global_load_lds_dwordx4 v[226:227], off
	s_waitcnt vmcnt(8)
	s_waitcnt lgkmcnt(0)
	s_barrier
	s_setprio 1
	s_waitcnt lgkmcnt(0)
	v_mfma_f32_16x16x32_bf16 v[124:127], v[146:149], v[186:189], v[124:127]
	v_mfma_f32_16x16x32_bf16 v[120:123], v[162:165], v[186:189], v[120:123]
	v_mfma_f32_16x16x32_bf16 v[108:111], v[146:149], v[194:197], v[108:111]
	v_mfma_f32_16x16x32_bf16 v[104:107], v[162:165], v[194:197], v[104:107]
	v_mfma_f32_16x16x32_bf16 v[92:95], v[146:149], v[202:205], v[92:95]
	v_mfma_f32_16x16x32_bf16 v[88:91], v[162:165], v[202:205], v[88:91]
	v_mfma_f32_16x16x32_bf16 v[76:79], v[146:149], v[210:213], v[76:79]
	v_mfma_f32_16x16x32_bf16 v[72:75], v[162:165], v[210:213], v[72:75]
	v_mfma_f32_16x16x32_bf16 v[124:127], v[158:161], v[190:193], v[124:127]
	v_mfma_f32_16x16x32_bf16 v[120:123], v[166:169], v[190:193], v[120:123]
	v_mfma_f32_16x16x32_bf16 v[108:111], v[158:161], v[198:201], v[108:111]
	v_mfma_f32_16x16x32_bf16 v[104:107], v[166:169], v[198:201], v[104:107]
	v_mfma_f32_16x16x32_bf16 v[92:95], v[158:161], v[206:209], v[92:95]
	v_mfma_f32_16x16x32_bf16 v[88:91], v[166:169], v[206:209], v[88:91]
	v_mfma_f32_16x16x32_bf16 v[76:79], v[158:161], v[214:217], v[76:79]
	v_mfma_f32_16x16x32_bf16 v[72:75], v[166:169], v[214:217], v[72:75]
	s_setprio 0
	s_setprio 1
	v_mfma_f32_16x16x32_bf16 v[116:119], v[170:173], v[186:189], v[116:119]
	v_mfma_f32_16x16x32_bf16 v[112:115], v[178:181], v[186:189], v[112:115]
	v_mfma_f32_16x16x32_bf16 v[100:103], v[170:173], v[194:197], v[100:103]
	v_mfma_f32_16x16x32_bf16 v[96:99], v[178:181], v[194:197], v[96:99]
	v_mfma_f32_16x16x32_bf16 v[84:87], v[170:173], v[202:205], v[84:87]
	v_mfma_f32_16x16x32_bf16 v[80:83], v[178:181], v[202:205], v[80:83]
	v_mfma_f32_16x16x32_bf16 v[68:71], v[170:173], v[210:213], v[68:71]
	v_mfma_f32_16x16x32_bf16 v[64:67], v[178:181], v[210:213], v[64:67]
	v_mfma_f32_16x16x32_bf16 v[116:119], v[174:177], v[190:193], v[116:119]
	v_mfma_f32_16x16x32_bf16 v[112:115], v[182:185], v[190:193], v[112:115]
	v_mfma_f32_16x16x32_bf16 v[100:103], v[174:177], v[198:201], v[100:103]
	v_mfma_f32_16x16x32_bf16 v[96:99], v[182:185], v[198:201], v[96:99]
	v_mfma_f32_16x16x32_bf16 v[84:87], v[174:177], v[206:209], v[84:87]
	v_mfma_f32_16x16x32_bf16 v[80:83], v[182:185], v[206:209], v[80:83]
	v_mfma_f32_16x16x32_bf16 v[68:71], v[174:177], v[214:217], v[68:71]
	v_mfma_f32_16x16x32_bf16 v[64:67], v[182:185], v[214:217], v[64:67]
	s_setprio 0
	s_barrier
	s_add_i32 s34, s61, s45
	v_lshl_add_u64 v[218:219], v[218:219], 0, s[10:11]
	s_mov_b32 m0, s34
	ds_read_b128 v[186:189], v155 offset:49152
	ds_read_b128 v[190:193], v155 offset:50176
	ds_read_b128 v[194:197], v155 offset:51200
	ds_read_b128 v[198:201], v155 offset:52224
	ds_read_b128 v[202:205], v155 offset:53248
	ds_read_b128 v[206:209], v155 offset:54272
	ds_read_b128 v[210:213], v155 offset:55296
	ds_read_b128 v[214:217], v155 offset:56320
	global_load_lds_dwordx4 v[218:219], off
	s_add_i32 m0, s34, 0x2000
	s_add_u32 s34, s40, 0x40080
	v_lshl_add_u64 v[218:219], v[220:221], 0, s[10:11]
	s_addc_u32 s35, s41, 0
	s_add_i32 s40, s62, s45
	global_load_lds_dwordx4 v[218:219], off
	v_lshl_add_u64 v[218:219], s[34:35], 0, v[132:133]
	s_mov_b32 m0, s40
	s_nop 0
	global_load_lds_dwordx4 v[218:219], off
	v_lshl_add_u64 v[218:219], s[34:35], 0, v[136:137]
	s_add_i32 m0, s40, 0x2000
	s_nop 0
	global_load_lds_dwordx4 v[218:219], off
	v_lshl_add_u64 v[218:219], v[222:223], 0, s[10:11]
	s_mov_b32 m0, s51
	s_nop 0
	global_load_lds_dwordx4 v[218:219], off
	v_lshl_add_u64 v[218:219], v[224:225], 0, s[10:11]
	s_mov_b32 m0, s52
	s_nop 0
	global_load_lds_dwordx4 v[218:219], off
	s_waitcnt vmcnt(8)
	s_waitcnt lgkmcnt(0)
	s_barrier
	s_add_u32 s38, s38, 0x100
	s_addc_u32 s39, s39, 0
	s_add_u32 s37, s37, 0x100
	s_addc_u32 s59, s59, 0
	s_setprio 1
	s_waitcnt lgkmcnt(0)
	v_mfma_f32_16x16x32_bf16 v[60:63], v[146:149], v[186:189], v[60:63]
	v_mfma_f32_16x16x32_bf16 v[56:59], v[162:165], v[186:189], v[56:59]
	v_mfma_f32_16x16x32_bf16 v[44:47], v[146:149], v[194:197], v[44:47]
	v_mfma_f32_16x16x32_bf16 v[40:43], v[162:165], v[194:197], v[40:43]
	v_mfma_f32_16x16x32_bf16 v[28:31], v[146:149], v[202:205], v[28:31]
	v_mfma_f32_16x16x32_bf16 v[24:27], v[162:165], v[202:205], v[24:27]
	v_mfma_f32_16x16x32_bf16 v[12:15], v[146:149], v[210:213], v[12:15]
	v_mfma_f32_16x16x32_bf16 v[8:11], v[162:165], v[210:213], v[8:11]
	v_mfma_f32_16x16x32_bf16 v[60:63], v[158:161], v[190:193], v[60:63]
	v_mfma_f32_16x16x32_bf16 v[56:59], v[166:169], v[190:193], v[56:59]
	v_mfma_f32_16x16x32_bf16 v[44:47], v[158:161], v[198:201], v[44:47]
	v_mfma_f32_16x16x32_bf16 v[40:43], v[166:169], v[198:201], v[40:43]
	v_mfma_f32_16x16x32_bf16 v[28:31], v[158:161], v[206:209], v[28:31]
	v_mfma_f32_16x16x32_bf16 v[24:27], v[166:169], v[206:209], v[24:27]
	v_mfma_f32_16x16x32_bf16 v[12:15], v[158:161], v[214:217], v[12:15]
	v_mfma_f32_16x16x32_bf16 v[8:11], v[166:169], v[214:217], v[8:11]
	s_setprio 0
	s_setprio 1
	v_mfma_f32_16x16x32_bf16 v[52:55], v[170:173], v[186:189], v[52:55]
	v_mfma_f32_16x16x32_bf16 v[48:51], v[178:181], v[186:189], v[48:51]
	v_mfma_f32_16x16x32_bf16 v[36:39], v[170:173], v[194:197], v[36:39]
	v_mfma_f32_16x16x32_bf16 v[32:35], v[178:181], v[194:197], v[32:35]
	v_mfma_f32_16x16x32_bf16 v[20:23], v[170:173], v[202:205], v[20:23]
	v_mfma_f32_16x16x32_bf16 v[16:19], v[178:181], v[202:205], v[16:19]
	v_mfma_f32_16x16x32_bf16 v[4:7], v[170:173], v[210:213], v[4:7]
	v_mfma_f32_16x16x32_bf16 v[0:3], v[178:181], v[210:213], v[0:3]
	v_mfma_f32_16x16x32_bf16 v[52:55], v[174:177], v[190:193], v[52:55]
	v_mfma_f32_16x16x32_bf16 v[48:51], v[182:185], v[190:193], v[48:51]
	v_mfma_f32_16x16x32_bf16 v[36:39], v[174:177], v[198:201], v[36:39]
	v_mfma_f32_16x16x32_bf16 v[32:35], v[182:185], v[198:201], v[32:35]
	v_mfma_f32_16x16x32_bf16 v[20:23], v[174:177], v[206:209], v[20:23]
	v_mfma_f32_16x16x32_bf16 v[16:19], v[182:185], v[206:209], v[16:19]
	v_mfma_f32_16x16x32_bf16 v[4:7], v[174:177], v[214:217], v[4:7]
	v_mfma_f32_16x16x32_bf16 v[0:3], v[182:185], v[214:217], v[0:3]
	s_setprio 0
	s_cmp_eq_u32 s60, s98
	s_cbranch_scc1 .Lmy_nobar_21
	s_barrier
.Lmy_nobar_21:
	s_add_i32 s60, s60, 2
	s_cmp_gt_u32 s60, 13
	s_cbranch_scc0 .LBB0_2001
	s_and_b64 vcc, exec, s[22:23]
	s_cbranch_vccz .LBB0_2004
	s_nop 0

.Lmy_nobar2_22:
	ds_read_b128 v[146:149], v153
	ds_read_b128 v[156:159], v153 offset:1024
	ds_read_b128 v[160:163], v153 offset:2048
	ds_read_b128 v[164:167], v153 offset:3072
	ds_read_b128 v[168:171], v154
	ds_read_b128 v[172:175], v154 offset:1024
	ds_read_b128 v[176:179], v154 offset:2048
	ds_read_b128 v[180:183], v154 offset:3072
	s_add_u32 s28, s26, 0xfffc0080
	s_addc_u32 s29, s27, -1
	s_cmp_eq_u32 s56, 12
	s_cselect_b32 s31, s19, s29
	s_cselect_b32 s30, s52, s28
	s_cselect_b32 s29, s11, s55
	s_cselect_b32 s28, s53, s54
	v_lshl_add_u64 v[216:217], s[26:27], 0, v[138:139]
	s_add_i32 m0, s25, 0xc000
	ds_read_b128 v[184:187], v155
	ds_read_b128 v[188:191], v155 offset:1024
	ds_read_b128 v[192:195], v155 offset:2048
	ds_read_b128 v[196:199], v155 offset:3072
	ds_read_b128 v[200:203], v155 offset:4096
	ds_read_b128 v[204:207], v155 offset:5120
	ds_read_b128 v[208:211], v155 offset:6144
	ds_read_b128 v[212:215], v155 offset:7168
	global_load_lds_dwordx4 v[216:217], off
	v_lshl_add_u64 v[216:217], s[26:27], 0, v[140:141]
	s_add_i32 m0, s25, 0xe000
	s_nop 0
	global_load_lds_dwordx4 v[216:217], off
	s_waitcnt vmcnt(8)
	s_waitcnt lgkmcnt(0)
	s_barrier
	s_setprio 1
	s_waitcnt lgkmcnt(0)
	v_mfma_f32_16x16x32_bf16 v[124:127], v[146:149], v[184:187], 0
	v_mfma_f32_16x16x32_bf16 v[120:123], v[160:163], v[184:187], 0
	v_mfma_f32_16x16x32_bf16 v[108:111], v[146:149], v[192:195], 0
	v_mfma_f32_16x16x32_bf16 v[104:107], v[160:163], v[192:195], 0
	v_mfma_f32_16x16x32_bf16 v[92:95], v[146:149], v[200:203], 0
	v_mfma_f32_16x16x32_bf16 v[88:91], v[160:163], v[200:203], 0
	v_mfma_f32_16x16x32_bf16 v[76:79], v[146:149], v[208:211], 0
	v_mfma_f32_16x16x32_bf16 v[72:75], v[160:163], v[208:211], 0
	v_mfma_f32_16x16x32_bf16 v[124:127], v[156:159], v[188:191], v[124:127]
	v_mfma_f32_16x16x32_bf16 v[120:123], v[164:167], v[188:191], v[120:123]
	v_mfma_f32_16x16x32_bf16 v[108:111], v[156:159], v[196:199], v[108:111]
	v_mfma_f32_16x16x32_bf16 v[104:107], v[164:167], v[196:199], v[104:107]
	v_mfma_f32_16x16x32_bf16 v[92:95], v[156:159], v[204:207], v[92:95]
	v_mfma_f32_16x16x32_bf16 v[88:91], v[164:167], v[204:207], v[88:91]
	v_mfma_f32_16x16x32_bf16 v[76:79], v[156:159], v[212:215], v[76:79]
	v_mfma_f32_16x16x32_bf16 v[72:75], v[164:167], v[212:215], v[72:75]
	s_setprio 0
	s_setprio 1
	v_mfma_f32_16x16x32_bf16 v[116:119], v[168:171], v[184:187], 0
	v_mfma_f32_16x16x32_bf16 v[112:115], v[176:179], v[184:187], 0
	v_mfma_f32_16x16x32_bf16 v[100:103], v[168:171], v[192:195], 0
	v_mfma_f32_16x16x32_bf16 v[96:99], v[176:179], v[192:195], 0
	v_mfma_f32_16x16x32_bf16 v[84:87], v[168:171], v[200:203], 0
	v_mfma_f32_16x16x32_bf16 v[80:83], v[176:179], v[200:203], 0
	v_mfma_f32_16x16x32_bf16 v[68:71], v[168:171], v[208:211], 0
	v_mfma_f32_16x16x32_bf16 v[64:67], v[176:179], v[208:211], 0
	v_mfma_f32_16x16x32_bf16 v[116:119], v[172:175], v[188:191], v[116:119]
	v_mfma_f32_16x16x32_bf16 v[112:115], v[180:183], v[188:191], v[112:115]
	v_mfma_f32_16x16x32_bf16 v[100:103], v[172:175], v[196:199], v[100:103]
	v_mfma_f32_16x16x32_bf16 v[96:99], v[180:183], v[196:199], v[96:99]
	v_mfma_f32_16x16x32_bf16 v[84:87], v[172:175], v[204:207], v[84:87]
	v_mfma_f32_16x16x32_bf16 v[80:83], v[180:183], v[204:207], v[80:83]
	v_mfma_f32_16x16x32_bf16 v[68:71], v[172:175], v[212:215], v[68:71]
	v_mfma_f32_16x16x32_bf16 v[64:67], v[180:183], v[212:215], v[64:67]
	s_setprio 0
	s_barrier
	s_add_i32 s34, s47, s38
	v_lshl_add_u64 v[216:217], s[28:29], 0, v[134:135]
	s_mov_b32 m0, s34
	ds_read_b128 v[184:187], v155 offset:16384
	ds_read_b128 v[188:191], v155 offset:17408
	ds_read_b128 v[192:195], v155 offset:18432
	ds_read_b128 v[196:199], v155 offset:19456
	ds_read_b128 v[200:203], v155 offset:20480
	ds_read_b128 v[204:207], v155 offset:21504
	ds_read_b128 v[208:211], v155 offset:22528
	ds_read_b128 v[212:215], v155 offset:23552
	global_load_lds_dwordx4 v[216:217], off
	s_add_i32 m0, s34, 0x2000
	s_add_u32 s34, s28, 0x40000
	v_lshl_add_u64 v[218:219], s[28:29], 0, v[130:131]
	s_addc_u32 s35, s29, 0
	s_add_i32 s57, s48, s38
	global_load_lds_dwordx4 v[218:219], off
	v_lshl_add_u64 v[220:221], s[34:35], 0, v[134:135]
	s_mov_b32 m0, s57
	v_lshl_add_u64 v[222:223], s[30:31], 0, v[132:133]
	global_load_lds_dwordx4 v[220:221], off
	v_lshl_add_u64 v[220:221], s[34:35], 0, v[130:131]
	s_add_i32 m0, s57, 0x2000
	s_nop 0
	global_load_lds_dwordx4 v[220:221], off
	v_lshl_add_u64 v[220:221], s[30:31], 0, v[136:137]
	s_mov_b32 m0, s25
	s_nop 0
	global_load_lds_dwordx4 v[220:221], off
	s_mov_b32 m0, s42
	s_nop 0
	global_load_lds_dwordx4 v[222:223], off
	s_waitcnt vmcnt(8)
	s_waitcnt lgkmcnt(0)
	s_barrier
	s_setprio 1
	s_waitcnt lgkmcnt(0)
	v_mfma_f32_16x16x32_bf16 v[60:63], v[146:149], v[184:187], 0
	v_mfma_f32_16x16x32_bf16 v[56:59], v[160:163], v[184:187], 0
	v_mfma_f32_16x16x32_bf16 v[44:47], v[146:149], v[192:195], 0
	v_mfma_f32_16x16x32_bf16 v[40:43], v[160:163], v[192:195], 0
	v_mfma_f32_16x16x32_bf16 v[28:31], v[146:149], v[200:203], 0
	v_mfma_f32_16x16x32_bf16 v[24:27], v[160:163], v[200:203], 0
	v_mfma_f32_16x16x32_bf16 v[12:15], v[146:149], v[208:211], 0
	v_mfma_f32_16x16x32_bf16 v[8:11], v[160:163], v[208:211], 0
	v_mfma_f32_16x16x32_bf16 v[60:63], v[156:159], v[188:191], v[60:63]
	v_mfma_f32_16x16x32_bf16 v[56:59], v[164:167], v[188:191], v[56:59]
	v_mfma_f32_16x16x32_bf16 v[44:47], v[156:159], v[196:199], v[44:47]
	v_mfma_f32_16x16x32_bf16 v[40:43], v[164:167], v[196:199], v[40:43]
	v_mfma_f32_16x16x32_bf16 v[28:31], v[156:159], v[204:207], v[28:31]
	v_mfma_f32_16x16x32_bf16 v[24:27], v[164:167], v[204:207], v[24:27]
	v_mfma_f32_16x16x32_bf16 v[12:15], v[156:159], v[212:215], v[12:15]
	v_mfma_f32_16x16x32_bf16 v[8:11], v[164:167], v[212:215], v[8:11]
	s_setprio 0
	s_setprio 1
	v_mfma_f32_16x16x32_bf16 v[52:55], v[168:171], v[184:187], 0
	v_mfma_f32_16x16x32_bf16 v[48:51], v[176:179], v[184:187], 0
	v_mfma_f32_16x16x32_bf16 v[36:39], v[168:171], v[192:195], 0
	v_mfma_f32_16x16x32_bf16 v[32:35], v[176:179], v[192:195], 0
	v_mfma_f32_16x16x32_bf16 v[20:23], v[168:171], v[200:203], 0
	v_mfma_f32_16x16x32_bf16 v[16:19], v[176:179], v[200:203], 0
	v_mfma_f32_16x16x32_bf16 v[4:7], v[168:171], v[208:211], 0
	v_mfma_f32_16x16x32_bf16 v[0:3], v[176:179], v[208:211], 0
	v_mfma_f32_16x16x32_bf16 v[52:55], v[172:175], v[188:191], v[52:55]
	v_mfma_f32_16x16x32_bf16 v[48:51], v[180:183], v[188:191], v[48:51]
	v_mfma_f32_16x16x32_bf16 v[36:39], v[172:175], v[196:199], v[36:39]
	v_mfma_f32_16x16x32_bf16 v[32:35], v[180:183], v[196:199], v[32:35]
	v_mfma_f32_16x16x32_bf16 v[20:23], v[172:175], v[204:207], v[20:23]
	v_mfma_f32_16x16x32_bf16 v[16:19], v[180:183], v[204:207], v[16:19]
	v_mfma_f32_16x16x32_bf16 v[4:7], v[172:175], v[212:215], v[4:7]
	v_mfma_f32_16x16x32_bf16 v[0:3], v[180:183], v[212:215], v[0:3]
	s_setprio 0
	s_barrier
	s_add_i32 s34, 0, 0x18000
	s_add_i32 s35, 0, 0x1c000
	v_add_u32_e32 v164, s34, v150
	v_add_u32_e32 v180, s35, v150
	ds_read_b128 v[146:149], v164
	ds_read_b128 v[156:159], v164 offset:1024
	ds_read_b128 v[160:163], v164 offset:2048
	ds_read_b128 v[164:167], v164 offset:3072
	ds_read_b128 v[168:171], v180
	ds_read_b128 v[172:175], v180 offset:1024
	ds_read_b128 v[176:179], v180 offset:2048
	ds_read_b128 v[180:183], v180 offset:3072
	s_add_u32 s30, s30, 0x40000
	s_addc_u32 s31, s31, 0
	s_mov_b32 m0, s43
	v_lshl_add_u64 v[224:225], s[30:31], 0, v[136:137]
	ds_read_b128 v[184:187], v155 offset:32768
	ds_read_b128 v[188:191], v155 offset:33792
	ds_read_b128 v[192:195], v155 offset:34816
	ds_read_b128 v[196:199], v155 offset:35840
	ds_read_b128 v[200:203], v155 offset:36864
	ds_read_b128 v[204:207], v155 offset:37888
	ds_read_b128 v[208:211], v155 offset:38912
	ds_read_b128 v[212:215], v155 offset:39936
	global_load_lds_dwordx4 v[224:225], off
	v_lshl_add_u64 v[224:225], s[30:31], 0, v[132:133]
	s_mov_b32 m0, s44
	s_nop 0
	global_load_lds_dwordx4 v[224:225], off
	s_waitcnt vmcnt(8)
	s_waitcnt lgkmcnt(0)
	s_barrier
	s_setprio 1
	s_waitcnt lgkmcnt(0)
	v_mfma_f32_16x16x32_bf16 v[124:127], v[146:149], v[184:187], v[124:127]
	v_mfma_f32_16x16x32_bf16 v[120:123], v[160:163], v[184:187], v[120:123]
	v_mfma_f32_16x16x32_bf16 v[108:111], v[146:149], v[192:195], v[108:111]
	v_mfma_f32_16x16x32_bf16 v[104:107], v[160:163], v[192:195], v[104:107]
	v_mfma_f32_16x16x32_bf16 v[92:95], v[146:149], v[200:203], v[92:95]
	v_mfma_f32_16x16x32_bf16 v[88:91], v[160:163], v[200:203], v[88:91]
	v_mfma_f32_16x16x32_bf16 v[76:79], v[146:149], v[208:211], v[76:79]
	v_mfma_f32_16x16x32_bf16 v[72:75], v[160:163], v[208:211], v[72:75]
	v_mfma_f32_16x16x32_bf16 v[124:127], v[156:159], v[188:191], v[124:127]
	v_mfma_f32_16x16x32_bf16 v[120:123], v[164:167], v[188:191], v[120:123]
	v_mfma_f32_16x16x32_bf16 v[108:111], v[156:159], v[196:199], v[108:111]
	v_mfma_f32_16x16x32_bf16 v[104:107], v[164:167], v[196:199], v[104:107]
	v_mfma_f32_16x16x32_bf16 v[92:95], v[156:159], v[204:207], v[92:95]
	v_mfma_f32_16x16x32_bf16 v[88:91], v[164:167], v[204:207], v[88:91]
	v_mfma_f32_16x16x32_bf16 v[76:79], v[156:159], v[212:215], v[76:79]
	v_mfma_f32_16x16x32_bf16 v[72:75], v[164:167], v[212:215], v[72:75]
	s_setprio 0
	s_setprio 1
	v_mfma_f32_16x16x32_bf16 v[116:119], v[168:171], v[184:187], v[116:119]
	v_mfma_f32_16x16x32_bf16 v[112:115], v[176:179], v[184:187], v[112:115]
	v_mfma_f32_16x16x32_bf16 v[100:103], v[168:171], v[192:195], v[100:103]
	v_mfma_f32_16x16x32_bf16 v[96:99], v[176:179], v[192:195], v[96:99]
	v_mfma_f32_16x16x32_bf16 v[84:87], v[168:171], v[200:203], v[84:87]
	v_mfma_f32_16x16x32_bf16 v[80:83], v[176:179], v[200:203], v[80:83]
	v_mfma_f32_16x16x32_bf16 v[68:71], v[168:171], v[208:211], v[68:71]
	v_mfma_f32_16x16x32_bf16 v[64:67], v[176:179], v[208:211], v[64:67]
	v_mfma_f32_16x16x32_bf16 v[116:119], v[172:175], v[188:191], v[116:119]
	v_mfma_f32_16x16x32_bf16 v[112:115], v[180:183], v[188:191], v[112:115]
	v_mfma_f32_16x16x32_bf16 v[100:103], v[172:175], v[196:199], v[100:103]
	v_mfma_f32_16x16x32_bf16 v[96:99], v[180:183], v[196:199], v[96:99]
	v_mfma_f32_16x16x32_bf16 v[84:87], v[172:175], v[204:207], v[84:87]
	v_mfma_f32_16x16x32_bf16 v[80:83], v[180:183], v[204:207], v[80:83]
	v_mfma_f32_16x16x32_bf16 v[68:71], v[172:175], v[212:215], v[68:71]
	v_mfma_f32_16x16x32_bf16 v[64:67], v[180:183], v[212:215], v[64:67]
	s_setprio 0
	s_barrier
	s_add_i32 s30, s34, s38
	v_lshl_add_u64 v[216:217], v[216:217], 0, s[6:7]
	s_mov_b32 m0, s30
	ds_read_b128 v[184:187], v155 offset:49152
	ds_read_b128 v[188:191], v155 offset:50176
	ds_read_b128 v[192:195], v155 offset:51200
	ds_read_b128 v[196:199], v155 offset:52224
	ds_read_b128 v[200:203], v155 offset:53248
	ds_read_b128 v[204:207], v155 offset:54272
	ds_read_b128 v[208:211], v155 offset:55296
	ds_read_b128 v[212:215], v155 offset:56320
	global_load_lds_dwordx4 v[216:217], off
	s_add_i32 m0, s30, 0x2000
	s_add_u32 s28, s28, 0x40080
	v_lshl_add_u64 v[216:217], v[218:219], 0, s[6:7]
	s_addc_u32 s29, s29, 0
	s_add_i32 s30, s35, s38
	global_load_lds_dwordx4 v[216:217], off
	v_lshl_add_u64 v[216:217], s[28:29], 0, v[134:135]
	s_mov_b32 m0, s30
	s_nop 0
	global_load_lds_dwordx4 v[216:217], off
	v_lshl_add_u64 v[216:217], s[28:29], 0, v[130:131]
	s_add_i32 m0, s30, 0x2000
	s_nop 0
	global_load_lds_dwordx4 v[216:217], off
	v_lshl_add_u64 v[216:217], v[220:221], 0, s[6:7]
	s_mov_b32 m0, s45
	s_nop 0
	global_load_lds_dwordx4 v[216:217], off
	v_lshl_add_u64 v[216:217], v[222:223], 0, s[6:7]
	s_mov_b32 m0, s46
	s_nop 0
	global_load_lds_dwordx4 v[216:217], off
	s_waitcnt vmcnt(8)
	s_waitcnt lgkmcnt(0)
	s_barrier
	s_add_u32 s26, s26, 0x100
	s_addc_u32 s27, s27, 0
	s_add_u32 s54, s54, 0x100
	s_addc_u32 s55, s55, 0
	s_setprio 1
	s_waitcnt lgkmcnt(0)
	v_mfma_f32_16x16x32_bf16 v[60:63], v[146:149], v[184:187], v[60:63]
	v_mfma_f32_16x16x32_bf16 v[56:59], v[160:163], v[184:187], v[56:59]
	v_mfma_f32_16x16x32_bf16 v[44:47], v[146:149], v[192:195], v[44:47]
	v_mfma_f32_16x16x32_bf16 v[40:43], v[160:163], v[192:195], v[40:43]
	v_mfma_f32_16x16x32_bf16 v[28:31], v[146:149], v[200:203], v[28:31]
	v_mfma_f32_16x16x32_bf16 v[24:27], v[160:163], v[200:203], v[24:27]
	v_mfma_f32_16x16x32_bf16 v[12:15], v[146:149], v[208:211], v[12:15]
	v_mfma_f32_16x16x32_bf16 v[8:11], v[160:163], v[208:211], v[8:11]
	v_mfma_f32_16x16x32_bf16 v[60:63], v[156:159], v[188:191], v[60:63]
	v_mfma_f32_16x16x32_bf16 v[56:59], v[164:167], v[188:191], v[56:59]
	v_mfma_f32_16x16x32_bf16 v[44:47], v[156:159], v[196:199], v[44:47]
	v_mfma_f32_16x16x32_bf16 v[40:43], v[164:167], v[196:199], v[40:43]
	v_mfma_f32_16x16x32_bf16 v[28:31], v[156:159], v[204:207], v[28:31]
	v_mfma_f32_16x16x32_bf16 v[24:27], v[164:167], v[204:207], v[24:27]
	v_mfma_f32_16x16x32_bf16 v[12:15], v[156:159], v[212:215], v[12:15]
	v_mfma_f32_16x16x32_bf16 v[8:11], v[164:167], v[212:215], v[8:11]
	s_setprio 0
	s_setprio 1
	v_mfma_f32_16x16x32_bf16 v[52:55], v[168:171], v[184:187], v[52:55]
	v_mfma_f32_16x16x32_bf16 v[48:51], v[176:179], v[184:187], v[48:51]
	v_mfma_f32_16x16x32_bf16 v[36:39], v[168:171], v[192:195], v[36:39]
	v_mfma_f32_16x16x32_bf16 v[32:35], v[176:179], v[192:195], v[32:35]
	v_mfma_f32_16x16x32_bf16 v[20:23], v[168:171], v[200:203], v[20:23]
	v_mfma_f32_16x16x32_bf16 v[16:19], v[176:179], v[200:203], v[16:19]
	v_mfma_f32_16x16x32_bf16 v[4:7], v[168:171], v[208:211], v[4:7]
	v_mfma_f32_16x16x32_bf16 v[0:3], v[176:179], v[208:211], v[0:3]
	v_mfma_f32_16x16x32_bf16 v[52:55], v[172:175], v[188:191], v[52:55]
	v_mfma_f32_16x16x32_bf16 v[48:51], v[180:183], v[188:191], v[48:51]
	v_mfma_f32_16x16x32_bf16 v[36:39], v[172:175], v[196:199], v[36:39]
	v_mfma_f32_16x16x32_bf16 v[32:35], v[180:183], v[196:199], v[32:35]
	v_mfma_f32_16x16x32_bf16 v[20:23], v[172:175], v[204:207], v[20:23]
	v_mfma_f32_16x16x32_bf16 v[16:19], v[180:183], v[204:207], v[16:19]
	v_mfma_f32_16x16x32_bf16 v[4:7], v[172:175], v[212:215], v[4:7]
	v_mfma_f32_16x16x32_bf16 v[0:3], v[180:183], v[212:215], v[0:3]
	s_setprio 0
	s_barrier
	s_add_i32 s56, s56, 2
.LBB0_2091:
	ds_read_b128 v[146:149], v153
	ds_read_b128 v[156:159], v153 offset:1024
	ds_read_b128 v[160:163], v153 offset:2048
	ds_read_b128 v[164:167], v153 offset:3072
	ds_read_b128 v[168:171], v154
	ds_read_b128 v[172:175], v154 offset:1024
	ds_read_b128 v[176:179], v154 offset:2048
	ds_read_b128 v[180:183], v154 offset:3072
	s_add_u32 s28, s26, 0xfffc0080
	s_addc_u32 s29, s27, -1
	s_cmp_eq_u32 s56, 12
	s_cselect_b32 s31, s19, s29
	s_cselect_b32 s30, s52, s28
	s_cselect_b32 s29, s11, s55
	s_cselect_b32 s28, s53, s54
	v_lshl_add_u64 v[216:217], s[26:27], 0, v[138:139]
	s_add_i32 m0, s25, 0xc000
	ds_read_b128 v[184:187], v155
	ds_read_b128 v[188:191], v155 offset:1024
	ds_read_b128 v[192:195], v155 offset:2048
	ds_read_b128 v[196:199], v155 offset:3072
	ds_read_b128 v[200:203], v155 offset:4096
	ds_read_b128 v[204:207], v155 offset:5120
	ds_read_b128 v[208:211], v155 offset:6144
	ds_read_b128 v[212:215], v155 offset:7168
	global_load_lds_dwordx4 v[216:217], off
	v_lshl_add_u64 v[216:217], s[26:27], 0, v[140:141]
	s_add_i32 m0, s25, 0xe000
	s_nop 0
	global_load_lds_dwordx4 v[216:217], off
	s_waitcnt vmcnt(8)
	s_waitcnt lgkmcnt(0)
	s_barrier
	s_setprio 1
	s_waitcnt lgkmcnt(0)
	v_mfma_f32_16x16x32_bf16 v[124:127], v[146:149], v[184:187], v[124:127]
	v_mfma_f32_16x16x32_bf16 v[120:123], v[160:163], v[184:187], v[120:123]
	v_mfma_f32_16x16x32_bf16 v[108:111], v[146:149], v[192:195], v[108:111]
	v_mfma_f32_16x16x32_bf16 v[104:107], v[160:163], v[192:195], v[104:107]
	v_mfma_f32_16x16x32_bf16 v[92:95], v[146:149], v[200:203], v[92:95]
	v_mfma_f32_16x16x32_bf16 v[88:91], v[160:163], v[200:203], v[88:91]
	v_mfma_f32_16x16x32_bf16 v[76:79], v[146:149], v[208:211], v[76:79]
	v_mfma_f32_16x16x32_bf16 v[72:75], v[160:163], v[208:211], v[72:75]
	v_mfma_f32_16x16x32_bf16 v[124:127], v[156:159], v[188:191], v[124:127]
	v_mfma_f32_16x16x32_bf16 v[120:123], v[164:167], v[188:191], v[120:123]
	v_mfma_f32_16x16x32_bf16 v[108:111], v[156:159], v[196:199], v[108:111]
	v_mfma_f32_16x16x32_bf16 v[104:107], v[164:167], v[196:199], v[104:107]
	v_mfma_f32_16x16x32_bf16 v[92:95], v[156:159], v[204:207], v[92:95]
	v_mfma_f32_16x16x32_bf16 v[88:91], v[164:167], v[204:207], v[88:91]
	v_mfma_f32_16x16x32_bf16 v[76:79], v[156:159], v[212:215], v[76:79]
	v_mfma_f32_16x16x32_bf16 v[72:75], v[164:167], v[212:215], v[72:75]
	s_setprio 0
	s_setprio 1
	v_mfma_f32_16x16x32_bf16 v[116:119], v[168:171], v[184:187], v[116:119]
	v_mfma_f32_16x16x32_bf16 v[112:115], v[176:179], v[184:187], v[112:115]
	v_mfma_f32_16x16x32_bf16 v[100:103], v[168:171], v[192:195], v[100:103]
	v_mfma_f32_16x16x32_bf16 v[96:99], v[176:179], v[192:195], v[96:99]
	v_mfma_f32_16x16x32_bf16 v[84:87], v[168:171], v[200:203], v[84:87]
	v_mfma_f32_16x16x32_bf16 v[80:83], v[176:179], v[200:203], v[80:83]
	v_mfma_f32_16x16x32_bf16 v[68:71], v[168:171], v[208:211], v[68:71]
	v_mfma_f32_16x16x32_bf16 v[64:67], v[176:179], v[208:211], v[64:67]
	v_mfma_f32_16x16x32_bf16 v[116:119], v[172:175], v[188:191], v[116:119]
	v_mfma_f32_16x16x32_bf16 v[112:115], v[180:183], v[188:191], v[112:115]
	v_mfma_f32_16x16x32_bf16 v[100:103], v[172:175], v[196:199], v[100:103]
	v_mfma_f32_16x16x32_bf16 v[96:99], v[180:183], v[196:199], v[96:99]
	v_mfma_f32_16x16x32_bf16 v[84:87], v[172:175], v[204:207], v[84:87]
	v_mfma_f32_16x16x32_bf16 v[80:83], v[180:183], v[204:207], v[80:83]
	v_mfma_f32_16x16x32_bf16 v[68:71], v[172:175], v[212:215], v[68:71]
	v_mfma_f32_16x16x32_bf16 v[64:67], v[180:183], v[212:215], v[64:67]
	s_setprio 0
	s_barrier
	s_add_i32 s34, s47, s38
	v_lshl_add_u64 v[216:217], s[28:29], 0, v[134:135]
	s_mov_b32 m0, s34
	ds_read_b128 v[184:187], v155 offset:16384
	ds_read_b128 v[188:191], v155 offset:17408
	ds_read_b128 v[192:195], v155 offset:18432
	ds_read_b128 v[196:199], v155 offset:19456
	ds_read_b128 v[200:203], v155 offset:20480
	ds_read_b128 v[204:207], v155 offset:21504
	ds_read_b128 v[208:211], v155 offset:22528
	ds_read_b128 v[212:215], v155 offset:23552
	global_load_lds_dwordx4 v[216:217], off
	s_add_i32 m0, s34, 0x2000
	s_add_u32 s34, s28, 0x40000
	v_lshl_add_u64 v[218:219], s[28:29], 0, v[130:131]
	s_addc_u32 s35, s29, 0
	s_add_i32 s57, s48, s38
	global_load_lds_dwordx4 v[218:219], off
	v_lshl_add_u64 v[220:221], s[34:35], 0, v[134:135]
	s_mov_b32 m0, s57
	v_lshl_add_u64 v[222:223], s[30:31], 0, v[132:133]
	global_load_lds_dwordx4 v[220:221], off
	v_lshl_add_u64 v[220:221], s[34:35], 0, v[130:131]
	s_add_i32 m0, s57, 0x2000
	s_nop 0
	global_load_lds_dwordx4 v[220:221], off
	v_lshl_add_u64 v[220:221], s[30:31], 0, v[136:137]
	s_mov_b32 m0, s25
	s_nop 0
	global_load_lds_dwordx4 v[220:221], off
	s_mov_b32 m0, s42
	s_nop 0
	global_load_lds_dwordx4 v[222:223], off
	s_waitcnt vmcnt(8)
	s_waitcnt lgkmcnt(0)
	s_barrier
	s_setprio 1
	s_waitcnt lgkmcnt(0)
	v_mfma_f32_16x16x32_bf16 v[60:63], v[146:149], v[184:187], v[60:63]
	v_mfma_f32_16x16x32_bf16 v[56:59], v[160:163], v[184:187], v[56:59]
	v_mfma_f32_16x16x32_bf16 v[44:47], v[146:149], v[192:195], v[44:47]
	v_mfma_f32_16x16x32_bf16 v[40:43], v[160:163], v[192:195], v[40:43]
	v_mfma_f32_16x16x32_bf16 v[28:31], v[146:149], v[200:203], v[28:31]
	v_mfma_f32_16x16x32_bf16 v[24:27], v[160:163], v[200:203], v[24:27]
	v_mfma_f32_16x16x32_bf16 v[12:15], v[146:149], v[208:211], v[12:15]
	v_mfma_f32_16x16x32_bf16 v[8:11], v[160:163], v[208:211], v[8:11]
	v_mfma_f32_16x16x32_bf16 v[60:63], v[156:159], v[188:191], v[60:63]
	v_mfma_f32_16x16x32_bf16 v[56:59], v[164:167], v[188:191], v[56:59]
	v_mfma_f32_16x16x32_bf16 v[44:47], v[156:159], v[196:199], v[44:47]
	v_mfma_f32_16x16x32_bf16 v[40:43], v[164:167], v[196:199], v[40:43]
	v_mfma_f32_16x16x32_bf16 v[28:31], v[156:159], v[204:207], v[28:31]
	v_mfma_f32_16x16x32_bf16 v[24:27], v[164:167], v[204:207], v[24:27]
	v_mfma_f32_16x16x32_bf16 v[12:15], v[156:159], v[212:215], v[12:15]
	v_mfma_f32_16x16x32_bf16 v[8:11], v[164:167], v[212:215], v[8:11]
	s_setprio 0
	s_setprio 1
	v_mfma_f32_16x16x32_bf16 v[52:55], v[168:171], v[184:187], v[52:55]
	v_mfma_f32_16x16x32_bf16 v[48:51], v[176:179], v[184:187], v[48:51]
	v_mfma_f32_16x16x32_bf16 v[36:39], v[168:171], v[192:195], v[36:39]
	v_mfma_f32_16x16x32_bf16 v[32:35], v[176:179], v[192:195], v[32:35]
	v_mfma_f32_16x16x32_bf16 v[20:23], v[168:171], v[200:203], v[20:23]
	v_mfma_f32_16x16x32_bf16 v[16:19], v[176:179], v[200:203], v[16:19]
	v_mfma_f32_16x16x32_bf16 v[4:7], v[168:171], v[208:211], v[4:7]
	v_mfma_f32_16x16x32_bf16 v[0:3], v[176:179], v[208:211], v[0:3]
	v_mfma_f32_16x16x32_bf16 v[52:55], v[172:175], v[188:191], v[52:55]
	v_mfma_f32_16x16x32_bf16 v[48:51], v[180:183], v[188:191], v[48:51]
	v_mfma_f32_16x16x32_bf16 v[36:39], v[172:175], v[196:199], v[36:39]
	v_mfma_f32_16x16x32_bf16 v[32:35], v[180:183], v[196:199], v[32:35]
	v_mfma_f32_16x16x32_bf16 v[20:23], v[172:175], v[204:207], v[20:23]
	v_mfma_f32_16x16x32_bf16 v[16:19], v[180:183], v[204:207], v[16:19]
	v_mfma_f32_16x16x32_bf16 v[4:7], v[172:175], v[212:215], v[4:7]
	v_mfma_f32_16x16x32_bf16 v[0:3], v[180:183], v[212:215], v[0:3]
	s_setprio 0
	s_barrier
	s_add_i32 s34, 0, 0x18000
	s_add_i32 s35, 0, 0x1c000
	v_add_u32_e32 v164, s34, v150
	v_add_u32_e32 v180, s35, v150
	ds_read_b128 v[146:149], v164
	ds_read_b128 v[156:159], v164 offset:1024
	ds_read_b128 v[160:163], v164 offset:2048
	ds_read_b128 v[164:167], v164 offset:3072
	ds_read_b128 v[168:171], v180
	ds_read_b128 v[172:175], v180 offset:1024
	ds_read_b128 v[176:179], v180 offset:2048
	ds_read_b128 v[180:183], v180 offset:3072
	s_add_u32 s30, s30, 0x40000
	s_addc_u32 s31, s31, 0
	s_mov_b32 m0, s43
	v_lshl_add_u64 v[224:225], s[30:31], 0, v[136:137]
	ds_read_b128 v[184:187], v155 offset:32768
	ds_read_b128 v[188:191], v155 offset:33792
	ds_read_b128 v[192:195], v155 offset:34816
	ds_read_b128 v[196:199], v155 offset:35840
	ds_read_b128 v[200:203], v155 offset:36864
	ds_read_b128 v[204:207], v155 offset:37888
	ds_read_b128 v[208:211], v155 offset:38912
	ds_read_b128 v[212:215], v155 offset:39936
	global_load_lds_dwordx4 v[224:225], off
	v_lshl_add_u64 v[224:225], s[30:31], 0, v[132:133]
	s_mov_b32 m0, s44
	s_nop 0
	global_load_lds_dwordx4 v[224:225], off
	s_waitcnt vmcnt(8)
	s_waitcnt lgkmcnt(0)
	s_barrier
	s_setprio 1
	s_waitcnt lgkmcnt(0)
	v_mfma_f32_16x16x32_bf16 v[124:127], v[146:149], v[184:187], v[124:127]
	v_mfma_f32_16x16x32_bf16 v[120:123], v[160:163], v[184:187], v[120:123]
	v_mfma_f32_16x16x32_bf16 v[108:111], v[146:149], v[192:195], v[108:111]
	v_mfma_f32_16x16x32_bf16 v[104:107], v[160:163], v[192:195], v[104:107]
	v_mfma_f32_16x16x32_bf16 v[92:95], v[146:149], v[200:203], v[92:95]
	v_mfma_f32_16x16x32_bf16 v[88:91], v[160:163], v[200:203], v[88:91]
	v_mfma_f32_16x16x32_bf16 v[76:79], v[146:149], v[208:211], v[76:79]
	v_mfma_f32_16x16x32_bf16 v[72:75], v[160:163], v[208:211], v[72:75]
	v_mfma_f32_16x16x32_bf16 v[124:127], v[156:159], v[188:191], v[124:127]
	v_mfma_f32_16x16x32_bf16 v[120:123], v[164:167], v[188:191], v[120:123]
	v_mfma_f32_16x16x32_bf16 v[108:111], v[156:159], v[196:199], v[108:111]
	v_mfma_f32_16x16x32_bf16 v[104:107], v[164:167], v[196:199], v[104:107]
	v_mfma_f32_16x16x32_bf16 v[92:95], v[156:159], v[204:207], v[92:95]
	v_mfma_f32_16x16x32_bf16 v[88:91], v[164:167], v[204:207], v[88:91]
	v_mfma_f32_16x16x32_bf16 v[76:79], v[156:159], v[212:215], v[76:79]
	v_mfma_f32_16x16x32_bf16 v[72:75], v[164:167], v[212:215], v[72:75]
	s_setprio 0
	s_setprio 1
	v_mfma_f32_16x16x32_bf16 v[116:119], v[168:171], v[184:187], v[116:119]
	v_mfma_f32_16x16x32_bf16 v[112:115], v[176:179], v[184:187], v[112:115]
	v_mfma_f32_16x16x32_bf16 v[100:103], v[168:171], v[192:195], v[100:103]
	v_mfma_f32_16x16x32_bf16 v[96:99], v[176:179], v[192:195], v[96:99]
	v_mfma_f32_16x16x32_bf16 v[84:87], v[168:171], v[200:203], v[84:87]
	v_mfma_f32_16x16x32_bf16 v[80:83], v[176:179], v[200:203], v[80:83]
	v_mfma_f32_16x16x32_bf16 v[68:71], v[168:171], v[208:211], v[68:71]
	v_mfma_f32_16x16x32_bf16 v[64:67], v[176:179], v[208:211], v[64:67]
	v_mfma_f32_16x16x32_bf16 v[116:119], v[172:175], v[188:191], v[116:119]
	v_mfma_f32_16x16x32_bf16 v[112:115], v[180:183], v[188:191], v[112:115]
	v_mfma_f32_16x16x32_bf16 v[100:103], v[172:175], v[196:199], v[100:103]
	v_mfma_f32_16x16x32_bf16 v[96:99], v[180:183], v[196:199], v[96:99]
	v_mfma_f32_16x16x32_bf16 v[84:87], v[172:175], v[204:207], v[84:87]
	v_mfma_f32_16x16x32_bf16 v[80:83], v[180:183], v[204:207], v[80:83]
	v_mfma_f32_16x16x32_bf16 v[68:71], v[172:175], v[212:215], v[68:71]
	v_mfma_f32_16x16x32_bf16 v[64:67], v[180:183], v[212:215], v[64:67]
	s_setprio 0
	s_barrier
	s_add_i32 s30, s34, s38
	v_lshl_add_u64 v[216:217], v[216:217], 0, s[6:7]
	s_mov_b32 m0, s30
	ds_read_b128 v[184:187], v155 offset:49152
	ds_read_b128 v[188:191], v155 offset:50176
	ds_read_b128 v[192:195], v155 offset:51200
	ds_read_b128 v[196:199], v155 offset:52224
	ds_read_b128 v[200:203], v155 offset:53248
	ds_read_b128 v[204:207], v155 offset:54272
	ds_read_b128 v[208:211], v155 offset:55296
	ds_read_b128 v[212:215], v155 offset:56320
	global_load_lds_dwordx4 v[216:217], off
	s_add_i32 m0, s30, 0x2000
	s_add_u32 s28, s28, 0x40080
	v_lshl_add_u64 v[216:217], v[218:219], 0, s[6:7]
	s_addc_u32 s29, s29, 0
	s_add_i32 s30, s35, s38
	global_load_lds_dwordx4 v[216:217], off
	v_lshl_add_u64 v[216:217], s[28:29], 0, v[134:135]
	s_mov_b32 m0, s30
	s_nop 0
	global_load_lds_dwordx4 v[216:217], off
	v_lshl_add_u64 v[216:217], s[28:29], 0, v[130:131]
	s_add_i32 m0, s30, 0x2000
	s_nop 0
	global_load_lds_dwordx4 v[216:217], off
	v_lshl_add_u64 v[216:217], v[220:221], 0, s[6:7]
	s_mov_b32 m0, s45
	s_nop 0
	global_load_lds_dwordx4 v[216:217], off
	v_lshl_add_u64 v[216:217], v[222:223], 0, s[6:7]
	s_mov_b32 m0, s46
	s_nop 0
	global_load_lds_dwordx4 v[216:217], off
	s_waitcnt vmcnt(8)
	s_waitcnt lgkmcnt(0)
	s_barrier
	s_add_u32 s26, s26, 0x100
	s_addc_u32 s27, s27, 0
	s_add_u32 s54, s54, 0x100
	s_addc_u32 s55, s55, 0
	s_setprio 1
	s_waitcnt lgkmcnt(0)
	v_mfma_f32_16x16x32_bf16 v[60:63], v[146:149], v[184:187], v[60:63]
	v_mfma_f32_16x16x32_bf16 v[56:59], v[160:163], v[184:187], v[56:59]
	v_mfma_f32_16x16x32_bf16 v[44:47], v[146:149], v[192:195], v[44:47]
	v_mfma_f32_16x16x32_bf16 v[40:43], v[160:163], v[192:195], v[40:43]
	v_mfma_f32_16x16x32_bf16 v[28:31], v[146:149], v[200:203], v[28:31]
	v_mfma_f32_16x16x32_bf16 v[24:27], v[160:163], v[200:203], v[24:27]
	v_mfma_f32_16x16x32_bf16 v[12:15], v[146:149], v[208:211], v[12:15]
	v_mfma_f32_16x16x32_bf16 v[8:11], v[160:163], v[208:211], v[8:11]
	v_mfma_f32_16x16x32_bf16 v[60:63], v[156:159], v[188:191], v[60:63]
	v_mfma_f32_16x16x32_bf16 v[56:59], v[164:167], v[188:191], v[56:59]
	v_mfma_f32_16x16x32_bf16 v[44:47], v[156:159], v[196:199], v[44:47]
	v_mfma_f32_16x16x32_bf16 v[40:43], v[164:167], v[196:199], v[40:43]
	v_mfma_f32_16x16x32_bf16 v[28:31], v[156:159], v[204:207], v[28:31]
	v_mfma_f32_16x16x32_bf16 v[24:27], v[164:167], v[204:207], v[24:27]
	v_mfma_f32_16x16x32_bf16 v[12:15], v[156:159], v[212:215], v[12:15]
	v_mfma_f32_16x16x32_bf16 v[8:11], v[164:167], v[212:215], v[8:11]
	s_setprio 0
	s_setprio 1
	v_mfma_f32_16x16x32_bf16 v[52:55], v[168:171], v[184:187], v[52:55]
	v_mfma_f32_16x16x32_bf16 v[48:51], v[176:179], v[184:187], v[48:51]
	v_mfma_f32_16x16x32_bf16 v[36:39], v[168:171], v[192:195], v[36:39]
	v_mfma_f32_16x16x32_bf16 v[32:35], v[176:179], v[192:195], v[32:35]
	v_mfma_f32_16x16x32_bf16 v[20:23], v[168:171], v[200:203], v[20:23]
	v_mfma_f32_16x16x32_bf16 v[16:19], v[176:179], v[200:203], v[16:19]
	v_mfma_f32_16x16x32_bf16 v[4:7], v[168:171], v[208:211], v[4:7]
	v_mfma_f32_16x16x32_bf16 v[0:3], v[176:179], v[208:211], v[0:3]
	v_mfma_f32_16x16x32_bf16 v[52:55], v[172:175], v[188:191], v[52:55]
	v_mfma_f32_16x16x32_bf16 v[48:51], v[180:183], v[188:191], v[48:51]
	v_mfma_f32_16x16x32_bf16 v[36:39], v[172:175], v[196:199], v[36:39]
	v_mfma_f32_16x16x32_bf16 v[32:35], v[180:183], v[196:199], v[32:35]
	v_mfma_f32_16x16x32_bf16 v[20:23], v[172:175], v[204:207], v[20:23]
	v_mfma_f32_16x16x32_bf16 v[16:19], v[180:183], v[204:207], v[16:19]
	v_mfma_f32_16x16x32_bf16 v[4:7], v[172:175], v[212:215], v[4:7]
	v_mfma_f32_16x16x32_bf16 v[0:3], v[180:183], v[212:215], v[0:3]
	s_setprio 0
	s_cmp_eq_u32 s56, s98
	s_cbranch_scc1 .Lmy_nobar_22
	s_barrier
.Lmy_nobar_22:
	s_add_i32 s56, s56, 2
	s_cmp_gt_u32 s56, 13
	s_cbranch_scc0 .LBB0_2091
	s_and_b64 vcc, exec, s[8:9]
	s_cbranch_vccz .LBB0_2094
	s_nop 0

.Lmy_nobar2_23:
	ds_read_b128 v[144:147], v153
	ds_read_b128 v[156:159], v153 offset:1024
	ds_read_b128 v[160:163], v153 offset:2048
	ds_read_b128 v[164:167], v153 offset:3072
	ds_read_b128 v[168:171], v154
	ds_read_b128 v[172:175], v154 offset:1024
	ds_read_b128 v[176:179], v154 offset:2048
	ds_read_b128 v[180:183], v154 offset:3072
	s_add_u32 s30, s28, 0xfff50080
	s_addc_u32 s31, s29, -1
	s_cmp_eq_u32 s56, 40
	s_cselect_b32 s37, s1, s31
	s_cselect_b32 s36, s0, s30
	s_cselect_b32 s31, s27, s55
	s_cselect_b32 s30, s26, s54
	v_lshl_add_u64 v[148:149], s[28:29], 0, v[128:129]
	s_add_i32 m0, s41, 0xc000
	ds_read_b128 v[184:187], v155
	ds_read_b128 v[188:191], v155 offset:1024
	ds_read_b128 v[192:195], v155 offset:2048
	ds_read_b128 v[196:199], v155 offset:3072
	ds_read_b128 v[200:203], v155 offset:4096
	ds_read_b128 v[204:207], v155 offset:5120
	ds_read_b128 v[208:211], v155 offset:6144
	ds_read_b128 v[212:215], v155 offset:7168
	global_load_lds_dwordx4 v[148:149], off
	v_lshl_add_u64 v[148:149], s[28:29], 0, v[138:139]
	s_add_i32 m0, s41, 0xe000
	s_nop 0
	global_load_lds_dwordx4 v[148:149], off
	s_waitcnt vmcnt(8)
	s_waitcnt lgkmcnt(0)
	s_barrier
	s_setprio 1
	s_waitcnt lgkmcnt(0)
	v_mfma_f32_16x16x32_bf16 v[124:127], v[144:147], v[184:187], 0
	v_mfma_f32_16x16x32_bf16 v[120:123], v[160:163], v[184:187], 0
	v_mfma_f32_16x16x32_bf16 v[108:111], v[144:147], v[192:195], 0
	v_mfma_f32_16x16x32_bf16 v[104:107], v[160:163], v[192:195], 0
	v_mfma_f32_16x16x32_bf16 v[92:95], v[144:147], v[200:203], 0
	v_mfma_f32_16x16x32_bf16 v[88:91], v[160:163], v[200:203], 0
	v_mfma_f32_16x16x32_bf16 v[76:79], v[144:147], v[208:211], 0
	v_mfma_f32_16x16x32_bf16 v[72:75], v[160:163], v[208:211], 0
	v_mfma_f32_16x16x32_bf16 v[124:127], v[156:159], v[188:191], v[124:127]
	v_mfma_f32_16x16x32_bf16 v[120:123], v[164:167], v[188:191], v[120:123]
	v_mfma_f32_16x16x32_bf16 v[108:111], v[156:159], v[196:199], v[108:111]
	v_mfma_f32_16x16x32_bf16 v[104:107], v[164:167], v[196:199], v[104:107]
	v_mfma_f32_16x16x32_bf16 v[92:95], v[156:159], v[204:207], v[92:95]
	v_mfma_f32_16x16x32_bf16 v[88:91], v[164:167], v[204:207], v[88:91]
	v_mfma_f32_16x16x32_bf16 v[76:79], v[156:159], v[212:215], v[76:79]
	v_mfma_f32_16x16x32_bf16 v[72:75], v[164:167], v[212:215], v[72:75]
	s_setprio 0
	s_setprio 1
	v_mfma_f32_16x16x32_bf16 v[116:119], v[168:171], v[184:187], 0
	v_mfma_f32_16x16x32_bf16 v[112:115], v[176:179], v[184:187], 0
	v_mfma_f32_16x16x32_bf16 v[100:103], v[168:171], v[192:195], 0
	v_mfma_f32_16x16x32_bf16 v[96:99], v[176:179], v[192:195], 0
	v_mfma_f32_16x16x32_bf16 v[84:87], v[168:171], v[200:203], 0
	v_mfma_f32_16x16x32_bf16 v[80:83], v[176:179], v[200:203], 0
	v_mfma_f32_16x16x32_bf16 v[68:71], v[168:171], v[208:211], 0
	v_mfma_f32_16x16x32_bf16 v[64:67], v[176:179], v[208:211], 0
	v_mfma_f32_16x16x32_bf16 v[116:119], v[172:175], v[188:191], v[116:119]
	v_mfma_f32_16x16x32_bf16 v[112:115], v[180:183], v[188:191], v[112:115]
	v_mfma_f32_16x16x32_bf16 v[100:103], v[172:175], v[196:199], v[100:103]
	v_mfma_f32_16x16x32_bf16 v[96:99], v[180:183], v[196:199], v[96:99]
	v_mfma_f32_16x16x32_bf16 v[84:87], v[172:175], v[204:207], v[84:87]
	v_mfma_f32_16x16x32_bf16 v[80:83], v[180:183], v[204:207], v[80:83]
	v_mfma_f32_16x16x32_bf16 v[68:71], v[172:175], v[212:215], v[68:71]
	v_mfma_f32_16x16x32_bf16 v[64:67], v[180:183], v[212:215], v[64:67]
	s_setprio 0
	s_barrier
	s_add_i32 s34, s50, s40
	v_lshl_add_u64 v[148:149], s[30:31], 0, v[132:133]
	s_mov_b32 m0, s34
	ds_read_b128 v[184:187], v155 offset:16384
	ds_read_b128 v[188:191], v155 offset:17408
	ds_read_b128 v[192:195], v155 offset:18432
	ds_read_b128 v[196:199], v155 offset:19456
	ds_read_b128 v[200:203], v155 offset:20480
	ds_read_b128 v[204:207], v155 offset:21504
	ds_read_b128 v[208:211], v155 offset:22528
	ds_read_b128 v[212:215], v155 offset:23552
	global_load_lds_dwordx4 v[148:149], off
	s_add_i32 m0, s34, 0x2000
	s_add_u32 s34, s30, 0xb0000
	v_lshl_add_u64 v[216:217], s[30:31], 0, v[136:137]
	s_addc_u32 s35, s31, 0
	s_add_i32 s57, s51, s40
	global_load_lds_dwordx4 v[216:217], off
	v_lshl_add_u64 v[218:219], s[34:35], 0, v[132:133]
	s_mov_b32 m0, s57
	v_lshl_add_u64 v[220:221], s[36:37], 0, v[134:135]
	global_load_lds_dwordx4 v[218:219], off
	v_lshl_add_u64 v[218:219], s[34:35], 0, v[136:137]
	s_add_i32 m0, s57, 0x2000
	s_nop 0
	global_load_lds_dwordx4 v[218:219], off
	v_lshl_add_u64 v[218:219], s[36:37], 0, v[130:131]
	s_mov_b32 m0, s41
	s_nop 0
	global_load_lds_dwordx4 v[218:219], off
	s_mov_b32 m0, s42
	s_nop 0
	global_load_lds_dwordx4 v[220:221], off
	s_waitcnt vmcnt(8)
	s_waitcnt lgkmcnt(0)
	s_barrier
	s_setprio 1
	s_waitcnt lgkmcnt(0)
	v_mfma_f32_16x16x32_bf16 v[60:63], v[144:147], v[184:187], 0
	v_mfma_f32_16x16x32_bf16 v[56:59], v[160:163], v[184:187], 0
	v_mfma_f32_16x16x32_bf16 v[44:47], v[144:147], v[192:195], 0
	v_mfma_f32_16x16x32_bf16 v[40:43], v[160:163], v[192:195], 0
	v_mfma_f32_16x16x32_bf16 v[28:31], v[144:147], v[200:203], 0
	v_mfma_f32_16x16x32_bf16 v[24:27], v[160:163], v[200:203], 0
	v_mfma_f32_16x16x32_bf16 v[12:15], v[144:147], v[208:211], 0
	v_mfma_f32_16x16x32_bf16 v[8:11], v[160:163], v[208:211], 0
	v_mfma_f32_16x16x32_bf16 v[60:63], v[156:159], v[188:191], v[60:63]
	v_mfma_f32_16x16x32_bf16 v[56:59], v[164:167], v[188:191], v[56:59]
	v_mfma_f32_16x16x32_bf16 v[44:47], v[156:159], v[196:199], v[44:47]
	v_mfma_f32_16x16x32_bf16 v[40:43], v[164:167], v[196:199], v[40:43]
	v_mfma_f32_16x16x32_bf16 v[28:31], v[156:159], v[204:207], v[28:31]
	v_mfma_f32_16x16x32_bf16 v[24:27], v[164:167], v[204:207], v[24:27]
	v_mfma_f32_16x16x32_bf16 v[12:15], v[156:159], v[212:215], v[12:15]
	v_mfma_f32_16x16x32_bf16 v[8:11], v[164:167], v[212:215], v[8:11]
	s_setprio 0
	s_setprio 1
	v_mfma_f32_16x16x32_bf16 v[52:55], v[168:171], v[184:187], 0
	v_mfma_f32_16x16x32_bf16 v[48:51], v[176:179], v[184:187], 0
	v_mfma_f32_16x16x32_bf16 v[36:39], v[168:171], v[192:195], 0
	v_mfma_f32_16x16x32_bf16 v[32:35], v[176:179], v[192:195], 0
	v_mfma_f32_16x16x32_bf16 v[20:23], v[168:171], v[200:203], 0
	v_mfma_f32_16x16x32_bf16 v[16:19], v[176:179], v[200:203], 0
	v_mfma_f32_16x16x32_bf16 v[4:7], v[168:171], v[208:211], 0
	v_mfma_f32_16x16x32_bf16 v[0:3], v[176:179], v[208:211], 0
	v_mfma_f32_16x16x32_bf16 v[52:55], v[172:175], v[188:191], v[52:55]
	v_mfma_f32_16x16x32_bf16 v[48:51], v[180:183], v[188:191], v[48:51]
	v_mfma_f32_16x16x32_bf16 v[36:39], v[172:175], v[196:199], v[36:39]
	v_mfma_f32_16x16x32_bf16 v[32:35], v[180:183], v[196:199], v[32:35]
	v_mfma_f32_16x16x32_bf16 v[20:23], v[172:175], v[204:207], v[20:23]
	v_mfma_f32_16x16x32_bf16 v[16:19], v[180:183], v[204:207], v[16:19]
	v_mfma_f32_16x16x32_bf16 v[4:7], v[172:175], v[212:215], v[4:7]
	v_mfma_f32_16x16x32_bf16 v[0:3], v[180:183], v[212:215], v[0:3]
	s_setprio 0
	s_barrier
	s_add_i32 s57, 0, 0x18000
	s_add_i32 s58, 0, 0x1c000
	v_add_u32_e32 v164, s57, v151
	v_add_u32_e32 v180, s58, v151
	ds_read_b128 v[144:147], v164
	ds_read_b128 v[156:159], v164 offset:1024
	ds_read_b128 v[160:163], v164 offset:2048
	ds_read_b128 v[164:167], v164 offset:3072
	ds_read_b128 v[168:171], v180
	ds_read_b128 v[172:175], v180 offset:1024
	ds_read_b128 v[176:179], v180 offset:2048
	ds_read_b128 v[180:183], v180 offset:3072
	s_add_u32 s34, s36, 0xb0000
	s_addc_u32 s35, s37, 0
	s_mov_b32 m0, s43
	v_lshl_add_u64 v[222:223], s[34:35], 0, v[130:131]
	ds_read_b128 v[184:187], v155 offset:32768
	ds_read_b128 v[188:191], v155 offset:33792
	ds_read_b128 v[192:195], v155 offset:34816
	ds_read_b128 v[196:199], v155 offset:35840
	ds_read_b128 v[200:203], v155 offset:36864
	ds_read_b128 v[204:207], v155 offset:37888
	ds_read_b128 v[208:211], v155 offset:38912
	ds_read_b128 v[212:215], v155 offset:39936
	global_load_lds_dwordx4 v[222:223], off
	v_lshl_add_u64 v[222:223], s[34:35], 0, v[134:135]
	s_mov_b32 m0, s44
	s_nop 0
	global_load_lds_dwordx4 v[222:223], off
	s_waitcnt vmcnt(8)
	s_waitcnt lgkmcnt(0)
	s_barrier
	s_setprio 1
	s_waitcnt lgkmcnt(0)
	v_mfma_f32_16x16x32_bf16 v[124:127], v[144:147], v[184:187], v[124:127]
	v_mfma_f32_16x16x32_bf16 v[120:123], v[160:163], v[184:187], v[120:123]
	v_mfma_f32_16x16x32_bf16 v[108:111], v[144:147], v[192:195], v[108:111]
	v_mfma_f32_16x16x32_bf16 v[104:107], v[160:163], v[192:195], v[104:107]
	v_mfma_f32_16x16x32_bf16 v[92:95], v[144:147], v[200:203], v[92:95]
	v_mfma_f32_16x16x32_bf16 v[88:91], v[160:163], v[200:203], v[88:91]
	v_mfma_f32_16x16x32_bf16 v[76:79], v[144:147], v[208:211], v[76:79]
	v_mfma_f32_16x16x32_bf16 v[72:75], v[160:163], v[208:211], v[72:75]
	v_mfma_f32_16x16x32_bf16 v[124:127], v[156:159], v[188:191], v[124:127]
	v_mfma_f32_16x16x32_bf16 v[120:123], v[164:167], v[188:191], v[120:123]
	v_mfma_f32_16x16x32_bf16 v[108:111], v[156:159], v[196:199], v[108:111]
	v_mfma_f32_16x16x32_bf16 v[104:107], v[164:167], v[196:199], v[104:107]
	v_mfma_f32_16x16x32_bf16 v[92:95], v[156:159], v[204:207], v[92:95]
	v_mfma_f32_16x16x32_bf16 v[88:91], v[164:167], v[204:207], v[88:91]
	v_mfma_f32_16x16x32_bf16 v[76:79], v[156:159], v[212:215], v[76:79]
	v_mfma_f32_16x16x32_bf16 v[72:75], v[164:167], v[212:215], v[72:75]
	s_setprio 0
	s_setprio 1
	v_mfma_f32_16x16x32_bf16 v[116:119], v[168:171], v[184:187], v[116:119]
	v_mfma_f32_16x16x32_bf16 v[112:115], v[176:179], v[184:187], v[112:115]
	v_mfma_f32_16x16x32_bf16 v[100:103], v[168:171], v[192:195], v[100:103]
	v_mfma_f32_16x16x32_bf16 v[96:99], v[176:179], v[192:195], v[96:99]
	v_mfma_f32_16x16x32_bf16 v[84:87], v[168:171], v[200:203], v[84:87]
	v_mfma_f32_16x16x32_bf16 v[80:83], v[176:179], v[200:203], v[80:83]
	v_mfma_f32_16x16x32_bf16 v[68:71], v[168:171], v[208:211], v[68:71]
	v_mfma_f32_16x16x32_bf16 v[64:67], v[176:179], v[208:211], v[64:67]
	v_mfma_f32_16x16x32_bf16 v[116:119], v[172:175], v[188:191], v[116:119]
	v_mfma_f32_16x16x32_bf16 v[112:115], v[180:183], v[188:191], v[112:115]
	v_mfma_f32_16x16x32_bf16 v[100:103], v[172:175], v[196:199], v[100:103]
	v_mfma_f32_16x16x32_bf16 v[96:99], v[180:183], v[196:199], v[96:99]
	v_mfma_f32_16x16x32_bf16 v[84:87], v[172:175], v[204:207], v[84:87]
	v_mfma_f32_16x16x32_bf16 v[80:83], v[180:183], v[204:207], v[80:83]
	v_mfma_f32_16x16x32_bf16 v[68:71], v[172:175], v[212:215], v[68:71]
	v_mfma_f32_16x16x32_bf16 v[64:67], v[180:183], v[212:215], v[64:67]
	s_setprio 0
	s_barrier
	s_add_i32 s34, s57, s40
	v_lshl_add_u64 v[148:149], v[148:149], 0, s[8:9]
	s_mov_b32 m0, s34
	ds_read_b128 v[184:187], v155 offset:49152
	ds_read_b128 v[188:191], v155 offset:50176
	ds_read_b128 v[192:195], v155 offset:51200
	ds_read_b128 v[196:199], v155 offset:52224
	ds_read_b128 v[200:203], v155 offset:53248
	ds_read_b128 v[204:207], v155 offset:54272
	ds_read_b128 v[208:211], v155 offset:55296
	ds_read_b128 v[212:215], v155 offset:56320
	global_load_lds_dwordx4 v[148:149], off
	s_add_i32 m0, s34, 0x2000
	s_add_u32 s30, s30, 0xb0080
	v_lshl_add_u64 v[148:149], v[216:217], 0, s[8:9]
	s_addc_u32 s31, s31, 0
	s_add_i32 s34, s58, s40
	global_load_lds_dwordx4 v[148:149], off
	v_lshl_add_u64 v[148:149], s[30:31], 0, v[132:133]
	s_mov_b32 m0, s34
	s_nop 0
	global_load_lds_dwordx4 v[148:149], off
	v_lshl_add_u64 v[148:149], s[30:31], 0, v[136:137]
	s_add_i32 m0, s34, 0x2000
	s_nop 0
	global_load_lds_dwordx4 v[148:149], off
	v_lshl_add_u64 v[148:149], v[218:219], 0, s[8:9]
	s_mov_b32 m0, s46
	s_nop 0
	global_load_lds_dwordx4 v[148:149], off
	v_lshl_add_u64 v[148:149], v[220:221], 0, s[8:9]
	s_mov_b32 m0, s47
	s_nop 0
	global_load_lds_dwordx4 v[148:149], off
	s_waitcnt vmcnt(8)
	s_waitcnt lgkmcnt(0)
	s_barrier
	s_add_u32 s28, s28, 0x100
	s_addc_u32 s29, s29, 0
	s_add_u32 s54, s54, 0x100
	s_addc_u32 s55, s55, 0
	s_setprio 1
	s_waitcnt lgkmcnt(0)
	v_mfma_f32_16x16x32_bf16 v[60:63], v[144:147], v[184:187], v[60:63]
	v_mfma_f32_16x16x32_bf16 v[56:59], v[160:163], v[184:187], v[56:59]
	v_mfma_f32_16x16x32_bf16 v[44:47], v[144:147], v[192:195], v[44:47]
	v_mfma_f32_16x16x32_bf16 v[40:43], v[160:163], v[192:195], v[40:43]
	v_mfma_f32_16x16x32_bf16 v[28:31], v[144:147], v[200:203], v[28:31]
	v_mfma_f32_16x16x32_bf16 v[24:27], v[160:163], v[200:203], v[24:27]
	v_mfma_f32_16x16x32_bf16 v[12:15], v[144:147], v[208:211], v[12:15]
	v_mfma_f32_16x16x32_bf16 v[8:11], v[160:163], v[208:211], v[8:11]
	v_mfma_f32_16x16x32_bf16 v[60:63], v[156:159], v[188:191], v[60:63]
	v_mfma_f32_16x16x32_bf16 v[56:59], v[164:167], v[188:191], v[56:59]
	v_mfma_f32_16x16x32_bf16 v[44:47], v[156:159], v[196:199], v[44:47]
	v_mfma_f32_16x16x32_bf16 v[40:43], v[164:167], v[196:199], v[40:43]
	v_mfma_f32_16x16x32_bf16 v[28:31], v[156:159], v[204:207], v[28:31]
	v_mfma_f32_16x16x32_bf16 v[24:27], v[164:167], v[204:207], v[24:27]
	v_mfma_f32_16x16x32_bf16 v[12:15], v[156:159], v[212:215], v[12:15]
	v_mfma_f32_16x16x32_bf16 v[8:11], v[164:167], v[212:215], v[8:11]
	s_setprio 0
	s_setprio 1
	v_mfma_f32_16x16x32_bf16 v[52:55], v[168:171], v[184:187], v[52:55]
	v_mfma_f32_16x16x32_bf16 v[48:51], v[176:179], v[184:187], v[48:51]
	v_mfma_f32_16x16x32_bf16 v[36:39], v[168:171], v[192:195], v[36:39]
	v_mfma_f32_16x16x32_bf16 v[32:35], v[176:179], v[192:195], v[32:35]
	v_mfma_f32_16x16x32_bf16 v[20:23], v[168:171], v[200:203], v[20:23]
	v_mfma_f32_16x16x32_bf16 v[16:19], v[176:179], v[200:203], v[16:19]
	v_mfma_f32_16x16x32_bf16 v[4:7], v[168:171], v[208:211], v[4:7]
	v_mfma_f32_16x16x32_bf16 v[0:3], v[176:179], v[208:211], v[0:3]
	v_mfma_f32_16x16x32_bf16 v[52:55], v[172:175], v[188:191], v[52:55]
	v_mfma_f32_16x16x32_bf16 v[48:51], v[180:183], v[188:191], v[48:51]
	v_mfma_f32_16x16x32_bf16 v[36:39], v[172:175], v[196:199], v[36:39]
	v_mfma_f32_16x16x32_bf16 v[32:35], v[180:183], v[196:199], v[32:35]
	v_mfma_f32_16x16x32_bf16 v[20:23], v[172:175], v[204:207], v[20:23]
	v_mfma_f32_16x16x32_bf16 v[16:19], v[180:183], v[204:207], v[16:19]
	v_mfma_f32_16x16x32_bf16 v[4:7], v[172:175], v[212:215], v[4:7]
	v_mfma_f32_16x16x32_bf16 v[0:3], v[180:183], v[212:215], v[0:3]
	s_setprio 0
	s_barrier
	s_add_i32 s56, s56, 2
.LBB0_2174:
	ds_read_b128 v[144:147], v153
	ds_read_b128 v[156:159], v153 offset:1024
	ds_read_b128 v[160:163], v153 offset:2048
	ds_read_b128 v[164:167], v153 offset:3072
	ds_read_b128 v[168:171], v154
	ds_read_b128 v[172:175], v154 offset:1024
	ds_read_b128 v[176:179], v154 offset:2048
	ds_read_b128 v[180:183], v154 offset:3072
	s_add_u32 s30, s28, 0xfff50080
	s_addc_u32 s31, s29, -1
	s_cmp_eq_u32 s56, 40
	s_cselect_b32 s37, s1, s31
	s_cselect_b32 s36, s0, s30
	s_cselect_b32 s31, s27, s55
	s_cselect_b32 s30, s26, s54
	v_lshl_add_u64 v[148:149], s[28:29], 0, v[128:129]
	s_add_i32 m0, s41, 0xc000
	ds_read_b128 v[184:187], v155
	ds_read_b128 v[188:191], v155 offset:1024
	ds_read_b128 v[192:195], v155 offset:2048
	ds_read_b128 v[196:199], v155 offset:3072
	ds_read_b128 v[200:203], v155 offset:4096
	ds_read_b128 v[204:207], v155 offset:5120
	ds_read_b128 v[208:211], v155 offset:6144
	ds_read_b128 v[212:215], v155 offset:7168
	global_load_lds_dwordx4 v[148:149], off
	v_lshl_add_u64 v[148:149], s[28:29], 0, v[138:139]
	s_add_i32 m0, s41, 0xe000
	s_nop 0
	global_load_lds_dwordx4 v[148:149], off
	s_waitcnt vmcnt(8)
	s_waitcnt lgkmcnt(0)
	s_barrier
	s_setprio 1
	s_waitcnt lgkmcnt(0)
	v_mfma_f32_16x16x32_bf16 v[124:127], v[144:147], v[184:187], v[124:127]
	v_mfma_f32_16x16x32_bf16 v[120:123], v[160:163], v[184:187], v[120:123]
	v_mfma_f32_16x16x32_bf16 v[108:111], v[144:147], v[192:195], v[108:111]
	v_mfma_f32_16x16x32_bf16 v[104:107], v[160:163], v[192:195], v[104:107]
	v_mfma_f32_16x16x32_bf16 v[92:95], v[144:147], v[200:203], v[92:95]
	v_mfma_f32_16x16x32_bf16 v[88:91], v[160:163], v[200:203], v[88:91]
	v_mfma_f32_16x16x32_bf16 v[76:79], v[144:147], v[208:211], v[76:79]
	v_mfma_f32_16x16x32_bf16 v[72:75], v[160:163], v[208:211], v[72:75]
	v_mfma_f32_16x16x32_bf16 v[124:127], v[156:159], v[188:191], v[124:127]
	v_mfma_f32_16x16x32_bf16 v[120:123], v[164:167], v[188:191], v[120:123]
	v_mfma_f32_16x16x32_bf16 v[108:111], v[156:159], v[196:199], v[108:111]
	v_mfma_f32_16x16x32_bf16 v[104:107], v[164:167], v[196:199], v[104:107]
	v_mfma_f32_16x16x32_bf16 v[92:95], v[156:159], v[204:207], v[92:95]
	v_mfma_f32_16x16x32_bf16 v[88:91], v[164:167], v[204:207], v[88:91]
	v_mfma_f32_16x16x32_bf16 v[76:79], v[156:159], v[212:215], v[76:79]
	v_mfma_f32_16x16x32_bf16 v[72:75], v[164:167], v[212:215], v[72:75]
	s_setprio 0
	s_setprio 1
	v_mfma_f32_16x16x32_bf16 v[116:119], v[168:171], v[184:187], v[116:119]
	v_mfma_f32_16x16x32_bf16 v[112:115], v[176:179], v[184:187], v[112:115]
	v_mfma_f32_16x16x32_bf16 v[100:103], v[168:171], v[192:195], v[100:103]
	v_mfma_f32_16x16x32_bf16 v[96:99], v[176:179], v[192:195], v[96:99]
	v_mfma_f32_16x16x32_bf16 v[84:87], v[168:171], v[200:203], v[84:87]
	v_mfma_f32_16x16x32_bf16 v[80:83], v[176:179], v[200:203], v[80:83]
	v_mfma_f32_16x16x32_bf16 v[68:71], v[168:171], v[208:211], v[68:71]
	v_mfma_f32_16x16x32_bf16 v[64:67], v[176:179], v[208:211], v[64:67]
	v_mfma_f32_16x16x32_bf16 v[116:119], v[172:175], v[188:191], v[116:119]
	v_mfma_f32_16x16x32_bf16 v[112:115], v[180:183], v[188:191], v[112:115]
	v_mfma_f32_16x16x32_bf16 v[100:103], v[172:175], v[196:199], v[100:103]
	v_mfma_f32_16x16x32_bf16 v[96:99], v[180:183], v[196:199], v[96:99]
	v_mfma_f32_16x16x32_bf16 v[84:87], v[172:175], v[204:207], v[84:87]
	v_mfma_f32_16x16x32_bf16 v[80:83], v[180:183], v[204:207], v[80:83]
	v_mfma_f32_16x16x32_bf16 v[68:71], v[172:175], v[212:215], v[68:71]
	v_mfma_f32_16x16x32_bf16 v[64:67], v[180:183], v[212:215], v[64:67]
	s_setprio 0
	s_barrier
	s_add_i32 s34, s50, s40
	v_lshl_add_u64 v[148:149], s[30:31], 0, v[132:133]
	s_mov_b32 m0, s34
	ds_read_b128 v[184:187], v155 offset:16384
	ds_read_b128 v[188:191], v155 offset:17408
	ds_read_b128 v[192:195], v155 offset:18432
	ds_read_b128 v[196:199], v155 offset:19456
	ds_read_b128 v[200:203], v155 offset:20480
	ds_read_b128 v[204:207], v155 offset:21504
	ds_read_b128 v[208:211], v155 offset:22528
	ds_read_b128 v[212:215], v155 offset:23552
	global_load_lds_dwordx4 v[148:149], off
	s_add_i32 m0, s34, 0x2000
	s_add_u32 s34, s30, 0xb0000
	v_lshl_add_u64 v[216:217], s[30:31], 0, v[136:137]
	s_addc_u32 s35, s31, 0
	s_add_i32 s57, s51, s40
	global_load_lds_dwordx4 v[216:217], off
	v_lshl_add_u64 v[218:219], s[34:35], 0, v[132:133]
	s_mov_b32 m0, s57
	v_lshl_add_u64 v[220:221], s[36:37], 0, v[134:135]
	global_load_lds_dwordx4 v[218:219], off
	v_lshl_add_u64 v[218:219], s[34:35], 0, v[136:137]
	s_add_i32 m0, s57, 0x2000
	s_nop 0
	global_load_lds_dwordx4 v[218:219], off
	v_lshl_add_u64 v[218:219], s[36:37], 0, v[130:131]
	s_mov_b32 m0, s41
	s_nop 0
	global_load_lds_dwordx4 v[218:219], off
	s_mov_b32 m0, s42
	s_nop 0
	global_load_lds_dwordx4 v[220:221], off
	s_waitcnt vmcnt(8)
	s_waitcnt lgkmcnt(0)
	s_barrier
	s_setprio 1
	s_waitcnt lgkmcnt(0)
	v_mfma_f32_16x16x32_bf16 v[60:63], v[144:147], v[184:187], v[60:63]
	v_mfma_f32_16x16x32_bf16 v[56:59], v[160:163], v[184:187], v[56:59]
	v_mfma_f32_16x16x32_bf16 v[44:47], v[144:147], v[192:195], v[44:47]
	v_mfma_f32_16x16x32_bf16 v[40:43], v[160:163], v[192:195], v[40:43]
	v_mfma_f32_16x16x32_bf16 v[28:31], v[144:147], v[200:203], v[28:31]
	v_mfma_f32_16x16x32_bf16 v[24:27], v[160:163], v[200:203], v[24:27]
	v_mfma_f32_16x16x32_bf16 v[12:15], v[144:147], v[208:211], v[12:15]
	v_mfma_f32_16x16x32_bf16 v[8:11], v[160:163], v[208:211], v[8:11]
	v_mfma_f32_16x16x32_bf16 v[60:63], v[156:159], v[188:191], v[60:63]
	v_mfma_f32_16x16x32_bf16 v[56:59], v[164:167], v[188:191], v[56:59]
	v_mfma_f32_16x16x32_bf16 v[44:47], v[156:159], v[196:199], v[44:47]
	v_mfma_f32_16x16x32_bf16 v[40:43], v[164:167], v[196:199], v[40:43]
	v_mfma_f32_16x16x32_bf16 v[28:31], v[156:159], v[204:207], v[28:31]
	v_mfma_f32_16x16x32_bf16 v[24:27], v[164:167], v[204:207], v[24:27]
	v_mfma_f32_16x16x32_bf16 v[12:15], v[156:159], v[212:215], v[12:15]
	v_mfma_f32_16x16x32_bf16 v[8:11], v[164:167], v[212:215], v[8:11]
	s_setprio 0
	s_setprio 1
	v_mfma_f32_16x16x32_bf16 v[52:55], v[168:171], v[184:187], v[52:55]
	v_mfma_f32_16x16x32_bf16 v[48:51], v[176:179], v[184:187], v[48:51]
	v_mfma_f32_16x16x32_bf16 v[36:39], v[168:171], v[192:195], v[36:39]
	v_mfma_f32_16x16x32_bf16 v[32:35], v[176:179], v[192:195], v[32:35]
	v_mfma_f32_16x16x32_bf16 v[20:23], v[168:171], v[200:203], v[20:23]
	v_mfma_f32_16x16x32_bf16 v[16:19], v[176:179], v[200:203], v[16:19]
	v_mfma_f32_16x16x32_bf16 v[4:7], v[168:171], v[208:211], v[4:7]
	v_mfma_f32_16x16x32_bf16 v[0:3], v[176:179], v[208:211], v[0:3]
	v_mfma_f32_16x16x32_bf16 v[52:55], v[172:175], v[188:191], v[52:55]
	v_mfma_f32_16x16x32_bf16 v[48:51], v[180:183], v[188:191], v[48:51]
	v_mfma_f32_16x16x32_bf16 v[36:39], v[172:175], v[196:199], v[36:39]
	v_mfma_f32_16x16x32_bf16 v[32:35], v[180:183], v[196:199], v[32:35]
	v_mfma_f32_16x16x32_bf16 v[20:23], v[172:175], v[204:207], v[20:23]
	v_mfma_f32_16x16x32_bf16 v[16:19], v[180:183], v[204:207], v[16:19]
	v_mfma_f32_16x16x32_bf16 v[4:7], v[172:175], v[212:215], v[4:7]
	v_mfma_f32_16x16x32_bf16 v[0:3], v[180:183], v[212:215], v[0:3]
	s_setprio 0
	s_barrier
	s_add_i32 s57, 0, 0x18000
	s_add_i32 s58, 0, 0x1c000
	v_add_u32_e32 v164, s57, v151
	v_add_u32_e32 v180, s58, v151
	ds_read_b128 v[144:147], v164
	ds_read_b128 v[156:159], v164 offset:1024
	ds_read_b128 v[160:163], v164 offset:2048
	ds_read_b128 v[164:167], v164 offset:3072
	ds_read_b128 v[168:171], v180
	ds_read_b128 v[172:175], v180 offset:1024
	ds_read_b128 v[176:179], v180 offset:2048
	ds_read_b128 v[180:183], v180 offset:3072
	s_add_u32 s34, s36, 0xb0000
	s_addc_u32 s35, s37, 0
	s_mov_b32 m0, s43
	v_lshl_add_u64 v[222:223], s[34:35], 0, v[130:131]
	ds_read_b128 v[184:187], v155 offset:32768
	ds_read_b128 v[188:191], v155 offset:33792
	ds_read_b128 v[192:195], v155 offset:34816
	ds_read_b128 v[196:199], v155 offset:35840
	ds_read_b128 v[200:203], v155 offset:36864
	ds_read_b128 v[204:207], v155 offset:37888
	ds_read_b128 v[208:211], v155 offset:38912
	ds_read_b128 v[212:215], v155 offset:39936
	global_load_lds_dwordx4 v[222:223], off
	v_lshl_add_u64 v[222:223], s[34:35], 0, v[134:135]
	s_mov_b32 m0, s44
	s_nop 0
	global_load_lds_dwordx4 v[222:223], off
	s_waitcnt vmcnt(8)
	s_waitcnt lgkmcnt(0)
	s_barrier
	s_setprio 1
	s_waitcnt lgkmcnt(0)
	v_mfma_f32_16x16x32_bf16 v[124:127], v[144:147], v[184:187], v[124:127]
	v_mfma_f32_16x16x32_bf16 v[120:123], v[160:163], v[184:187], v[120:123]
	v_mfma_f32_16x16x32_bf16 v[108:111], v[144:147], v[192:195], v[108:111]
	v_mfma_f32_16x16x32_bf16 v[104:107], v[160:163], v[192:195], v[104:107]
	v_mfma_f32_16x16x32_bf16 v[92:95], v[144:147], v[200:203], v[92:95]
	v_mfma_f32_16x16x32_bf16 v[88:91], v[160:163], v[200:203], v[88:91]
	v_mfma_f32_16x16x32_bf16 v[76:79], v[144:147], v[208:211], v[76:79]
	v_mfma_f32_16x16x32_bf16 v[72:75], v[160:163], v[208:211], v[72:75]
	v_mfma_f32_16x16x32_bf16 v[124:127], v[156:159], v[188:191], v[124:127]
	v_mfma_f32_16x16x32_bf16 v[120:123], v[164:167], v[188:191], v[120:123]
	v_mfma_f32_16x16x32_bf16 v[108:111], v[156:159], v[196:199], v[108:111]
	v_mfma_f32_16x16x32_bf16 v[104:107], v[164:167], v[196:199], v[104:107]
	v_mfma_f32_16x16x32_bf16 v[92:95], v[156:159], v[204:207], v[92:95]
	v_mfma_f32_16x16x32_bf16 v[88:91], v[164:167], v[204:207], v[88:91]
	v_mfma_f32_16x16x32_bf16 v[76:79], v[156:159], v[212:215], v[76:79]
	v_mfma_f32_16x16x32_bf16 v[72:75], v[164:167], v[212:215], v[72:75]
	s_setprio 0
	s_setprio 1
	v_mfma_f32_16x16x32_bf16 v[116:119], v[168:171], v[184:187], v[116:119]
	v_mfma_f32_16x16x32_bf16 v[112:115], v[176:179], v[184:187], v[112:115]
	v_mfma_f32_16x16x32_bf16 v[100:103], v[168:171], v[192:195], v[100:103]
	v_mfma_f32_16x16x32_bf16 v[96:99], v[176:179], v[192:195], v[96:99]
	v_mfma_f32_16x16x32_bf16 v[84:87], v[168:171], v[200:203], v[84:87]
	v_mfma_f32_16x16x32_bf16 v[80:83], v[176:179], v[200:203], v[80:83]
	v_mfma_f32_16x16x32_bf16 v[68:71], v[168:171], v[208:211], v[68:71]
	v_mfma_f32_16x16x32_bf16 v[64:67], v[176:179], v[208:211], v[64:67]
	v_mfma_f32_16x16x32_bf16 v[116:119], v[172:175], v[188:191], v[116:119]
	v_mfma_f32_16x16x32_bf16 v[112:115], v[180:183], v[188:191], v[112:115]
	v_mfma_f32_16x16x32_bf16 v[100:103], v[172:175], v[196:199], v[100:103]
	v_mfma_f32_16x16x32_bf16 v[96:99], v[180:183], v[196:199], v[96:99]
	v_mfma_f32_16x16x32_bf16 v[84:87], v[172:175], v[204:207], v[84:87]
	v_mfma_f32_16x16x32_bf16 v[80:83], v[180:183], v[204:207], v[80:83]
	v_mfma_f32_16x16x32_bf16 v[68:71], v[172:175], v[212:215], v[68:71]
	v_mfma_f32_16x16x32_bf16 v[64:67], v[180:183], v[212:215], v[64:67]
	s_setprio 0
	s_barrier
	s_add_i32 s34, s57, s40
	v_lshl_add_u64 v[148:149], v[148:149], 0, s[8:9]
	s_mov_b32 m0, s34
	ds_read_b128 v[184:187], v155 offset:49152
	ds_read_b128 v[188:191], v155 offset:50176
	ds_read_b128 v[192:195], v155 offset:51200
	ds_read_b128 v[196:199], v155 offset:52224
	ds_read_b128 v[200:203], v155 offset:53248
	ds_read_b128 v[204:207], v155 offset:54272
	ds_read_b128 v[208:211], v155 offset:55296
	ds_read_b128 v[212:215], v155 offset:56320
	global_load_lds_dwordx4 v[148:149], off
	s_add_i32 m0, s34, 0x2000
	s_add_u32 s30, s30, 0xb0080
	v_lshl_add_u64 v[148:149], v[216:217], 0, s[8:9]
	s_addc_u32 s31, s31, 0
	s_add_i32 s34, s58, s40
	global_load_lds_dwordx4 v[148:149], off
	v_lshl_add_u64 v[148:149], s[30:31], 0, v[132:133]
	s_mov_b32 m0, s34
	s_nop 0
	global_load_lds_dwordx4 v[148:149], off
	v_lshl_add_u64 v[148:149], s[30:31], 0, v[136:137]
	s_add_i32 m0, s34, 0x2000
	s_nop 0
	global_load_lds_dwordx4 v[148:149], off
	v_lshl_add_u64 v[148:149], v[218:219], 0, s[8:9]
	s_mov_b32 m0, s46
	s_nop 0
	global_load_lds_dwordx4 v[148:149], off
	v_lshl_add_u64 v[148:149], v[220:221], 0, s[8:9]
	s_mov_b32 m0, s47
	s_nop 0
	global_load_lds_dwordx4 v[148:149], off
	s_waitcnt vmcnt(8)
	s_waitcnt lgkmcnt(0)
	s_barrier
	s_add_u32 s28, s28, 0x100
	s_addc_u32 s29, s29, 0
	s_add_u32 s54, s54, 0x100
	s_addc_u32 s55, s55, 0
	s_setprio 1
	s_waitcnt lgkmcnt(0)
	v_mfma_f32_16x16x32_bf16 v[60:63], v[144:147], v[184:187], v[60:63]
	v_mfma_f32_16x16x32_bf16 v[56:59], v[160:163], v[184:187], v[56:59]
	v_mfma_f32_16x16x32_bf16 v[44:47], v[144:147], v[192:195], v[44:47]
	v_mfma_f32_16x16x32_bf16 v[40:43], v[160:163], v[192:195], v[40:43]
	v_mfma_f32_16x16x32_bf16 v[28:31], v[144:147], v[200:203], v[28:31]
	v_mfma_f32_16x16x32_bf16 v[24:27], v[160:163], v[200:203], v[24:27]
	v_mfma_f32_16x16x32_bf16 v[12:15], v[144:147], v[208:211], v[12:15]
	v_mfma_f32_16x16x32_bf16 v[8:11], v[160:163], v[208:211], v[8:11]
	v_mfma_f32_16x16x32_bf16 v[60:63], v[156:159], v[188:191], v[60:63]
	v_mfma_f32_16x16x32_bf16 v[56:59], v[164:167], v[188:191], v[56:59]
	v_mfma_f32_16x16x32_bf16 v[44:47], v[156:159], v[196:199], v[44:47]
	v_mfma_f32_16x16x32_bf16 v[40:43], v[164:167], v[196:199], v[40:43]
	v_mfma_f32_16x16x32_bf16 v[28:31], v[156:159], v[204:207], v[28:31]
	v_mfma_f32_16x16x32_bf16 v[24:27], v[164:167], v[204:207], v[24:27]
	v_mfma_f32_16x16x32_bf16 v[12:15], v[156:159], v[212:215], v[12:15]
	v_mfma_f32_16x16x32_bf16 v[8:11], v[164:167], v[212:215], v[8:11]
	s_setprio 0
	s_setprio 1
	v_mfma_f32_16x16x32_bf16 v[52:55], v[168:171], v[184:187], v[52:55]
	v_mfma_f32_16x16x32_bf16 v[48:51], v[176:179], v[184:187], v[48:51]
	v_mfma_f32_16x16x32_bf16 v[36:39], v[168:171], v[192:195], v[36:39]
	v_mfma_f32_16x16x32_bf16 v[32:35], v[176:179], v[192:195], v[32:35]
	v_mfma_f32_16x16x32_bf16 v[20:23], v[168:171], v[200:203], v[20:23]
	v_mfma_f32_16x16x32_bf16 v[16:19], v[176:179], v[200:203], v[16:19]
	v_mfma_f32_16x16x32_bf16 v[4:7], v[168:171], v[208:211], v[4:7]
	v_mfma_f32_16x16x32_bf16 v[0:3], v[176:179], v[208:211], v[0:3]
	v_mfma_f32_16x16x32_bf16 v[52:55], v[172:175], v[188:191], v[52:55]
	v_mfma_f32_16x16x32_bf16 v[48:51], v[180:183], v[188:191], v[48:51]
	v_mfma_f32_16x16x32_bf16 v[36:39], v[172:175], v[196:199], v[36:39]
	v_mfma_f32_16x16x32_bf16 v[32:35], v[180:183], v[196:199], v[32:35]
	v_mfma_f32_16x16x32_bf16 v[20:23], v[172:175], v[204:207], v[20:23]
	v_mfma_f32_16x16x32_bf16 v[16:19], v[180:183], v[204:207], v[16:19]
	v_mfma_f32_16x16x32_bf16 v[4:7], v[172:175], v[212:215], v[4:7]
	v_mfma_f32_16x16x32_bf16 v[0:3], v[180:183], v[212:215], v[0:3]
	s_setprio 0
	s_cmp_eq_u32 s56, s98
	s_cbranch_scc1 .Lmy_nobar_23
	s_barrier
.Lmy_nobar_23:
	s_add_i32 s56, s56, 2
	s_cmp_gt_u32 s56, 41
	s_cbranch_scc0 .LBB0_2174
	s_and_b64 vcc, exec, s[10:11]
	s_cbranch_vccz .LBB0_2177
	s_nop 0
